# GEMM K-loops: fragment ds_reads ordered by first use with counted lgkmcnt waits per MFMA group (was one full drain before 16 MFMAs)
# speedup vs baseline: 1.0329x; 1.0033x over previous
.LBB0_259:
	s_and_b32 s8, s7, 0x4000
	s_xor_b32 s9, s8, 0x4000
	s_lshl_b32 s9, s9, 1
	s_add_i32 s9, s9, 32
	s_add_u32 s90, s52, s4
	s_addc_u32 s91, s53, s5
	s_add_i32 m0, s9, s82
	s_lshl_b32 s8, s8, 1
	global_load_lds_dwordx4 v184, s[90:91]
	s_add_i32 m0, s9, s83
	s_add_i32 s8, s8, 32
	global_load_lds_dwordx4 v185, s[90:91]
	s_add_i32 m0, s9, s84
	v_lshl_add_u32 v64, v120, 1, s8
	global_load_lds_dwordx4 v186, s[90:91]
	s_add_i32 m0, s9, s85
	v_lshl_add_u32 v95, v121, 1, s8
	global_load_lds_dwordx4 v187, s[90:91]
	s_add_i32 m0, s9, s86
	v_add_u32_e32 v166, v64, v142
	global_load_lds_dwordx4 v188, s[90:91]
	s_add_i32 m0, s9, s87
	v_add_u32_e32 v174, v95, v142
	global_load_lds_dwordx4 v189, s[90:91]
	s_add_i32 m0, s9, s88
	s_addk_i32 s7, 0x4000
	global_load_lds_dwordx4 v190, s[90:91]
	s_add_i32 m0, s9, s89
	s_add_u32 s4, s4, 0x80
	s_addc_u32 s5, s5, 0
	global_load_lds_dwordx4 v191, s[90:91]
	ds_read_b128 v[146:149], v166
	ds_read_b128 v[154:157], v174 offset:16384
	ds_read_b128 v[158:161], v174 offset:18432
	ds_read_b128 v[170:173], v174 offset:20480
	ds_read_b128 v[174:177], v174 offset:22528
	ds_read_b128 v[150:153], v166 offset:2048
	ds_read_b128 v[162:165], v166 offset:4096
	ds_read_b128 v[166:169], v166 offset:6144
	s_setprio 1
	s_waitcnt lgkmcnt(3)
	v_mfma_f32_16x16x32_bf16 v[60:63], v[146:149], v[154:157], v[60:63]
	v_mfma_f32_16x16x32_bf16 v[56:59], v[146:149], v[158:161], v[56:59]
	v_mfma_f32_16x16x32_bf16 v[52:55], v[146:149], v[170:173], v[52:55]
	v_mfma_f32_16x16x32_bf16 v[48:51], v[146:149], v[174:177], v[48:51]
	s_waitcnt lgkmcnt(2)
	v_mfma_f32_16x16x32_bf16 v[44:47], v[150:153], v[154:157], v[44:47]
	v_mfma_f32_16x16x32_bf16 v[40:43], v[150:153], v[158:161], v[40:43]
	v_mfma_f32_16x16x32_bf16 v[36:39], v[150:153], v[170:173], v[36:39]
	v_mfma_f32_16x16x32_bf16 v[32:35], v[150:153], v[174:177], v[32:35]
	s_waitcnt lgkmcnt(1)
	v_mfma_f32_16x16x32_bf16 v[28:31], v[162:165], v[154:157], v[28:31]
	v_mfma_f32_16x16x32_bf16 v[24:27], v[162:165], v[158:161], v[24:27]
	v_mfma_f32_16x16x32_bf16 v[20:23], v[162:165], v[170:173], v[20:23]
	v_mfma_f32_16x16x32_bf16 v[16:19], v[162:165], v[174:177], v[16:19]
	s_waitcnt lgkmcnt(0)
	v_mfma_f32_16x16x32_bf16 v[12:15], v[166:169], v[154:157], v[12:15]
	v_mfma_f32_16x16x32_bf16 v[8:11], v[166:169], v[158:161], v[8:11]
	v_mfma_f32_16x16x32_bf16 v[4:7], v[166:169], v[170:173], v[4:7]
	v_mfma_f32_16x16x32_bf16 v[0:3], v[166:169], v[174:177], v[0:3]
	s_setprio 0
	v_add_u32_e32 v64, v64, v143
	v_add_u32_e32 v95, v95, v143
	ds_read_b128 v[146:149], v64
	ds_read_b128 v[154:157], v95 offset:16384
	ds_read_b128 v[158:161], v95 offset:18432
	ds_read_b128 v[170:173], v95 offset:20480
	ds_read_b128 v[174:177], v95 offset:22528
	ds_read_b128 v[150:153], v64 offset:2048
	ds_read_b128 v[162:165], v64 offset:4096
	ds_read_b128 v[166:169], v64 offset:6144
	s_setprio 1
	s_waitcnt lgkmcnt(3)
	v_mfma_f32_16x16x32_bf16 v[60:63], v[146:149], v[154:157], v[60:63]
	v_mfma_f32_16x16x32_bf16 v[56:59], v[146:149], v[158:161], v[56:59]
	v_mfma_f32_16x16x32_bf16 v[52:55], v[146:149], v[170:173], v[52:55]
	v_mfma_f32_16x16x32_bf16 v[48:51], v[146:149], v[174:177], v[48:51]
	s_waitcnt lgkmcnt(2)
	v_mfma_f32_16x16x32_bf16 v[44:47], v[150:153], v[154:157], v[44:47]
	v_mfma_f32_16x16x32_bf16 v[40:43], v[150:153], v[158:161], v[40:43]
	v_mfma_f32_16x16x32_bf16 v[36:39], v[150:153], v[170:173], v[36:39]
	v_mfma_f32_16x16x32_bf16 v[32:35], v[150:153], v[174:177], v[32:35]
	s_waitcnt lgkmcnt(1)
	v_mfma_f32_16x16x32_bf16 v[28:31], v[162:165], v[154:157], v[28:31]
	v_mfma_f32_16x16x32_bf16 v[24:27], v[162:165], v[158:161], v[24:27]
	v_mfma_f32_16x16x32_bf16 v[20:23], v[162:165], v[170:173], v[20:23]
	v_mfma_f32_16x16x32_bf16 v[16:19], v[162:165], v[174:177], v[16:19]
	s_waitcnt lgkmcnt(0)
	v_mfma_f32_16x16x32_bf16 v[12:15], v[166:169], v[154:157], v[12:15]
	v_mfma_f32_16x16x32_bf16 v[8:11], v[166:169], v[158:161], v[8:11]
	v_mfma_f32_16x16x32_bf16 v[4:7], v[166:169], v[170:173], v[4:7]
	v_mfma_f32_16x16x32_bf16 v[0:3], v[166:169], v[174:177], v[0:3]
	s_setprio 0
	s_cmpk_eq_i32 s4, 0x780
	s_waitcnt vmcnt(0)
	s_barrier
	s_cbranch_scc0 .LBB0_259
	ds_read_b128 v[96:99], v122 offset:55296
	ds_read_b128 v[100:103], v122 offset:53248
	ds_read_b128 v[104:107], v123 offset:38912
	ds_read_b128 v[108:111], v123 offset:36864
	ds_read_b128 v[146:149], v122 offset:51200
	ds_read_b128 v[150:153], v122 offset:49152
	ds_read_b128 v[154:157], v123 offset:34816
	ds_read_b128 v[158:161], v123 offset:32768
	s_setprio 1
	s_waitcnt lgkmcnt(3)
	v_mfma_f32_16x16x32_bf16 v[24:27], v[108:111], v[146:149], v[24:27]
	v_mfma_f32_16x16x32_bf16 v[20:23], v[108:111], v[100:103], v[20:23]
	v_mfma_f32_16x16x32_bf16 v[16:19], v[108:111], v[96:99], v[16:19]
	s_waitcnt lgkmcnt(0)
	v_mfma_f32_16x16x32_bf16 v[60:63], v[158:161], v[150:153], v[60:63]
	v_mfma_f32_16x16x32_bf16 v[56:59], v[158:161], v[146:149], v[56:59]
	v_mfma_f32_16x16x32_bf16 v[52:55], v[158:161], v[100:103], v[52:55]
	v_mfma_f32_16x16x32_bf16 v[48:51], v[158:161], v[96:99], v[48:51]
	v_mfma_f32_16x16x32_bf16 v[44:47], v[154:157], v[150:153], v[44:47]
	v_mfma_f32_16x16x32_bf16 v[40:43], v[154:157], v[146:149], v[40:43]
	v_mfma_f32_16x16x32_bf16 v[36:39], v[154:157], v[100:103], v[36:39]
	v_mfma_f32_16x16x32_bf16 v[32:35], v[154:157], v[96:99], v[32:35]
	v_mfma_f32_16x16x32_bf16 v[28:31], v[108:111], v[150:153], v[28:31]
	v_mfma_f32_16x16x32_bf16 v[12:15], v[104:107], v[150:153], v[12:15]
	v_mfma_f32_16x16x32_bf16 v[8:11], v[104:107], v[146:149], v[8:11]
	v_mfma_f32_16x16x32_bf16 v[4:7], v[104:107], v[100:103], v[4:7]
	v_mfma_f32_16x16x32_bf16 v[0:3], v[104:107], v[96:99], v[0:3]
	s_setprio 0
	ds_read_b128 v[96:99], v124 offset:32768
	ds_read_b128 v[100:103], v124 offset:34816
	ds_read_b128 v[104:107], v125 offset:49152
	ds_read_b128 v[108:111], v125 offset:51200
	ds_read_b128 v[146:149], v124 offset:36864
	ds_read_b128 v[150:153], v124 offset:38912
	ds_read_b128 v[154:157], v125 offset:53248
	ds_read_b128 v[158:161], v125 offset:55296
	s_setprio 1
	s_waitcnt lgkmcnt(3)
	v_mfma_f32_16x16x32_bf16 v[24:27], v[146:149], v[108:111], v[24:27]
	s_waitcnt lgkmcnt(1)
	v_mfma_f32_16x16x32_bf16 v[20:23], v[146:149], v[154:157], v[20:23]
	s_waitcnt lgkmcnt(0)
	v_mfma_f32_16x16x32_bf16 v[16:19], v[146:149], v[158:161], v[16:19]
	v_mfma_f32_16x16x32_bf16 v[60:63], v[96:99], v[104:107], v[60:63]
	v_mfma_f32_16x16x32_bf16 v[56:59], v[96:99], v[108:111], v[56:59]
	v_mfma_f32_16x16x32_bf16 v[52:55], v[96:99], v[154:157], v[52:55]
	v_mfma_f32_16x16x32_bf16 v[48:51], v[96:99], v[158:161], v[48:51]
	v_mfma_f32_16x16x32_bf16 v[44:47], v[100:103], v[104:107], v[44:47]
	v_mfma_f32_16x16x32_bf16 v[40:43], v[100:103], v[108:111], v[40:43]
	v_mfma_f32_16x16x32_bf16 v[36:39], v[100:103], v[154:157], v[36:39]
	v_mfma_f32_16x16x32_bf16 v[32:35], v[100:103], v[158:161], v[32:35]
	v_mfma_f32_16x16x32_bf16 v[28:31], v[146:149], v[104:107], v[28:31]
	v_mfma_f32_16x16x32_bf16 v[12:15], v[150:153], v[104:107], v[12:15]
	v_mfma_f32_16x16x32_bf16 v[8:11], v[150:153], v[108:111], v[8:11]
	v_mfma_f32_16x16x32_bf16 v[4:7], v[150:153], v[154:157], v[4:7]
	v_mfma_f32_16x16x32_bf16 v[0:3], v[150:153], v[158:161], v[0:3]
	s_setprio 0
	s_barrier
	ds_write2_b32 v126, v60, v56 offset1:16
	ds_write2_b32 v126, v61, v57 offset0:132 offset1:148
	v_add_u32_e32 v56, 0x400, v126
	ds_write2_b32 v56, v62, v58 offset0:8 offset1:24
	ds_write2_b32 v56, v63, v59 offset0:140 offset1:156
	ds_write2_b32 v126, v52, v48 offset0:32 offset1:48
	ds_write2_b32 v126, v53, v49 offset0:164 offset1:180
	ds_write2_b32 v56, v54, v50 offset0:40 offset1:56
	ds_write2_b32 v56, v55, v51 offset0:172 offset1:188
	v_add_u32_e32 v48, 0x2000, v126
	ds_write2_b32 v48, v44, v40 offset0:64 offset1:80
	ds_write2_b32 v48, v45, v41 offset0:196 offset1:212
	v_add_u32_e32 v40, 0x2400, v126
	ds_write2_b32 v40, v46, v42 offset0:72 offset1:88
	ds_write2_b32 v40, v47, v43 offset0:204 offset1:220
	ds_write2_b32 v48, v36, v32 offset0:96 offset1:112
	ds_write2_b32 v48, v37, v33 offset0:228 offset1:244
	ds_write2_b32 v40, v38, v34 offset0:104 offset1:120
	ds_write2_b32 v40, v39, v35 offset0:236 offset1:252
	v_add_u32_e32 v32, 0x4000, v126
	ds_write2_b32 v32, v28, v24 offset0:128 offset1:144
	v_add_u32_e32 v24, 0x4400, v126
	ds_write2_b32 v24, v29, v25 offset0:4 offset1:20
	ds_write2_b32 v24, v30, v26 offset0:136 offset1:152
	v_add_u32_e32 v25, 0x4800, v126
	ds_write2_b32 v25, v31, v27 offset0:12 offset1:28
	ds_write2_b32 v32, v20, v16 offset0:160 offset1:176
	ds_write2_b32 v24, v21, v17 offset0:36 offset1:52
	ds_write2_b32 v24, v22, v18 offset0:168 offset1:184
	ds_write2_b32 v25, v23, v19 offset0:44 offset1:60
	v_add_u32_e32 v16, 0x6000, v126
	ds_write2_b32 v16, v12, v8 offset0:192 offset1:208
	v_add_u32_e32 v8, 0x6400, v126
	ds_write2_b32 v8, v13, v9 offset0:68 offset1:84
	ds_write2_b32 v8, v14, v10 offset0:200 offset1:216
	v_add_u32_e32 v9, 0x6800, v126
	v_or_b32_e32 v64, s6, v127
	ds_write2_b32 v9, v15, v11 offset0:76 offset1:92
	ds_write2_b32 v16, v4, v0 offset0:224 offset1:240
	ds_write2_b32 v8, v5, v1 offset0:100 offset1:116
	ds_write2_b32 v8, v6, v2 offset0:232 offset1:248
	ds_write2_b32 v9, v7, v3 offset0:108 offset1:124
	v_ashrrev_i32_e32 v1, 31, v64
	v_mov_b32_e32 v0, v64
	v_lshlrev_b64 v[2:3], 1, v[64:65]
	v_lshl_add_u64 v[20:21], v[0:1], 1, s[10:11]
	v_mov_b32_e32 v0, s15
	v_mov_b32_e32 v1, s13
	v_cmp_gt_i32_e64 s[8:9], s38, v64
	v_lshl_add_u64 v[16:17], s[18:19], 0, v[2:3]
	v_lshl_add_u64 v[18:19], s[16:17], 0, v[2:3]
	v_cndmask_b32_e64 v1, v0, v1, s[8:9]
	v_mov_b32_e32 v0, s14
	v_mov_b32_e32 v2, s12
	v_cndmask_b32_e64 v0, v0, v2, s[8:9]
	v_mov_b32_e32 v95, v65
	v_cmp_lt_i32_e64 s[4:5], s39, v64
	v_cmp_lt_i32_e64 s[6:7], s40, v64
	v_lshl_add_u64 v[22:23], v[0:1], 0, v[94:95]
	v_add_u32_e32 v24, s30, v135
	s_mov_b32 s45, 0
	s_waitcnt lgkmcnt(0)
	s_barrier
	s_branch .LBB0_263

.LBB0_278:
	s_and_b32 s8, s7, 0x4000
	s_xor_b32 s9, s8, 0x4000
	s_lshl_b32 s9, s9, 1
	s_add_i32 s9, s9, 32
	s_add_u32 s90, s52, s4
	s_addc_u32 s91, s53, s5
	s_add_i32 m0, s9, s82
	s_lshl_b32 s8, s8, 1
	global_load_lds_dwordx4 v184, s[90:91]
	s_add_i32 m0, s9, s83
	s_add_i32 s8, s8, 32
	global_load_lds_dwordx4 v185, s[90:91]
	s_add_i32 m0, s9, s84
	v_lshl_add_u32 v64, v121, 1, s8
	global_load_lds_dwordx4 v186, s[90:91]
	s_add_i32 m0, s9, s85
	v_lshl_add_u32 v95, v122, 1, s8
	global_load_lds_dwordx4 v187, s[90:91]
	s_add_i32 m0, s9, s86
	v_add_u32_e32 v164, v64, v139
	global_load_lds_dwordx4 v188, s[90:91]
	s_add_i32 m0, s9, s87
	v_add_u32_e32 v172, v95, v139
	global_load_lds_dwordx4 v189, s[90:91]
	s_add_i32 m0, s9, s88
	s_addk_i32 s7, 0x4000
	global_load_lds_dwordx4 v190, s[90:91]
	s_add_i32 m0, s9, s89
	s_add_u32 s4, s4, 0x80
	s_addc_u32 s5, s5, 0
	global_load_lds_dwordx4 v191, s[90:91]
	ds_read_b128 v[144:147], v164
	ds_read_b128 v[152:155], v172 offset:16384
	ds_read_b128 v[156:159], v172 offset:18432
	ds_read_b128 v[168:171], v172 offset:20480
	ds_read_b128 v[172:175], v172 offset:22528
	ds_read_b128 v[148:151], v164 offset:2048
	ds_read_b128 v[160:163], v164 offset:4096
	ds_read_b128 v[164:167], v164 offset:6144
	s_setprio 1
	s_waitcnt lgkmcnt(3)
	v_mfma_f32_16x16x32_bf16 v[60:63], v[144:147], v[152:155], v[60:63]
	v_mfma_f32_16x16x32_bf16 v[56:59], v[144:147], v[156:159], v[56:59]
	v_mfma_f32_16x16x32_bf16 v[52:55], v[144:147], v[168:171], v[52:55]
	v_mfma_f32_16x16x32_bf16 v[48:51], v[144:147], v[172:175], v[48:51]
	s_waitcnt lgkmcnt(2)
	v_mfma_f32_16x16x32_bf16 v[44:47], v[148:151], v[152:155], v[44:47]
	v_mfma_f32_16x16x32_bf16 v[40:43], v[148:151], v[156:159], v[40:43]
	v_mfma_f32_16x16x32_bf16 v[36:39], v[148:151], v[168:171], v[36:39]
	v_mfma_f32_16x16x32_bf16 v[32:35], v[148:151], v[172:175], v[32:35]
	s_waitcnt lgkmcnt(1)
	v_mfma_f32_16x16x32_bf16 v[28:31], v[160:163], v[152:155], v[28:31]
	v_mfma_f32_16x16x32_bf16 v[24:27], v[160:163], v[156:159], v[24:27]
	v_mfma_f32_16x16x32_bf16 v[20:23], v[160:163], v[168:171], v[20:23]
	v_mfma_f32_16x16x32_bf16 v[16:19], v[160:163], v[172:175], v[16:19]
	s_waitcnt lgkmcnt(0)
	v_mfma_f32_16x16x32_bf16 v[12:15], v[164:167], v[152:155], v[12:15]
	v_mfma_f32_16x16x32_bf16 v[8:11], v[164:167], v[156:159], v[8:11]
	v_mfma_f32_16x16x32_bf16 v[4:7], v[164:167], v[168:171], v[4:7]
	v_mfma_f32_16x16x32_bf16 v[0:3], v[164:167], v[172:175], v[0:3]
	s_setprio 0
	v_add_u32_e32 v64, v64, v140
	v_add_u32_e32 v95, v95, v140
	ds_read_b128 v[144:147], v64
	ds_read_b128 v[152:155], v95 offset:16384
	ds_read_b128 v[156:159], v95 offset:18432
	ds_read_b128 v[168:171], v95 offset:20480
	ds_read_b128 v[172:175], v95 offset:22528
	ds_read_b128 v[148:151], v64 offset:2048
	ds_read_b128 v[160:163], v64 offset:4096
	ds_read_b128 v[164:167], v64 offset:6144
	s_setprio 1
	s_waitcnt lgkmcnt(3)
	v_mfma_f32_16x16x32_bf16 v[60:63], v[144:147], v[152:155], v[60:63]
	v_mfma_f32_16x16x32_bf16 v[56:59], v[144:147], v[156:159], v[56:59]
	v_mfma_f32_16x16x32_bf16 v[52:55], v[144:147], v[168:171], v[52:55]
	v_mfma_f32_16x16x32_bf16 v[48:51], v[144:147], v[172:175], v[48:51]
	s_waitcnt lgkmcnt(2)
	v_mfma_f32_16x16x32_bf16 v[44:47], v[148:151], v[152:155], v[44:47]
	v_mfma_f32_16x16x32_bf16 v[40:43], v[148:151], v[156:159], v[40:43]
	v_mfma_f32_16x16x32_bf16 v[36:39], v[148:151], v[168:171], v[36:39]
	v_mfma_f32_16x16x32_bf16 v[32:35], v[148:151], v[172:175], v[32:35]
	s_waitcnt lgkmcnt(1)
	v_mfma_f32_16x16x32_bf16 v[28:31], v[160:163], v[152:155], v[28:31]
	v_mfma_f32_16x16x32_bf16 v[24:27], v[160:163], v[156:159], v[24:27]
	v_mfma_f32_16x16x32_bf16 v[20:23], v[160:163], v[168:171], v[20:23]
	v_mfma_f32_16x16x32_bf16 v[16:19], v[160:163], v[172:175], v[16:19]
	s_waitcnt lgkmcnt(0)
	v_mfma_f32_16x16x32_bf16 v[12:15], v[164:167], v[152:155], v[12:15]
	v_mfma_f32_16x16x32_bf16 v[8:11], v[164:167], v[156:159], v[8:11]
	v_mfma_f32_16x16x32_bf16 v[4:7], v[164:167], v[168:171], v[4:7]
	v_mfma_f32_16x16x32_bf16 v[0:3], v[164:167], v[172:175], v[0:3]
	s_setprio 0
	s_cmpk_eq_i32 s4, 0x780
	s_waitcnt vmcnt(0)
	s_barrier
	s_cbranch_scc0 .LBB0_278
	ds_read_b128 v[96:99], v123 offset:55296
	ds_read_b128 v[100:103], v123 offset:53248
	ds_read_b128 v[104:107], v124 offset:38912
	ds_read_b128 v[108:111], v124 offset:36864
	ds_read_b128 v[144:147], v123 offset:51200
	ds_read_b128 v[148:151], v123 offset:49152
	ds_read_b128 v[152:155], v124 offset:34816
	ds_read_b128 v[156:159], v124 offset:32768
	s_setprio 1
	s_waitcnt lgkmcnt(3)
	v_mfma_f32_16x16x32_bf16 v[24:27], v[108:111], v[144:147], v[24:27]
	v_mfma_f32_16x16x32_bf16 v[20:23], v[108:111], v[100:103], v[20:23]
	v_mfma_f32_16x16x32_bf16 v[16:19], v[108:111], v[96:99], v[16:19]
	s_waitcnt lgkmcnt(0)
	v_mfma_f32_16x16x32_bf16 v[60:63], v[156:159], v[148:151], v[60:63]
	v_mfma_f32_16x16x32_bf16 v[56:59], v[156:159], v[144:147], v[56:59]
	v_mfma_f32_16x16x32_bf16 v[52:55], v[156:159], v[100:103], v[52:55]
	v_mfma_f32_16x16x32_bf16 v[48:51], v[156:159], v[96:99], v[48:51]
	v_mfma_f32_16x16x32_bf16 v[44:47], v[152:155], v[148:151], v[44:47]
	v_mfma_f32_16x16x32_bf16 v[40:43], v[152:155], v[144:147], v[40:43]
	v_mfma_f32_16x16x32_bf16 v[36:39], v[152:155], v[100:103], v[36:39]
	v_mfma_f32_16x16x32_bf16 v[32:35], v[152:155], v[96:99], v[32:35]
	v_mfma_f32_16x16x32_bf16 v[28:31], v[108:111], v[148:151], v[28:31]
	v_mfma_f32_16x16x32_bf16 v[12:15], v[104:107], v[148:151], v[12:15]
	v_mfma_f32_16x16x32_bf16 v[8:11], v[104:107], v[144:147], v[8:11]
	v_mfma_f32_16x16x32_bf16 v[4:7], v[104:107], v[100:103], v[4:7]
	v_mfma_f32_16x16x32_bf16 v[0:3], v[104:107], v[96:99], v[0:3]
	s_setprio 0
	ds_read_b128 v[96:99], v125 offset:32768
	ds_read_b128 v[100:103], v125 offset:34816
	ds_read_b128 v[104:107], v126 offset:49152
	ds_read_b128 v[108:111], v126 offset:51200
	ds_read_b128 v[144:147], v125 offset:36864
	ds_read_b128 v[148:151], v125 offset:38912
	ds_read_b128 v[152:155], v126 offset:53248
	ds_read_b128 v[156:159], v126 offset:55296
	s_setprio 1
	s_waitcnt lgkmcnt(3)
	v_mfma_f32_16x16x32_bf16 v[24:27], v[144:147], v[108:111], v[24:27]
	s_waitcnt lgkmcnt(1)
	v_mfma_f32_16x16x32_bf16 v[20:23], v[144:147], v[152:155], v[20:23]
	s_waitcnt lgkmcnt(0)
	v_mfma_f32_16x16x32_bf16 v[16:19], v[144:147], v[156:159], v[16:19]
	v_mfma_f32_16x16x32_bf16 v[60:63], v[96:99], v[104:107], v[60:63]
	v_mfma_f32_16x16x32_bf16 v[56:59], v[96:99], v[108:111], v[56:59]
	v_mfma_f32_16x16x32_bf16 v[52:55], v[96:99], v[152:155], v[52:55]
	v_mfma_f32_16x16x32_bf16 v[48:51], v[96:99], v[156:159], v[48:51]
	v_mfma_f32_16x16x32_bf16 v[44:47], v[100:103], v[104:107], v[44:47]
	v_mfma_f32_16x16x32_bf16 v[40:43], v[100:103], v[108:111], v[40:43]
	v_mfma_f32_16x16x32_bf16 v[36:39], v[100:103], v[152:155], v[36:39]
	v_mfma_f32_16x16x32_bf16 v[32:35], v[100:103], v[156:159], v[32:35]
	v_mfma_f32_16x16x32_bf16 v[28:31], v[144:147], v[104:107], v[28:31]
	v_mfma_f32_16x16x32_bf16 v[12:15], v[148:151], v[104:107], v[12:15]
	v_mfma_f32_16x16x32_bf16 v[8:11], v[148:151], v[108:111], v[8:11]
	v_mfma_f32_16x16x32_bf16 v[4:7], v[148:151], v[152:155], v[4:7]
	v_mfma_f32_16x16x32_bf16 v[0:3], v[148:151], v[156:159], v[0:3]
	s_setprio 0
	s_barrier
	ds_write2_b32 v127, v60, v56 offset1:16
	ds_write2_b32 v127, v61, v57 offset0:132 offset1:148
	v_add_u32_e32 v56, 0x400, v127
	ds_write2_b32 v56, v62, v58 offset0:8 offset1:24
	ds_write2_b32 v56, v63, v59 offset0:140 offset1:156
	ds_write2_b32 v127, v52, v48 offset0:32 offset1:48
	ds_write2_b32 v127, v53, v49 offset0:164 offset1:180
	ds_write2_b32 v56, v54, v50 offset0:40 offset1:56
	ds_write2_b32 v56, v55, v51 offset0:172 offset1:188
	v_add_u32_e32 v48, 0x2000, v127
	ds_write2_b32 v48, v44, v40 offset0:64 offset1:80
	ds_write2_b32 v48, v45, v41 offset0:196 offset1:212
	v_add_u32_e32 v40, 0x2400, v127
	ds_write2_b32 v40, v46, v42 offset0:72 offset1:88
	ds_write2_b32 v40, v47, v43 offset0:204 offset1:220
	ds_write2_b32 v48, v36, v32 offset0:96 offset1:112
	ds_write2_b32 v48, v37, v33 offset0:228 offset1:244
	ds_write2_b32 v40, v38, v34 offset0:104 offset1:120
	ds_write2_b32 v40, v39, v35 offset0:236 offset1:252
	v_add_u32_e32 v32, 0x4000, v127
	ds_write2_b32 v32, v28, v24 offset0:128 offset1:144
	v_add_u32_e32 v24, 0x4400, v127
	ds_write2_b32 v24, v29, v25 offset0:4 offset1:20
	ds_write2_b32 v24, v30, v26 offset0:136 offset1:152
	v_add_u32_e32 v25, 0x4800, v127
	ds_write2_b32 v25, v31, v27 offset0:12 offset1:28
	ds_write2_b32 v32, v20, v16 offset0:160 offset1:176
	ds_write2_b32 v24, v21, v17 offset0:36 offset1:52
	ds_write2_b32 v24, v22, v18 offset0:168 offset1:184
	ds_write2_b32 v25, v23, v19 offset0:44 offset1:60
	v_add_u32_e32 v16, 0x6000, v127
	ds_write2_b32 v16, v12, v8 offset0:192 offset1:208
	v_add_u32_e32 v8, 0x6400, v127
	ds_write2_b32 v8, v13, v9 offset0:68 offset1:84
	ds_write2_b32 v8, v14, v10 offset0:200 offset1:216
	v_add_u32_e32 v9, 0x6800, v127
	v_or_b32_e32 v64, s6, v128
	ds_write2_b32 v9, v15, v11 offset0:76 offset1:92
	ds_write2_b32 v16, v4, v0 offset0:224 offset1:240
	ds_write2_b32 v8, v5, v1 offset0:100 offset1:116
	ds_write2_b32 v8, v6, v2 offset0:232 offset1:248
	ds_write2_b32 v9, v7, v3 offset0:108 offset1:124
	v_ashrrev_i32_e32 v1, 31, v64
	v_mov_b32_e32 v0, v64
	v_lshlrev_b64 v[2:3], 1, v[64:65]
	v_lshl_add_u64 v[20:21], v[0:1], 1, s[10:11]
	v_mov_b32_e32 v0, s15
	v_mov_b32_e32 v1, s13
	v_cmp_gt_i32_e64 s[8:9], s24, v64
	v_lshl_add_u64 v[16:17], s[18:19], 0, v[2:3]
	v_lshl_add_u64 v[18:19], s[16:17], 0, v[2:3]
	v_cndmask_b32_e64 v1, v0, v1, s[8:9]
	v_mov_b32_e32 v0, s14
	v_mov_b32_e32 v2, s12
	v_cndmask_b32_e64 v0, v0, v2, s[8:9]
	v_mov_b32_e32 v95, v65
	v_cmp_lt_i32_e64 s[4:5], s26, v64
	v_cmp_lt_i32_e64 s[6:7], s27, v64
	v_lshl_add_u64 v[22:23], v[0:1], 0, v[94:95]
	v_add_u32_e32 v24, v132, v143
	s_mov_b32 s35, 0
	s_waitcnt lgkmcnt(0)
	s_barrier
	s_branch .LBB0_282

.LBB0_423:
	s_and_b32 s25, s24, 0x4000
	s_xor_b32 s26, s25, 0x4000
	s_lshl_b32 s26, s26, 1
	s_add_i32 s26, s26, 32
	s_add_u32 s90, s52, s14
	s_addc_u32 s91, s53, s15
	s_add_i32 m0, s26, s82
	s_lshl_b32 s25, s25, 1
	global_load_lds_dwordx4 v188, s[90:91]
	s_add_i32 m0, s26, s83
	s_add_i32 s25, s25, 32
	global_load_lds_dwordx4 v189, s[90:91]
	s_add_i32 m0, s26, s84
	v_add3_u32 v170, s25, v114, v135
	global_load_lds_dwordx4 v190, s[90:91]
	s_add_i32 m0, s26, s85
	v_add3_u32 v171, s25, v115, v135
	global_load_lds_dwordx4 v191, s[90:91]
	s_add_i32 m0, s26, s86
	v_add_u32_e32 v158, v170, v136
	global_load_lds_dwordx4 v192, s[90:91]
	s_add_i32 m0, s26, s87
	v_add_u32_e32 v166, v171, v136
	global_load_lds_dwordx4 v193, s[90:91]
	s_add_i32 m0, s26, s88
	s_addk_i32 s24, 0x4000
	global_load_lds_dwordx4 v194, s[90:91]
	s_add_i32 m0, s26, s89
	s_add_u32 s14, s14, 0x80
	s_addc_u32 s15, s15, 0
	global_load_lds_dwordx4 v195, s[90:91]
	ds_read_b128 v[138:141], v158
	ds_read_b128 v[146:149], v166 offset:16384
	ds_read_b128 v[150:153], v166 offset:18432
	ds_read_b128 v[162:165], v166 offset:20480
	ds_read_b128 v[166:169], v166 offset:22528
	ds_read_b128 v[142:145], v158 offset:2048
	ds_read_b128 v[154:157], v158 offset:4096
	ds_read_b128 v[158:161], v158 offset:6144
	s_setprio 1
	s_waitcnt lgkmcnt(3)
	v_mfma_f32_16x16x32_bf16 v[60:63], v[138:141], v[146:149], v[60:63]
	v_mfma_f32_16x16x32_bf16 v[56:59], v[138:141], v[150:153], v[56:59]
	v_mfma_f32_16x16x32_bf16 v[52:55], v[138:141], v[162:165], v[52:55]
	v_mfma_f32_16x16x32_bf16 v[48:51], v[138:141], v[166:169], v[48:51]
	s_waitcnt lgkmcnt(2)
	v_mfma_f32_16x16x32_bf16 v[44:47], v[142:145], v[146:149], v[44:47]
	v_mfma_f32_16x16x32_bf16 v[40:43], v[142:145], v[150:153], v[40:43]
	v_mfma_f32_16x16x32_bf16 v[36:39], v[142:145], v[162:165], v[36:39]
	v_mfma_f32_16x16x32_bf16 v[32:35], v[142:145], v[166:169], v[32:35]
	s_waitcnt lgkmcnt(1)
	v_mfma_f32_16x16x32_bf16 v[28:31], v[154:157], v[146:149], v[28:31]
	v_mfma_f32_16x16x32_bf16 v[24:27], v[154:157], v[150:153], v[24:27]
	v_mfma_f32_16x16x32_bf16 v[20:23], v[154:157], v[162:165], v[20:23]
	v_mfma_f32_16x16x32_bf16 v[16:19], v[154:157], v[166:169], v[16:19]
	s_waitcnt lgkmcnt(0)
	v_mfma_f32_16x16x32_bf16 v[12:15], v[158:161], v[146:149], v[12:15]
	v_mfma_f32_16x16x32_bf16 v[8:11], v[158:161], v[150:153], v[8:11]
	v_mfma_f32_16x16x32_bf16 v[4:7], v[158:161], v[162:165], v[4:7]
	v_mfma_f32_16x16x32_bf16 v[0:3], v[158:161], v[166:169], v[0:3]
	s_setprio 0
	v_add_u32_e32 v158, v170, v137
	v_add_u32_e32 v166, v171, v137
	ds_read_b128 v[138:141], v158
	ds_read_b128 v[146:149], v166 offset:16384
	ds_read_b128 v[150:153], v166 offset:18432
	ds_read_b128 v[162:165], v166 offset:20480
	ds_read_b128 v[166:169], v166 offset:22528
	ds_read_b128 v[142:145], v158 offset:2048
	ds_read_b128 v[154:157], v158 offset:4096
	ds_read_b128 v[158:161], v158 offset:6144
	s_setprio 1
	s_waitcnt lgkmcnt(3)
	v_mfma_f32_16x16x32_bf16 v[60:63], v[138:141], v[146:149], v[60:63]
	v_mfma_f32_16x16x32_bf16 v[56:59], v[138:141], v[150:153], v[56:59]
	v_mfma_f32_16x16x32_bf16 v[52:55], v[138:141], v[162:165], v[52:55]
	v_mfma_f32_16x16x32_bf16 v[48:51], v[138:141], v[166:169], v[48:51]
	s_waitcnt lgkmcnt(2)
	v_mfma_f32_16x16x32_bf16 v[44:47], v[142:145], v[146:149], v[44:47]
	v_mfma_f32_16x16x32_bf16 v[40:43], v[142:145], v[150:153], v[40:43]
	v_mfma_f32_16x16x32_bf16 v[36:39], v[142:145], v[162:165], v[36:39]
	v_mfma_f32_16x16x32_bf16 v[32:35], v[142:145], v[166:169], v[32:35]
	s_waitcnt lgkmcnt(1)
	v_mfma_f32_16x16x32_bf16 v[28:31], v[154:157], v[146:149], v[28:31]
	v_mfma_f32_16x16x32_bf16 v[24:27], v[154:157], v[150:153], v[24:27]
	v_mfma_f32_16x16x32_bf16 v[20:23], v[154:157], v[162:165], v[20:23]
	v_mfma_f32_16x16x32_bf16 v[16:19], v[154:157], v[166:169], v[16:19]
	s_waitcnt lgkmcnt(0)
	v_mfma_f32_16x16x32_bf16 v[12:15], v[158:161], v[146:149], v[12:15]
	v_mfma_f32_16x16x32_bf16 v[8:11], v[158:161], v[150:153], v[8:11]
	v_mfma_f32_16x16x32_bf16 v[4:7], v[158:161], v[162:165], v[4:7]
	v_mfma_f32_16x16x32_bf16 v[0:3], v[158:161], v[166:169], v[0:3]
	s_setprio 0
	s_cmpk_eq_i32 s14, 0x780
	s_waitcnt vmcnt(0)
	s_barrier
	s_cbranch_scc0 .LBB0_423
	ds_read_b128 v[90:93], v118 offset:55296
	ds_read_b128 v[94:97], v118 offset:53248
	ds_read_b128 v[98:101], v119 offset:38912
	ds_read_b128 v[102:105], v119 offset:36864
	ds_read_b128 v[138:141], v118 offset:51200
	ds_read_b128 v[142:145], v118 offset:49152
	ds_read_b128 v[146:149], v119 offset:34816
	ds_read_b128 v[150:153], v119 offset:32768
	s_setprio 1
	s_waitcnt lgkmcnt(5)
	v_mfma_f32_16x16x32_bf16 v[4:7], v[98:101], v[94:97], v[4:7]
	v_mfma_f32_16x16x32_bf16 v[0:3], v[98:101], v[90:93], v[0:3]
	s_waitcnt lgkmcnt(0)
	v_mfma_f32_16x16x32_bf16 v[60:63], v[150:153], v[142:145], v[60:63]
	v_mfma_f32_16x16x32_bf16 v[56:59], v[150:153], v[138:141], v[56:59]
	v_mfma_f32_16x16x32_bf16 v[52:55], v[150:153], v[94:97], v[52:55]
	v_mfma_f32_16x16x32_bf16 v[48:51], v[150:153], v[90:93], v[48:51]
	v_mfma_f32_16x16x32_bf16 v[44:47], v[146:149], v[142:145], v[44:47]
	v_mfma_f32_16x16x32_bf16 v[40:43], v[146:149], v[138:141], v[40:43]
	v_mfma_f32_16x16x32_bf16 v[36:39], v[146:149], v[94:97], v[36:39]
	v_mfma_f32_16x16x32_bf16 v[32:35], v[146:149], v[90:93], v[32:35]
	v_mfma_f32_16x16x32_bf16 v[28:31], v[102:105], v[142:145], v[28:31]
	v_mfma_f32_16x16x32_bf16 v[24:27], v[102:105], v[138:141], v[24:27]
	v_mfma_f32_16x16x32_bf16 v[20:23], v[102:105], v[94:97], v[20:23]
	v_mfma_f32_16x16x32_bf16 v[16:19], v[102:105], v[90:93], v[16:19]
	v_mfma_f32_16x16x32_bf16 v[12:15], v[98:101], v[142:145], v[12:15]
	v_mfma_f32_16x16x32_bf16 v[8:11], v[98:101], v[138:141], v[8:11]
	s_setprio 0
	ds_read_b128 v[90:93], v120 offset:32768
	ds_read_b128 v[94:97], v120 offset:34816
	ds_read_b128 v[98:101], v121 offset:49152
	ds_read_b128 v[102:105], v121 offset:51200
	ds_read_b128 v[138:141], v120 offset:36864
	ds_read_b128 v[142:145], v120 offset:38912
	ds_read_b128 v[146:149], v121 offset:53248
	ds_read_b128 v[150:153], v121 offset:55296
	s_setprio 1
	s_waitcnt lgkmcnt(1)
	v_mfma_f32_16x16x32_bf16 v[4:7], v[142:145], v[146:149], v[4:7]
	s_waitcnt lgkmcnt(0)
	v_mfma_f32_16x16x32_bf16 v[0:3], v[142:145], v[150:153], v[0:3]
	v_mfma_f32_16x16x32_bf16 v[60:63], v[90:93], v[98:101], v[60:63]
	v_mfma_f32_16x16x32_bf16 v[56:59], v[90:93], v[102:105], v[56:59]
	v_mfma_f32_16x16x32_bf16 v[52:55], v[90:93], v[146:149], v[52:55]
	v_mfma_f32_16x16x32_bf16 v[48:51], v[90:93], v[150:153], v[48:51]
	v_mfma_f32_16x16x32_bf16 v[44:47], v[94:97], v[98:101], v[44:47]
	v_mfma_f32_16x16x32_bf16 v[40:43], v[94:97], v[102:105], v[40:43]
	v_mfma_f32_16x16x32_bf16 v[36:39], v[94:97], v[146:149], v[36:39]
	v_mfma_f32_16x16x32_bf16 v[32:35], v[94:97], v[150:153], v[32:35]
	v_mfma_f32_16x16x32_bf16 v[28:31], v[138:141], v[98:101], v[28:31]
	v_mfma_f32_16x16x32_bf16 v[24:27], v[138:141], v[102:105], v[24:27]
	v_mfma_f32_16x16x32_bf16 v[20:23], v[138:141], v[146:149], v[20:23]
	v_mfma_f32_16x16x32_bf16 v[16:19], v[138:141], v[150:153], v[16:19]
	v_mfma_f32_16x16x32_bf16 v[12:15], v[142:145], v[98:101], v[12:15]
	v_mfma_f32_16x16x32_bf16 v[8:11], v[142:145], v[102:105], v[8:11]
	s_setprio 0
	s_barrier
	ds_write2_b32 v116, v60, v56 offset1:16
	ds_write2_b32 v116, v61, v57 offset0:132 offset1:148
	v_add_u32_e32 v56, 0x400, v116
	ds_write2_b32 v56, v62, v58 offset0:8 offset1:24
	ds_write2_b32 v56, v63, v59 offset0:140 offset1:156
	ds_write2_b32 v116, v52, v48 offset0:32 offset1:48
	ds_write2_b32 v116, v53, v49 offset0:164 offset1:180
	ds_write2_b32 v56, v54, v50 offset0:40 offset1:56
	ds_write2_b32 v56, v55, v51 offset0:172 offset1:188
	v_add_u32_e32 v48, 0x2000, v116
	ds_write2_b32 v48, v44, v40 offset0:64 offset1:80
	ds_write2_b32 v48, v45, v41 offset0:196 offset1:212
	v_add_u32_e32 v40, 0x2400, v116
	ds_write2_b32 v40, v46, v42 offset0:72 offset1:88
	ds_write2_b32 v40, v47, v43 offset0:204 offset1:220
	ds_write2_b32 v48, v36, v32 offset0:96 offset1:112
	ds_write2_b32 v48, v37, v33 offset0:228 offset1:244
	ds_write2_b32 v40, v38, v34 offset0:104 offset1:120
	ds_write2_b32 v40, v39, v35 offset0:236 offset1:252
	v_add_u32_e32 v32, 0x4000, v116
	ds_write2_b32 v32, v28, v24 offset0:128 offset1:144
	v_add_u32_e32 v24, 0x4400, v116
	ds_write2_b32 v24, v29, v25 offset0:4 offset1:20
	ds_write2_b32 v24, v30, v26 offset0:136 offset1:152
	v_add_u32_e32 v25, 0x4800, v116
	ds_write2_b32 v25, v31, v27 offset0:12 offset1:28
	ds_write2_b32 v32, v20, v16 offset0:160 offset1:176
	ds_write2_b32 v24, v21, v17 offset0:36 offset1:52
	ds_write2_b32 v24, v22, v18 offset0:168 offset1:184
	ds_write2_b32 v25, v23, v19 offset0:44 offset1:60
	v_add_u32_e32 v16, 0x6000, v116
	ds_write2_b32 v16, v12, v8 offset0:192 offset1:208
	v_add_u32_e32 v8, 0x6400, v116
	ds_write2_b32 v8, v13, v9 offset0:68 offset1:84
	ds_write2_b32 v8, v14, v10 offset0:200 offset1:216
	v_add_u32_e32 v9, 0x6800, v116
	ds_write2_b32 v9, v15, v11 offset0:76 offset1:92
	ds_write2_b32 v16, v4, v0 offset0:224 offset1:240
	ds_write2_b32 v8, v5, v1 offset0:100 offset1:116
	ds_write2_b32 v8, v6, v2 offset0:232 offset1:248
	ds_write2_b32 v9, v7, v3 offset0:108 offset1:124
	v_or_b32_e32 v0, s23, v117
	v_ashrrev_i32_e32 v1, 31, v0
	v_lshlrev_b64 v[2:3], 2, v[0:1]
	v_lshl_add_u64 v[0:1], s[12:13], 0, v[2:3]
	v_lshl_add_u64 v[2:3], s[8:9], 0, v[2:3]
	v_add_u32_e32 v4, s22, v128
	s_mov_b32 s14, 0
	s_waitcnt lgkmcnt(0)
	s_barrier

.LBB0_432:
	s_and_b32 s26, s25, 0x4000
	s_xor_b32 s27, s26, 0x4000
	s_lshl_b32 s27, s27, 1
	s_add_i32 s27, s27, 32
	s_add_u32 s90, s52, s14
	s_addc_u32 s91, s53, s15
	s_add_i32 m0, s27, s82
	s_lshl_b32 s26, s26, 1
	global_load_lds_dwordx4 v188, s[90:91]
	s_add_i32 m0, s27, s83
	s_add_i32 s26, s26, 32
	global_load_lds_dwordx4 v189, s[90:91]
	s_add_i32 m0, s27, s84
	v_add3_u32 v139, s26, v113, v136
	global_load_lds_dwordx4 v190, s[90:91]
	s_add_i32 m0, s27, s85
	v_add3_u32 v172, s26, v114, v136
	global_load_lds_dwordx4 v191, s[90:91]
	s_add_i32 m0, s27, s86
	v_add_u32_e32 v160, v139, v137
	global_load_lds_dwordx4 v192, s[90:91]
	s_add_i32 m0, s27, s87
	v_add_u32_e32 v168, v172, v137
	global_load_lds_dwordx4 v193, s[90:91]
	s_add_i32 m0, s27, s88
	s_addk_i32 s25, 0x4000
	global_load_lds_dwordx4 v194, s[90:91]
	s_add_i32 m0, s27, s89
	s_add_u32 s14, s14, 0x80
	s_addc_u32 s15, s15, 0
	global_load_lds_dwordx4 v195, s[90:91]
	ds_read_b128 v[140:143], v160
	ds_read_b128 v[148:151], v168 offset:16384
	ds_read_b128 v[152:155], v168 offset:18432
	ds_read_b128 v[164:167], v168 offset:20480
	ds_read_b128 v[168:171], v168 offset:22528
	ds_read_b128 v[144:147], v160 offset:2048
	ds_read_b128 v[156:159], v160 offset:4096
	ds_read_b128 v[160:163], v160 offset:6144
	s_setprio 1
	s_waitcnt lgkmcnt(3)
	v_mfma_f32_16x16x32_bf16 v[60:63], v[140:143], v[148:151], v[60:63]
	v_mfma_f32_16x16x32_bf16 v[56:59], v[140:143], v[152:155], v[56:59]
	v_mfma_f32_16x16x32_bf16 v[52:55], v[140:143], v[164:167], v[52:55]
	v_mfma_f32_16x16x32_bf16 v[48:51], v[140:143], v[168:171], v[48:51]
	s_waitcnt lgkmcnt(2)
	v_mfma_f32_16x16x32_bf16 v[44:47], v[144:147], v[148:151], v[44:47]
	v_mfma_f32_16x16x32_bf16 v[40:43], v[144:147], v[152:155], v[40:43]
	v_mfma_f32_16x16x32_bf16 v[36:39], v[144:147], v[164:167], v[36:39]
	v_mfma_f32_16x16x32_bf16 v[32:35], v[144:147], v[168:171], v[32:35]
	s_waitcnt lgkmcnt(1)
	v_mfma_f32_16x16x32_bf16 v[28:31], v[156:159], v[148:151], v[28:31]
	v_mfma_f32_16x16x32_bf16 v[24:27], v[156:159], v[152:155], v[24:27]
	v_mfma_f32_16x16x32_bf16 v[20:23], v[156:159], v[164:167], v[20:23]
	v_mfma_f32_16x16x32_bf16 v[16:19], v[156:159], v[168:171], v[16:19]
	s_waitcnt lgkmcnt(0)
	v_mfma_f32_16x16x32_bf16 v[12:15], v[160:163], v[148:151], v[12:15]
	v_mfma_f32_16x16x32_bf16 v[8:11], v[160:163], v[152:155], v[8:11]
	v_mfma_f32_16x16x32_bf16 v[4:7], v[160:163], v[164:167], v[4:7]
	v_mfma_f32_16x16x32_bf16 v[0:3], v[160:163], v[168:171], v[0:3]
	s_setprio 0
	v_add_u32_e32 v139, v139, v138
	v_add_u32_e32 v168, v172, v138
	ds_read_b128 v[140:143], v139
	ds_read_b128 v[148:151], v168 offset:16384
	ds_read_b128 v[152:155], v168 offset:18432
	ds_read_b128 v[164:167], v168 offset:20480
	ds_read_b128 v[168:171], v168 offset:22528
	ds_read_b128 v[144:147], v139 offset:2048
	ds_read_b128 v[156:159], v139 offset:4096
	ds_read_b128 v[160:163], v139 offset:6144
	s_setprio 1
	s_waitcnt lgkmcnt(3)
	v_mfma_f32_16x16x32_bf16 v[60:63], v[140:143], v[148:151], v[60:63]
	v_mfma_f32_16x16x32_bf16 v[56:59], v[140:143], v[152:155], v[56:59]
	v_mfma_f32_16x16x32_bf16 v[52:55], v[140:143], v[164:167], v[52:55]
	v_mfma_f32_16x16x32_bf16 v[48:51], v[140:143], v[168:171], v[48:51]
	s_waitcnt lgkmcnt(2)
	v_mfma_f32_16x16x32_bf16 v[44:47], v[144:147], v[148:151], v[44:47]
	v_mfma_f32_16x16x32_bf16 v[40:43], v[144:147], v[152:155], v[40:43]
	v_mfma_f32_16x16x32_bf16 v[36:39], v[144:147], v[164:167], v[36:39]
	v_mfma_f32_16x16x32_bf16 v[32:35], v[144:147], v[168:171], v[32:35]
	s_waitcnt lgkmcnt(1)
	v_mfma_f32_16x16x32_bf16 v[28:31], v[156:159], v[148:151], v[28:31]
	v_mfma_f32_16x16x32_bf16 v[24:27], v[156:159], v[152:155], v[24:27]
	v_mfma_f32_16x16x32_bf16 v[20:23], v[156:159], v[164:167], v[20:23]
	v_mfma_f32_16x16x32_bf16 v[16:19], v[156:159], v[168:171], v[16:19]
	s_waitcnt lgkmcnt(0)
	v_mfma_f32_16x16x32_bf16 v[12:15], v[160:163], v[148:151], v[12:15]
	v_mfma_f32_16x16x32_bf16 v[8:11], v[160:163], v[152:155], v[8:11]
	v_mfma_f32_16x16x32_bf16 v[4:7], v[160:163], v[164:167], v[4:7]
	v_mfma_f32_16x16x32_bf16 v[0:3], v[160:163], v[168:171], v[0:3]
	s_setprio 0
	s_cmpk_eq_i32 s14, 0x780
	s_waitcnt vmcnt(0)
	s_barrier
	s_cbranch_scc0 .LBB0_432
	ds_read_b128 v[88:91], v117 offset:55296
	ds_read_b128 v[92:95], v117 offset:53248
	ds_read_b128 v[96:99], v118 offset:38912
	ds_read_b128 v[100:103], v118 offset:36864
	ds_read_b128 v[140:143], v117 offset:51200
	ds_read_b128 v[144:147], v117 offset:49152
	ds_read_b128 v[148:151], v118 offset:34816
	ds_read_b128 v[152:155], v118 offset:32768
	s_setprio 1
	s_waitcnt lgkmcnt(5)
	v_mfma_f32_16x16x32_bf16 v[4:7], v[96:99], v[92:95], v[4:7]
	v_mfma_f32_16x16x32_bf16 v[0:3], v[96:99], v[88:91], v[0:3]
	s_waitcnt lgkmcnt(0)
	v_mfma_f32_16x16x32_bf16 v[60:63], v[152:155], v[144:147], v[60:63]
	v_mfma_f32_16x16x32_bf16 v[56:59], v[152:155], v[140:143], v[56:59]
	v_mfma_f32_16x16x32_bf16 v[52:55], v[152:155], v[92:95], v[52:55]
	v_mfma_f32_16x16x32_bf16 v[48:51], v[152:155], v[88:91], v[48:51]
	v_mfma_f32_16x16x32_bf16 v[44:47], v[148:151], v[144:147], v[44:47]
	v_mfma_f32_16x16x32_bf16 v[40:43], v[148:151], v[140:143], v[40:43]
	v_mfma_f32_16x16x32_bf16 v[36:39], v[148:151], v[92:95], v[36:39]
	v_mfma_f32_16x16x32_bf16 v[32:35], v[148:151], v[88:91], v[32:35]
	v_mfma_f32_16x16x32_bf16 v[28:31], v[100:103], v[144:147], v[28:31]
	v_mfma_f32_16x16x32_bf16 v[24:27], v[100:103], v[140:143], v[24:27]
	v_mfma_f32_16x16x32_bf16 v[20:23], v[100:103], v[92:95], v[20:23]
	v_mfma_f32_16x16x32_bf16 v[16:19], v[100:103], v[88:91], v[16:19]
	v_mfma_f32_16x16x32_bf16 v[12:15], v[96:99], v[144:147], v[12:15]
	v_mfma_f32_16x16x32_bf16 v[8:11], v[96:99], v[140:143], v[8:11]
	s_setprio 0
	ds_read_b128 v[88:91], v119 offset:32768
	ds_read_b128 v[92:95], v119 offset:34816
	ds_read_b128 v[96:99], v120 offset:49152
	ds_read_b128 v[100:103], v120 offset:51200
	ds_read_b128 v[140:143], v119 offset:36864
	ds_read_b128 v[144:147], v119 offset:38912
	ds_read_b128 v[148:151], v120 offset:53248
	ds_read_b128 v[152:155], v120 offset:55296
	s_setprio 1
	s_waitcnt lgkmcnt(1)
	v_mfma_f32_16x16x32_bf16 v[4:7], v[144:147], v[148:151], v[4:7]
	s_waitcnt lgkmcnt(0)
	v_mfma_f32_16x16x32_bf16 v[0:3], v[144:147], v[152:155], v[0:3]
	v_mfma_f32_16x16x32_bf16 v[60:63], v[88:91], v[96:99], v[60:63]
	v_mfma_f32_16x16x32_bf16 v[56:59], v[88:91], v[100:103], v[56:59]
	v_mfma_f32_16x16x32_bf16 v[52:55], v[88:91], v[148:151], v[52:55]
	v_mfma_f32_16x16x32_bf16 v[48:51], v[88:91], v[152:155], v[48:51]
	v_mfma_f32_16x16x32_bf16 v[44:47], v[92:95], v[96:99], v[44:47]
	v_mfma_f32_16x16x32_bf16 v[40:43], v[92:95], v[100:103], v[40:43]
	v_mfma_f32_16x16x32_bf16 v[36:39], v[92:95], v[148:151], v[36:39]
	v_mfma_f32_16x16x32_bf16 v[32:35], v[92:95], v[152:155], v[32:35]
	v_mfma_f32_16x16x32_bf16 v[28:31], v[140:143], v[96:99], v[28:31]
	v_mfma_f32_16x16x32_bf16 v[24:27], v[140:143], v[100:103], v[24:27]
	v_mfma_f32_16x16x32_bf16 v[20:23], v[140:143], v[148:151], v[20:23]
	v_mfma_f32_16x16x32_bf16 v[16:19], v[140:143], v[152:155], v[16:19]
	v_mfma_f32_16x16x32_bf16 v[12:15], v[144:147], v[96:99], v[12:15]
	v_mfma_f32_16x16x32_bf16 v[8:11], v[144:147], v[100:103], v[8:11]
	s_setprio 0
	s_barrier
	ds_write2_b32 v115, v60, v56 offset1:16
	ds_write2_b32 v115, v61, v57 offset0:132 offset1:148
	v_add_u32_e32 v56, 0x400, v115
	ds_write2_b32 v56, v62, v58 offset0:8 offset1:24
	ds_write2_b32 v56, v63, v59 offset0:140 offset1:156
	ds_write2_b32 v115, v52, v48 offset0:32 offset1:48
	ds_write2_b32 v115, v53, v49 offset0:164 offset1:180
	ds_write2_b32 v56, v54, v50 offset0:40 offset1:56
	ds_write2_b32 v56, v55, v51 offset0:172 offset1:188
	v_add_u32_e32 v48, 0x2000, v115
	ds_write2_b32 v48, v44, v40 offset0:64 offset1:80
	ds_write2_b32 v48, v45, v41 offset0:196 offset1:212
	v_add_u32_e32 v40, 0x2400, v115
	ds_write2_b32 v40, v46, v42 offset0:72 offset1:88
	ds_write2_b32 v40, v47, v43 offset0:204 offset1:220
	ds_write2_b32 v48, v36, v32 offset0:96 offset1:112
	ds_write2_b32 v48, v37, v33 offset0:228 offset1:244
	ds_write2_b32 v40, v38, v34 offset0:104 offset1:120
	ds_write2_b32 v40, v39, v35 offset0:236 offset1:252
	v_add_u32_e32 v32, 0x4000, v115
	ds_write2_b32 v32, v28, v24 offset0:128 offset1:144
	v_add_u32_e32 v24, 0x4400, v115
	ds_write2_b32 v24, v29, v25 offset0:4 offset1:20
	ds_write2_b32 v24, v30, v26 offset0:136 offset1:152
	v_add_u32_e32 v25, 0x4800, v115
	ds_write2_b32 v25, v31, v27 offset0:12 offset1:28
	ds_write2_b32 v32, v20, v16 offset0:160 offset1:176
	ds_write2_b32 v24, v21, v17 offset0:36 offset1:52
	ds_write2_b32 v24, v22, v18 offset0:168 offset1:184
	ds_write2_b32 v25, v23, v19 offset0:44 offset1:60
	v_add_u32_e32 v16, 0x6000, v115
	ds_write2_b32 v16, v12, v8 offset0:192 offset1:208
	v_add_u32_e32 v8, 0x6400, v115
	ds_write2_b32 v8, v13, v9 offset0:68 offset1:84
	ds_write2_b32 v8, v14, v10 offset0:200 offset1:216
	v_add_u32_e32 v9, 0x6800, v115
	ds_write2_b32 v9, v15, v11 offset0:76 offset1:92
	ds_write2_b32 v16, v4, v0 offset0:224 offset1:240
	ds_write2_b32 v8, v5, v1 offset0:100 offset1:116
	ds_write2_b32 v8, v6, v2 offset0:232 offset1:248
	ds_write2_b32 v9, v7, v3 offset0:108 offset1:124
	v_or_b32_e32 v0, s23, v116
	v_ashrrev_i32_e32 v1, 31, v0
	v_lshlrev_b64 v[2:3], 2, v[0:1]
	v_lshl_add_u64 v[0:1], s[12:13], 0, v[2:3]
	v_lshl_add_u64 v[2:3], s[8:9], 0, v[2:3]
	v_add_u32_e32 v4, s24, v129
	s_mov_b32 s14, 0
	s_waitcnt lgkmcnt(0)
	s_barrier

.LBB0_443:
	s_and_b32 s25, s24, 0x4000
	s_xor_b32 s26, s25, 0x4000
	s_lshl_b32 s26, s26, 1
	s_add_i32 s26, s26, 32
	s_add_u32 s90, s52, s10
	s_addc_u32 s91, s53, s11
	s_add_i32 m0, s26, s82
	s_lshl_b32 s25, s25, 1
	global_load_lds_dwordx4 v189, s[90:91]
	s_add_i32 m0, s26, s83
	s_add_i32 s25, s25, 32
	global_load_lds_dwordx4 v190, s[90:91]
	s_add_i32 m0, s26, s84
	v_lshlrev_b32_e32 v70, 1, v129
	global_load_lds_dwordx4 v191, s[90:91]
	s_add_i32 m0, s26, s85
	v_add3_u32 v151, s25, v124, v70
	global_load_lds_dwordx4 v192, s[90:91]
	s_add_i32 m0, s26, s86
	v_lshlrev_b32_e32 v152, 1, v117
	global_load_lds_dwordx4 v193, s[90:91]
	s_add_i32 m0, s26, s87
	v_add3_u32 v70, s25, v125, v70
	global_load_lds_dwordx4 v194, s[90:91]
	s_add_i32 m0, s26, s88
	v_add_u32_e32 v172, v151, v152
	global_load_lds_dwordx4 v195, s[90:91]
	s_add_i32 m0, s26, s89
	v_add_u32_e32 v181, v70, v152
	global_load_lds_dwordx4 v196, s[90:91]
	ds_read_b128 v[152:155], v172
	ds_read_b128 v[160:163], v181 offset:16384
	ds_read_b128 v[164:167], v181 offset:18432
	ds_read_b128 v[176:179], v181 offset:20480
	ds_read_b128 v[182:185], v181 offset:22528
	ds_read_b128 v[156:159], v172 offset:2048
	ds_read_b128 v[168:171], v172 offset:4096
	ds_read_b128 v[172:175], v172 offset:6144
	s_setprio 1
	s_waitcnt lgkmcnt(3)
	v_mfma_f32_16x16x32_bf16 v[60:63], v[152:155], v[160:163], v[60:63]
	v_mfma_f32_16x16x32_bf16 v[56:59], v[152:155], v[164:167], v[56:59]
	v_mfma_f32_16x16x32_bf16 v[52:55], v[152:155], v[176:179], v[52:55]
	v_mfma_f32_16x16x32_bf16 v[48:51], v[152:155], v[182:185], v[48:51]
	s_waitcnt lgkmcnt(2)
	v_mfma_f32_16x16x32_bf16 v[44:47], v[156:159], v[160:163], v[44:47]
	v_mfma_f32_16x16x32_bf16 v[40:43], v[156:159], v[164:167], v[40:43]
	v_mfma_f32_16x16x32_bf16 v[36:39], v[156:159], v[176:179], v[36:39]
	v_mfma_f32_16x16x32_bf16 v[32:35], v[156:159], v[182:185], v[32:35]
	s_waitcnt lgkmcnt(1)
	v_mfma_f32_16x16x32_bf16 v[28:31], v[168:171], v[160:163], v[28:31]
	v_mfma_f32_16x16x32_bf16 v[24:27], v[168:171], v[164:167], v[24:27]
	v_mfma_f32_16x16x32_bf16 v[20:23], v[168:171], v[176:179], v[20:23]
	v_mfma_f32_16x16x32_bf16 v[16:19], v[168:171], v[182:185], v[16:19]
	s_waitcnt lgkmcnt(0)
	v_mfma_f32_16x16x32_bf16 v[12:15], v[172:175], v[160:163], v[12:15]
	v_mfma_f32_16x16x32_bf16 v[8:11], v[172:175], v[164:167], v[8:11]
	v_mfma_f32_16x16x32_bf16 v[4:7], v[172:175], v[176:179], v[4:7]
	v_mfma_f32_16x16x32_bf16 v[0:3], v[172:175], v[182:185], v[0:3]
	s_setprio 0
	v_lshlrev_b32_e32 v152, 1, v116
	v_add_u32_e32 v151, v151, v152
	v_add_u32_e32 v70, v70, v152
	ds_read_b128 v[152:155], v151
	ds_read_b128 v[160:163], v70 offset:16384
	ds_read_b128 v[164:167], v70 offset:18432
	ds_read_b128 v[176:179], v70 offset:20480
	ds_read_b128 v[182:185], v70 offset:22528
	ds_read_b128 v[156:159], v151 offset:2048
	ds_read_b128 v[168:171], v151 offset:4096
	ds_read_b128 v[172:175], v151 offset:6144
	s_setprio 1
	s_waitcnt lgkmcnt(3)
	v_mfma_f32_16x16x32_bf16 v[60:63], v[152:155], v[160:163], v[60:63]
	v_mfma_f32_16x16x32_bf16 v[56:59], v[152:155], v[164:167], v[56:59]
	v_mfma_f32_16x16x32_bf16 v[52:55], v[152:155], v[176:179], v[52:55]
	v_mfma_f32_16x16x32_bf16 v[48:51], v[152:155], v[182:185], v[48:51]
	s_waitcnt lgkmcnt(2)
	v_mfma_f32_16x16x32_bf16 v[44:47], v[156:159], v[160:163], v[44:47]
	v_mfma_f32_16x16x32_bf16 v[40:43], v[156:159], v[164:167], v[40:43]
	v_mfma_f32_16x16x32_bf16 v[36:39], v[156:159], v[176:179], v[36:39]
	v_mfma_f32_16x16x32_bf16 v[32:35], v[156:159], v[182:185], v[32:35]
	s_waitcnt lgkmcnt(1)
	v_mfma_f32_16x16x32_bf16 v[28:31], v[168:171], v[160:163], v[28:31]
	v_mfma_f32_16x16x32_bf16 v[24:27], v[168:171], v[164:167], v[24:27]
	v_mfma_f32_16x16x32_bf16 v[20:23], v[168:171], v[176:179], v[20:23]
	v_mfma_f32_16x16x32_bf16 v[16:19], v[168:171], v[182:185], v[16:19]
	s_waitcnt lgkmcnt(0)
	v_mfma_f32_16x16x32_bf16 v[12:15], v[172:175], v[160:163], v[12:15]
	v_mfma_f32_16x16x32_bf16 v[8:11], v[172:175], v[164:167], v[8:11]
	v_mfma_f32_16x16x32_bf16 v[4:7], v[172:175], v[176:179], v[4:7]
	v_mfma_f32_16x16x32_bf16 v[0:3], v[172:175], v[182:185], v[0:3]
	s_setprio 0
	s_add_u32 s10, s10, 0x80
	s_addc_u32 s11, s11, 0
	s_addk_i32 s24, 0x4000
	s_cmpk_eq_i32 s10, 0x780
	s_waitcnt vmcnt(0)
	s_barrier
	s_cbranch_scc0 .LBB0_443
	ds_read_b128 v[96:99], v69 offset:32768
	ds_read_b128 v[100:103], v69 offset:34816
	ds_read_b128 v[104:107], v135 offset:49152
	ds_read_b128 v[108:111], v135 offset:51200
	ds_read_b128 v[152:155], v69 offset:36864
	ds_read_b128 v[156:159], v69 offset:38912
	ds_read_b128 v[160:163], v135 offset:53248
	ds_read_b128 v[164:167], v135 offset:55296
	s_setprio 1
	s_waitcnt lgkmcnt(1)
	v_mfma_f32_16x16x32_bf16 v[4:7], v[156:159], v[160:163], v[4:7]
	s_waitcnt lgkmcnt(0)
	v_mfma_f32_16x16x32_bf16 v[0:3], v[156:159], v[164:167], v[0:3]
	v_mfma_f32_16x16x32_bf16 v[60:63], v[96:99], v[104:107], v[60:63]
	v_mfma_f32_16x16x32_bf16 v[56:59], v[96:99], v[108:111], v[56:59]
	v_mfma_f32_16x16x32_bf16 v[52:55], v[96:99], v[160:163], v[52:55]
	v_mfma_f32_16x16x32_bf16 v[48:51], v[96:99], v[164:167], v[48:51]
	v_mfma_f32_16x16x32_bf16 v[44:47], v[100:103], v[104:107], v[44:47]
	v_mfma_f32_16x16x32_bf16 v[40:43], v[100:103], v[108:111], v[40:43]
	v_mfma_f32_16x16x32_bf16 v[36:39], v[100:103], v[160:163], v[36:39]
	v_mfma_f32_16x16x32_bf16 v[32:35], v[100:103], v[164:167], v[32:35]
	v_mfma_f32_16x16x32_bf16 v[28:31], v[152:155], v[104:107], v[28:31]
	v_mfma_f32_16x16x32_bf16 v[24:27], v[152:155], v[108:111], v[24:27]
	v_mfma_f32_16x16x32_bf16 v[20:23], v[152:155], v[160:163], v[20:23]
	v_mfma_f32_16x16x32_bf16 v[16:19], v[152:155], v[164:167], v[16:19]
	v_mfma_f32_16x16x32_bf16 v[12:15], v[156:159], v[104:107], v[12:15]
	v_mfma_f32_16x16x32_bf16 v[8:11], v[156:159], v[108:111], v[8:11]
	s_setprio 0
	ds_read_b128 v[96:99], v136 offset:32768
	ds_read_b128 v[100:103], v136 offset:34816
	ds_read_b128 v[104:107], v137 offset:49152
	ds_read_b128 v[108:111], v137 offset:51200
	ds_read_b128 v[152:155], v136 offset:36864
	ds_read_b128 v[156:159], v136 offset:38912
	ds_read_b128 v[160:163], v137 offset:53248
	ds_read_b128 v[164:167], v137 offset:55296
	s_setprio 1
	s_waitcnt lgkmcnt(1)
	v_mfma_f32_16x16x32_bf16 v[4:7], v[156:159], v[160:163], v[4:7]
	s_waitcnt lgkmcnt(0)
	v_mfma_f32_16x16x32_bf16 v[0:3], v[156:159], v[164:167], v[0:3]
	v_mfma_f32_16x16x32_bf16 v[60:63], v[96:99], v[104:107], v[60:63]
	v_mfma_f32_16x16x32_bf16 v[56:59], v[96:99], v[108:111], v[56:59]
	v_mfma_f32_16x16x32_bf16 v[52:55], v[96:99], v[160:163], v[52:55]
	v_mfma_f32_16x16x32_bf16 v[48:51], v[96:99], v[164:167], v[48:51]
	v_mfma_f32_16x16x32_bf16 v[44:47], v[100:103], v[104:107], v[44:47]
	v_mfma_f32_16x16x32_bf16 v[40:43], v[100:103], v[108:111], v[40:43]
	v_mfma_f32_16x16x32_bf16 v[36:39], v[100:103], v[160:163], v[36:39]
	v_mfma_f32_16x16x32_bf16 v[32:35], v[100:103], v[164:167], v[32:35]
	v_mfma_f32_16x16x32_bf16 v[28:31], v[152:155], v[104:107], v[28:31]
	v_mfma_f32_16x16x32_bf16 v[24:27], v[152:155], v[108:111], v[24:27]
	v_mfma_f32_16x16x32_bf16 v[20:23], v[152:155], v[160:163], v[20:23]
	v_mfma_f32_16x16x32_bf16 v[16:19], v[152:155], v[164:167], v[16:19]
	v_mfma_f32_16x16x32_bf16 v[12:15], v[156:159], v[104:107], v[12:15]
	v_mfma_f32_16x16x32_bf16 v[8:11], v[156:159], v[108:111], v[8:11]
	s_setprio 0
	s_barrier
	ds_write2_b32 v134, v60, v56 offset1:16
	ds_write2_b32 v134, v61, v57 offset0:132 offset1:148
	v_add_u32_e32 v56, 0x400, v134
	ds_write2_b32 v56, v62, v58 offset0:8 offset1:24
	ds_write2_b32 v56, v63, v59 offset0:140 offset1:156
	ds_write2_b32 v134, v52, v48 offset0:32 offset1:48
	ds_write2_b32 v134, v53, v49 offset0:164 offset1:180
	ds_write2_b32 v56, v54, v50 offset0:40 offset1:56
	ds_write2_b32 v56, v55, v51 offset0:172 offset1:188
	v_add_u32_e32 v48, 0x2000, v134
	ds_write2_b32 v48, v44, v40 offset0:64 offset1:80
	ds_write2_b32 v48, v45, v41 offset0:196 offset1:212
	v_add_u32_e32 v40, 0x2400, v134
	ds_write2_b32 v40, v46, v42 offset0:72 offset1:88
	ds_write2_b32 v40, v47, v43 offset0:204 offset1:220
	ds_write2_b32 v48, v36, v32 offset0:96 offset1:112
	ds_write2_b32 v48, v37, v33 offset0:228 offset1:244
	ds_write2_b32 v40, v38, v34 offset0:104 offset1:120
	ds_write2_b32 v40, v39, v35 offset0:236 offset1:252
	v_add_u32_e32 v32, 0x4000, v134
	ds_write2_b32 v32, v28, v24 offset0:128 offset1:144
	v_add_u32_e32 v24, 0x4400, v134
	ds_write2_b32 v24, v29, v25 offset0:4 offset1:20
	ds_write2_b32 v24, v30, v26 offset0:136 offset1:152
	v_add_u32_e32 v25, 0x4800, v134
	ds_write2_b32 v25, v31, v27 offset0:12 offset1:28
	ds_write2_b32 v32, v20, v16 offset0:160 offset1:176
	ds_write2_b32 v24, v21, v17 offset0:36 offset1:52
	ds_write2_b32 v24, v22, v18 offset0:168 offset1:184
	ds_write2_b32 v25, v23, v19 offset0:44 offset1:60
	v_add_u32_e32 v16, 0x6000, v134
	ds_write2_b32 v16, v12, v8 offset0:192 offset1:208
	v_add_u32_e32 v8, 0x6400, v134
	ds_write2_b32 v8, v13, v9 offset0:68 offset1:84
	ds_write2_b32 v8, v14, v10 offset0:200 offset1:216
	v_add_u32_e32 v9, 0x6800, v134
	ds_write2_b32 v9, v15, v11 offset0:76 offset1:92
	ds_write2_b32 v16, v4, v0 offset0:224 offset1:240
	ds_write2_b32 v8, v5, v1 offset0:100 offset1:116
	ds_write2_b32 v8, v6, v2 offset0:232 offset1:248
	ds_write2_b32 v9, v7, v3 offset0:108 offset1:124
	v_or_b32_e32 v0, s22, v113
	v_lshlrev_b32_e32 v70, 2, v0
	v_lshl_add_u64 v[0:1], s[12:13], 0, v[70:71]
	v_lshl_add_u64 v[2:3], s[8:9], 0, v[70:71]
	v_add_u32_e32 v4, s23, v146
	s_mov_b32 s10, 0
	s_waitcnt lgkmcnt(0)
	s_barrier

.LBB0_605:
	s_and_b32 s18, s17, 0x4000
	s_xor_b32 s19, s18, 0x4000
	s_lshl_b32 s19, s19, 1
	s_add_i32 s19, s19, 32
	s_add_u32 s90, s52, s10
	s_addc_u32 s91, s53, s11
	s_add_i32 m0, s19, s82
	s_lshl_b32 s18, s18, 1
	global_load_lds_dwordx4 v184, s[90:91]
	s_add_i32 m0, s19, s83
	s_add_i32 s18, s18, 32
	global_load_lds_dwordx4 v185, s[90:91]
	s_add_i32 m0, s19, s84
	v_lshl_add_u32 v137, v114, 1, s18
	global_load_lds_dwordx4 v186, s[90:91]
	s_add_i32 m0, s19, s85
	v_lshl_add_u32 v170, v115, 1, s18
	global_load_lds_dwordx4 v187, s[90:91]
	s_add_i32 m0, s19, s86
	v_add_u32_e32 v158, v137, v135
	global_load_lds_dwordx4 v188, s[90:91]
	s_add_i32 m0, s19, s87
	v_add_u32_e32 v166, v170, v135
	global_load_lds_dwordx4 v189, s[90:91]
	s_add_i32 m0, s19, s88
	s_addk_i32 s17, 0x4000
	global_load_lds_dwordx4 v190, s[90:91]
	s_add_i32 m0, s19, s89
	s_add_u32 s10, s10, 0x80
	s_addc_u32 s11, s11, 0
	global_load_lds_dwordx4 v191, s[90:91]
	ds_read_b128 v[138:141], v158
	ds_read_b128 v[146:149], v166 offset:16384
	ds_read_b128 v[150:153], v166 offset:18432
	ds_read_b128 v[162:165], v166 offset:20480
	ds_read_b128 v[166:169], v166 offset:22528
	ds_read_b128 v[142:145], v158 offset:2048
	ds_read_b128 v[154:157], v158 offset:4096
	ds_read_b128 v[158:161], v158 offset:6144
	s_setprio 1
	s_waitcnt lgkmcnt(3)
	v_mfma_f32_16x16x32_bf16 v[60:63], v[138:141], v[146:149], v[60:63]
	v_mfma_f32_16x16x32_bf16 v[56:59], v[138:141], v[150:153], v[56:59]
	v_mfma_f32_16x16x32_bf16 v[52:55], v[138:141], v[162:165], v[52:55]
	v_mfma_f32_16x16x32_bf16 v[48:51], v[138:141], v[166:169], v[48:51]
	s_waitcnt lgkmcnt(2)
	v_mfma_f32_16x16x32_bf16 v[44:47], v[142:145], v[146:149], v[44:47]
	v_mfma_f32_16x16x32_bf16 v[40:43], v[142:145], v[150:153], v[40:43]
	v_mfma_f32_16x16x32_bf16 v[36:39], v[142:145], v[162:165], v[36:39]
	v_mfma_f32_16x16x32_bf16 v[32:35], v[142:145], v[166:169], v[32:35]
	s_waitcnt lgkmcnt(1)
	v_mfma_f32_16x16x32_bf16 v[28:31], v[154:157], v[146:149], v[28:31]
	v_mfma_f32_16x16x32_bf16 v[24:27], v[154:157], v[150:153], v[24:27]
	v_mfma_f32_16x16x32_bf16 v[20:23], v[154:157], v[162:165], v[20:23]
	v_mfma_f32_16x16x32_bf16 v[16:19], v[154:157], v[166:169], v[16:19]
	s_waitcnt lgkmcnt(0)
	v_mfma_f32_16x16x32_bf16 v[12:15], v[158:161], v[146:149], v[12:15]
	v_mfma_f32_16x16x32_bf16 v[8:11], v[158:161], v[150:153], v[8:11]
	v_mfma_f32_16x16x32_bf16 v[4:7], v[158:161], v[162:165], v[4:7]
	v_mfma_f32_16x16x32_bf16 v[0:3], v[158:161], v[166:169], v[0:3]
	s_setprio 0
	v_add_u32_e32 v137, v137, v136
	v_add_u32_e32 v166, v170, v136
	ds_read_b128 v[138:141], v137
	ds_read_b128 v[146:149], v166 offset:16384
	ds_read_b128 v[150:153], v166 offset:18432
	ds_read_b128 v[162:165], v166 offset:20480
	ds_read_b128 v[166:169], v166 offset:22528
	ds_read_b128 v[142:145], v137 offset:2048
	ds_read_b128 v[154:157], v137 offset:4096
	ds_read_b128 v[158:161], v137 offset:6144
	s_setprio 1
	s_waitcnt lgkmcnt(3)
	v_mfma_f32_16x16x32_bf16 v[60:63], v[138:141], v[146:149], v[60:63]
	v_mfma_f32_16x16x32_bf16 v[56:59], v[138:141], v[150:153], v[56:59]
	v_mfma_f32_16x16x32_bf16 v[52:55], v[138:141], v[162:165], v[52:55]
	v_mfma_f32_16x16x32_bf16 v[48:51], v[138:141], v[166:169], v[48:51]
	s_waitcnt lgkmcnt(2)
	v_mfma_f32_16x16x32_bf16 v[44:47], v[142:145], v[146:149], v[44:47]
	v_mfma_f32_16x16x32_bf16 v[40:43], v[142:145], v[150:153], v[40:43]
	v_mfma_f32_16x16x32_bf16 v[36:39], v[142:145], v[162:165], v[36:39]
	v_mfma_f32_16x16x32_bf16 v[32:35], v[142:145], v[166:169], v[32:35]
	s_waitcnt lgkmcnt(1)
	v_mfma_f32_16x16x32_bf16 v[28:31], v[154:157], v[146:149], v[28:31]
	v_mfma_f32_16x16x32_bf16 v[24:27], v[154:157], v[150:153], v[24:27]
	v_mfma_f32_16x16x32_bf16 v[20:23], v[154:157], v[162:165], v[20:23]
	v_mfma_f32_16x16x32_bf16 v[16:19], v[154:157], v[166:169], v[16:19]
	s_waitcnt lgkmcnt(0)
	v_mfma_f32_16x16x32_bf16 v[12:15], v[158:161], v[146:149], v[12:15]
	v_mfma_f32_16x16x32_bf16 v[8:11], v[158:161], v[150:153], v[8:11]
	v_mfma_f32_16x16x32_bf16 v[4:7], v[158:161], v[162:165], v[4:7]
	v_mfma_f32_16x16x32_bf16 v[0:3], v[158:161], v[166:169], v[0:3]
	s_setprio 0
	s_cmpk_eq_i32 s10, 0x780
	s_waitcnt vmcnt(0)
	s_barrier
	s_cbranch_scc0 .LBB0_605
	ds_read_b128 v[90:93], v116 offset:55296
	ds_read_b128 v[94:97], v116 offset:53248
	ds_read_b128 v[98:101], v117 offset:38912
	ds_read_b128 v[102:105], v117 offset:36864
	ds_read_b128 v[138:141], v116 offset:51200
	ds_read_b128 v[142:145], v116 offset:49152
	ds_read_b128 v[146:149], v117 offset:34816
	ds_read_b128 v[150:153], v117 offset:32768
	s_setprio 1
	s_waitcnt lgkmcnt(5)
	v_mfma_f32_16x16x32_bf16 v[0:3], v[98:101], v[90:93], v[0:3]
	s_waitcnt lgkmcnt(0)
	v_mfma_f32_16x16x32_bf16 v[60:63], v[150:153], v[142:145], v[60:63]
	v_mfma_f32_16x16x32_bf16 v[56:59], v[150:153], v[138:141], v[56:59]
	v_mfma_f32_16x16x32_bf16 v[52:55], v[150:153], v[94:97], v[52:55]
	v_mfma_f32_16x16x32_bf16 v[48:51], v[150:153], v[90:93], v[48:51]
	v_mfma_f32_16x16x32_bf16 v[44:47], v[146:149], v[142:145], v[44:47]
	v_mfma_f32_16x16x32_bf16 v[40:43], v[146:149], v[138:141], v[40:43]
	v_mfma_f32_16x16x32_bf16 v[36:39], v[146:149], v[94:97], v[36:39]
	v_mfma_f32_16x16x32_bf16 v[32:35], v[146:149], v[90:93], v[32:35]
	v_mfma_f32_16x16x32_bf16 v[28:31], v[102:105], v[142:145], v[28:31]
	v_mfma_f32_16x16x32_bf16 v[24:27], v[102:105], v[138:141], v[24:27]
	v_mfma_f32_16x16x32_bf16 v[20:23], v[102:105], v[94:97], v[20:23]
	v_mfma_f32_16x16x32_bf16 v[16:19], v[102:105], v[90:93], v[16:19]
	v_mfma_f32_16x16x32_bf16 v[12:15], v[98:101], v[142:145], v[12:15]
	v_mfma_f32_16x16x32_bf16 v[8:11], v[98:101], v[138:141], v[8:11]
	v_mfma_f32_16x16x32_bf16 v[4:7], v[98:101], v[94:97], v[4:7]
	s_setprio 0
	ds_read_b128 v[90:93], v118 offset:32768
	ds_read_b128 v[94:97], v118 offset:34816
	ds_read_b128 v[98:101], v119 offset:49152
	ds_read_b128 v[102:105], v119 offset:51200
	ds_read_b128 v[138:141], v118 offset:36864
	ds_read_b128 v[142:145], v118 offset:38912
	ds_read_b128 v[146:149], v119 offset:53248
	ds_read_b128 v[150:153], v119 offset:55296
	s_setprio 1
	s_waitcnt lgkmcnt(0)
	v_mfma_f32_16x16x32_bf16 v[0:3], v[142:145], v[150:153], v[0:3]
	v_mfma_f32_16x16x32_bf16 v[60:63], v[90:93], v[98:101], v[60:63]
	v_mfma_f32_16x16x32_bf16 v[56:59], v[90:93], v[102:105], v[56:59]
	v_mfma_f32_16x16x32_bf16 v[52:55], v[90:93], v[146:149], v[52:55]
	v_mfma_f32_16x16x32_bf16 v[48:51], v[90:93], v[150:153], v[48:51]
	v_mfma_f32_16x16x32_bf16 v[44:47], v[94:97], v[98:101], v[44:47]
	v_mfma_f32_16x16x32_bf16 v[40:43], v[94:97], v[102:105], v[40:43]
	v_mfma_f32_16x16x32_bf16 v[36:39], v[94:97], v[146:149], v[36:39]
	v_mfma_f32_16x16x32_bf16 v[32:35], v[94:97], v[150:153], v[32:35]
	v_mfma_f32_16x16x32_bf16 v[28:31], v[138:141], v[98:101], v[28:31]
	v_mfma_f32_16x16x32_bf16 v[24:27], v[138:141], v[102:105], v[24:27]
	v_mfma_f32_16x16x32_bf16 v[20:23], v[138:141], v[146:149], v[20:23]
	v_mfma_f32_16x16x32_bf16 v[16:19], v[138:141], v[150:153], v[16:19]
	v_mfma_f32_16x16x32_bf16 v[12:15], v[142:145], v[98:101], v[12:15]
	v_mfma_f32_16x16x32_bf16 v[8:11], v[142:145], v[102:105], v[8:11]
	v_mfma_f32_16x16x32_bf16 v[4:7], v[142:145], v[146:149], v[4:7]
	s_setprio 0
	s_barrier
	ds_write2_b32 v120, v60, v56 offset1:16
	ds_write2_b32 v120, v61, v57 offset0:132 offset1:148
	v_add_u32_e32 v56, 0x400, v120
	ds_write2_b32 v56, v62, v58 offset0:8 offset1:24
	ds_write2_b32 v56, v63, v59 offset0:140 offset1:156
	ds_write2_b32 v120, v52, v48 offset0:32 offset1:48
	ds_write2_b32 v120, v53, v49 offset0:164 offset1:180
	ds_write2_b32 v56, v54, v50 offset0:40 offset1:56
	ds_write2_b32 v56, v55, v51 offset0:172 offset1:188
	v_add_u32_e32 v48, 0x2000, v120
	ds_write2_b32 v48, v44, v40 offset0:64 offset1:80
	ds_write2_b32 v48, v45, v41 offset0:196 offset1:212
	v_add_u32_e32 v40, 0x2400, v120
	ds_write2_b32 v40, v46, v42 offset0:72 offset1:88
	ds_write2_b32 v40, v47, v43 offset0:204 offset1:220
	ds_write2_b32 v48, v36, v32 offset0:96 offset1:112
	ds_write2_b32 v48, v37, v33 offset0:228 offset1:244
	ds_write2_b32 v40, v38, v34 offset0:104 offset1:120
	ds_write2_b32 v40, v39, v35 offset0:236 offset1:252
	v_add_u32_e32 v32, 0x4000, v120
	ds_write2_b32 v32, v28, v24 offset0:128 offset1:144
	v_add_u32_e32 v24, 0x4400, v120
	ds_write2_b32 v24, v29, v25 offset0:4 offset1:20
	ds_write2_b32 v24, v30, v26 offset0:136 offset1:152
	v_add_u32_e32 v25, 0x4800, v120
	ds_write2_b32 v25, v31, v27 offset0:12 offset1:28
	ds_write2_b32 v32, v20, v16 offset0:160 offset1:176
	ds_write2_b32 v24, v21, v17 offset0:36 offset1:52
	ds_write2_b32 v24, v22, v18 offset0:168 offset1:184
	ds_write2_b32 v25, v23, v19 offset0:44 offset1:60
	v_add_u32_e32 v16, 0x6000, v120
	ds_write2_b32 v16, v12, v8 offset0:192 offset1:208
	v_add_u32_e32 v8, 0x6400, v120
	ds_write2_b32 v8, v13, v9 offset0:68 offset1:84
	ds_write2_b32 v8, v14, v10 offset0:200 offset1:216
	v_add_u32_e32 v9, 0x6800, v120
	ds_write2_b32 v9, v15, v11 offset0:76 offset1:92
	ds_write2_b32 v16, v4, v0 offset0:224 offset1:240
	ds_write2_b32 v8, v5, v1 offset0:100 offset1:116
	ds_write2_b32 v8, v6, v2 offset0:232 offset1:248
	ds_write2_b32 v9, v7, v3 offset0:108 offset1:124
	v_or_b32_e32 v0, s16, v121
	v_ashrrev_i32_e32 v1, 31, v0
	v_lshl_add_u64 v[0:1], v[0:1], 1, s[4:5]
	v_add_u32_e32 v2, s15, v128
	s_mov_b32 s10, 0
	s_waitcnt lgkmcnt(0)
	s_barrier

.LBB0_616:
	s_and_b32 s15, s14, 0x4000
	s_xor_b32 s16, s15, 0x4000
	s_lshl_b32 s16, s16, 1
	s_add_i32 s16, s16, 32
	s_add_u32 s90, s52, s6
	s_addc_u32 s91, s53, s7
	s_add_i32 m0, s16, s82
	s_lshl_b32 s15, s15, 1
	global_load_lds_dwordx4 v184, s[90:91]
	s_add_i32 m0, s16, s83
	s_add_i32 s15, s15, 32
	global_load_lds_dwordx4 v185, s[90:91]
	s_add_i32 m0, s16, s84
	v_lshl_add_u32 v137, v113, 1, s15
	global_load_lds_dwordx4 v186, s[90:91]
	s_add_i32 m0, s16, s85
	v_lshl_add_u32 v170, v114, 1, s15
	global_load_lds_dwordx4 v187, s[90:91]
	s_add_i32 m0, s16, s86
	v_add_u32_e32 v158, v137, v135
	global_load_lds_dwordx4 v188, s[90:91]
	s_add_i32 m0, s16, s87
	v_add_u32_e32 v166, v170, v135
	global_load_lds_dwordx4 v189, s[90:91]
	s_add_i32 m0, s16, s88
	s_addk_i32 s14, 0x4000
	global_load_lds_dwordx4 v190, s[90:91]
	s_add_i32 m0, s16, s89
	s_add_u32 s6, s6, 0x80
	s_addc_u32 s7, s7, 0
	global_load_lds_dwordx4 v191, s[90:91]
	ds_read_b128 v[138:141], v158
	ds_read_b128 v[146:149], v166 offset:16384
	ds_read_b128 v[150:153], v166 offset:18432
	ds_read_b128 v[162:165], v166 offset:20480
	ds_read_b128 v[166:169], v166 offset:22528
	ds_read_b128 v[142:145], v158 offset:2048
	ds_read_b128 v[154:157], v158 offset:4096
	ds_read_b128 v[158:161], v158 offset:6144
	s_setprio 1
	s_waitcnt lgkmcnt(3)
	v_mfma_f32_16x16x32_bf16 v[60:63], v[138:141], v[146:149], v[60:63]
	v_mfma_f32_16x16x32_bf16 v[56:59], v[138:141], v[150:153], v[56:59]
	v_mfma_f32_16x16x32_bf16 v[52:55], v[138:141], v[162:165], v[52:55]
	v_mfma_f32_16x16x32_bf16 v[48:51], v[138:141], v[166:169], v[48:51]
	s_waitcnt lgkmcnt(2)
	v_mfma_f32_16x16x32_bf16 v[44:47], v[142:145], v[146:149], v[44:47]
	v_mfma_f32_16x16x32_bf16 v[40:43], v[142:145], v[150:153], v[40:43]
	v_mfma_f32_16x16x32_bf16 v[36:39], v[142:145], v[162:165], v[36:39]
	v_mfma_f32_16x16x32_bf16 v[32:35], v[142:145], v[166:169], v[32:35]
	s_waitcnt lgkmcnt(1)
	v_mfma_f32_16x16x32_bf16 v[28:31], v[154:157], v[146:149], v[28:31]
	v_mfma_f32_16x16x32_bf16 v[24:27], v[154:157], v[150:153], v[24:27]
	v_mfma_f32_16x16x32_bf16 v[20:23], v[154:157], v[162:165], v[20:23]
	v_mfma_f32_16x16x32_bf16 v[16:19], v[154:157], v[166:169], v[16:19]
	s_waitcnt lgkmcnt(0)
	v_mfma_f32_16x16x32_bf16 v[12:15], v[158:161], v[146:149], v[12:15]
	v_mfma_f32_16x16x32_bf16 v[8:11], v[158:161], v[150:153], v[8:11]
	v_mfma_f32_16x16x32_bf16 v[4:7], v[158:161], v[162:165], v[4:7]
	v_mfma_f32_16x16x32_bf16 v[0:3], v[158:161], v[166:169], v[0:3]
	s_setprio 0
	v_add_u32_e32 v137, v137, v136
	v_add_u32_e32 v166, v170, v136
	ds_read_b128 v[138:141], v137
	ds_read_b128 v[146:149], v166 offset:16384
	ds_read_b128 v[150:153], v166 offset:18432
	ds_read_b128 v[162:165], v166 offset:20480
	ds_read_b128 v[166:169], v166 offset:22528
	ds_read_b128 v[142:145], v137 offset:2048
	ds_read_b128 v[154:157], v137 offset:4096
	ds_read_b128 v[158:161], v137 offset:6144
	s_setprio 1
	s_waitcnt lgkmcnt(3)
	v_mfma_f32_16x16x32_bf16 v[60:63], v[138:141], v[146:149], v[60:63]
	v_mfma_f32_16x16x32_bf16 v[56:59], v[138:141], v[150:153], v[56:59]
	v_mfma_f32_16x16x32_bf16 v[52:55], v[138:141], v[162:165], v[52:55]
	v_mfma_f32_16x16x32_bf16 v[48:51], v[138:141], v[166:169], v[48:51]
	s_waitcnt lgkmcnt(2)
	v_mfma_f32_16x16x32_bf16 v[44:47], v[142:145], v[146:149], v[44:47]
	v_mfma_f32_16x16x32_bf16 v[40:43], v[142:145], v[150:153], v[40:43]
	v_mfma_f32_16x16x32_bf16 v[36:39], v[142:145], v[162:165], v[36:39]
	v_mfma_f32_16x16x32_bf16 v[32:35], v[142:145], v[166:169], v[32:35]
	s_waitcnt lgkmcnt(1)
	v_mfma_f32_16x16x32_bf16 v[28:31], v[154:157], v[146:149], v[28:31]
	v_mfma_f32_16x16x32_bf16 v[24:27], v[154:157], v[150:153], v[24:27]
	v_mfma_f32_16x16x32_bf16 v[20:23], v[154:157], v[162:165], v[20:23]
	v_mfma_f32_16x16x32_bf16 v[16:19], v[154:157], v[166:169], v[16:19]
	s_waitcnt lgkmcnt(0)
	v_mfma_f32_16x16x32_bf16 v[12:15], v[158:161], v[146:149], v[12:15]
	v_mfma_f32_16x16x32_bf16 v[8:11], v[158:161], v[150:153], v[8:11]
	v_mfma_f32_16x16x32_bf16 v[4:7], v[158:161], v[162:165], v[4:7]
	v_mfma_f32_16x16x32_bf16 v[0:3], v[158:161], v[166:169], v[0:3]
	s_setprio 0
	s_cmpk_eq_i32 s6, 0x780
	s_waitcnt vmcnt(0)
	s_barrier
	s_cbranch_scc0 .LBB0_616
	ds_read_b128 v[88:91], v115 offset:55296
	ds_read_b128 v[92:95], v115 offset:53248
	ds_read_b128 v[96:99], v116 offset:38912
	ds_read_b128 v[100:103], v116 offset:36864
	ds_read_b128 v[138:141], v115 offset:51200
	ds_read_b128 v[142:145], v115 offset:49152
	ds_read_b128 v[146:149], v116 offset:34816
	ds_read_b128 v[150:153], v116 offset:32768
	s_setprio 1
	s_waitcnt lgkmcnt(5)
	v_mfma_f32_16x16x32_bf16 v[0:3], v[96:99], v[88:91], v[0:3]
	s_waitcnt lgkmcnt(0)
	v_mfma_f32_16x16x32_bf16 v[60:63], v[150:153], v[142:145], v[60:63]
	v_mfma_f32_16x16x32_bf16 v[56:59], v[150:153], v[138:141], v[56:59]
	v_mfma_f32_16x16x32_bf16 v[52:55], v[150:153], v[92:95], v[52:55]
	v_mfma_f32_16x16x32_bf16 v[48:51], v[150:153], v[88:91], v[48:51]
	v_mfma_f32_16x16x32_bf16 v[44:47], v[146:149], v[142:145], v[44:47]
	v_mfma_f32_16x16x32_bf16 v[40:43], v[146:149], v[138:141], v[40:43]
	v_mfma_f32_16x16x32_bf16 v[36:39], v[146:149], v[92:95], v[36:39]
	v_mfma_f32_16x16x32_bf16 v[32:35], v[146:149], v[88:91], v[32:35]
	v_mfma_f32_16x16x32_bf16 v[28:31], v[100:103], v[142:145], v[28:31]
	v_mfma_f32_16x16x32_bf16 v[24:27], v[100:103], v[138:141], v[24:27]
	v_mfma_f32_16x16x32_bf16 v[20:23], v[100:103], v[92:95], v[20:23]
	v_mfma_f32_16x16x32_bf16 v[16:19], v[100:103], v[88:91], v[16:19]
	v_mfma_f32_16x16x32_bf16 v[12:15], v[96:99], v[142:145], v[12:15]
	v_mfma_f32_16x16x32_bf16 v[8:11], v[96:99], v[138:141], v[8:11]
	v_mfma_f32_16x16x32_bf16 v[4:7], v[96:99], v[92:95], v[4:7]
	s_setprio 0
	ds_read_b128 v[88:91], v117 offset:32768
	ds_read_b128 v[92:95], v117 offset:34816
	ds_read_b128 v[96:99], v118 offset:49152
	ds_read_b128 v[100:103], v118 offset:51200
	ds_read_b128 v[138:141], v117 offset:36864
	ds_read_b128 v[142:145], v117 offset:38912
	ds_read_b128 v[146:149], v118 offset:53248
	ds_read_b128 v[150:153], v118 offset:55296
	s_setprio 1
	s_waitcnt lgkmcnt(0)
	v_mfma_f32_16x16x32_bf16 v[0:3], v[142:145], v[150:153], v[0:3]
	v_mfma_f32_16x16x32_bf16 v[60:63], v[88:91], v[96:99], v[60:63]
	v_mfma_f32_16x16x32_bf16 v[56:59], v[88:91], v[100:103], v[56:59]
	v_mfma_f32_16x16x32_bf16 v[52:55], v[88:91], v[146:149], v[52:55]
	v_mfma_f32_16x16x32_bf16 v[48:51], v[88:91], v[150:153], v[48:51]
	v_mfma_f32_16x16x32_bf16 v[44:47], v[92:95], v[96:99], v[44:47]
	v_mfma_f32_16x16x32_bf16 v[40:43], v[92:95], v[100:103], v[40:43]
	v_mfma_f32_16x16x32_bf16 v[36:39], v[92:95], v[146:149], v[36:39]
	v_mfma_f32_16x16x32_bf16 v[32:35], v[92:95], v[150:153], v[32:35]
	v_mfma_f32_16x16x32_bf16 v[28:31], v[138:141], v[96:99], v[28:31]
	v_mfma_f32_16x16x32_bf16 v[24:27], v[138:141], v[100:103], v[24:27]
	v_mfma_f32_16x16x32_bf16 v[20:23], v[138:141], v[146:149], v[20:23]
	v_mfma_f32_16x16x32_bf16 v[16:19], v[138:141], v[150:153], v[16:19]
	v_mfma_f32_16x16x32_bf16 v[12:15], v[142:145], v[96:99], v[12:15]
	v_mfma_f32_16x16x32_bf16 v[8:11], v[142:145], v[100:103], v[8:11]
	v_mfma_f32_16x16x32_bf16 v[4:7], v[142:145], v[146:149], v[4:7]
	s_setprio 0
	s_barrier
	ds_write2_b32 v119, v60, v56 offset1:16
	ds_write2_b32 v119, v61, v57 offset0:132 offset1:148
	v_add_u32_e32 v56, 0x400, v119
	ds_write2_b32 v56, v62, v58 offset0:8 offset1:24
	ds_write2_b32 v56, v63, v59 offset0:140 offset1:156
	ds_write2_b32 v119, v52, v48 offset0:32 offset1:48
	ds_write2_b32 v119, v53, v49 offset0:164 offset1:180
	ds_write2_b32 v56, v54, v50 offset0:40 offset1:56
	ds_write2_b32 v56, v55, v51 offset0:172 offset1:188
	v_add_u32_e32 v48, 0x2000, v119
	ds_write2_b32 v48, v44, v40 offset0:64 offset1:80
	ds_write2_b32 v48, v45, v41 offset0:196 offset1:212
	v_add_u32_e32 v40, 0x2400, v119
	ds_write2_b32 v40, v46, v42 offset0:72 offset1:88
	ds_write2_b32 v40, v47, v43 offset0:204 offset1:220
	ds_write2_b32 v48, v36, v32 offset0:96 offset1:112
	ds_write2_b32 v48, v37, v33 offset0:228 offset1:244
	ds_write2_b32 v40, v38, v34 offset0:104 offset1:120
	ds_write2_b32 v40, v39, v35 offset0:236 offset1:252
	v_add_u32_e32 v32, 0x4000, v119
	ds_write2_b32 v32, v28, v24 offset0:128 offset1:144
	v_add_u32_e32 v24, 0x4400, v119
	ds_write2_b32 v24, v29, v25 offset0:4 offset1:20
	ds_write2_b32 v24, v30, v26 offset0:136 offset1:152
	v_add_u32_e32 v25, 0x4800, v119
	ds_write2_b32 v25, v31, v27 offset0:12 offset1:28
	ds_write2_b32 v32, v20, v16 offset0:160 offset1:176
	ds_write2_b32 v24, v21, v17 offset0:36 offset1:52
	ds_write2_b32 v24, v22, v18 offset0:168 offset1:184
	ds_write2_b32 v25, v23, v19 offset0:44 offset1:60
	v_add_u32_e32 v16, 0x6000, v119
	ds_write2_b32 v16, v12, v8 offset0:192 offset1:208
	v_add_u32_e32 v8, 0x6400, v119
	ds_write2_b32 v8, v13, v9 offset0:68 offset1:84
	ds_write2_b32 v8, v14, v10 offset0:200 offset1:216
	v_add_u32_e32 v9, 0x6800, v119
	ds_write2_b32 v9, v15, v11 offset0:76 offset1:92
	ds_write2_b32 v16, v4, v0 offset0:224 offset1:240
	ds_write2_b32 v8, v5, v1 offset0:100 offset1:116
	ds_write2_b32 v8, v6, v2 offset0:232 offset1:248
	ds_write2_b32 v9, v7, v3 offset0:108 offset1:124
	v_or_b32_e32 v0, s12, v120
	v_ashrrev_i32_e32 v1, 31, v0
	v_lshl_add_u64 v[0:1], v[0:1], 1, s[4:5]
	v_add_u32_e32 v2, s13, v128
	s_mov_b32 s6, 0
	s_waitcnt lgkmcnt(0)
	s_barrier

.LBB0_682:
	s_and_b32 s25, s24, 0x4000
	s_xor_b32 s26, s25, 0x4000
	s_lshl_b32 s26, s26, 1
	s_add_i32 s26, s26, 32
	s_add_u32 s90, s52, s14
	s_addc_u32 s91, s53, s15
	s_add_i32 m0, s26, s82
	s_lshl_b32 s25, s25, 1
	global_load_lds_dwordx4 v192, s[90:91]
	s_add_i32 m0, s26, s83
	s_add_i32 s25, s25, 32
	global_load_lds_dwordx4 v193, s[90:91]
	s_add_i32 m0, s26, s84
	v_add3_u32 v170, s25, v114, v135
	global_load_lds_dwordx4 v194, s[90:91]
	s_add_i32 m0, s26, s85
	v_add3_u32 v171, s25, v115, v135
	global_load_lds_dwordx4 v195, s[90:91]
	s_add_i32 m0, s26, s86
	v_add_u32_e32 v158, v170, v136
	global_load_lds_dwordx4 v196, s[90:91]
	s_add_i32 m0, s26, s87
	v_add_u32_e32 v166, v171, v136
	global_load_lds_dwordx4 v197, s[90:91]
	s_add_i32 m0, s26, s88
	s_addk_i32 s24, 0x4000
	global_load_lds_dwordx4 v198, s[90:91]
	s_add_i32 m0, s26, s89
	s_add_u32 s14, s14, 0x80
	s_addc_u32 s15, s15, 0
	global_load_lds_dwordx4 v199, s[90:91]
	ds_read_b128 v[138:141], v158
	ds_read_b128 v[146:149], v166 offset:16384
	ds_read_b128 v[150:153], v166 offset:18432
	ds_read_b128 v[162:165], v166 offset:20480
	ds_read_b128 v[166:169], v166 offset:22528
	ds_read_b128 v[142:145], v158 offset:2048
	ds_read_b128 v[154:157], v158 offset:4096
	ds_read_b128 v[158:161], v158 offset:6144
	s_setprio 1
	s_waitcnt lgkmcnt(3)
	v_mfma_f32_16x16x32_bf16 v[60:63], v[138:141], v[146:149], v[60:63]
	v_mfma_f32_16x16x32_bf16 v[56:59], v[138:141], v[150:153], v[56:59]
	v_mfma_f32_16x16x32_bf16 v[52:55], v[138:141], v[162:165], v[52:55]
	v_mfma_f32_16x16x32_bf16 v[48:51], v[138:141], v[166:169], v[48:51]
	s_waitcnt lgkmcnt(2)
	v_mfma_f32_16x16x32_bf16 v[44:47], v[142:145], v[146:149], v[44:47]
	v_mfma_f32_16x16x32_bf16 v[40:43], v[142:145], v[150:153], v[40:43]
	v_mfma_f32_16x16x32_bf16 v[36:39], v[142:145], v[162:165], v[36:39]
	v_mfma_f32_16x16x32_bf16 v[32:35], v[142:145], v[166:169], v[32:35]
	s_waitcnt lgkmcnt(1)
	v_mfma_f32_16x16x32_bf16 v[28:31], v[154:157], v[146:149], v[28:31]
	v_mfma_f32_16x16x32_bf16 v[24:27], v[154:157], v[150:153], v[24:27]
	v_mfma_f32_16x16x32_bf16 v[20:23], v[154:157], v[162:165], v[20:23]
	v_mfma_f32_16x16x32_bf16 v[16:19], v[154:157], v[166:169], v[16:19]
	s_waitcnt lgkmcnt(0)
	v_mfma_f32_16x16x32_bf16 v[12:15], v[158:161], v[146:149], v[12:15]
	v_mfma_f32_16x16x32_bf16 v[8:11], v[158:161], v[150:153], v[8:11]
	v_mfma_f32_16x16x32_bf16 v[4:7], v[158:161], v[162:165], v[4:7]
	v_mfma_f32_16x16x32_bf16 v[0:3], v[158:161], v[166:169], v[0:3]
	s_setprio 0
	v_add_u32_e32 v158, v170, v137
	v_add_u32_e32 v166, v171, v137
	ds_read_b128 v[138:141], v158
	ds_read_b128 v[146:149], v166 offset:16384
	ds_read_b128 v[150:153], v166 offset:18432
	ds_read_b128 v[162:165], v166 offset:20480
	ds_read_b128 v[166:169], v166 offset:22528
	ds_read_b128 v[142:145], v158 offset:2048
	ds_read_b128 v[154:157], v158 offset:4096
	ds_read_b128 v[158:161], v158 offset:6144
	s_setprio 1
	s_waitcnt lgkmcnt(3)
	v_mfma_f32_16x16x32_bf16 v[60:63], v[138:141], v[146:149], v[60:63]
	v_mfma_f32_16x16x32_bf16 v[56:59], v[138:141], v[150:153], v[56:59]
	v_mfma_f32_16x16x32_bf16 v[52:55], v[138:141], v[162:165], v[52:55]
	v_mfma_f32_16x16x32_bf16 v[48:51], v[138:141], v[166:169], v[48:51]
	s_waitcnt lgkmcnt(2)
	v_mfma_f32_16x16x32_bf16 v[44:47], v[142:145], v[146:149], v[44:47]
	v_mfma_f32_16x16x32_bf16 v[40:43], v[142:145], v[150:153], v[40:43]
	v_mfma_f32_16x16x32_bf16 v[36:39], v[142:145], v[162:165], v[36:39]
	v_mfma_f32_16x16x32_bf16 v[32:35], v[142:145], v[166:169], v[32:35]
	s_waitcnt lgkmcnt(1)
	v_mfma_f32_16x16x32_bf16 v[28:31], v[154:157], v[146:149], v[28:31]
	v_mfma_f32_16x16x32_bf16 v[24:27], v[154:157], v[150:153], v[24:27]
	v_mfma_f32_16x16x32_bf16 v[20:23], v[154:157], v[162:165], v[20:23]
	v_mfma_f32_16x16x32_bf16 v[16:19], v[154:157], v[166:169], v[16:19]
	s_waitcnt lgkmcnt(0)
	v_mfma_f32_16x16x32_bf16 v[12:15], v[158:161], v[146:149], v[12:15]
	v_mfma_f32_16x16x32_bf16 v[8:11], v[158:161], v[150:153], v[8:11]
	v_mfma_f32_16x16x32_bf16 v[4:7], v[158:161], v[162:165], v[4:7]
	v_mfma_f32_16x16x32_bf16 v[0:3], v[158:161], v[166:169], v[0:3]
	s_setprio 0
	s_cmpk_eq_i32 s14, 0x1f80
	s_waitcnt vmcnt(0)
	s_barrier
	s_cbranch_scc0 .LBB0_682
	ds_read_b128 v[90:93], v118 offset:55296
	ds_read_b128 v[94:97], v118 offset:53248
	ds_read_b128 v[98:101], v119 offset:38912
	ds_read_b128 v[102:105], v119 offset:36864
	ds_read_b128 v[138:141], v118 offset:51200
	ds_read_b128 v[142:145], v118 offset:49152
	ds_read_b128 v[146:149], v119 offset:34816
	ds_read_b128 v[150:153], v119 offset:32768
	s_setprio 1
	s_waitcnt lgkmcnt(5)
	v_mfma_f32_16x16x32_bf16 v[4:7], v[98:101], v[94:97], v[4:7]
	v_mfma_f32_16x16x32_bf16 v[0:3], v[98:101], v[90:93], v[0:3]
	s_waitcnt lgkmcnt(0)
	v_mfma_f32_16x16x32_bf16 v[60:63], v[150:153], v[142:145], v[60:63]
	v_mfma_f32_16x16x32_bf16 v[56:59], v[150:153], v[138:141], v[56:59]
	v_mfma_f32_16x16x32_bf16 v[52:55], v[150:153], v[94:97], v[52:55]
	v_mfma_f32_16x16x32_bf16 v[48:51], v[150:153], v[90:93], v[48:51]
	v_mfma_f32_16x16x32_bf16 v[44:47], v[146:149], v[142:145], v[44:47]
	v_mfma_f32_16x16x32_bf16 v[40:43], v[146:149], v[138:141], v[40:43]
	v_mfma_f32_16x16x32_bf16 v[36:39], v[146:149], v[94:97], v[36:39]
	v_mfma_f32_16x16x32_bf16 v[32:35], v[146:149], v[90:93], v[32:35]
	v_mfma_f32_16x16x32_bf16 v[28:31], v[102:105], v[142:145], v[28:31]
	v_mfma_f32_16x16x32_bf16 v[24:27], v[102:105], v[138:141], v[24:27]
	v_mfma_f32_16x16x32_bf16 v[20:23], v[102:105], v[94:97], v[20:23]
	v_mfma_f32_16x16x32_bf16 v[16:19], v[102:105], v[90:93], v[16:19]
	v_mfma_f32_16x16x32_bf16 v[12:15], v[98:101], v[142:145], v[12:15]
	v_mfma_f32_16x16x32_bf16 v[8:11], v[98:101], v[138:141], v[8:11]
	s_setprio 0
	ds_read_b128 v[90:93], v120 offset:32768
	ds_read_b128 v[94:97], v120 offset:34816
	ds_read_b128 v[98:101], v121 offset:49152
	ds_read_b128 v[102:105], v121 offset:51200
	ds_read_b128 v[138:141], v120 offset:36864
	ds_read_b128 v[142:145], v120 offset:38912
	ds_read_b128 v[146:149], v121 offset:53248
	ds_read_b128 v[150:153], v121 offset:55296
	s_setprio 1
	s_waitcnt lgkmcnt(1)
	v_mfma_f32_16x16x32_bf16 v[4:7], v[142:145], v[146:149], v[4:7]
	s_waitcnt lgkmcnt(0)
	v_mfma_f32_16x16x32_bf16 v[0:3], v[142:145], v[150:153], v[0:3]
	v_mfma_f32_16x16x32_bf16 v[60:63], v[90:93], v[98:101], v[60:63]
	v_mfma_f32_16x16x32_bf16 v[56:59], v[90:93], v[102:105], v[56:59]
	v_mfma_f32_16x16x32_bf16 v[52:55], v[90:93], v[146:149], v[52:55]
	v_mfma_f32_16x16x32_bf16 v[48:51], v[90:93], v[150:153], v[48:51]
	v_mfma_f32_16x16x32_bf16 v[44:47], v[94:97], v[98:101], v[44:47]
	v_mfma_f32_16x16x32_bf16 v[40:43], v[94:97], v[102:105], v[40:43]
	v_mfma_f32_16x16x32_bf16 v[36:39], v[94:97], v[146:149], v[36:39]
	v_mfma_f32_16x16x32_bf16 v[32:35], v[94:97], v[150:153], v[32:35]
	v_mfma_f32_16x16x32_bf16 v[28:31], v[138:141], v[98:101], v[28:31]
	v_mfma_f32_16x16x32_bf16 v[24:27], v[138:141], v[102:105], v[24:27]
	v_mfma_f32_16x16x32_bf16 v[20:23], v[138:141], v[146:149], v[20:23]
	v_mfma_f32_16x16x32_bf16 v[16:19], v[138:141], v[150:153], v[16:19]
	v_mfma_f32_16x16x32_bf16 v[12:15], v[142:145], v[98:101], v[12:15]
	v_mfma_f32_16x16x32_bf16 v[8:11], v[142:145], v[102:105], v[8:11]
	s_setprio 0
	s_barrier
	ds_write2_b32 v116, v60, v56 offset1:16
	ds_write2_b32 v116, v61, v57 offset0:132 offset1:148
	v_add_u32_e32 v56, 0x400, v116
	ds_write2_b32 v56, v62, v58 offset0:8 offset1:24
	ds_write2_b32 v56, v63, v59 offset0:140 offset1:156
	ds_write2_b32 v116, v52, v48 offset0:32 offset1:48
	ds_write2_b32 v116, v53, v49 offset0:164 offset1:180
	ds_write2_b32 v56, v54, v50 offset0:40 offset1:56
	ds_write2_b32 v56, v55, v51 offset0:172 offset1:188
	v_add_u32_e32 v48, 0x2000, v116
	ds_write2_b32 v48, v44, v40 offset0:64 offset1:80
	ds_write2_b32 v48, v45, v41 offset0:196 offset1:212
	v_add_u32_e32 v40, 0x2400, v116
	ds_write2_b32 v40, v46, v42 offset0:72 offset1:88
	ds_write2_b32 v40, v47, v43 offset0:204 offset1:220
	ds_write2_b32 v48, v36, v32 offset0:96 offset1:112
	ds_write2_b32 v48, v37, v33 offset0:228 offset1:244
	ds_write2_b32 v40, v38, v34 offset0:104 offset1:120
	ds_write2_b32 v40, v39, v35 offset0:236 offset1:252
	v_add_u32_e32 v32, 0x4000, v116
	ds_write2_b32 v32, v28, v24 offset0:128 offset1:144
	v_add_u32_e32 v24, 0x4400, v116
	ds_write2_b32 v24, v29, v25 offset0:4 offset1:20
	ds_write2_b32 v24, v30, v26 offset0:136 offset1:152
	v_add_u32_e32 v25, 0x4800, v116
	ds_write2_b32 v25, v31, v27 offset0:12 offset1:28
	ds_write2_b32 v32, v20, v16 offset0:160 offset1:176
	ds_write2_b32 v24, v21, v17 offset0:36 offset1:52
	ds_write2_b32 v24, v22, v18 offset0:168 offset1:184
	ds_write2_b32 v25, v23, v19 offset0:44 offset1:60
	v_add_u32_e32 v16, 0x6000, v116
	ds_write2_b32 v16, v12, v8 offset0:192 offset1:208
	v_add_u32_e32 v8, 0x6400, v116
	ds_write2_b32 v8, v13, v9 offset0:68 offset1:84
	ds_write2_b32 v8, v14, v10 offset0:200 offset1:216
	v_add_u32_e32 v9, 0x6800, v116
	ds_write2_b32 v9, v15, v11 offset0:76 offset1:92
	ds_write2_b32 v16, v4, v0 offset0:224 offset1:240
	ds_write2_b32 v8, v5, v1 offset0:100 offset1:116
	ds_write2_b32 v8, v6, v2 offset0:232 offset1:248
	ds_write2_b32 v9, v7, v3 offset0:108 offset1:124
	v_or_b32_e32 v0, s23, v117
	v_ashrrev_i32_e32 v1, 31, v0
	v_lshlrev_b64 v[2:3], 2, v[0:1]
	v_lshl_add_u64 v[0:1], s[12:13], 0, v[2:3]
	v_lshl_add_u64 v[2:3], s[10:11], 0, v[2:3]
	v_add_u32_e32 v4, s22, v128
	s_mov_b32 s14, 0
	s_waitcnt lgkmcnt(0)
	s_barrier

.LBB0_691:
	s_and_b32 s26, s25, 0x4000
	s_xor_b32 s27, s26, 0x4000
	s_lshl_b32 s27, s27, 1
	s_add_i32 s27, s27, 32
	s_add_u32 s90, s52, s14
	s_addc_u32 s91, s53, s15
	s_add_i32 m0, s27, s82
	s_lshl_b32 s26, s26, 1
	global_load_lds_dwordx4 v192, s[90:91]
	s_add_i32 m0, s27, s83
	s_add_i32 s26, s26, 32
	global_load_lds_dwordx4 v193, s[90:91]
	s_add_i32 m0, s27, s84
	v_add3_u32 v139, s26, v113, v136
	global_load_lds_dwordx4 v194, s[90:91]
	s_add_i32 m0, s27, s85
	v_add3_u32 v172, s26, v114, v136
	global_load_lds_dwordx4 v195, s[90:91]
	s_add_i32 m0, s27, s86
	v_add_u32_e32 v160, v139, v137
	global_load_lds_dwordx4 v196, s[90:91]
	s_add_i32 m0, s27, s87
	v_add_u32_e32 v168, v172, v137
	global_load_lds_dwordx4 v197, s[90:91]
	s_add_i32 m0, s27, s88
	s_addk_i32 s25, 0x4000
	global_load_lds_dwordx4 v198, s[90:91]
	s_add_i32 m0, s27, s89
	s_add_u32 s14, s14, 0x80
	s_addc_u32 s15, s15, 0
	global_load_lds_dwordx4 v199, s[90:91]
	ds_read_b128 v[140:143], v160
	ds_read_b128 v[148:151], v168 offset:16384
	ds_read_b128 v[152:155], v168 offset:18432
	ds_read_b128 v[164:167], v168 offset:20480
	ds_read_b128 v[168:171], v168 offset:22528
	ds_read_b128 v[144:147], v160 offset:2048
	ds_read_b128 v[156:159], v160 offset:4096
	ds_read_b128 v[160:163], v160 offset:6144
	s_setprio 1
	s_waitcnt lgkmcnt(3)
	v_mfma_f32_16x16x32_bf16 v[60:63], v[140:143], v[148:151], v[60:63]
	v_mfma_f32_16x16x32_bf16 v[56:59], v[140:143], v[152:155], v[56:59]
	v_mfma_f32_16x16x32_bf16 v[52:55], v[140:143], v[164:167], v[52:55]
	v_mfma_f32_16x16x32_bf16 v[48:51], v[140:143], v[168:171], v[48:51]
	s_waitcnt lgkmcnt(2)
	v_mfma_f32_16x16x32_bf16 v[44:47], v[144:147], v[148:151], v[44:47]
	v_mfma_f32_16x16x32_bf16 v[40:43], v[144:147], v[152:155], v[40:43]
	v_mfma_f32_16x16x32_bf16 v[36:39], v[144:147], v[164:167], v[36:39]
	v_mfma_f32_16x16x32_bf16 v[32:35], v[144:147], v[168:171], v[32:35]
	s_waitcnt lgkmcnt(1)
	v_mfma_f32_16x16x32_bf16 v[28:31], v[156:159], v[148:151], v[28:31]
	v_mfma_f32_16x16x32_bf16 v[24:27], v[156:159], v[152:155], v[24:27]
	v_mfma_f32_16x16x32_bf16 v[20:23], v[156:159], v[164:167], v[20:23]
	v_mfma_f32_16x16x32_bf16 v[16:19], v[156:159], v[168:171], v[16:19]
	s_waitcnt lgkmcnt(0)
	v_mfma_f32_16x16x32_bf16 v[12:15], v[160:163], v[148:151], v[12:15]
	v_mfma_f32_16x16x32_bf16 v[8:11], v[160:163], v[152:155], v[8:11]
	v_mfma_f32_16x16x32_bf16 v[4:7], v[160:163], v[164:167], v[4:7]
	v_mfma_f32_16x16x32_bf16 v[0:3], v[160:163], v[168:171], v[0:3]
	s_setprio 0
	v_add_u32_e32 v139, v139, v138
	v_add_u32_e32 v168, v172, v138
	ds_read_b128 v[140:143], v139
	ds_read_b128 v[148:151], v168 offset:16384
	ds_read_b128 v[152:155], v168 offset:18432
	ds_read_b128 v[164:167], v168 offset:20480
	ds_read_b128 v[168:171], v168 offset:22528
	ds_read_b128 v[144:147], v139 offset:2048
	ds_read_b128 v[156:159], v139 offset:4096
	ds_read_b128 v[160:163], v139 offset:6144
	s_setprio 1
	s_waitcnt lgkmcnt(3)
	v_mfma_f32_16x16x32_bf16 v[60:63], v[140:143], v[148:151], v[60:63]
	v_mfma_f32_16x16x32_bf16 v[56:59], v[140:143], v[152:155], v[56:59]
	v_mfma_f32_16x16x32_bf16 v[52:55], v[140:143], v[164:167], v[52:55]
	v_mfma_f32_16x16x32_bf16 v[48:51], v[140:143], v[168:171], v[48:51]
	s_waitcnt lgkmcnt(2)
	v_mfma_f32_16x16x32_bf16 v[44:47], v[144:147], v[148:151], v[44:47]
	v_mfma_f32_16x16x32_bf16 v[40:43], v[144:147], v[152:155], v[40:43]
	v_mfma_f32_16x16x32_bf16 v[36:39], v[144:147], v[164:167], v[36:39]
	v_mfma_f32_16x16x32_bf16 v[32:35], v[144:147], v[168:171], v[32:35]
	s_waitcnt lgkmcnt(1)
	v_mfma_f32_16x16x32_bf16 v[28:31], v[156:159], v[148:151], v[28:31]
	v_mfma_f32_16x16x32_bf16 v[24:27], v[156:159], v[152:155], v[24:27]
	v_mfma_f32_16x16x32_bf16 v[20:23], v[156:159], v[164:167], v[20:23]
	v_mfma_f32_16x16x32_bf16 v[16:19], v[156:159], v[168:171], v[16:19]
	s_waitcnt lgkmcnt(0)
	v_mfma_f32_16x16x32_bf16 v[12:15], v[160:163], v[148:151], v[12:15]
	v_mfma_f32_16x16x32_bf16 v[8:11], v[160:163], v[152:155], v[8:11]
	v_mfma_f32_16x16x32_bf16 v[4:7], v[160:163], v[164:167], v[4:7]
	v_mfma_f32_16x16x32_bf16 v[0:3], v[160:163], v[168:171], v[0:3]
	s_setprio 0
	s_cmpk_eq_i32 s14, 0x1f80
	s_waitcnt vmcnt(0)
	s_barrier
	s_cbranch_scc0 .LBB0_691
	ds_read_b128 v[88:91], v117 offset:55296
	ds_read_b128 v[92:95], v117 offset:53248
	ds_read_b128 v[96:99], v118 offset:38912
	ds_read_b128 v[100:103], v118 offset:36864
	ds_read_b128 v[140:143], v117 offset:51200
	ds_read_b128 v[144:147], v117 offset:49152
	ds_read_b128 v[148:151], v118 offset:34816
	ds_read_b128 v[152:155], v118 offset:32768
	s_setprio 1
	s_waitcnt lgkmcnt(5)
	v_mfma_f32_16x16x32_bf16 v[4:7], v[96:99], v[92:95], v[4:7]
	v_mfma_f32_16x16x32_bf16 v[0:3], v[96:99], v[88:91], v[0:3]
	s_waitcnt lgkmcnt(0)
	v_mfma_f32_16x16x32_bf16 v[60:63], v[152:155], v[144:147], v[60:63]
	v_mfma_f32_16x16x32_bf16 v[56:59], v[152:155], v[140:143], v[56:59]
	v_mfma_f32_16x16x32_bf16 v[52:55], v[152:155], v[92:95], v[52:55]
	v_mfma_f32_16x16x32_bf16 v[48:51], v[152:155], v[88:91], v[48:51]
	v_mfma_f32_16x16x32_bf16 v[44:47], v[148:151], v[144:147], v[44:47]
	v_mfma_f32_16x16x32_bf16 v[40:43], v[148:151], v[140:143], v[40:43]
	v_mfma_f32_16x16x32_bf16 v[36:39], v[148:151], v[92:95], v[36:39]
	v_mfma_f32_16x16x32_bf16 v[32:35], v[148:151], v[88:91], v[32:35]
	v_mfma_f32_16x16x32_bf16 v[28:31], v[100:103], v[144:147], v[28:31]
	v_mfma_f32_16x16x32_bf16 v[24:27], v[100:103], v[140:143], v[24:27]
	v_mfma_f32_16x16x32_bf16 v[20:23], v[100:103], v[92:95], v[20:23]
	v_mfma_f32_16x16x32_bf16 v[16:19], v[100:103], v[88:91], v[16:19]
	v_mfma_f32_16x16x32_bf16 v[12:15], v[96:99], v[144:147], v[12:15]
	v_mfma_f32_16x16x32_bf16 v[8:11], v[96:99], v[140:143], v[8:11]
	s_setprio 0
	ds_read_b128 v[88:91], v119 offset:32768
	ds_read_b128 v[92:95], v119 offset:34816
	ds_read_b128 v[96:99], v120 offset:49152
	ds_read_b128 v[100:103], v120 offset:51200
	ds_read_b128 v[140:143], v119 offset:36864
	ds_read_b128 v[144:147], v119 offset:38912
	ds_read_b128 v[148:151], v120 offset:53248
	ds_read_b128 v[152:155], v120 offset:55296
	s_setprio 1
	s_waitcnt lgkmcnt(1)
	v_mfma_f32_16x16x32_bf16 v[4:7], v[144:147], v[148:151], v[4:7]
	s_waitcnt lgkmcnt(0)
	v_mfma_f32_16x16x32_bf16 v[0:3], v[144:147], v[152:155], v[0:3]
	v_mfma_f32_16x16x32_bf16 v[60:63], v[88:91], v[96:99], v[60:63]
	v_mfma_f32_16x16x32_bf16 v[56:59], v[88:91], v[100:103], v[56:59]
	v_mfma_f32_16x16x32_bf16 v[52:55], v[88:91], v[148:151], v[52:55]
	v_mfma_f32_16x16x32_bf16 v[48:51], v[88:91], v[152:155], v[48:51]
	v_mfma_f32_16x16x32_bf16 v[44:47], v[92:95], v[96:99], v[44:47]
	v_mfma_f32_16x16x32_bf16 v[40:43], v[92:95], v[100:103], v[40:43]
	v_mfma_f32_16x16x32_bf16 v[36:39], v[92:95], v[148:151], v[36:39]
	v_mfma_f32_16x16x32_bf16 v[32:35], v[92:95], v[152:155], v[32:35]
	v_mfma_f32_16x16x32_bf16 v[28:31], v[140:143], v[96:99], v[28:31]
	v_mfma_f32_16x16x32_bf16 v[24:27], v[140:143], v[100:103], v[24:27]
	v_mfma_f32_16x16x32_bf16 v[20:23], v[140:143], v[148:151], v[20:23]
	v_mfma_f32_16x16x32_bf16 v[16:19], v[140:143], v[152:155], v[16:19]
	v_mfma_f32_16x16x32_bf16 v[12:15], v[144:147], v[96:99], v[12:15]
	v_mfma_f32_16x16x32_bf16 v[8:11], v[144:147], v[100:103], v[8:11]
	s_setprio 0
	s_barrier
	ds_write2_b32 v115, v60, v56 offset1:16
	ds_write2_b32 v115, v61, v57 offset0:132 offset1:148
	v_add_u32_e32 v56, 0x400, v115
	ds_write2_b32 v56, v62, v58 offset0:8 offset1:24
	ds_write2_b32 v56, v63, v59 offset0:140 offset1:156
	ds_write2_b32 v115, v52, v48 offset0:32 offset1:48
	ds_write2_b32 v115, v53, v49 offset0:164 offset1:180
	ds_write2_b32 v56, v54, v50 offset0:40 offset1:56
	ds_write2_b32 v56, v55, v51 offset0:172 offset1:188
	v_add_u32_e32 v48, 0x2000, v115
	ds_write2_b32 v48, v44, v40 offset0:64 offset1:80
	ds_write2_b32 v48, v45, v41 offset0:196 offset1:212
	v_add_u32_e32 v40, 0x2400, v115
	ds_write2_b32 v40, v46, v42 offset0:72 offset1:88
	ds_write2_b32 v40, v47, v43 offset0:204 offset1:220
	ds_write2_b32 v48, v36, v32 offset0:96 offset1:112
	ds_write2_b32 v48, v37, v33 offset0:228 offset1:244
	ds_write2_b32 v40, v38, v34 offset0:104 offset1:120
	ds_write2_b32 v40, v39, v35 offset0:236 offset1:252
	v_add_u32_e32 v32, 0x4000, v115
	ds_write2_b32 v32, v28, v24 offset0:128 offset1:144
	v_add_u32_e32 v24, 0x4400, v115
	ds_write2_b32 v24, v29, v25 offset0:4 offset1:20
	ds_write2_b32 v24, v30, v26 offset0:136 offset1:152
	v_add_u32_e32 v25, 0x4800, v115
	ds_write2_b32 v25, v31, v27 offset0:12 offset1:28
	ds_write2_b32 v32, v20, v16 offset0:160 offset1:176
	ds_write2_b32 v24, v21, v17 offset0:36 offset1:52
	ds_write2_b32 v24, v22, v18 offset0:168 offset1:184
	ds_write2_b32 v25, v23, v19 offset0:44 offset1:60
	v_add_u32_e32 v16, 0x6000, v115
	ds_write2_b32 v16, v12, v8 offset0:192 offset1:208
	v_add_u32_e32 v8, 0x6400, v115
	ds_write2_b32 v8, v13, v9 offset0:68 offset1:84
	ds_write2_b32 v8, v14, v10 offset0:200 offset1:216
	v_add_u32_e32 v9, 0x6800, v115
	ds_write2_b32 v9, v15, v11 offset0:76 offset1:92
	ds_write2_b32 v16, v4, v0 offset0:224 offset1:240
	ds_write2_b32 v8, v5, v1 offset0:100 offset1:116
	ds_write2_b32 v8, v6, v2 offset0:232 offset1:248
	ds_write2_b32 v9, v7, v3 offset0:108 offset1:124
	v_or_b32_e32 v0, s23, v116
	v_ashrrev_i32_e32 v1, 31, v0
	v_lshlrev_b64 v[2:3], 2, v[0:1]
	v_lshl_add_u64 v[0:1], s[12:13], 0, v[2:3]
	v_lshl_add_u64 v[2:3], s[10:11], 0, v[2:3]
	v_add_u32_e32 v4, s24, v129
	s_mov_b32 s14, 0
	s_waitcnt lgkmcnt(0)
	s_barrier

.LBB0_702:
	s_and_b32 s27, s26, 0x4000
	s_xor_b32 s28, s27, 0x4000
	s_lshl_b32 s28, s28, 1
	s_add_i32 s28, s28, 32
	s_add_u32 s90, s52, s14
	s_addc_u32 s91, s53, s15
	s_add_i32 m0, s28, s82
	s_lshl_b32 s27, s27, 1
	global_load_lds_dwordx4 v193, s[90:91]
	s_add_i32 m0, s28, s83
	s_add_i32 s27, s27, 32
	global_load_lds_dwordx4 v194, s[90:91]
	s_add_i32 m0, s28, s84
	v_lshlrev_b32_e32 v72, 1, v131
	global_load_lds_dwordx4 v195, s[90:91]
	s_add_i32 m0, s28, s85
	v_add3_u32 v178, s27, v129, v72
	global_load_lds_dwordx4 v196, s[90:91]
	s_add_i32 m0, s28, s86
	v_lshlrev_b32_e32 v154, 1, v121
	global_load_lds_dwordx4 v197, s[90:91]
	s_add_i32 m0, s28, s87
	v_add3_u32 v72, s27, v130, v72
	global_load_lds_dwordx4 v198, s[90:91]
	s_add_i32 m0, s28, s88
	v_add_u32_e32 v174, v178, v154
	global_load_lds_dwordx4 v199, s[90:91]
	s_add_i32 m0, s28, s89
	v_add_u32_e32 v179, v72, v154
	global_load_lds_dwordx4 v200, s[90:91]
	ds_read_b128 v[154:157], v174
	ds_read_b128 v[162:165], v179 offset:16384
	ds_read_b128 v[166:169], v179 offset:18432
	ds_read_b128 v[182:185], v179 offset:20480
	ds_read_b128 v[186:189], v179 offset:22528
	ds_read_b128 v[158:161], v174 offset:2048
	ds_read_b128 v[170:173], v174 offset:4096
	ds_read_b128 v[174:177], v174 offset:6144
	s_setprio 1
	s_waitcnt lgkmcnt(3)
	v_mfma_f32_16x16x32_bf16 v[60:63], v[154:157], v[162:165], v[60:63]
	v_mfma_f32_16x16x32_bf16 v[56:59], v[154:157], v[166:169], v[56:59]
	v_mfma_f32_16x16x32_bf16 v[52:55], v[154:157], v[182:185], v[52:55]
	v_mfma_f32_16x16x32_bf16 v[48:51], v[154:157], v[186:189], v[48:51]
	s_waitcnt lgkmcnt(2)
	v_mfma_f32_16x16x32_bf16 v[44:47], v[158:161], v[162:165], v[44:47]
	v_mfma_f32_16x16x32_bf16 v[40:43], v[158:161], v[166:169], v[40:43]
	v_mfma_f32_16x16x32_bf16 v[36:39], v[158:161], v[182:185], v[36:39]
	v_mfma_f32_16x16x32_bf16 v[32:35], v[158:161], v[186:189], v[32:35]
	s_waitcnt lgkmcnt(1)
	v_mfma_f32_16x16x32_bf16 v[28:31], v[170:173], v[162:165], v[28:31]
	v_mfma_f32_16x16x32_bf16 v[24:27], v[170:173], v[166:169], v[24:27]
	v_mfma_f32_16x16x32_bf16 v[20:23], v[170:173], v[182:185], v[20:23]
	v_mfma_f32_16x16x32_bf16 v[16:19], v[170:173], v[186:189], v[16:19]
	s_waitcnt lgkmcnt(0)
	v_mfma_f32_16x16x32_bf16 v[12:15], v[174:177], v[162:165], v[12:15]
	v_mfma_f32_16x16x32_bf16 v[8:11], v[174:177], v[166:169], v[8:11]
	v_mfma_f32_16x16x32_bf16 v[4:7], v[174:177], v[182:185], v[4:7]
	v_mfma_f32_16x16x32_bf16 v[0:3], v[174:177], v[186:189], v[0:3]
	s_setprio 0
	v_lshlrev_b32_e32 v154, 1, v122
	v_add_u32_e32 v174, v178, v154
	v_add_u32_e32 v72, v72, v154
	ds_read_b128 v[154:157], v174
	ds_read_b128 v[162:165], v72 offset:16384
	ds_read_b128 v[166:169], v72 offset:18432
	ds_read_b128 v[182:185], v72 offset:20480
	ds_read_b128 v[186:189], v72 offset:22528
	ds_read_b128 v[158:161], v174 offset:2048
	ds_read_b128 v[170:173], v174 offset:4096
	ds_read_b128 v[174:177], v174 offset:6144
	s_setprio 1
	s_waitcnt lgkmcnt(3)
	v_mfma_f32_16x16x32_bf16 v[60:63], v[154:157], v[162:165], v[60:63]
	v_mfma_f32_16x16x32_bf16 v[56:59], v[154:157], v[166:169], v[56:59]
	v_mfma_f32_16x16x32_bf16 v[52:55], v[154:157], v[182:185], v[52:55]
	v_mfma_f32_16x16x32_bf16 v[48:51], v[154:157], v[186:189], v[48:51]
	s_waitcnt lgkmcnt(2)
	v_mfma_f32_16x16x32_bf16 v[44:47], v[158:161], v[162:165], v[44:47]
	v_mfma_f32_16x16x32_bf16 v[40:43], v[158:161], v[166:169], v[40:43]
	v_mfma_f32_16x16x32_bf16 v[36:39], v[158:161], v[182:185], v[36:39]
	v_mfma_f32_16x16x32_bf16 v[32:35], v[158:161], v[186:189], v[32:35]
	s_waitcnt lgkmcnt(1)
	v_mfma_f32_16x16x32_bf16 v[28:31], v[170:173], v[162:165], v[28:31]
	v_mfma_f32_16x16x32_bf16 v[24:27], v[170:173], v[166:169], v[24:27]
	v_mfma_f32_16x16x32_bf16 v[20:23], v[170:173], v[182:185], v[20:23]
	v_mfma_f32_16x16x32_bf16 v[16:19], v[170:173], v[186:189], v[16:19]
	s_waitcnt lgkmcnt(0)
	v_mfma_f32_16x16x32_bf16 v[12:15], v[174:177], v[162:165], v[12:15]
	v_mfma_f32_16x16x32_bf16 v[8:11], v[174:177], v[166:169], v[8:11]
	v_mfma_f32_16x16x32_bf16 v[4:7], v[174:177], v[182:185], v[4:7]
	v_mfma_f32_16x16x32_bf16 v[0:3], v[174:177], v[186:189], v[0:3]
	s_setprio 0
	s_add_u32 s14, s14, 0x80
	s_addc_u32 s15, s15, 0
	s_addk_i32 s26, 0x4000
	s_cmpk_eq_i32 s14, 0x1f80
	s_waitcnt vmcnt(0)
	s_barrier
	s_cbranch_scc0 .LBB0_702
	ds_read_b128 v[98:101], v71 offset:32768
	ds_read_b128 v[102:105], v71 offset:34816
	ds_read_b128 v[106:109], v138 offset:49152
	ds_read_b128 v[110:113], v138 offset:51200
	ds_read_b128 v[154:157], v71 offset:36864
	ds_read_b128 v[158:161], v71 offset:38912
	ds_read_b128 v[162:165], v138 offset:53248
	ds_read_b128 v[166:169], v138 offset:55296
	s_setprio 1
	s_waitcnt lgkmcnt(1)
	v_mfma_f32_16x16x32_bf16 v[4:7], v[158:161], v[162:165], v[4:7]
	s_waitcnt lgkmcnt(0)
	v_mfma_f32_16x16x32_bf16 v[0:3], v[158:161], v[166:169], v[0:3]
	v_mfma_f32_16x16x32_bf16 v[60:63], v[98:101], v[106:109], v[60:63]
	v_mfma_f32_16x16x32_bf16 v[56:59], v[98:101], v[110:113], v[56:59]
	v_mfma_f32_16x16x32_bf16 v[52:55], v[98:101], v[162:165], v[52:55]
	v_mfma_f32_16x16x32_bf16 v[48:51], v[98:101], v[166:169], v[48:51]
	v_mfma_f32_16x16x32_bf16 v[44:47], v[102:105], v[106:109], v[44:47]
	v_mfma_f32_16x16x32_bf16 v[40:43], v[102:105], v[110:113], v[40:43]
	v_mfma_f32_16x16x32_bf16 v[36:39], v[102:105], v[162:165], v[36:39]
	v_mfma_f32_16x16x32_bf16 v[32:35], v[102:105], v[166:169], v[32:35]
	v_mfma_f32_16x16x32_bf16 v[28:31], v[154:157], v[106:109], v[28:31]
	v_mfma_f32_16x16x32_bf16 v[24:27], v[154:157], v[110:113], v[24:27]
	v_mfma_f32_16x16x32_bf16 v[20:23], v[154:157], v[162:165], v[20:23]
	v_mfma_f32_16x16x32_bf16 v[16:19], v[154:157], v[166:169], v[16:19]
	v_mfma_f32_16x16x32_bf16 v[12:15], v[158:161], v[106:109], v[12:15]
	v_mfma_f32_16x16x32_bf16 v[8:11], v[158:161], v[110:113], v[8:11]
	s_setprio 0
	ds_read_b128 v[98:101], v139 offset:32768
	ds_read_b128 v[102:105], v139 offset:34816
	ds_read_b128 v[106:109], v140 offset:49152
	ds_read_b128 v[110:113], v140 offset:51200
	ds_read_b128 v[154:157], v139 offset:36864
	ds_read_b128 v[158:161], v139 offset:38912
	ds_read_b128 v[162:165], v140 offset:53248
	ds_read_b128 v[166:169], v140 offset:55296
	s_setprio 1
	s_waitcnt lgkmcnt(1)
	v_mfma_f32_16x16x32_bf16 v[4:7], v[158:161], v[162:165], v[4:7]
	s_waitcnt lgkmcnt(0)
	v_mfma_f32_16x16x32_bf16 v[0:3], v[158:161], v[166:169], v[0:3]
	v_mfma_f32_16x16x32_bf16 v[60:63], v[98:101], v[106:109], v[60:63]
	v_mfma_f32_16x16x32_bf16 v[56:59], v[98:101], v[110:113], v[56:59]
	v_mfma_f32_16x16x32_bf16 v[52:55], v[98:101], v[162:165], v[52:55]
	v_mfma_f32_16x16x32_bf16 v[48:51], v[98:101], v[166:169], v[48:51]
	v_mfma_f32_16x16x32_bf16 v[44:47], v[102:105], v[106:109], v[44:47]
	v_mfma_f32_16x16x32_bf16 v[40:43], v[102:105], v[110:113], v[40:43]
	v_mfma_f32_16x16x32_bf16 v[36:39], v[102:105], v[162:165], v[36:39]
	v_mfma_f32_16x16x32_bf16 v[32:35], v[102:105], v[166:169], v[32:35]
	v_mfma_f32_16x16x32_bf16 v[28:31], v[154:157], v[106:109], v[28:31]
	v_mfma_f32_16x16x32_bf16 v[24:27], v[154:157], v[110:113], v[24:27]
	v_mfma_f32_16x16x32_bf16 v[20:23], v[154:157], v[162:165], v[20:23]
	v_mfma_f32_16x16x32_bf16 v[16:19], v[154:157], v[166:169], v[16:19]
	v_mfma_f32_16x16x32_bf16 v[12:15], v[158:161], v[106:109], v[12:15]
	v_mfma_f32_16x16x32_bf16 v[8:11], v[158:161], v[110:113], v[8:11]
	s_setprio 0
	s_barrier
	ds_write2_b32 v136, v60, v56 offset1:16
	ds_write2_b32 v136, v61, v57 offset0:132 offset1:148
	v_add_u32_e32 v56, 0x400, v136
	ds_write2_b32 v56, v62, v58 offset0:8 offset1:24
	ds_write2_b32 v56, v63, v59 offset0:140 offset1:156
	ds_write2_b32 v136, v52, v48 offset0:32 offset1:48
	ds_write2_b32 v136, v53, v49 offset0:164 offset1:180
	ds_write2_b32 v56, v54, v50 offset0:40 offset1:56
	ds_write2_b32 v56, v55, v51 offset0:172 offset1:188
	v_add_u32_e32 v48, 0x2000, v136
	ds_write2_b32 v48, v44, v40 offset0:64 offset1:80
	ds_write2_b32 v48, v45, v41 offset0:196 offset1:212
	v_add_u32_e32 v40, 0x2400, v136
	ds_write2_b32 v40, v46, v42 offset0:72 offset1:88
	ds_write2_b32 v40, v47, v43 offset0:204 offset1:220
	ds_write2_b32 v48, v36, v32 offset0:96 offset1:112
	ds_write2_b32 v48, v37, v33 offset0:228 offset1:244
	ds_write2_b32 v40, v38, v34 offset0:104 offset1:120
	ds_write2_b32 v40, v39, v35 offset0:236 offset1:252
	v_add_u32_e32 v32, 0x4000, v136
	ds_write2_b32 v32, v28, v24 offset0:128 offset1:144
	v_add_u32_e32 v24, 0x4400, v136
	ds_write2_b32 v24, v29, v25 offset0:4 offset1:20
	ds_write2_b32 v24, v30, v26 offset0:136 offset1:152
	v_add_u32_e32 v25, 0x4800, v136
	ds_write2_b32 v25, v31, v27 offset0:12 offset1:28
	ds_write2_b32 v32, v20, v16 offset0:160 offset1:176
	ds_write2_b32 v24, v21, v17 offset0:36 offset1:52
	ds_write2_b32 v24, v22, v18 offset0:168 offset1:184
	ds_write2_b32 v25, v23, v19 offset0:44 offset1:60
	v_add_u32_e32 v16, 0x6000, v136
	ds_write2_b32 v16, v12, v8 offset0:192 offset1:208
	v_add_u32_e32 v8, 0x6400, v136
	ds_write2_b32 v8, v13, v9 offset0:68 offset1:84
	ds_write2_b32 v8, v14, v10 offset0:200 offset1:216
	v_add_u32_e32 v9, 0x6800, v136
	ds_write2_b32 v9, v15, v11 offset0:76 offset1:92
	ds_write2_b32 v16, v4, v0 offset0:224 offset1:240
	ds_write2_b32 v8, v5, v1 offset0:100 offset1:116
	ds_write2_b32 v8, v6, v2 offset0:232 offset1:248
	ds_write2_b32 v9, v7, v3 offset0:108 offset1:124
	v_or_b32_e32 v0, s24, v137
	v_lshlrev_b32_e32 v72, 2, v0
	v_lshl_add_u64 v[0:1], s[12:13], 0, v[72:73]
	v_lshl_add_u64 v[2:3], s[10:11], 0, v[72:73]
	v_add_u32_e32 v4, s25, v149
	s_mov_b32 s14, 0
	s_waitcnt lgkmcnt(0)
	s_barrier

.LBB0_708:
	s_and_b32 s6, s11, 0x4000
	s_xor_b32 s7, s6, 0x4000
	s_lshl_b32 s7, s7, 1
	s_add_i32 s7, s7, 32
	s_add_u32 s90, s52, s4
	s_addc_u32 s91, s53, s5
	s_add_i32 m0, s7, s82
	s_lshl_b32 s6, s6, 1
	global_load_lds_dwordx4 v192, s[90:91]
	s_add_i32 m0, s7, s83
	s_add_i32 s6, s6, 32
	global_load_lds_dwordx4 v193, s[90:91]
	s_add_i32 m0, s7, s84
	v_lshlrev_b32_e32 v85, 1, v80
	global_load_lds_dwordx4 v194, s[90:91]
	s_add_i32 m0, s7, s85
	v_add3_u32 v112, s6, v81, v85
	global_load_lds_dwordx4 v195, s[90:91]
	s_add_i32 m0, s7, s86
	v_lshlrev_b32_e32 v86, 1, v121
	global_load_lds_dwordx4 v196, s[90:91]
	s_add_i32 m0, s7, s87
	v_add3_u32 v113, s6, v82, v85
	global_load_lds_dwordx4 v197, s[90:91]
	s_add_i32 m0, s7, s88
	v_add_u32_e32 v87, v112, v86
	global_load_lds_dwordx4 v198, s[90:91]
	s_add_i32 m0, s7, s89
	v_add_u32_e32 v123, v113, v86
	global_load_lds_dwordx4 v199, s[90:91]
	ds_read_b128 v[88:91], v87
	ds_read_b128 v[96:99], v123 offset:16384
	ds_read_b128 v[100:103], v123 offset:18432
	ds_read_b128 v[124:127], v123 offset:20480
	ds_read_b128 v[128:131], v123 offset:22528
	ds_read_b128 v[92:95], v87 offset:2048
	ds_read_b128 v[104:107], v87 offset:4096
	ds_read_b128 v[108:111], v87 offset:6144
	s_setprio 1
	s_waitcnt lgkmcnt(3)
	v_mfma_f32_16x16x32_bf16 v[60:63], v[88:91], v[96:99], v[60:63]
	v_mfma_f32_16x16x32_bf16 v[56:59], v[88:91], v[100:103], v[56:59]
	v_mfma_f32_16x16x32_bf16 v[52:55], v[88:91], v[124:127], v[52:55]
	v_mfma_f32_16x16x32_bf16 v[48:51], v[88:91], v[128:131], v[48:51]
	s_waitcnt lgkmcnt(2)
	v_mfma_f32_16x16x32_bf16 v[44:47], v[92:95], v[96:99], v[44:47]
	v_mfma_f32_16x16x32_bf16 v[40:43], v[92:95], v[100:103], v[40:43]
	v_mfma_f32_16x16x32_bf16 v[36:39], v[92:95], v[124:127], v[36:39]
	v_mfma_f32_16x16x32_bf16 v[32:35], v[92:95], v[128:131], v[32:35]
	s_waitcnt lgkmcnt(1)
	v_mfma_f32_16x16x32_bf16 v[28:31], v[104:107], v[96:99], v[28:31]
	v_mfma_f32_16x16x32_bf16 v[24:27], v[104:107], v[100:103], v[24:27]
	v_mfma_f32_16x16x32_bf16 v[20:23], v[104:107], v[124:127], v[20:23]
	v_mfma_f32_16x16x32_bf16 v[16:19], v[104:107], v[128:131], v[16:19]
	s_waitcnt lgkmcnt(0)
	v_mfma_f32_16x16x32_bf16 v[12:15], v[108:111], v[96:99], v[12:15]
	v_mfma_f32_16x16x32_bf16 v[8:11], v[108:111], v[100:103], v[8:11]
	v_mfma_f32_16x16x32_bf16 v[4:7], v[108:111], v[124:127], v[4:7]
	v_mfma_f32_16x16x32_bf16 v[0:3], v[108:111], v[128:131], v[0:3]
	s_setprio 0
	v_lshlrev_b32_e32 v87, 1, v122
	v_add_u32_e32 v108, v112, v87
	v_add_u32_e32 v112, v113, v87
	ds_read_b128 v[88:91], v108
	ds_read_b128 v[96:99], v112 offset:16384
	ds_read_b128 v[100:103], v112 offset:18432
	ds_read_b128 v[124:127], v112 offset:20480
	ds_read_b128 v[128:131], v112 offset:22528
	ds_read_b128 v[92:95], v108 offset:2048
	ds_read_b128 v[104:107], v108 offset:4096
	ds_read_b128 v[108:111], v108 offset:6144
	s_setprio 1
	s_waitcnt lgkmcnt(3)
	v_mfma_f32_16x16x32_bf16 v[60:63], v[88:91], v[96:99], v[60:63]
	v_mfma_f32_16x16x32_bf16 v[56:59], v[88:91], v[100:103], v[56:59]
	v_mfma_f32_16x16x32_bf16 v[52:55], v[88:91], v[124:127], v[52:55]
	v_mfma_f32_16x16x32_bf16 v[48:51], v[88:91], v[128:131], v[48:51]
	s_waitcnt lgkmcnt(2)
	v_mfma_f32_16x16x32_bf16 v[44:47], v[92:95], v[96:99], v[44:47]
	v_mfma_f32_16x16x32_bf16 v[40:43], v[92:95], v[100:103], v[40:43]
	v_mfma_f32_16x16x32_bf16 v[36:39], v[92:95], v[124:127], v[36:39]
	v_mfma_f32_16x16x32_bf16 v[32:35], v[92:95], v[128:131], v[32:35]
	s_waitcnt lgkmcnt(1)
	v_mfma_f32_16x16x32_bf16 v[28:31], v[104:107], v[96:99], v[28:31]
	v_mfma_f32_16x16x32_bf16 v[24:27], v[104:107], v[100:103], v[24:27]
	v_mfma_f32_16x16x32_bf16 v[20:23], v[104:107], v[124:127], v[20:23]
	v_mfma_f32_16x16x32_bf16 v[16:19], v[104:107], v[128:131], v[16:19]
	s_waitcnt lgkmcnt(0)
	v_mfma_f32_16x16x32_bf16 v[12:15], v[108:111], v[96:99], v[12:15]
	v_mfma_f32_16x16x32_bf16 v[8:11], v[108:111], v[100:103], v[8:11]
	v_mfma_f32_16x16x32_bf16 v[4:7], v[108:111], v[124:127], v[4:7]
	v_mfma_f32_16x16x32_bf16 v[0:3], v[108:111], v[128:131], v[0:3]
	s_setprio 0
	s_add_u32 s4, s4, 0x80
	s_addc_u32 s5, s5, 0
	s_addk_i32 s11, 0x4000
	s_cmpk_eq_i32 s4, 0x780
	s_waitcnt vmcnt(0)
	s_barrier
	s_cbranch_scc0 .LBB0_708
	v_add3_u32 v84, 32, v81, v85
	v_add3_u32 v85, 32, v82, v85
	v_add_u32_e32 v88, v84, v86
	v_add_u32_e32 v86, v85, v86
	ds_read_b128 v[64:67], v88 offset:32768
	ds_read_b128 v[68:71], v88 offset:34816
	ds_read_b128 v[72:75], v86 offset:49152
	ds_read_b128 v[76:79], v86 offset:51200
	ds_read_b128 v[80:83], v88 offset:36864
	ds_read_b128 v[88:91], v88 offset:38912
	ds_read_b128 v[92:95], v86 offset:53248
	ds_read_b128 v[96:99], v86 offset:55296
	s_setprio 1
	s_waitcnt lgkmcnt(0)
	v_mfma_f32_16x16x32_bf16 v[0:3], v[88:91], v[96:99], v[0:3]
	v_mfma_f32_16x16x32_bf16 v[60:63], v[64:67], v[72:75], v[60:63]
	v_mfma_f32_16x16x32_bf16 v[56:59], v[64:67], v[76:79], v[56:59]
	v_mfma_f32_16x16x32_bf16 v[52:55], v[64:67], v[92:95], v[52:55]
	v_mfma_f32_16x16x32_bf16 v[48:51], v[64:67], v[96:99], v[48:51]
	v_mfma_f32_16x16x32_bf16 v[44:47], v[68:71], v[72:75], v[44:47]
	v_mfma_f32_16x16x32_bf16 v[40:43], v[68:71], v[76:79], v[40:43]
	v_mfma_f32_16x16x32_bf16 v[36:39], v[68:71], v[92:95], v[36:39]
	v_mfma_f32_16x16x32_bf16 v[32:35], v[68:71], v[96:99], v[32:35]
	v_mfma_f32_16x16x32_bf16 v[28:31], v[80:83], v[72:75], v[28:31]
	v_mfma_f32_16x16x32_bf16 v[24:27], v[80:83], v[76:79], v[24:27]
	v_mfma_f32_16x16x32_bf16 v[20:23], v[80:83], v[92:95], v[20:23]
	v_mfma_f32_16x16x32_bf16 v[16:19], v[80:83], v[96:99], v[16:19]
	v_mfma_f32_16x16x32_bf16 v[12:15], v[88:91], v[72:75], v[12:15]
	v_mfma_f32_16x16x32_bf16 v[8:11], v[88:91], v[76:79], v[8:11]
	v_mfma_f32_16x16x32_bf16 v[4:7], v[88:91], v[92:95], v[4:7]
	s_setprio 0
	v_add_u32_e32 v84, v84, v87
	v_add_u32_e32 v92, v85, v87
	ds_read_b128 v[64:67], v84 offset:32768
	ds_read_b128 v[68:71], v84 offset:34816
	ds_read_b128 v[72:75], v92 offset:49152
	ds_read_b128 v[76:79], v92 offset:51200
	ds_read_b128 v[80:83], v84 offset:36864
	ds_read_b128 v[84:87], v84 offset:38912
	ds_read_b128 v[88:91], v92 offset:53248
	ds_read_b128 v[92:95], v92 offset:55296
	s_setprio 1
	s_waitcnt lgkmcnt(0)
	v_mfma_f32_16x16x32_bf16 v[0:3], v[84:87], v[92:95], v[0:3]
	v_mfma_f32_16x16x32_bf16 v[60:63], v[64:67], v[72:75], v[60:63]
	v_mfma_f32_16x16x32_bf16 v[56:59], v[64:67], v[76:79], v[56:59]
	v_mfma_f32_16x16x32_bf16 v[52:55], v[64:67], v[88:91], v[52:55]
	v_mfma_f32_16x16x32_bf16 v[48:51], v[64:67], v[92:95], v[48:51]
	v_mfma_f32_16x16x32_bf16 v[44:47], v[68:71], v[72:75], v[44:47]
	v_mfma_f32_16x16x32_bf16 v[40:43], v[68:71], v[76:79], v[40:43]
	v_mfma_f32_16x16x32_bf16 v[36:39], v[68:71], v[88:91], v[36:39]
	v_mfma_f32_16x16x32_bf16 v[32:35], v[68:71], v[92:95], v[32:35]
	v_mfma_f32_16x16x32_bf16 v[28:31], v[80:83], v[72:75], v[28:31]
	v_mfma_f32_16x16x32_bf16 v[24:27], v[80:83], v[76:79], v[24:27]
	v_mfma_f32_16x16x32_bf16 v[20:23], v[80:83], v[88:91], v[20:23]
	v_mfma_f32_16x16x32_bf16 v[16:19], v[80:83], v[92:95], v[16:19]
	v_mfma_f32_16x16x32_bf16 v[12:15], v[84:87], v[72:75], v[12:15]
	v_mfma_f32_16x16x32_bf16 v[8:11], v[84:87], v[76:79], v[8:11]
	v_mfma_f32_16x16x32_bf16 v[4:7], v[84:87], v[88:91], v[4:7]
	s_setprio 0
	v_lshl_or_b32 v64, v114, 2, v116
	v_mul_u32_u24_e32 v64, 0x210, v64
	v_add3_u32 v64, v115, v117, v64
	s_barrier
	ds_write2_b32 v64, v60, v56 offset1:16
	ds_write2_b32 v64, v61, v57 offset0:132 offset1:148
	v_add_u32_e32 v56, 0x400, v64
	ds_write2_b32 v56, v62, v58 offset0:8 offset1:24
	ds_write2_b32 v56, v63, v59 offset0:140 offset1:156
	ds_write2_b32 v64, v52, v48 offset0:32 offset1:48
	ds_write2_b32 v64, v53, v49 offset0:164 offset1:180
	ds_write2_b32 v56, v54, v50 offset0:40 offset1:56
	ds_write2_b32 v56, v55, v51 offset0:172 offset1:188
	v_add_u32_e32 v48, 0x2000, v64
	ds_write2_b32 v48, v44, v40 offset0:64 offset1:80
	ds_write2_b32 v48, v45, v41 offset0:196 offset1:212
	v_add_u32_e32 v40, 0x2400, v64
	ds_write2_b32 v40, v46, v42 offset0:72 offset1:88
	ds_write2_b32 v40, v47, v43 offset0:204 offset1:220
	ds_write2_b32 v48, v36, v32 offset0:96 offset1:112
	ds_write2_b32 v48, v37, v33 offset0:228 offset1:244
	ds_write2_b32 v40, v38, v34 offset0:104 offset1:120
	ds_write2_b32 v40, v39, v35 offset0:236 offset1:252
	v_add_u32_e32 v32, 0x4000, v64
	ds_write2_b32 v32, v28, v24 offset0:128 offset1:144
	v_add_u32_e32 v24, 0x4400, v64
	ds_write2_b32 v24, v29, v25 offset0:4 offset1:20
	ds_write2_b32 v24, v30, v26 offset0:136 offset1:152
	v_add_u32_e32 v25, 0x4800, v64
	ds_write2_b32 v25, v31, v27 offset0:12 offset1:28
	ds_write2_b32 v32, v20, v16 offset0:160 offset1:176
	ds_write2_b32 v24, v21, v17 offset0:36 offset1:52
	ds_write2_b32 v24, v22, v18 offset0:168 offset1:184
	ds_write2_b32 v25, v23, v19 offset0:44 offset1:60
	v_add_u32_e32 v16, 0x6000, v64
	ds_write2_b32 v16, v12, v8 offset0:192 offset1:208
	v_add_u32_e32 v8, 0x6400, v64
	ds_write2_b32 v8, v13, v9 offset0:68 offset1:84
	ds_write2_b32 v8, v14, v10 offset0:200 offset1:216
	v_add_u32_e32 v9, 0x6800, v64
	ds_write2_b32 v9, v15, v11 offset0:76 offset1:92
	ds_write2_b32 v16, v4, v0 offset0:224 offset1:240
	ds_write2_b32 v8, v5, v1 offset0:100 offset1:116
	ds_write2_b32 v8, v6, v2 offset0:232 offset1:248
	ds_write2_b32 v9, v7, v3 offset0:108 offset1:124
	v_lshlrev_b32_e32 v0, 4, v180
	v_and_b32_e32 v0, 0x70, v0
	s_lshl_b32 s5, s14, 23
	v_or_b32_e32 v0, s9, v0
	s_add_u32 s6, s12, s5
	s_addc_u32 s7, s13, 0
	v_lshlrev_b32_e32 v0, 2, v0
	v_mov_b32_e32 v1, 0
	v_lshrrev_b32_e32 v2, 3, v180
	v_and_b32_e32 v4, 7, v180
	v_lshl_add_u64 v[0:1], s[6:7], 0, v[0:1]
	s_mov_b64 s[6:7], 0x11600000
	v_mul_u32_u24_e32 v3, 0x210, v2
	v_lshlrev_b32_e32 v4, 6, v4
	s_mov_b32 s4, 0
	v_lshl_add_u64 v[0:1], v[0:1], 0, s[6:7]
	v_add3_u32 v3, v3, v4, 32
	s_mov_b32 s5, 0x38e38e39
	s_mov_b32 s6, 0x1ffffee
	s_movk_i32 s7, 0xf800
	s_waitcnt lgkmcnt(0)
	s_barrier

.LBB0_1814:
	s_and_b32 s27, s26, 0x4000
	s_xor_b32 s28, s27, 0x4000
	s_lshl_b32 s28, s28, 1
	s_add_i32 s28, s28, 32
	s_add_u32 s90, s52, s16
	s_addc_u32 s91, s53, s17
	s_add_i32 m0, s28, s82
	s_lshl_b32 s27, s27, 1
	global_load_lds_dwordx4 v188, s[90:91]
	s_add_i32 m0, s28, s83
	s_add_i32 s27, s27, 32
	global_load_lds_dwordx4 v189, s[90:91]
	s_add_i32 m0, s28, s84
	v_add3_u32 v170, s27, v114, v135
	global_load_lds_dwordx4 v190, s[90:91]
	s_add_i32 m0, s28, s85
	v_add3_u32 v171, s27, v115, v135
	global_load_lds_dwordx4 v191, s[90:91]
	s_add_i32 m0, s28, s86
	v_add_u32_e32 v158, v170, v136
	global_load_lds_dwordx4 v192, s[90:91]
	s_add_i32 m0, s28, s87
	v_add_u32_e32 v166, v171, v136
	global_load_lds_dwordx4 v193, s[90:91]
	s_add_i32 m0, s28, s88
	s_addk_i32 s26, 0x4000
	global_load_lds_dwordx4 v194, s[90:91]
	s_add_i32 m0, s28, s89
	s_add_u32 s16, s16, 0x80
	s_addc_u32 s17, s17, 0
	global_load_lds_dwordx4 v195, s[90:91]
	ds_read_b128 v[138:141], v158
	ds_read_b128 v[146:149], v166 offset:16384
	ds_read_b128 v[150:153], v166 offset:18432
	ds_read_b128 v[162:165], v166 offset:20480
	ds_read_b128 v[166:169], v166 offset:22528
	ds_read_b128 v[142:145], v158 offset:2048
	ds_read_b128 v[154:157], v158 offset:4096
	ds_read_b128 v[158:161], v158 offset:6144
	s_setprio 1
	s_waitcnt lgkmcnt(3)
	v_mfma_f32_16x16x32_bf16 v[60:63], v[138:141], v[146:149], v[60:63]
	v_mfma_f32_16x16x32_bf16 v[56:59], v[138:141], v[150:153], v[56:59]
	v_mfma_f32_16x16x32_bf16 v[52:55], v[138:141], v[162:165], v[52:55]
	v_mfma_f32_16x16x32_bf16 v[48:51], v[138:141], v[166:169], v[48:51]
	s_waitcnt lgkmcnt(2)
	v_mfma_f32_16x16x32_bf16 v[44:47], v[142:145], v[146:149], v[44:47]
	v_mfma_f32_16x16x32_bf16 v[40:43], v[142:145], v[150:153], v[40:43]
	v_mfma_f32_16x16x32_bf16 v[36:39], v[142:145], v[162:165], v[36:39]
	v_mfma_f32_16x16x32_bf16 v[32:35], v[142:145], v[166:169], v[32:35]
	s_waitcnt lgkmcnt(1)
	v_mfma_f32_16x16x32_bf16 v[28:31], v[154:157], v[146:149], v[28:31]
	v_mfma_f32_16x16x32_bf16 v[24:27], v[154:157], v[150:153], v[24:27]
	v_mfma_f32_16x16x32_bf16 v[20:23], v[154:157], v[162:165], v[20:23]
	v_mfma_f32_16x16x32_bf16 v[16:19], v[154:157], v[166:169], v[16:19]
	s_waitcnt lgkmcnt(0)
	v_mfma_f32_16x16x32_bf16 v[12:15], v[158:161], v[146:149], v[12:15]
	v_mfma_f32_16x16x32_bf16 v[8:11], v[158:161], v[150:153], v[8:11]
	v_mfma_f32_16x16x32_bf16 v[4:7], v[158:161], v[162:165], v[4:7]
	v_mfma_f32_16x16x32_bf16 v[0:3], v[158:161], v[166:169], v[0:3]
	s_setprio 0
	v_add_u32_e32 v158, v170, v137
	v_add_u32_e32 v166, v171, v137
	ds_read_b128 v[138:141], v158
	ds_read_b128 v[146:149], v166 offset:16384
	ds_read_b128 v[150:153], v166 offset:18432
	ds_read_b128 v[162:165], v166 offset:20480
	ds_read_b128 v[166:169], v166 offset:22528
	ds_read_b128 v[142:145], v158 offset:2048
	ds_read_b128 v[154:157], v158 offset:4096
	ds_read_b128 v[158:161], v158 offset:6144
	s_setprio 1
	s_waitcnt lgkmcnt(3)
	v_mfma_f32_16x16x32_bf16 v[60:63], v[138:141], v[146:149], v[60:63]
	v_mfma_f32_16x16x32_bf16 v[56:59], v[138:141], v[150:153], v[56:59]
	v_mfma_f32_16x16x32_bf16 v[52:55], v[138:141], v[162:165], v[52:55]
	v_mfma_f32_16x16x32_bf16 v[48:51], v[138:141], v[166:169], v[48:51]
	s_waitcnt lgkmcnt(2)
	v_mfma_f32_16x16x32_bf16 v[44:47], v[142:145], v[146:149], v[44:47]
	v_mfma_f32_16x16x32_bf16 v[40:43], v[142:145], v[150:153], v[40:43]
	v_mfma_f32_16x16x32_bf16 v[36:39], v[142:145], v[162:165], v[36:39]
	v_mfma_f32_16x16x32_bf16 v[32:35], v[142:145], v[166:169], v[32:35]
	s_waitcnt lgkmcnt(1)
	v_mfma_f32_16x16x32_bf16 v[28:31], v[154:157], v[146:149], v[28:31]
	v_mfma_f32_16x16x32_bf16 v[24:27], v[154:157], v[150:153], v[24:27]
	v_mfma_f32_16x16x32_bf16 v[20:23], v[154:157], v[162:165], v[20:23]
	v_mfma_f32_16x16x32_bf16 v[16:19], v[154:157], v[166:169], v[16:19]
	s_waitcnt lgkmcnt(0)
	v_mfma_f32_16x16x32_bf16 v[12:15], v[158:161], v[146:149], v[12:15]
	v_mfma_f32_16x16x32_bf16 v[8:11], v[158:161], v[150:153], v[8:11]
	v_mfma_f32_16x16x32_bf16 v[4:7], v[158:161], v[162:165], v[4:7]
	v_mfma_f32_16x16x32_bf16 v[0:3], v[158:161], v[166:169], v[0:3]
	s_setprio 0
	s_cmpk_eq_i32 s16, 0x780
	s_waitcnt vmcnt(0)
	s_barrier
	s_cbranch_scc0 .LBB0_1814
	ds_read_b128 v[90:93], v118 offset:55296
	ds_read_b128 v[94:97], v118 offset:53248
	ds_read_b128 v[98:101], v119 offset:38912
	ds_read_b128 v[102:105], v119 offset:36864
	ds_read_b128 v[138:141], v118 offset:51200
	ds_read_b128 v[142:145], v118 offset:49152
	ds_read_b128 v[146:149], v119 offset:34816
	ds_read_b128 v[150:153], v119 offset:32768
	s_setprio 1
	s_waitcnt lgkmcnt(5)
	v_mfma_f32_16x16x32_bf16 v[4:7], v[98:101], v[94:97], v[4:7]
	v_mfma_f32_16x16x32_bf16 v[0:3], v[98:101], v[90:93], v[0:3]
	s_waitcnt lgkmcnt(0)
	v_mfma_f32_16x16x32_bf16 v[60:63], v[150:153], v[142:145], v[60:63]
	v_mfma_f32_16x16x32_bf16 v[56:59], v[150:153], v[138:141], v[56:59]
	v_mfma_f32_16x16x32_bf16 v[52:55], v[150:153], v[94:97], v[52:55]
	v_mfma_f32_16x16x32_bf16 v[48:51], v[150:153], v[90:93], v[48:51]
	v_mfma_f32_16x16x32_bf16 v[44:47], v[146:149], v[142:145], v[44:47]
	v_mfma_f32_16x16x32_bf16 v[40:43], v[146:149], v[138:141], v[40:43]
	v_mfma_f32_16x16x32_bf16 v[36:39], v[146:149], v[94:97], v[36:39]
	v_mfma_f32_16x16x32_bf16 v[32:35], v[146:149], v[90:93], v[32:35]
	v_mfma_f32_16x16x32_bf16 v[28:31], v[102:105], v[142:145], v[28:31]
	v_mfma_f32_16x16x32_bf16 v[24:27], v[102:105], v[138:141], v[24:27]
	v_mfma_f32_16x16x32_bf16 v[20:23], v[102:105], v[94:97], v[20:23]
	v_mfma_f32_16x16x32_bf16 v[16:19], v[102:105], v[90:93], v[16:19]
	v_mfma_f32_16x16x32_bf16 v[12:15], v[98:101], v[142:145], v[12:15]
	v_mfma_f32_16x16x32_bf16 v[8:11], v[98:101], v[138:141], v[8:11]
	s_setprio 0
	ds_read_b128 v[90:93], v120 offset:32768
	ds_read_b128 v[94:97], v120 offset:34816
	ds_read_b128 v[98:101], v121 offset:49152
	ds_read_b128 v[102:105], v121 offset:51200
	ds_read_b128 v[138:141], v120 offset:36864
	ds_read_b128 v[142:145], v120 offset:38912
	ds_read_b128 v[146:149], v121 offset:53248
	ds_read_b128 v[150:153], v121 offset:55296
	s_setprio 1
	s_waitcnt lgkmcnt(1)
	v_mfma_f32_16x16x32_bf16 v[4:7], v[142:145], v[146:149], v[4:7]
	s_waitcnt lgkmcnt(0)
	v_mfma_f32_16x16x32_bf16 v[0:3], v[142:145], v[150:153], v[0:3]
	v_mfma_f32_16x16x32_bf16 v[60:63], v[90:93], v[98:101], v[60:63]
	v_mfma_f32_16x16x32_bf16 v[56:59], v[90:93], v[102:105], v[56:59]
	v_mfma_f32_16x16x32_bf16 v[52:55], v[90:93], v[146:149], v[52:55]
	v_mfma_f32_16x16x32_bf16 v[48:51], v[90:93], v[150:153], v[48:51]
	v_mfma_f32_16x16x32_bf16 v[44:47], v[94:97], v[98:101], v[44:47]
	v_mfma_f32_16x16x32_bf16 v[40:43], v[94:97], v[102:105], v[40:43]
	v_mfma_f32_16x16x32_bf16 v[36:39], v[94:97], v[146:149], v[36:39]
	v_mfma_f32_16x16x32_bf16 v[32:35], v[94:97], v[150:153], v[32:35]
	v_mfma_f32_16x16x32_bf16 v[28:31], v[138:141], v[98:101], v[28:31]
	v_mfma_f32_16x16x32_bf16 v[24:27], v[138:141], v[102:105], v[24:27]
	v_mfma_f32_16x16x32_bf16 v[20:23], v[138:141], v[146:149], v[20:23]
	v_mfma_f32_16x16x32_bf16 v[16:19], v[138:141], v[150:153], v[16:19]
	v_mfma_f32_16x16x32_bf16 v[12:15], v[142:145], v[98:101], v[12:15]
	v_mfma_f32_16x16x32_bf16 v[8:11], v[142:145], v[102:105], v[8:11]
	s_setprio 0
	s_barrier
	ds_write2_b32 v116, v60, v56 offset1:16
	ds_write2_b32 v116, v61, v57 offset0:132 offset1:148
	v_add_u32_e32 v56, 0x400, v116
	ds_write2_b32 v56, v62, v58 offset0:8 offset1:24
	ds_write2_b32 v56, v63, v59 offset0:140 offset1:156
	ds_write2_b32 v116, v52, v48 offset0:32 offset1:48
	ds_write2_b32 v116, v53, v49 offset0:164 offset1:180
	ds_write2_b32 v56, v54, v50 offset0:40 offset1:56
	ds_write2_b32 v56, v55, v51 offset0:172 offset1:188
	v_add_u32_e32 v48, 0x2000, v116
	ds_write2_b32 v48, v44, v40 offset0:64 offset1:80
	ds_write2_b32 v48, v45, v41 offset0:196 offset1:212
	v_add_u32_e32 v40, 0x2400, v116
	ds_write2_b32 v40, v46, v42 offset0:72 offset1:88
	ds_write2_b32 v40, v47, v43 offset0:204 offset1:220
	ds_write2_b32 v48, v36, v32 offset0:96 offset1:112
	ds_write2_b32 v48, v37, v33 offset0:228 offset1:244
	ds_write2_b32 v40, v38, v34 offset0:104 offset1:120
	ds_write2_b32 v40, v39, v35 offset0:236 offset1:252
	v_add_u32_e32 v32, 0x4000, v116
	ds_write2_b32 v32, v28, v24 offset0:128 offset1:144
	v_add_u32_e32 v24, 0x4400, v116
	ds_write2_b32 v24, v29, v25 offset0:4 offset1:20
	ds_write2_b32 v24, v30, v26 offset0:136 offset1:152
	v_add_u32_e32 v25, 0x4800, v116
	ds_write2_b32 v25, v31, v27 offset0:12 offset1:28
	ds_write2_b32 v32, v20, v16 offset0:160 offset1:176
	ds_write2_b32 v24, v21, v17 offset0:36 offset1:52
	ds_write2_b32 v24, v22, v18 offset0:168 offset1:184
	ds_write2_b32 v25, v23, v19 offset0:44 offset1:60
	v_add_u32_e32 v16, 0x6000, v116
	ds_write2_b32 v16, v12, v8 offset0:192 offset1:208
	v_add_u32_e32 v8, 0x6400, v116
	ds_write2_b32 v8, v13, v9 offset0:68 offset1:84
	ds_write2_b32 v8, v14, v10 offset0:200 offset1:216
	v_add_u32_e32 v9, 0x6800, v116
	ds_write2_b32 v9, v15, v11 offset0:76 offset1:92
	ds_write2_b32 v16, v4, v0 offset0:224 offset1:240
	ds_write2_b32 v8, v5, v1 offset0:100 offset1:116
	ds_write2_b32 v8, v6, v2 offset0:232 offset1:248
	ds_write2_b32 v9, v7, v3 offset0:108 offset1:124
	v_or_b32_e32 v0, s25, v117
	v_ashrrev_i32_e32 v1, 31, v0
	v_lshlrev_b64 v[2:3], 2, v[0:1]
	v_lshl_add_u64 v[0:1], s[14:15], 0, v[2:3]
	v_lshl_add_u64 v[2:3], s[10:11], 0, v[2:3]
	v_add_u32_e32 v4, s24, v128
	s_mov_b32 s16, 0
	s_waitcnt lgkmcnt(0)
	s_barrier

.LBB0_1823:
	s_and_b32 s28, s27, 0x4000
	s_xor_b32 s29, s28, 0x4000
	s_lshl_b32 s29, s29, 1
	s_add_i32 s29, s29, 32
	s_add_u32 s90, s52, s16
	s_addc_u32 s91, s53, s17
	s_add_i32 m0, s29, s82
	s_lshl_b32 s28, s28, 1
	global_load_lds_dwordx4 v188, s[90:91]
	s_add_i32 m0, s29, s83
	s_add_i32 s28, s28, 32
	global_load_lds_dwordx4 v189, s[90:91]
	s_add_i32 m0, s29, s84
	v_add3_u32 v139, s28, v113, v136
	global_load_lds_dwordx4 v190, s[90:91]
	s_add_i32 m0, s29, s85
	v_add3_u32 v172, s28, v114, v136
	global_load_lds_dwordx4 v191, s[90:91]
	s_add_i32 m0, s29, s86
	v_add_u32_e32 v160, v139, v137
	global_load_lds_dwordx4 v192, s[90:91]
	s_add_i32 m0, s29, s87
	v_add_u32_e32 v168, v172, v137
	global_load_lds_dwordx4 v193, s[90:91]
	s_add_i32 m0, s29, s88
	s_addk_i32 s27, 0x4000
	global_load_lds_dwordx4 v194, s[90:91]
	s_add_i32 m0, s29, s89
	s_add_u32 s16, s16, 0x80
	s_addc_u32 s17, s17, 0
	global_load_lds_dwordx4 v195, s[90:91]
	ds_read_b128 v[140:143], v160
	ds_read_b128 v[148:151], v168 offset:16384
	ds_read_b128 v[152:155], v168 offset:18432
	ds_read_b128 v[164:167], v168 offset:20480
	ds_read_b128 v[168:171], v168 offset:22528
	ds_read_b128 v[144:147], v160 offset:2048
	ds_read_b128 v[156:159], v160 offset:4096
	ds_read_b128 v[160:163], v160 offset:6144
	s_setprio 1
	s_waitcnt lgkmcnt(3)
	v_mfma_f32_16x16x32_bf16 v[60:63], v[140:143], v[148:151], v[60:63]
	v_mfma_f32_16x16x32_bf16 v[56:59], v[140:143], v[152:155], v[56:59]
	v_mfma_f32_16x16x32_bf16 v[52:55], v[140:143], v[164:167], v[52:55]
	v_mfma_f32_16x16x32_bf16 v[48:51], v[140:143], v[168:171], v[48:51]
	s_waitcnt lgkmcnt(2)
	v_mfma_f32_16x16x32_bf16 v[44:47], v[144:147], v[148:151], v[44:47]
	v_mfma_f32_16x16x32_bf16 v[40:43], v[144:147], v[152:155], v[40:43]
	v_mfma_f32_16x16x32_bf16 v[36:39], v[144:147], v[164:167], v[36:39]
	v_mfma_f32_16x16x32_bf16 v[32:35], v[144:147], v[168:171], v[32:35]
	s_waitcnt lgkmcnt(1)
	v_mfma_f32_16x16x32_bf16 v[28:31], v[156:159], v[148:151], v[28:31]
	v_mfma_f32_16x16x32_bf16 v[24:27], v[156:159], v[152:155], v[24:27]
	v_mfma_f32_16x16x32_bf16 v[20:23], v[156:159], v[164:167], v[20:23]
	v_mfma_f32_16x16x32_bf16 v[16:19], v[156:159], v[168:171], v[16:19]
	s_waitcnt lgkmcnt(0)
	v_mfma_f32_16x16x32_bf16 v[12:15], v[160:163], v[148:151], v[12:15]
	v_mfma_f32_16x16x32_bf16 v[8:11], v[160:163], v[152:155], v[8:11]
	v_mfma_f32_16x16x32_bf16 v[4:7], v[160:163], v[164:167], v[4:7]
	v_mfma_f32_16x16x32_bf16 v[0:3], v[160:163], v[168:171], v[0:3]
	s_setprio 0
	v_add_u32_e32 v139, v139, v138
	v_add_u32_e32 v168, v172, v138
	ds_read_b128 v[140:143], v139
	ds_read_b128 v[148:151], v168 offset:16384
	ds_read_b128 v[152:155], v168 offset:18432
	ds_read_b128 v[164:167], v168 offset:20480
	ds_read_b128 v[168:171], v168 offset:22528
	ds_read_b128 v[144:147], v139 offset:2048
	ds_read_b128 v[156:159], v139 offset:4096
	ds_read_b128 v[160:163], v139 offset:6144
	s_setprio 1
	s_waitcnt lgkmcnt(3)
	v_mfma_f32_16x16x32_bf16 v[60:63], v[140:143], v[148:151], v[60:63]
	v_mfma_f32_16x16x32_bf16 v[56:59], v[140:143], v[152:155], v[56:59]
	v_mfma_f32_16x16x32_bf16 v[52:55], v[140:143], v[164:167], v[52:55]
	v_mfma_f32_16x16x32_bf16 v[48:51], v[140:143], v[168:171], v[48:51]
	s_waitcnt lgkmcnt(2)
	v_mfma_f32_16x16x32_bf16 v[44:47], v[144:147], v[148:151], v[44:47]
	v_mfma_f32_16x16x32_bf16 v[40:43], v[144:147], v[152:155], v[40:43]
	v_mfma_f32_16x16x32_bf16 v[36:39], v[144:147], v[164:167], v[36:39]
	v_mfma_f32_16x16x32_bf16 v[32:35], v[144:147], v[168:171], v[32:35]
	s_waitcnt lgkmcnt(1)
	v_mfma_f32_16x16x32_bf16 v[28:31], v[156:159], v[148:151], v[28:31]
	v_mfma_f32_16x16x32_bf16 v[24:27], v[156:159], v[152:155], v[24:27]
	v_mfma_f32_16x16x32_bf16 v[20:23], v[156:159], v[164:167], v[20:23]
	v_mfma_f32_16x16x32_bf16 v[16:19], v[156:159], v[168:171], v[16:19]
	s_waitcnt lgkmcnt(0)
	v_mfma_f32_16x16x32_bf16 v[12:15], v[160:163], v[148:151], v[12:15]
	v_mfma_f32_16x16x32_bf16 v[8:11], v[160:163], v[152:155], v[8:11]
	v_mfma_f32_16x16x32_bf16 v[4:7], v[160:163], v[164:167], v[4:7]
	v_mfma_f32_16x16x32_bf16 v[0:3], v[160:163], v[168:171], v[0:3]
	s_setprio 0
	s_cmpk_eq_i32 s16, 0x780
	s_waitcnt vmcnt(0)
	s_barrier
	s_cbranch_scc0 .LBB0_1823
	ds_read_b128 v[88:91], v117 offset:55296
	ds_read_b128 v[92:95], v117 offset:53248
	ds_read_b128 v[96:99], v118 offset:38912
	ds_read_b128 v[100:103], v118 offset:36864
	ds_read_b128 v[140:143], v117 offset:51200
	ds_read_b128 v[144:147], v117 offset:49152
	ds_read_b128 v[148:151], v118 offset:34816
	ds_read_b128 v[152:155], v118 offset:32768
	s_setprio 1
	s_waitcnt lgkmcnt(5)
	v_mfma_f32_16x16x32_bf16 v[4:7], v[96:99], v[92:95], v[4:7]
	v_mfma_f32_16x16x32_bf16 v[0:3], v[96:99], v[88:91], v[0:3]
	s_waitcnt lgkmcnt(0)
	v_mfma_f32_16x16x32_bf16 v[60:63], v[152:155], v[144:147], v[60:63]
	v_mfma_f32_16x16x32_bf16 v[56:59], v[152:155], v[140:143], v[56:59]
	v_mfma_f32_16x16x32_bf16 v[52:55], v[152:155], v[92:95], v[52:55]
	v_mfma_f32_16x16x32_bf16 v[48:51], v[152:155], v[88:91], v[48:51]
	v_mfma_f32_16x16x32_bf16 v[44:47], v[148:151], v[144:147], v[44:47]
	v_mfma_f32_16x16x32_bf16 v[40:43], v[148:151], v[140:143], v[40:43]
	v_mfma_f32_16x16x32_bf16 v[36:39], v[148:151], v[92:95], v[36:39]
	v_mfma_f32_16x16x32_bf16 v[32:35], v[148:151], v[88:91], v[32:35]
	v_mfma_f32_16x16x32_bf16 v[28:31], v[100:103], v[144:147], v[28:31]
	v_mfma_f32_16x16x32_bf16 v[24:27], v[100:103], v[140:143], v[24:27]
	v_mfma_f32_16x16x32_bf16 v[20:23], v[100:103], v[92:95], v[20:23]
	v_mfma_f32_16x16x32_bf16 v[16:19], v[100:103], v[88:91], v[16:19]
	v_mfma_f32_16x16x32_bf16 v[12:15], v[96:99], v[144:147], v[12:15]
	v_mfma_f32_16x16x32_bf16 v[8:11], v[96:99], v[140:143], v[8:11]
	s_setprio 0
	ds_read_b128 v[88:91], v119 offset:32768
	ds_read_b128 v[92:95], v119 offset:34816
	ds_read_b128 v[96:99], v120 offset:49152
	ds_read_b128 v[100:103], v120 offset:51200
	ds_read_b128 v[140:143], v119 offset:36864
	ds_read_b128 v[144:147], v119 offset:38912
	ds_read_b128 v[148:151], v120 offset:53248
	ds_read_b128 v[152:155], v120 offset:55296
	s_setprio 1
	s_waitcnt lgkmcnt(1)
	v_mfma_f32_16x16x32_bf16 v[4:7], v[144:147], v[148:151], v[4:7]
	s_waitcnt lgkmcnt(0)
	v_mfma_f32_16x16x32_bf16 v[0:3], v[144:147], v[152:155], v[0:3]
	v_mfma_f32_16x16x32_bf16 v[60:63], v[88:91], v[96:99], v[60:63]
	v_mfma_f32_16x16x32_bf16 v[56:59], v[88:91], v[100:103], v[56:59]
	v_mfma_f32_16x16x32_bf16 v[52:55], v[88:91], v[148:151], v[52:55]
	v_mfma_f32_16x16x32_bf16 v[48:51], v[88:91], v[152:155], v[48:51]
	v_mfma_f32_16x16x32_bf16 v[44:47], v[92:95], v[96:99], v[44:47]
	v_mfma_f32_16x16x32_bf16 v[40:43], v[92:95], v[100:103], v[40:43]
	v_mfma_f32_16x16x32_bf16 v[36:39], v[92:95], v[148:151], v[36:39]
	v_mfma_f32_16x16x32_bf16 v[32:35], v[92:95], v[152:155], v[32:35]
	v_mfma_f32_16x16x32_bf16 v[28:31], v[140:143], v[96:99], v[28:31]
	v_mfma_f32_16x16x32_bf16 v[24:27], v[140:143], v[100:103], v[24:27]
	v_mfma_f32_16x16x32_bf16 v[20:23], v[140:143], v[148:151], v[20:23]
	v_mfma_f32_16x16x32_bf16 v[16:19], v[140:143], v[152:155], v[16:19]
	v_mfma_f32_16x16x32_bf16 v[12:15], v[144:147], v[96:99], v[12:15]
	v_mfma_f32_16x16x32_bf16 v[8:11], v[144:147], v[100:103], v[8:11]
	s_setprio 0
	s_barrier
	ds_write2_b32 v115, v60, v56 offset1:16
	ds_write2_b32 v115, v61, v57 offset0:132 offset1:148
	v_add_u32_e32 v56, 0x400, v115
	ds_write2_b32 v56, v62, v58 offset0:8 offset1:24
	ds_write2_b32 v56, v63, v59 offset0:140 offset1:156
	ds_write2_b32 v115, v52, v48 offset0:32 offset1:48
	ds_write2_b32 v115, v53, v49 offset0:164 offset1:180
	ds_write2_b32 v56, v54, v50 offset0:40 offset1:56
	ds_write2_b32 v56, v55, v51 offset0:172 offset1:188
	v_add_u32_e32 v48, 0x2000, v115
	ds_write2_b32 v48, v44, v40 offset0:64 offset1:80
	ds_write2_b32 v48, v45, v41 offset0:196 offset1:212
	v_add_u32_e32 v40, 0x2400, v115
	ds_write2_b32 v40, v46, v42 offset0:72 offset1:88
	ds_write2_b32 v40, v47, v43 offset0:204 offset1:220
	ds_write2_b32 v48, v36, v32 offset0:96 offset1:112
	ds_write2_b32 v48, v37, v33 offset0:228 offset1:244
	ds_write2_b32 v40, v38, v34 offset0:104 offset1:120
	ds_write2_b32 v40, v39, v35 offset0:236 offset1:252
	v_add_u32_e32 v32, 0x4000, v115
	ds_write2_b32 v32, v28, v24 offset0:128 offset1:144
	v_add_u32_e32 v24, 0x4400, v115
	ds_write2_b32 v24, v29, v25 offset0:4 offset1:20
	ds_write2_b32 v24, v30, v26 offset0:136 offset1:152
	v_add_u32_e32 v25, 0x4800, v115
	ds_write2_b32 v25, v31, v27 offset0:12 offset1:28
	ds_write2_b32 v32, v20, v16 offset0:160 offset1:176
	ds_write2_b32 v24, v21, v17 offset0:36 offset1:52
	ds_write2_b32 v24, v22, v18 offset0:168 offset1:184
	ds_write2_b32 v25, v23, v19 offset0:44 offset1:60
	v_add_u32_e32 v16, 0x6000, v115
	ds_write2_b32 v16, v12, v8 offset0:192 offset1:208
	v_add_u32_e32 v8, 0x6400, v115
	ds_write2_b32 v8, v13, v9 offset0:68 offset1:84
	ds_write2_b32 v8, v14, v10 offset0:200 offset1:216
	v_add_u32_e32 v9, 0x6800, v115
	ds_write2_b32 v9, v15, v11 offset0:76 offset1:92
	ds_write2_b32 v16, v4, v0 offset0:224 offset1:240
	ds_write2_b32 v8, v5, v1 offset0:100 offset1:116
	ds_write2_b32 v8, v6, v2 offset0:232 offset1:248
	ds_write2_b32 v9, v7, v3 offset0:108 offset1:124
	v_or_b32_e32 v0, s25, v116
	v_ashrrev_i32_e32 v1, 31, v0
	v_lshlrev_b64 v[2:3], 2, v[0:1]
	v_lshl_add_u64 v[0:1], s[14:15], 0, v[2:3]
	v_lshl_add_u64 v[2:3], s[10:11], 0, v[2:3]
	v_add_u32_e32 v4, s26, v129
	s_mov_b32 s16, 0
	s_waitcnt lgkmcnt(0)
	s_barrier

.LBB0_1834:
	s_and_b32 s27, s26, 0x4000
	s_xor_b32 s28, s27, 0x4000
	s_lshl_b32 s28, s28, 1
	s_add_i32 s28, s28, 32
	s_add_u32 s90, s52, s12
	s_addc_u32 s91, s53, s13
	s_add_i32 m0, s28, s82
	s_lshl_b32 s27, s27, 1
	global_load_lds_dwordx4 v189, s[90:91]
	s_add_i32 m0, s28, s83
	s_add_i32 s27, s27, 32
	global_load_lds_dwordx4 v190, s[90:91]
	s_add_i32 m0, s28, s84
	v_lshlrev_b32_e32 v70, 1, v129
	global_load_lds_dwordx4 v191, s[90:91]
	s_add_i32 m0, s28, s85
	v_add3_u32 v151, s27, v124, v70
	global_load_lds_dwordx4 v192, s[90:91]
	s_add_i32 m0, s28, s86
	v_add3_u32 v70, s27, v125, v70
	global_load_lds_dwordx4 v193, s[90:91]
	s_add_i32 m0, s28, s87
	v_lshlrev_b32_e32 v152, 1, v117
	global_load_lds_dwordx4 v194, s[90:91]
	s_add_i32 m0, s28, s88
	v_add_u32_e32 v172, v151, v152
	global_load_lds_dwordx4 v195, s[90:91]
	s_add_i32 m0, s28, s89
	v_add_u32_e32 v182, v70, v152
	global_load_lds_dwordx4 v196, s[90:91]
	ds_read_b128 v[152:155], v172
	ds_read_b128 v[160:163], v182 offset:16384
	ds_read_b128 v[164:167], v182 offset:18432
	ds_read_b128 v[176:179], v182 offset:20480
	ds_read_b128 v[182:185], v182 offset:22528
	ds_read_b128 v[156:159], v172 offset:2048
	ds_read_b128 v[168:171], v172 offset:4096
	ds_read_b128 v[172:175], v172 offset:6144
	s_setprio 1
	s_waitcnt lgkmcnt(3)
	v_mfma_f32_16x16x32_bf16 v[60:63], v[152:155], v[160:163], v[60:63]
	v_mfma_f32_16x16x32_bf16 v[56:59], v[152:155], v[164:167], v[56:59]
	v_mfma_f32_16x16x32_bf16 v[52:55], v[152:155], v[176:179], v[52:55]
	v_mfma_f32_16x16x32_bf16 v[48:51], v[152:155], v[182:185], v[48:51]
	s_waitcnt lgkmcnt(2)
	v_mfma_f32_16x16x32_bf16 v[44:47], v[156:159], v[160:163], v[44:47]
	v_mfma_f32_16x16x32_bf16 v[40:43], v[156:159], v[164:167], v[40:43]
	v_mfma_f32_16x16x32_bf16 v[36:39], v[156:159], v[176:179], v[36:39]
	v_mfma_f32_16x16x32_bf16 v[32:35], v[156:159], v[182:185], v[32:35]
	s_waitcnt lgkmcnt(1)
	v_mfma_f32_16x16x32_bf16 v[28:31], v[168:171], v[160:163], v[28:31]
	v_mfma_f32_16x16x32_bf16 v[24:27], v[168:171], v[164:167], v[24:27]
	v_mfma_f32_16x16x32_bf16 v[20:23], v[168:171], v[176:179], v[20:23]
	v_mfma_f32_16x16x32_bf16 v[16:19], v[168:171], v[182:185], v[16:19]
	s_waitcnt lgkmcnt(0)
	v_mfma_f32_16x16x32_bf16 v[12:15], v[172:175], v[160:163], v[12:15]
	v_mfma_f32_16x16x32_bf16 v[8:11], v[172:175], v[164:167], v[8:11]
	v_mfma_f32_16x16x32_bf16 v[4:7], v[172:175], v[176:179], v[4:7]
	v_mfma_f32_16x16x32_bf16 v[0:3], v[172:175], v[182:185], v[0:3]
	s_setprio 0
	v_lshlrev_b32_e32 v152, 1, v116
	v_add_u32_e32 v151, v151, v152
	v_add_u32_e32 v70, v70, v152
	ds_read_b128 v[152:155], v151
	ds_read_b128 v[160:163], v70 offset:16384
	ds_read_b128 v[164:167], v70 offset:18432
	ds_read_b128 v[176:179], v70 offset:20480
	ds_read_b128 v[182:185], v70 offset:22528
	ds_read_b128 v[156:159], v151 offset:2048
	ds_read_b128 v[168:171], v151 offset:4096
	ds_read_b128 v[172:175], v151 offset:6144
	s_setprio 1
	s_waitcnt lgkmcnt(3)
	v_mfma_f32_16x16x32_bf16 v[60:63], v[152:155], v[160:163], v[60:63]
	v_mfma_f32_16x16x32_bf16 v[56:59], v[152:155], v[164:167], v[56:59]
	v_mfma_f32_16x16x32_bf16 v[52:55], v[152:155], v[176:179], v[52:55]
	v_mfma_f32_16x16x32_bf16 v[48:51], v[152:155], v[182:185], v[48:51]
	s_waitcnt lgkmcnt(2)
	v_mfma_f32_16x16x32_bf16 v[44:47], v[156:159], v[160:163], v[44:47]
	v_mfma_f32_16x16x32_bf16 v[40:43], v[156:159], v[164:167], v[40:43]
	v_mfma_f32_16x16x32_bf16 v[36:39], v[156:159], v[176:179], v[36:39]
	v_mfma_f32_16x16x32_bf16 v[32:35], v[156:159], v[182:185], v[32:35]
	s_waitcnt lgkmcnt(1)
	v_mfma_f32_16x16x32_bf16 v[28:31], v[168:171], v[160:163], v[28:31]
	v_mfma_f32_16x16x32_bf16 v[24:27], v[168:171], v[164:167], v[24:27]
	v_mfma_f32_16x16x32_bf16 v[20:23], v[168:171], v[176:179], v[20:23]
	v_mfma_f32_16x16x32_bf16 v[16:19], v[168:171], v[182:185], v[16:19]
	s_waitcnt lgkmcnt(0)
	v_mfma_f32_16x16x32_bf16 v[12:15], v[172:175], v[160:163], v[12:15]
	v_mfma_f32_16x16x32_bf16 v[8:11], v[172:175], v[164:167], v[8:11]
	v_mfma_f32_16x16x32_bf16 v[4:7], v[172:175], v[176:179], v[4:7]
	v_mfma_f32_16x16x32_bf16 v[0:3], v[172:175], v[182:185], v[0:3]
	s_setprio 0
	s_add_u32 s12, s12, 0x80
	s_addc_u32 s13, s13, 0
	s_addk_i32 s26, 0x4000
	s_cmpk_eq_i32 s12, 0x780
	s_waitcnt vmcnt(0)
	s_barrier
	s_cbranch_scc0 .LBB0_1834
	ds_read_b128 v[96:99], v69 offset:32768
	ds_read_b128 v[100:103], v69 offset:34816
	ds_read_b128 v[104:107], v135 offset:49152
	ds_read_b128 v[108:111], v135 offset:51200
	ds_read_b128 v[152:155], v69 offset:36864
	ds_read_b128 v[156:159], v69 offset:38912
	ds_read_b128 v[160:163], v135 offset:53248
	ds_read_b128 v[164:167], v135 offset:55296
	s_setprio 1
	s_waitcnt lgkmcnt(1)
	v_mfma_f32_16x16x32_bf16 v[4:7], v[156:159], v[160:163], v[4:7]
	s_waitcnt lgkmcnt(0)
	v_mfma_f32_16x16x32_bf16 v[0:3], v[156:159], v[164:167], v[0:3]
	v_mfma_f32_16x16x32_bf16 v[60:63], v[96:99], v[104:107], v[60:63]
	v_mfma_f32_16x16x32_bf16 v[56:59], v[96:99], v[108:111], v[56:59]
	v_mfma_f32_16x16x32_bf16 v[52:55], v[96:99], v[160:163], v[52:55]
	v_mfma_f32_16x16x32_bf16 v[48:51], v[96:99], v[164:167], v[48:51]
	v_mfma_f32_16x16x32_bf16 v[44:47], v[100:103], v[104:107], v[44:47]
	v_mfma_f32_16x16x32_bf16 v[40:43], v[100:103], v[108:111], v[40:43]
	v_mfma_f32_16x16x32_bf16 v[36:39], v[100:103], v[160:163], v[36:39]
	v_mfma_f32_16x16x32_bf16 v[32:35], v[100:103], v[164:167], v[32:35]
	v_mfma_f32_16x16x32_bf16 v[28:31], v[152:155], v[104:107], v[28:31]
	v_mfma_f32_16x16x32_bf16 v[24:27], v[152:155], v[108:111], v[24:27]
	v_mfma_f32_16x16x32_bf16 v[20:23], v[152:155], v[160:163], v[20:23]
	v_mfma_f32_16x16x32_bf16 v[16:19], v[152:155], v[164:167], v[16:19]
	v_mfma_f32_16x16x32_bf16 v[12:15], v[156:159], v[104:107], v[12:15]
	v_mfma_f32_16x16x32_bf16 v[8:11], v[156:159], v[108:111], v[8:11]
	s_setprio 0
	ds_read_b128 v[96:99], v136 offset:32768
	ds_read_b128 v[100:103], v136 offset:34816
	ds_read_b128 v[104:107], v137 offset:49152
	ds_read_b128 v[108:111], v137 offset:51200
	ds_read_b128 v[152:155], v136 offset:36864
	ds_read_b128 v[156:159], v136 offset:38912
	ds_read_b128 v[160:163], v137 offset:53248
	ds_read_b128 v[164:167], v137 offset:55296
	s_setprio 1
	s_waitcnt lgkmcnt(1)
	v_mfma_f32_16x16x32_bf16 v[4:7], v[156:159], v[160:163], v[4:7]
	s_waitcnt lgkmcnt(0)
	v_mfma_f32_16x16x32_bf16 v[0:3], v[156:159], v[164:167], v[0:3]
	v_mfma_f32_16x16x32_bf16 v[60:63], v[96:99], v[104:107], v[60:63]
	v_mfma_f32_16x16x32_bf16 v[56:59], v[96:99], v[108:111], v[56:59]
	v_mfma_f32_16x16x32_bf16 v[52:55], v[96:99], v[160:163], v[52:55]
	v_mfma_f32_16x16x32_bf16 v[48:51], v[96:99], v[164:167], v[48:51]
	v_mfma_f32_16x16x32_bf16 v[44:47], v[100:103], v[104:107], v[44:47]
	v_mfma_f32_16x16x32_bf16 v[40:43], v[100:103], v[108:111], v[40:43]
	v_mfma_f32_16x16x32_bf16 v[36:39], v[100:103], v[160:163], v[36:39]
	v_mfma_f32_16x16x32_bf16 v[32:35], v[100:103], v[164:167], v[32:35]
	v_mfma_f32_16x16x32_bf16 v[28:31], v[152:155], v[104:107], v[28:31]
	v_mfma_f32_16x16x32_bf16 v[24:27], v[152:155], v[108:111], v[24:27]
	v_mfma_f32_16x16x32_bf16 v[20:23], v[152:155], v[160:163], v[20:23]
	v_mfma_f32_16x16x32_bf16 v[16:19], v[152:155], v[164:167], v[16:19]
	v_mfma_f32_16x16x32_bf16 v[12:15], v[156:159], v[104:107], v[12:15]
	v_mfma_f32_16x16x32_bf16 v[8:11], v[156:159], v[108:111], v[8:11]
	s_setprio 0
	s_barrier
	ds_write2_b32 v134, v60, v56 offset1:16
	ds_write2_b32 v134, v61, v57 offset0:132 offset1:148
	v_add_u32_e32 v56, 0x400, v134
	ds_write2_b32 v56, v62, v58 offset0:8 offset1:24
	ds_write2_b32 v56, v63, v59 offset0:140 offset1:156
	ds_write2_b32 v134, v52, v48 offset0:32 offset1:48
	ds_write2_b32 v134, v53, v49 offset0:164 offset1:180
	ds_write2_b32 v56, v54, v50 offset0:40 offset1:56
	ds_write2_b32 v56, v55, v51 offset0:172 offset1:188
	v_add_u32_e32 v48, 0x2000, v134
	ds_write2_b32 v48, v44, v40 offset0:64 offset1:80
	ds_write2_b32 v48, v45, v41 offset0:196 offset1:212
	v_add_u32_e32 v40, 0x2400, v134
	ds_write2_b32 v40, v46, v42 offset0:72 offset1:88
	ds_write2_b32 v40, v47, v43 offset0:204 offset1:220
	ds_write2_b32 v48, v36, v32 offset0:96 offset1:112
	ds_write2_b32 v48, v37, v33 offset0:228 offset1:244
	ds_write2_b32 v40, v38, v34 offset0:104 offset1:120
	ds_write2_b32 v40, v39, v35 offset0:236 offset1:252
	v_add_u32_e32 v32, 0x4000, v134
	ds_write2_b32 v32, v28, v24 offset0:128 offset1:144
	v_add_u32_e32 v24, 0x4400, v134
	ds_write2_b32 v24, v29, v25 offset0:4 offset1:20
	ds_write2_b32 v24, v30, v26 offset0:136 offset1:152
	v_add_u32_e32 v25, 0x4800, v134
	ds_write2_b32 v25, v31, v27 offset0:12 offset1:28
	ds_write2_b32 v32, v20, v16 offset0:160 offset1:176
	ds_write2_b32 v24, v21, v17 offset0:36 offset1:52
	ds_write2_b32 v24, v22, v18 offset0:168 offset1:184
	ds_write2_b32 v25, v23, v19 offset0:44 offset1:60
	v_add_u32_e32 v16, 0x6000, v134
	ds_write2_b32 v16, v12, v8 offset0:192 offset1:208
	v_add_u32_e32 v8, 0x6400, v134
	ds_write2_b32 v8, v13, v9 offset0:68 offset1:84
	ds_write2_b32 v8, v14, v10 offset0:200 offset1:216
	v_add_u32_e32 v9, 0x6800, v134
	ds_write2_b32 v9, v15, v11 offset0:76 offset1:92
	ds_write2_b32 v16, v4, v0 offset0:224 offset1:240
	ds_write2_b32 v8, v5, v1 offset0:100 offset1:116
	ds_write2_b32 v8, v6, v2 offset0:232 offset1:248
	ds_write2_b32 v9, v7, v3 offset0:108 offset1:124
	v_or_b32_e32 v0, s24, v113
	v_lshlrev_b32_e32 v70, 2, v0
	v_lshl_add_u64 v[0:1], s[14:15], 0, v[70:71]
	v_lshl_add_u64 v[2:3], s[10:11], 0, v[70:71]
	v_add_u32_e32 v4, s25, v146
	s_mov_b32 s12, 0
	s_waitcnt lgkmcnt(0)
	s_barrier

.LBB0_1998:
	s_and_b32 s20, s19, 0x4000
	s_xor_b32 s21, s20, 0x4000
	s_lshl_b32 s21, s21, 1
	s_add_i32 s21, s21, 32
	s_add_u32 s90, s52, s12
	s_addc_u32 s91, s53, s13
	s_add_i32 m0, s21, s82
	s_lshl_b32 s20, s20, 1
	global_load_lds_dwordx4 v184, s[90:91]
	s_add_i32 m0, s21, s83
	s_add_i32 s20, s20, 32
	global_load_lds_dwordx4 v185, s[90:91]
	s_add_i32 m0, s21, s84
	v_lshl_add_u32 v137, v114, 1, s20
	global_load_lds_dwordx4 v186, s[90:91]
	s_add_i32 m0, s21, s85
	v_lshl_add_u32 v170, v115, 1, s20
	global_load_lds_dwordx4 v187, s[90:91]
	s_add_i32 m0, s21, s86
	v_add_u32_e32 v158, v137, v135
	global_load_lds_dwordx4 v188, s[90:91]
	s_add_i32 m0, s21, s87
	v_add_u32_e32 v166, v170, v135
	global_load_lds_dwordx4 v189, s[90:91]
	s_add_i32 m0, s21, s88
	s_addk_i32 s19, 0x4000
	global_load_lds_dwordx4 v190, s[90:91]
	s_add_i32 m0, s21, s89
	s_add_u32 s12, s12, 0x80
	s_addc_u32 s13, s13, 0
	global_load_lds_dwordx4 v191, s[90:91]
	ds_read_b128 v[138:141], v158
	ds_read_b128 v[146:149], v166 offset:16384
	ds_read_b128 v[150:153], v166 offset:18432
	ds_read_b128 v[162:165], v166 offset:20480
	ds_read_b128 v[166:169], v166 offset:22528
	ds_read_b128 v[142:145], v158 offset:2048
	ds_read_b128 v[154:157], v158 offset:4096
	ds_read_b128 v[158:161], v158 offset:6144
	s_setprio 1
	s_waitcnt lgkmcnt(3)
	v_mfma_f32_16x16x32_bf16 v[60:63], v[138:141], v[146:149], v[60:63]
	v_mfma_f32_16x16x32_bf16 v[56:59], v[138:141], v[150:153], v[56:59]
	v_mfma_f32_16x16x32_bf16 v[52:55], v[138:141], v[162:165], v[52:55]
	v_mfma_f32_16x16x32_bf16 v[48:51], v[138:141], v[166:169], v[48:51]
	s_waitcnt lgkmcnt(2)
	v_mfma_f32_16x16x32_bf16 v[44:47], v[142:145], v[146:149], v[44:47]
	v_mfma_f32_16x16x32_bf16 v[40:43], v[142:145], v[150:153], v[40:43]
	v_mfma_f32_16x16x32_bf16 v[36:39], v[142:145], v[162:165], v[36:39]
	v_mfma_f32_16x16x32_bf16 v[32:35], v[142:145], v[166:169], v[32:35]
	s_waitcnt lgkmcnt(1)
	v_mfma_f32_16x16x32_bf16 v[28:31], v[154:157], v[146:149], v[28:31]
	v_mfma_f32_16x16x32_bf16 v[24:27], v[154:157], v[150:153], v[24:27]
	v_mfma_f32_16x16x32_bf16 v[20:23], v[154:157], v[162:165], v[20:23]
	v_mfma_f32_16x16x32_bf16 v[16:19], v[154:157], v[166:169], v[16:19]
	s_waitcnt lgkmcnt(0)
	v_mfma_f32_16x16x32_bf16 v[12:15], v[158:161], v[146:149], v[12:15]
	v_mfma_f32_16x16x32_bf16 v[8:11], v[158:161], v[150:153], v[8:11]
	v_mfma_f32_16x16x32_bf16 v[4:7], v[158:161], v[162:165], v[4:7]
	v_mfma_f32_16x16x32_bf16 v[0:3], v[158:161], v[166:169], v[0:3]
	s_setprio 0
	v_add_u32_e32 v137, v137, v136
	v_add_u32_e32 v166, v170, v136
	ds_read_b128 v[138:141], v137
	ds_read_b128 v[146:149], v166 offset:16384
	ds_read_b128 v[150:153], v166 offset:18432
	ds_read_b128 v[162:165], v166 offset:20480
	ds_read_b128 v[166:169], v166 offset:22528
	ds_read_b128 v[142:145], v137 offset:2048
	ds_read_b128 v[154:157], v137 offset:4096
	ds_read_b128 v[158:161], v137 offset:6144
	s_setprio 1
	s_waitcnt lgkmcnt(3)
	v_mfma_f32_16x16x32_bf16 v[60:63], v[138:141], v[146:149], v[60:63]
	v_mfma_f32_16x16x32_bf16 v[56:59], v[138:141], v[150:153], v[56:59]
	v_mfma_f32_16x16x32_bf16 v[52:55], v[138:141], v[162:165], v[52:55]
	v_mfma_f32_16x16x32_bf16 v[48:51], v[138:141], v[166:169], v[48:51]
	s_waitcnt lgkmcnt(2)
	v_mfma_f32_16x16x32_bf16 v[44:47], v[142:145], v[146:149], v[44:47]
	v_mfma_f32_16x16x32_bf16 v[40:43], v[142:145], v[150:153], v[40:43]
	v_mfma_f32_16x16x32_bf16 v[36:39], v[142:145], v[162:165], v[36:39]
	v_mfma_f32_16x16x32_bf16 v[32:35], v[142:145], v[166:169], v[32:35]
	s_waitcnt lgkmcnt(1)
	v_mfma_f32_16x16x32_bf16 v[28:31], v[154:157], v[146:149], v[28:31]
	v_mfma_f32_16x16x32_bf16 v[24:27], v[154:157], v[150:153], v[24:27]
	v_mfma_f32_16x16x32_bf16 v[20:23], v[154:157], v[162:165], v[20:23]
	v_mfma_f32_16x16x32_bf16 v[16:19], v[154:157], v[166:169], v[16:19]
	s_waitcnt lgkmcnt(0)
	v_mfma_f32_16x16x32_bf16 v[12:15], v[158:161], v[146:149], v[12:15]
	v_mfma_f32_16x16x32_bf16 v[8:11], v[158:161], v[150:153], v[8:11]
	v_mfma_f32_16x16x32_bf16 v[4:7], v[158:161], v[162:165], v[4:7]
	v_mfma_f32_16x16x32_bf16 v[0:3], v[158:161], v[166:169], v[0:3]
	s_setprio 0
	s_cmpk_eq_i32 s12, 0x780
	s_waitcnt vmcnt(0)
	s_barrier
	s_cbranch_scc0 .LBB0_1998
	ds_read_b128 v[90:93], v116 offset:55296
	ds_read_b128 v[94:97], v116 offset:53248
	ds_read_b128 v[98:101], v117 offset:38912
	ds_read_b128 v[102:105], v117 offset:36864
	ds_read_b128 v[138:141], v116 offset:51200
	ds_read_b128 v[142:145], v116 offset:49152
	ds_read_b128 v[146:149], v117 offset:34816
	ds_read_b128 v[150:153], v117 offset:32768
	s_setprio 1
	s_waitcnt lgkmcnt(5)
	v_mfma_f32_16x16x32_bf16 v[0:3], v[98:101], v[90:93], v[0:3]
	s_waitcnt lgkmcnt(0)
	v_mfma_f32_16x16x32_bf16 v[60:63], v[150:153], v[142:145], v[60:63]
	v_mfma_f32_16x16x32_bf16 v[56:59], v[150:153], v[138:141], v[56:59]
	v_mfma_f32_16x16x32_bf16 v[52:55], v[150:153], v[94:97], v[52:55]
	v_mfma_f32_16x16x32_bf16 v[48:51], v[150:153], v[90:93], v[48:51]
	v_mfma_f32_16x16x32_bf16 v[44:47], v[146:149], v[142:145], v[44:47]
	v_mfma_f32_16x16x32_bf16 v[40:43], v[146:149], v[138:141], v[40:43]
	v_mfma_f32_16x16x32_bf16 v[36:39], v[146:149], v[94:97], v[36:39]
	v_mfma_f32_16x16x32_bf16 v[32:35], v[146:149], v[90:93], v[32:35]
	v_mfma_f32_16x16x32_bf16 v[28:31], v[102:105], v[142:145], v[28:31]
	v_mfma_f32_16x16x32_bf16 v[24:27], v[102:105], v[138:141], v[24:27]
	v_mfma_f32_16x16x32_bf16 v[20:23], v[102:105], v[94:97], v[20:23]
	v_mfma_f32_16x16x32_bf16 v[16:19], v[102:105], v[90:93], v[16:19]
	v_mfma_f32_16x16x32_bf16 v[12:15], v[98:101], v[142:145], v[12:15]
	v_mfma_f32_16x16x32_bf16 v[8:11], v[98:101], v[138:141], v[8:11]
	v_mfma_f32_16x16x32_bf16 v[4:7], v[98:101], v[94:97], v[4:7]
	s_setprio 0
	ds_read_b128 v[90:93], v118 offset:32768
	ds_read_b128 v[94:97], v118 offset:34816
	ds_read_b128 v[98:101], v119 offset:49152
	ds_read_b128 v[102:105], v119 offset:51200
	ds_read_b128 v[138:141], v118 offset:36864
	ds_read_b128 v[142:145], v118 offset:38912
	ds_read_b128 v[146:149], v119 offset:53248
	ds_read_b128 v[150:153], v119 offset:55296
	s_setprio 1
	s_waitcnt lgkmcnt(0)
	v_mfma_f32_16x16x32_bf16 v[0:3], v[142:145], v[150:153], v[0:3]
	v_mfma_f32_16x16x32_bf16 v[60:63], v[90:93], v[98:101], v[60:63]
	v_mfma_f32_16x16x32_bf16 v[56:59], v[90:93], v[102:105], v[56:59]
	v_mfma_f32_16x16x32_bf16 v[52:55], v[90:93], v[146:149], v[52:55]
	v_mfma_f32_16x16x32_bf16 v[48:51], v[90:93], v[150:153], v[48:51]
	v_mfma_f32_16x16x32_bf16 v[44:47], v[94:97], v[98:101], v[44:47]
	v_mfma_f32_16x16x32_bf16 v[40:43], v[94:97], v[102:105], v[40:43]
	v_mfma_f32_16x16x32_bf16 v[36:39], v[94:97], v[146:149], v[36:39]
	v_mfma_f32_16x16x32_bf16 v[32:35], v[94:97], v[150:153], v[32:35]
	v_mfma_f32_16x16x32_bf16 v[28:31], v[138:141], v[98:101], v[28:31]
	v_mfma_f32_16x16x32_bf16 v[24:27], v[138:141], v[102:105], v[24:27]
	v_mfma_f32_16x16x32_bf16 v[20:23], v[138:141], v[146:149], v[20:23]
	v_mfma_f32_16x16x32_bf16 v[16:19], v[138:141], v[150:153], v[16:19]
	v_mfma_f32_16x16x32_bf16 v[12:15], v[142:145], v[98:101], v[12:15]
	v_mfma_f32_16x16x32_bf16 v[8:11], v[142:145], v[102:105], v[8:11]
	v_mfma_f32_16x16x32_bf16 v[4:7], v[142:145], v[146:149], v[4:7]
	s_setprio 0
	s_barrier
	ds_write2_b32 v120, v60, v56 offset1:16
	ds_write2_b32 v120, v61, v57 offset0:132 offset1:148
	v_add_u32_e32 v56, 0x400, v120
	ds_write2_b32 v56, v62, v58 offset0:8 offset1:24
	ds_write2_b32 v56, v63, v59 offset0:140 offset1:156
	ds_write2_b32 v120, v52, v48 offset0:32 offset1:48
	ds_write2_b32 v120, v53, v49 offset0:164 offset1:180
	ds_write2_b32 v56, v54, v50 offset0:40 offset1:56
	ds_write2_b32 v56, v55, v51 offset0:172 offset1:188
	v_add_u32_e32 v48, 0x2000, v120
	ds_write2_b32 v48, v44, v40 offset0:64 offset1:80
	ds_write2_b32 v48, v45, v41 offset0:196 offset1:212
	v_add_u32_e32 v40, 0x2400, v120
	ds_write2_b32 v40, v46, v42 offset0:72 offset1:88
	ds_write2_b32 v40, v47, v43 offset0:204 offset1:220
	ds_write2_b32 v48, v36, v32 offset0:96 offset1:112
	ds_write2_b32 v48, v37, v33 offset0:228 offset1:244
	ds_write2_b32 v40, v38, v34 offset0:104 offset1:120
	ds_write2_b32 v40, v39, v35 offset0:236 offset1:252
	v_add_u32_e32 v32, 0x4000, v120
	ds_write2_b32 v32, v28, v24 offset0:128 offset1:144
	v_add_u32_e32 v24, 0x4400, v120
	ds_write2_b32 v24, v29, v25 offset0:4 offset1:20
	ds_write2_b32 v24, v30, v26 offset0:136 offset1:152
	v_add_u32_e32 v25, 0x4800, v120
	ds_write2_b32 v25, v31, v27 offset0:12 offset1:28
	ds_write2_b32 v32, v20, v16 offset0:160 offset1:176
	ds_write2_b32 v24, v21, v17 offset0:36 offset1:52
	ds_write2_b32 v24, v22, v18 offset0:168 offset1:184
	ds_write2_b32 v25, v23, v19 offset0:44 offset1:60
	v_add_u32_e32 v16, 0x6000, v120
	ds_write2_b32 v16, v12, v8 offset0:192 offset1:208
	v_add_u32_e32 v8, 0x6400, v120
	ds_write2_b32 v8, v13, v9 offset0:68 offset1:84
	ds_write2_b32 v8, v14, v10 offset0:200 offset1:216
	v_add_u32_e32 v9, 0x6800, v120
	ds_write2_b32 v9, v15, v11 offset0:76 offset1:92
	ds_write2_b32 v16, v4, v0 offset0:224 offset1:240
	ds_write2_b32 v8, v5, v1 offset0:100 offset1:116
	ds_write2_b32 v8, v6, v2 offset0:232 offset1:248
	ds_write2_b32 v9, v7, v3 offset0:108 offset1:124
	v_or_b32_e32 v0, s18, v121
	v_ashrrev_i32_e32 v1, 31, v0
	v_lshl_add_u64 v[0:1], v[0:1], 1, s[6:7]
	v_add_u32_e32 v2, s17, v128
	s_mov_b32 s12, 0
	s_waitcnt lgkmcnt(0)
	s_barrier

.LBB0_2009:
	s_and_b32 s17, s16, 0x4000
	s_xor_b32 s18, s17, 0x4000
	s_lshl_b32 s18, s18, 1
	s_add_i32 s18, s18, 32
	s_add_u32 s90, s52, s8
	s_addc_u32 s91, s53, s9
	s_add_i32 m0, s18, s82
	s_lshl_b32 s17, s17, 1
	global_load_lds_dwordx4 v184, s[90:91]
	s_add_i32 m0, s18, s83
	s_add_i32 s17, s17, 32
	global_load_lds_dwordx4 v185, s[90:91]
	s_add_i32 m0, s18, s84
	v_lshl_add_u32 v137, v113, 1, s17
	global_load_lds_dwordx4 v186, s[90:91]
	s_add_i32 m0, s18, s85
	v_lshl_add_u32 v170, v114, 1, s17
	global_load_lds_dwordx4 v187, s[90:91]
	s_add_i32 m0, s18, s86
	v_add_u32_e32 v158, v137, v135
	global_load_lds_dwordx4 v188, s[90:91]
	s_add_i32 m0, s18, s87
	v_add_u32_e32 v166, v170, v135
	global_load_lds_dwordx4 v189, s[90:91]
	s_add_i32 m0, s18, s88
	s_addk_i32 s16, 0x4000
	global_load_lds_dwordx4 v190, s[90:91]
	s_add_i32 m0, s18, s89
	s_add_u32 s8, s8, 0x80
	s_addc_u32 s9, s9, 0
	global_load_lds_dwordx4 v191, s[90:91]
	ds_read_b128 v[138:141], v158
	ds_read_b128 v[146:149], v166 offset:16384
	ds_read_b128 v[150:153], v166 offset:18432
	ds_read_b128 v[162:165], v166 offset:20480
	ds_read_b128 v[166:169], v166 offset:22528
	ds_read_b128 v[142:145], v158 offset:2048
	ds_read_b128 v[154:157], v158 offset:4096
	ds_read_b128 v[158:161], v158 offset:6144
	s_setprio 1
	s_waitcnt lgkmcnt(3)
	v_mfma_f32_16x16x32_bf16 v[60:63], v[138:141], v[146:149], v[60:63]
	v_mfma_f32_16x16x32_bf16 v[56:59], v[138:141], v[150:153], v[56:59]
	v_mfma_f32_16x16x32_bf16 v[52:55], v[138:141], v[162:165], v[52:55]
	v_mfma_f32_16x16x32_bf16 v[48:51], v[138:141], v[166:169], v[48:51]
	s_waitcnt lgkmcnt(2)
	v_mfma_f32_16x16x32_bf16 v[44:47], v[142:145], v[146:149], v[44:47]
	v_mfma_f32_16x16x32_bf16 v[40:43], v[142:145], v[150:153], v[40:43]
	v_mfma_f32_16x16x32_bf16 v[36:39], v[142:145], v[162:165], v[36:39]
	v_mfma_f32_16x16x32_bf16 v[32:35], v[142:145], v[166:169], v[32:35]
	s_waitcnt lgkmcnt(1)
	v_mfma_f32_16x16x32_bf16 v[28:31], v[154:157], v[146:149], v[28:31]
	v_mfma_f32_16x16x32_bf16 v[24:27], v[154:157], v[150:153], v[24:27]
	v_mfma_f32_16x16x32_bf16 v[20:23], v[154:157], v[162:165], v[20:23]
	v_mfma_f32_16x16x32_bf16 v[16:19], v[154:157], v[166:169], v[16:19]
	s_waitcnt lgkmcnt(0)
	v_mfma_f32_16x16x32_bf16 v[12:15], v[158:161], v[146:149], v[12:15]
	v_mfma_f32_16x16x32_bf16 v[8:11], v[158:161], v[150:153], v[8:11]
	v_mfma_f32_16x16x32_bf16 v[4:7], v[158:161], v[162:165], v[4:7]
	v_mfma_f32_16x16x32_bf16 v[0:3], v[158:161], v[166:169], v[0:3]
	s_setprio 0
	v_add_u32_e32 v137, v137, v136
	v_add_u32_e32 v166, v170, v136
	ds_read_b128 v[138:141], v137
	ds_read_b128 v[146:149], v166 offset:16384
	ds_read_b128 v[150:153], v166 offset:18432
	ds_read_b128 v[162:165], v166 offset:20480
	ds_read_b128 v[166:169], v166 offset:22528
	ds_read_b128 v[142:145], v137 offset:2048
	ds_read_b128 v[154:157], v137 offset:4096
	ds_read_b128 v[158:161], v137 offset:6144
	s_setprio 1
	s_waitcnt lgkmcnt(3)
	v_mfma_f32_16x16x32_bf16 v[60:63], v[138:141], v[146:149], v[60:63]
	v_mfma_f32_16x16x32_bf16 v[56:59], v[138:141], v[150:153], v[56:59]
	v_mfma_f32_16x16x32_bf16 v[52:55], v[138:141], v[162:165], v[52:55]
	v_mfma_f32_16x16x32_bf16 v[48:51], v[138:141], v[166:169], v[48:51]
	s_waitcnt lgkmcnt(2)
	v_mfma_f32_16x16x32_bf16 v[44:47], v[142:145], v[146:149], v[44:47]
	v_mfma_f32_16x16x32_bf16 v[40:43], v[142:145], v[150:153], v[40:43]
	v_mfma_f32_16x16x32_bf16 v[36:39], v[142:145], v[162:165], v[36:39]
	v_mfma_f32_16x16x32_bf16 v[32:35], v[142:145], v[166:169], v[32:35]
	s_waitcnt lgkmcnt(1)
	v_mfma_f32_16x16x32_bf16 v[28:31], v[154:157], v[146:149], v[28:31]
	v_mfma_f32_16x16x32_bf16 v[24:27], v[154:157], v[150:153], v[24:27]
	v_mfma_f32_16x16x32_bf16 v[20:23], v[154:157], v[162:165], v[20:23]
	v_mfma_f32_16x16x32_bf16 v[16:19], v[154:157], v[166:169], v[16:19]
	s_waitcnt lgkmcnt(0)
	v_mfma_f32_16x16x32_bf16 v[12:15], v[158:161], v[146:149], v[12:15]
	v_mfma_f32_16x16x32_bf16 v[8:11], v[158:161], v[150:153], v[8:11]
	v_mfma_f32_16x16x32_bf16 v[4:7], v[158:161], v[162:165], v[4:7]
	v_mfma_f32_16x16x32_bf16 v[0:3], v[158:161], v[166:169], v[0:3]
	s_setprio 0
	s_cmpk_eq_i32 s8, 0x780
	s_waitcnt vmcnt(0)
	s_barrier
	s_cbranch_scc0 .LBB0_2009
	ds_read_b128 v[88:91], v115 offset:55296
	ds_read_b128 v[92:95], v115 offset:53248
	ds_read_b128 v[96:99], v116 offset:38912
	ds_read_b128 v[100:103], v116 offset:36864
	ds_read_b128 v[138:141], v115 offset:51200
	ds_read_b128 v[142:145], v115 offset:49152
	ds_read_b128 v[146:149], v116 offset:34816
	ds_read_b128 v[150:153], v116 offset:32768
	s_setprio 1
	s_waitcnt lgkmcnt(5)
	v_mfma_f32_16x16x32_bf16 v[0:3], v[96:99], v[88:91], v[0:3]
	s_waitcnt lgkmcnt(0)
	v_mfma_f32_16x16x32_bf16 v[60:63], v[150:153], v[142:145], v[60:63]
	v_mfma_f32_16x16x32_bf16 v[56:59], v[150:153], v[138:141], v[56:59]
	v_mfma_f32_16x16x32_bf16 v[52:55], v[150:153], v[92:95], v[52:55]
	v_mfma_f32_16x16x32_bf16 v[48:51], v[150:153], v[88:91], v[48:51]
	v_mfma_f32_16x16x32_bf16 v[44:47], v[146:149], v[142:145], v[44:47]
	v_mfma_f32_16x16x32_bf16 v[40:43], v[146:149], v[138:141], v[40:43]
	v_mfma_f32_16x16x32_bf16 v[36:39], v[146:149], v[92:95], v[36:39]
	v_mfma_f32_16x16x32_bf16 v[32:35], v[146:149], v[88:91], v[32:35]
	v_mfma_f32_16x16x32_bf16 v[28:31], v[100:103], v[142:145], v[28:31]
	v_mfma_f32_16x16x32_bf16 v[24:27], v[100:103], v[138:141], v[24:27]
	v_mfma_f32_16x16x32_bf16 v[20:23], v[100:103], v[92:95], v[20:23]
	v_mfma_f32_16x16x32_bf16 v[16:19], v[100:103], v[88:91], v[16:19]
	v_mfma_f32_16x16x32_bf16 v[12:15], v[96:99], v[142:145], v[12:15]
	v_mfma_f32_16x16x32_bf16 v[8:11], v[96:99], v[138:141], v[8:11]
	v_mfma_f32_16x16x32_bf16 v[4:7], v[96:99], v[92:95], v[4:7]
	s_setprio 0
	ds_read_b128 v[88:91], v117 offset:32768
	ds_read_b128 v[92:95], v117 offset:34816
	ds_read_b128 v[96:99], v118 offset:49152
	ds_read_b128 v[100:103], v118 offset:51200
	ds_read_b128 v[138:141], v117 offset:36864
	ds_read_b128 v[142:145], v117 offset:38912
	ds_read_b128 v[146:149], v118 offset:53248
	ds_read_b128 v[150:153], v118 offset:55296
	s_setprio 1
	s_waitcnt lgkmcnt(0)
	v_mfma_f32_16x16x32_bf16 v[0:3], v[142:145], v[150:153], v[0:3]
	v_mfma_f32_16x16x32_bf16 v[60:63], v[88:91], v[96:99], v[60:63]
	v_mfma_f32_16x16x32_bf16 v[56:59], v[88:91], v[100:103], v[56:59]
	v_mfma_f32_16x16x32_bf16 v[52:55], v[88:91], v[146:149], v[52:55]
	v_mfma_f32_16x16x32_bf16 v[48:51], v[88:91], v[150:153], v[48:51]
	v_mfma_f32_16x16x32_bf16 v[44:47], v[92:95], v[96:99], v[44:47]
	v_mfma_f32_16x16x32_bf16 v[40:43], v[92:95], v[100:103], v[40:43]
	v_mfma_f32_16x16x32_bf16 v[36:39], v[92:95], v[146:149], v[36:39]
	v_mfma_f32_16x16x32_bf16 v[32:35], v[92:95], v[150:153], v[32:35]
	v_mfma_f32_16x16x32_bf16 v[28:31], v[138:141], v[96:99], v[28:31]
	v_mfma_f32_16x16x32_bf16 v[24:27], v[138:141], v[100:103], v[24:27]
	v_mfma_f32_16x16x32_bf16 v[20:23], v[138:141], v[146:149], v[20:23]
	v_mfma_f32_16x16x32_bf16 v[16:19], v[138:141], v[150:153], v[16:19]
	v_mfma_f32_16x16x32_bf16 v[12:15], v[142:145], v[96:99], v[12:15]
	v_mfma_f32_16x16x32_bf16 v[8:11], v[142:145], v[100:103], v[8:11]
	v_mfma_f32_16x16x32_bf16 v[4:7], v[142:145], v[146:149], v[4:7]
	s_setprio 0
	s_barrier
	ds_write2_b32 v119, v60, v56 offset1:16
	ds_write2_b32 v119, v61, v57 offset0:132 offset1:148
	v_add_u32_e32 v56, 0x400, v119
	ds_write2_b32 v56, v62, v58 offset0:8 offset1:24
	ds_write2_b32 v56, v63, v59 offset0:140 offset1:156
	ds_write2_b32 v119, v52, v48 offset0:32 offset1:48
	ds_write2_b32 v119, v53, v49 offset0:164 offset1:180
	ds_write2_b32 v56, v54, v50 offset0:40 offset1:56
	ds_write2_b32 v56, v55, v51 offset0:172 offset1:188
	v_add_u32_e32 v48, 0x2000, v119
	ds_write2_b32 v48, v44, v40 offset0:64 offset1:80
	ds_write2_b32 v48, v45, v41 offset0:196 offset1:212
	v_add_u32_e32 v40, 0x2400, v119
	ds_write2_b32 v40, v46, v42 offset0:72 offset1:88
	ds_write2_b32 v40, v47, v43 offset0:204 offset1:220
	ds_write2_b32 v48, v36, v32 offset0:96 offset1:112
	ds_write2_b32 v48, v37, v33 offset0:228 offset1:244
	ds_write2_b32 v40, v38, v34 offset0:104 offset1:120
	ds_write2_b32 v40, v39, v35 offset0:236 offset1:252
	v_add_u32_e32 v32, 0x4000, v119
	ds_write2_b32 v32, v28, v24 offset0:128 offset1:144
	v_add_u32_e32 v24, 0x4400, v119
	ds_write2_b32 v24, v29, v25 offset0:4 offset1:20
	ds_write2_b32 v24, v30, v26 offset0:136 offset1:152
	v_add_u32_e32 v25, 0x4800, v119
	ds_write2_b32 v25, v31, v27 offset0:12 offset1:28
	ds_write2_b32 v32, v20, v16 offset0:160 offset1:176
	ds_write2_b32 v24, v21, v17 offset0:36 offset1:52
	ds_write2_b32 v24, v22, v18 offset0:168 offset1:184
	ds_write2_b32 v25, v23, v19 offset0:44 offset1:60
	v_add_u32_e32 v16, 0x6000, v119
	ds_write2_b32 v16, v12, v8 offset0:192 offset1:208
	v_add_u32_e32 v8, 0x6400, v119
	ds_write2_b32 v8, v13, v9 offset0:68 offset1:84
	ds_write2_b32 v8, v14, v10 offset0:200 offset1:216
	v_add_u32_e32 v9, 0x6800, v119
	ds_write2_b32 v9, v15, v11 offset0:76 offset1:92
	ds_write2_b32 v16, v4, v0 offset0:224 offset1:240
	ds_write2_b32 v8, v5, v1 offset0:100 offset1:116
	ds_write2_b32 v8, v6, v2 offset0:232 offset1:248
	ds_write2_b32 v9, v7, v3 offset0:108 offset1:124
	v_or_b32_e32 v0, s14, v120
	v_ashrrev_i32_e32 v1, 31, v0
	v_lshl_add_u64 v[0:1], v[0:1], 1, s[6:7]
	v_add_u32_e32 v2, s15, v128
	s_mov_b32 s8, 0
	s_waitcnt lgkmcnt(0)
	s_barrier

.LBB0_2076:
	s_and_b32 s27, s26, 0x4000
	s_xor_b32 s28, s27, 0x4000
	s_lshl_b32 s28, s28, 1
	s_add_i32 s28, s28, 32
	s_add_u32 s90, s52, s16
	s_addc_u32 s91, s53, s17
	s_add_i32 m0, s28, s82
	s_lshl_b32 s27, s27, 1
	global_load_lds_dwordx4 v192, s[90:91]
	s_add_i32 m0, s28, s83
	s_add_i32 s27, s27, 32
	global_load_lds_dwordx4 v193, s[90:91]
	s_add_i32 m0, s28, s84
	v_add3_u32 v170, s27, v114, v135
	global_load_lds_dwordx4 v194, s[90:91]
	s_add_i32 m0, s28, s85
	v_add3_u32 v171, s27, v115, v135
	global_load_lds_dwordx4 v195, s[90:91]
	s_add_i32 m0, s28, s86
	v_add_u32_e32 v158, v170, v136
	global_load_lds_dwordx4 v196, s[90:91]
	s_add_i32 m0, s28, s87
	v_add_u32_e32 v166, v171, v136
	global_load_lds_dwordx4 v197, s[90:91]
	s_add_i32 m0, s28, s88
	s_addk_i32 s26, 0x4000
	global_load_lds_dwordx4 v198, s[90:91]
	s_add_i32 m0, s28, s89
	s_add_u32 s16, s16, 0x80
	s_addc_u32 s17, s17, 0
	global_load_lds_dwordx4 v199, s[90:91]
	ds_read_b128 v[138:141], v158
	ds_read_b128 v[146:149], v166 offset:16384
	ds_read_b128 v[150:153], v166 offset:18432
	ds_read_b128 v[162:165], v166 offset:20480
	ds_read_b128 v[166:169], v166 offset:22528
	ds_read_b128 v[142:145], v158 offset:2048
	ds_read_b128 v[154:157], v158 offset:4096
	ds_read_b128 v[158:161], v158 offset:6144
	s_setprio 1
	s_waitcnt lgkmcnt(3)
	v_mfma_f32_16x16x32_bf16 v[60:63], v[138:141], v[146:149], v[60:63]
	v_mfma_f32_16x16x32_bf16 v[56:59], v[138:141], v[150:153], v[56:59]
	v_mfma_f32_16x16x32_bf16 v[52:55], v[138:141], v[162:165], v[52:55]
	v_mfma_f32_16x16x32_bf16 v[48:51], v[138:141], v[166:169], v[48:51]
	s_waitcnt lgkmcnt(2)
	v_mfma_f32_16x16x32_bf16 v[44:47], v[142:145], v[146:149], v[44:47]
	v_mfma_f32_16x16x32_bf16 v[40:43], v[142:145], v[150:153], v[40:43]
	v_mfma_f32_16x16x32_bf16 v[36:39], v[142:145], v[162:165], v[36:39]
	v_mfma_f32_16x16x32_bf16 v[32:35], v[142:145], v[166:169], v[32:35]
	s_waitcnt lgkmcnt(1)
	v_mfma_f32_16x16x32_bf16 v[28:31], v[154:157], v[146:149], v[28:31]
	v_mfma_f32_16x16x32_bf16 v[24:27], v[154:157], v[150:153], v[24:27]
	v_mfma_f32_16x16x32_bf16 v[20:23], v[154:157], v[162:165], v[20:23]
	v_mfma_f32_16x16x32_bf16 v[16:19], v[154:157], v[166:169], v[16:19]
	s_waitcnt lgkmcnt(0)
	v_mfma_f32_16x16x32_bf16 v[12:15], v[158:161], v[146:149], v[12:15]
	v_mfma_f32_16x16x32_bf16 v[8:11], v[158:161], v[150:153], v[8:11]
	v_mfma_f32_16x16x32_bf16 v[4:7], v[158:161], v[162:165], v[4:7]
	v_mfma_f32_16x16x32_bf16 v[0:3], v[158:161], v[166:169], v[0:3]
	s_setprio 0
	v_add_u32_e32 v158, v170, v137
	v_add_u32_e32 v166, v171, v137
	ds_read_b128 v[138:141], v158
	ds_read_b128 v[146:149], v166 offset:16384
	ds_read_b128 v[150:153], v166 offset:18432
	ds_read_b128 v[162:165], v166 offset:20480
	ds_read_b128 v[166:169], v166 offset:22528
	ds_read_b128 v[142:145], v158 offset:2048
	ds_read_b128 v[154:157], v158 offset:4096
	ds_read_b128 v[158:161], v158 offset:6144
	s_setprio 1
	s_waitcnt lgkmcnt(3)
	v_mfma_f32_16x16x32_bf16 v[60:63], v[138:141], v[146:149], v[60:63]
	v_mfma_f32_16x16x32_bf16 v[56:59], v[138:141], v[150:153], v[56:59]
	v_mfma_f32_16x16x32_bf16 v[52:55], v[138:141], v[162:165], v[52:55]
	v_mfma_f32_16x16x32_bf16 v[48:51], v[138:141], v[166:169], v[48:51]
	s_waitcnt lgkmcnt(2)
	v_mfma_f32_16x16x32_bf16 v[44:47], v[142:145], v[146:149], v[44:47]
	v_mfma_f32_16x16x32_bf16 v[40:43], v[142:145], v[150:153], v[40:43]
	v_mfma_f32_16x16x32_bf16 v[36:39], v[142:145], v[162:165], v[36:39]
	v_mfma_f32_16x16x32_bf16 v[32:35], v[142:145], v[166:169], v[32:35]
	s_waitcnt lgkmcnt(1)
	v_mfma_f32_16x16x32_bf16 v[28:31], v[154:157], v[146:149], v[28:31]
	v_mfma_f32_16x16x32_bf16 v[24:27], v[154:157], v[150:153], v[24:27]
	v_mfma_f32_16x16x32_bf16 v[20:23], v[154:157], v[162:165], v[20:23]
	v_mfma_f32_16x16x32_bf16 v[16:19], v[154:157], v[166:169], v[16:19]
	s_waitcnt lgkmcnt(0)
	v_mfma_f32_16x16x32_bf16 v[12:15], v[158:161], v[146:149], v[12:15]
	v_mfma_f32_16x16x32_bf16 v[8:11], v[158:161], v[150:153], v[8:11]
	v_mfma_f32_16x16x32_bf16 v[4:7], v[158:161], v[162:165], v[4:7]
	v_mfma_f32_16x16x32_bf16 v[0:3], v[158:161], v[166:169], v[0:3]
	s_setprio 0
	s_cmpk_eq_i32 s16, 0x1f80
	s_waitcnt vmcnt(0)
	s_barrier
	s_cbranch_scc0 .LBB0_2076
	ds_read_b128 v[90:93], v118 offset:55296
	ds_read_b128 v[94:97], v118 offset:53248
	ds_read_b128 v[98:101], v119 offset:38912
	ds_read_b128 v[102:105], v119 offset:36864
	ds_read_b128 v[138:141], v118 offset:51200
	ds_read_b128 v[142:145], v118 offset:49152
	ds_read_b128 v[146:149], v119 offset:34816
	ds_read_b128 v[150:153], v119 offset:32768
	s_setprio 1
	s_waitcnt lgkmcnt(5)
	v_mfma_f32_16x16x32_bf16 v[4:7], v[98:101], v[94:97], v[4:7]
	v_mfma_f32_16x16x32_bf16 v[0:3], v[98:101], v[90:93], v[0:3]
	s_waitcnt lgkmcnt(0)
	v_mfma_f32_16x16x32_bf16 v[60:63], v[150:153], v[142:145], v[60:63]
	v_mfma_f32_16x16x32_bf16 v[56:59], v[150:153], v[138:141], v[56:59]
	v_mfma_f32_16x16x32_bf16 v[52:55], v[150:153], v[94:97], v[52:55]
	v_mfma_f32_16x16x32_bf16 v[48:51], v[150:153], v[90:93], v[48:51]
	v_mfma_f32_16x16x32_bf16 v[44:47], v[146:149], v[142:145], v[44:47]
	v_mfma_f32_16x16x32_bf16 v[40:43], v[146:149], v[138:141], v[40:43]
	v_mfma_f32_16x16x32_bf16 v[36:39], v[146:149], v[94:97], v[36:39]
	v_mfma_f32_16x16x32_bf16 v[32:35], v[146:149], v[90:93], v[32:35]
	v_mfma_f32_16x16x32_bf16 v[28:31], v[102:105], v[142:145], v[28:31]
	v_mfma_f32_16x16x32_bf16 v[24:27], v[102:105], v[138:141], v[24:27]
	v_mfma_f32_16x16x32_bf16 v[20:23], v[102:105], v[94:97], v[20:23]
	v_mfma_f32_16x16x32_bf16 v[16:19], v[102:105], v[90:93], v[16:19]
	v_mfma_f32_16x16x32_bf16 v[12:15], v[98:101], v[142:145], v[12:15]
	v_mfma_f32_16x16x32_bf16 v[8:11], v[98:101], v[138:141], v[8:11]
	s_setprio 0
	ds_read_b128 v[90:93], v120 offset:32768
	ds_read_b128 v[94:97], v120 offset:34816
	ds_read_b128 v[98:101], v121 offset:49152
	ds_read_b128 v[102:105], v121 offset:51200
	ds_read_b128 v[138:141], v120 offset:36864
	ds_read_b128 v[142:145], v120 offset:38912
	ds_read_b128 v[146:149], v121 offset:53248
	ds_read_b128 v[150:153], v121 offset:55296
	s_setprio 1
	s_waitcnt lgkmcnt(1)
	v_mfma_f32_16x16x32_bf16 v[4:7], v[142:145], v[146:149], v[4:7]
	s_waitcnt lgkmcnt(0)
	v_mfma_f32_16x16x32_bf16 v[0:3], v[142:145], v[150:153], v[0:3]
	v_mfma_f32_16x16x32_bf16 v[60:63], v[90:93], v[98:101], v[60:63]
	v_mfma_f32_16x16x32_bf16 v[56:59], v[90:93], v[102:105], v[56:59]
	v_mfma_f32_16x16x32_bf16 v[52:55], v[90:93], v[146:149], v[52:55]
	v_mfma_f32_16x16x32_bf16 v[48:51], v[90:93], v[150:153], v[48:51]
	v_mfma_f32_16x16x32_bf16 v[44:47], v[94:97], v[98:101], v[44:47]
	v_mfma_f32_16x16x32_bf16 v[40:43], v[94:97], v[102:105], v[40:43]
	v_mfma_f32_16x16x32_bf16 v[36:39], v[94:97], v[146:149], v[36:39]
	v_mfma_f32_16x16x32_bf16 v[32:35], v[94:97], v[150:153], v[32:35]
	v_mfma_f32_16x16x32_bf16 v[28:31], v[138:141], v[98:101], v[28:31]
	v_mfma_f32_16x16x32_bf16 v[24:27], v[138:141], v[102:105], v[24:27]
	v_mfma_f32_16x16x32_bf16 v[20:23], v[138:141], v[146:149], v[20:23]
	v_mfma_f32_16x16x32_bf16 v[16:19], v[138:141], v[150:153], v[16:19]
	v_mfma_f32_16x16x32_bf16 v[12:15], v[142:145], v[98:101], v[12:15]
	v_mfma_f32_16x16x32_bf16 v[8:11], v[142:145], v[102:105], v[8:11]
	s_setprio 0
	s_barrier
	ds_write2_b32 v116, v60, v56 offset1:16
	ds_write2_b32 v116, v61, v57 offset0:132 offset1:148
	v_add_u32_e32 v56, 0x400, v116
	ds_write2_b32 v56, v62, v58 offset0:8 offset1:24
	ds_write2_b32 v56, v63, v59 offset0:140 offset1:156
	ds_write2_b32 v116, v52, v48 offset0:32 offset1:48
	ds_write2_b32 v116, v53, v49 offset0:164 offset1:180
	ds_write2_b32 v56, v54, v50 offset0:40 offset1:56
	ds_write2_b32 v56, v55, v51 offset0:172 offset1:188
	v_add_u32_e32 v48, 0x2000, v116
	ds_write2_b32 v48, v44, v40 offset0:64 offset1:80
	ds_write2_b32 v48, v45, v41 offset0:196 offset1:212
	v_add_u32_e32 v40, 0x2400, v116
	ds_write2_b32 v40, v46, v42 offset0:72 offset1:88
	ds_write2_b32 v40, v47, v43 offset0:204 offset1:220
	ds_write2_b32 v48, v36, v32 offset0:96 offset1:112
	ds_write2_b32 v48, v37, v33 offset0:228 offset1:244
	ds_write2_b32 v40, v38, v34 offset0:104 offset1:120
	ds_write2_b32 v40, v39, v35 offset0:236 offset1:252
	v_add_u32_e32 v32, 0x4000, v116
	ds_write2_b32 v32, v28, v24 offset0:128 offset1:144
	v_add_u32_e32 v24, 0x4400, v116
	ds_write2_b32 v24, v29, v25 offset0:4 offset1:20
	ds_write2_b32 v24, v30, v26 offset0:136 offset1:152
	v_add_u32_e32 v25, 0x4800, v116
	ds_write2_b32 v25, v31, v27 offset0:12 offset1:28
	ds_write2_b32 v32, v20, v16 offset0:160 offset1:176
	ds_write2_b32 v24, v21, v17 offset0:36 offset1:52
	ds_write2_b32 v24, v22, v18 offset0:168 offset1:184
	ds_write2_b32 v25, v23, v19 offset0:44 offset1:60
	v_add_u32_e32 v16, 0x6000, v116
	ds_write2_b32 v16, v12, v8 offset0:192 offset1:208
	v_add_u32_e32 v8, 0x6400, v116
	ds_write2_b32 v8, v13, v9 offset0:68 offset1:84
	ds_write2_b32 v8, v14, v10 offset0:200 offset1:216
	v_add_u32_e32 v9, 0x6800, v116
	ds_write2_b32 v9, v15, v11 offset0:76 offset1:92
	ds_write2_b32 v16, v4, v0 offset0:224 offset1:240
	ds_write2_b32 v8, v5, v1 offset0:100 offset1:116
	ds_write2_b32 v8, v6, v2 offset0:232 offset1:248
	ds_write2_b32 v9, v7, v3 offset0:108 offset1:124
	v_or_b32_e32 v0, s25, v117
	v_ashrrev_i32_e32 v1, 31, v0
	v_lshlrev_b64 v[2:3], 2, v[0:1]
	v_lshl_add_u64 v[0:1], s[14:15], 0, v[2:3]
	v_lshl_add_u64 v[2:3], s[12:13], 0, v[2:3]
	v_add_u32_e32 v4, s24, v128
	s_mov_b32 s16, 0
	s_waitcnt lgkmcnt(0)
	s_barrier

.LBB0_2085:
	s_and_b32 s28, s27, 0x4000
	s_xor_b32 s29, s28, 0x4000
	s_lshl_b32 s29, s29, 1
	s_add_i32 s29, s29, 32
	s_add_u32 s90, s52, s16
	s_addc_u32 s91, s53, s17
	s_add_i32 m0, s29, s82
	s_lshl_b32 s28, s28, 1
	global_load_lds_dwordx4 v192, s[90:91]
	s_add_i32 m0, s29, s83
	s_add_i32 s28, s28, 32
	global_load_lds_dwordx4 v193, s[90:91]
	s_add_i32 m0, s29, s84
	v_add3_u32 v139, s28, v113, v136
	global_load_lds_dwordx4 v194, s[90:91]
	s_add_i32 m0, s29, s85
	v_add3_u32 v172, s28, v114, v136
	global_load_lds_dwordx4 v195, s[90:91]
	s_add_i32 m0, s29, s86
	v_add_u32_e32 v160, v139, v137
	global_load_lds_dwordx4 v196, s[90:91]
	s_add_i32 m0, s29, s87
	v_add_u32_e32 v168, v172, v137
	global_load_lds_dwordx4 v197, s[90:91]
	s_add_i32 m0, s29, s88
	s_addk_i32 s27, 0x4000
	global_load_lds_dwordx4 v198, s[90:91]
	s_add_i32 m0, s29, s89
	s_add_u32 s16, s16, 0x80
	s_addc_u32 s17, s17, 0
	global_load_lds_dwordx4 v199, s[90:91]
	ds_read_b128 v[140:143], v160
	ds_read_b128 v[148:151], v168 offset:16384
	ds_read_b128 v[152:155], v168 offset:18432
	ds_read_b128 v[164:167], v168 offset:20480
	ds_read_b128 v[168:171], v168 offset:22528
	ds_read_b128 v[144:147], v160 offset:2048
	ds_read_b128 v[156:159], v160 offset:4096
	ds_read_b128 v[160:163], v160 offset:6144
	s_setprio 1
	s_waitcnt lgkmcnt(3)
	v_mfma_f32_16x16x32_bf16 v[60:63], v[140:143], v[148:151], v[60:63]
	v_mfma_f32_16x16x32_bf16 v[56:59], v[140:143], v[152:155], v[56:59]
	v_mfma_f32_16x16x32_bf16 v[52:55], v[140:143], v[164:167], v[52:55]
	v_mfma_f32_16x16x32_bf16 v[48:51], v[140:143], v[168:171], v[48:51]
	s_waitcnt lgkmcnt(2)
	v_mfma_f32_16x16x32_bf16 v[44:47], v[144:147], v[148:151], v[44:47]
	v_mfma_f32_16x16x32_bf16 v[40:43], v[144:147], v[152:155], v[40:43]
	v_mfma_f32_16x16x32_bf16 v[36:39], v[144:147], v[164:167], v[36:39]
	v_mfma_f32_16x16x32_bf16 v[32:35], v[144:147], v[168:171], v[32:35]
	s_waitcnt lgkmcnt(1)
	v_mfma_f32_16x16x32_bf16 v[28:31], v[156:159], v[148:151], v[28:31]
	v_mfma_f32_16x16x32_bf16 v[24:27], v[156:159], v[152:155], v[24:27]
	v_mfma_f32_16x16x32_bf16 v[20:23], v[156:159], v[164:167], v[20:23]
	v_mfma_f32_16x16x32_bf16 v[16:19], v[156:159], v[168:171], v[16:19]
	s_waitcnt lgkmcnt(0)
	v_mfma_f32_16x16x32_bf16 v[12:15], v[160:163], v[148:151], v[12:15]
	v_mfma_f32_16x16x32_bf16 v[8:11], v[160:163], v[152:155], v[8:11]
	v_mfma_f32_16x16x32_bf16 v[4:7], v[160:163], v[164:167], v[4:7]
	v_mfma_f32_16x16x32_bf16 v[0:3], v[160:163], v[168:171], v[0:3]
	s_setprio 0
	v_add_u32_e32 v139, v139, v138
	v_add_u32_e32 v168, v172, v138
	ds_read_b128 v[140:143], v139
	ds_read_b128 v[148:151], v168 offset:16384
	ds_read_b128 v[152:155], v168 offset:18432
	ds_read_b128 v[164:167], v168 offset:20480
	ds_read_b128 v[168:171], v168 offset:22528
	ds_read_b128 v[144:147], v139 offset:2048
	ds_read_b128 v[156:159], v139 offset:4096
	ds_read_b128 v[160:163], v139 offset:6144
	s_setprio 1
	s_waitcnt lgkmcnt(3)
	v_mfma_f32_16x16x32_bf16 v[60:63], v[140:143], v[148:151], v[60:63]
	v_mfma_f32_16x16x32_bf16 v[56:59], v[140:143], v[152:155], v[56:59]
	v_mfma_f32_16x16x32_bf16 v[52:55], v[140:143], v[164:167], v[52:55]
	v_mfma_f32_16x16x32_bf16 v[48:51], v[140:143], v[168:171], v[48:51]
	s_waitcnt lgkmcnt(2)
	v_mfma_f32_16x16x32_bf16 v[44:47], v[144:147], v[148:151], v[44:47]
	v_mfma_f32_16x16x32_bf16 v[40:43], v[144:147], v[152:155], v[40:43]
	v_mfma_f32_16x16x32_bf16 v[36:39], v[144:147], v[164:167], v[36:39]
	v_mfma_f32_16x16x32_bf16 v[32:35], v[144:147], v[168:171], v[32:35]
	s_waitcnt lgkmcnt(1)
	v_mfma_f32_16x16x32_bf16 v[28:31], v[156:159], v[148:151], v[28:31]
	v_mfma_f32_16x16x32_bf16 v[24:27], v[156:159], v[152:155], v[24:27]
	v_mfma_f32_16x16x32_bf16 v[20:23], v[156:159], v[164:167], v[20:23]
	v_mfma_f32_16x16x32_bf16 v[16:19], v[156:159], v[168:171], v[16:19]
	s_waitcnt lgkmcnt(0)
	v_mfma_f32_16x16x32_bf16 v[12:15], v[160:163], v[148:151], v[12:15]
	v_mfma_f32_16x16x32_bf16 v[8:11], v[160:163], v[152:155], v[8:11]
	v_mfma_f32_16x16x32_bf16 v[4:7], v[160:163], v[164:167], v[4:7]
	v_mfma_f32_16x16x32_bf16 v[0:3], v[160:163], v[168:171], v[0:3]
	s_setprio 0
	s_cmpk_eq_i32 s16, 0x1f80
	s_waitcnt vmcnt(0)
	s_barrier
	s_cbranch_scc0 .LBB0_2085
	ds_read_b128 v[88:91], v117 offset:55296
	ds_read_b128 v[92:95], v117 offset:53248
	ds_read_b128 v[96:99], v118 offset:38912
	ds_read_b128 v[100:103], v118 offset:36864
	ds_read_b128 v[140:143], v117 offset:51200
	ds_read_b128 v[144:147], v117 offset:49152
	ds_read_b128 v[148:151], v118 offset:34816
	ds_read_b128 v[152:155], v118 offset:32768
	s_setprio 1
	s_waitcnt lgkmcnt(5)
	v_mfma_f32_16x16x32_bf16 v[4:7], v[96:99], v[92:95], v[4:7]
	v_mfma_f32_16x16x32_bf16 v[0:3], v[96:99], v[88:91], v[0:3]
	s_waitcnt lgkmcnt(0)
	v_mfma_f32_16x16x32_bf16 v[60:63], v[152:155], v[144:147], v[60:63]
	v_mfma_f32_16x16x32_bf16 v[56:59], v[152:155], v[140:143], v[56:59]
	v_mfma_f32_16x16x32_bf16 v[52:55], v[152:155], v[92:95], v[52:55]
	v_mfma_f32_16x16x32_bf16 v[48:51], v[152:155], v[88:91], v[48:51]
	v_mfma_f32_16x16x32_bf16 v[44:47], v[148:151], v[144:147], v[44:47]
	v_mfma_f32_16x16x32_bf16 v[40:43], v[148:151], v[140:143], v[40:43]
	v_mfma_f32_16x16x32_bf16 v[36:39], v[148:151], v[92:95], v[36:39]
	v_mfma_f32_16x16x32_bf16 v[32:35], v[148:151], v[88:91], v[32:35]
	v_mfma_f32_16x16x32_bf16 v[28:31], v[100:103], v[144:147], v[28:31]
	v_mfma_f32_16x16x32_bf16 v[24:27], v[100:103], v[140:143], v[24:27]
	v_mfma_f32_16x16x32_bf16 v[20:23], v[100:103], v[92:95], v[20:23]
	v_mfma_f32_16x16x32_bf16 v[16:19], v[100:103], v[88:91], v[16:19]
	v_mfma_f32_16x16x32_bf16 v[12:15], v[96:99], v[144:147], v[12:15]
	v_mfma_f32_16x16x32_bf16 v[8:11], v[96:99], v[140:143], v[8:11]
	s_setprio 0
	ds_read_b128 v[88:91], v119 offset:32768
	ds_read_b128 v[92:95], v119 offset:34816
	ds_read_b128 v[96:99], v120 offset:49152
	ds_read_b128 v[100:103], v120 offset:51200
	ds_read_b128 v[140:143], v119 offset:36864
	ds_read_b128 v[144:147], v119 offset:38912
	ds_read_b128 v[148:151], v120 offset:53248
	ds_read_b128 v[152:155], v120 offset:55296
	s_setprio 1
	s_waitcnt lgkmcnt(1)
	v_mfma_f32_16x16x32_bf16 v[4:7], v[144:147], v[148:151], v[4:7]
	s_waitcnt lgkmcnt(0)
	v_mfma_f32_16x16x32_bf16 v[0:3], v[144:147], v[152:155], v[0:3]
	v_mfma_f32_16x16x32_bf16 v[60:63], v[88:91], v[96:99], v[60:63]
	v_mfma_f32_16x16x32_bf16 v[56:59], v[88:91], v[100:103], v[56:59]
	v_mfma_f32_16x16x32_bf16 v[52:55], v[88:91], v[148:151], v[52:55]
	v_mfma_f32_16x16x32_bf16 v[48:51], v[88:91], v[152:155], v[48:51]
	v_mfma_f32_16x16x32_bf16 v[44:47], v[92:95], v[96:99], v[44:47]
	v_mfma_f32_16x16x32_bf16 v[40:43], v[92:95], v[100:103], v[40:43]
	v_mfma_f32_16x16x32_bf16 v[36:39], v[92:95], v[148:151], v[36:39]
	v_mfma_f32_16x16x32_bf16 v[32:35], v[92:95], v[152:155], v[32:35]
	v_mfma_f32_16x16x32_bf16 v[28:31], v[140:143], v[96:99], v[28:31]
	v_mfma_f32_16x16x32_bf16 v[24:27], v[140:143], v[100:103], v[24:27]
	v_mfma_f32_16x16x32_bf16 v[20:23], v[140:143], v[148:151], v[20:23]
	v_mfma_f32_16x16x32_bf16 v[16:19], v[140:143], v[152:155], v[16:19]
	v_mfma_f32_16x16x32_bf16 v[12:15], v[144:147], v[96:99], v[12:15]
	v_mfma_f32_16x16x32_bf16 v[8:11], v[144:147], v[100:103], v[8:11]
	s_setprio 0
	s_barrier
	ds_write2_b32 v115, v60, v56 offset1:16
	ds_write2_b32 v115, v61, v57 offset0:132 offset1:148
	v_add_u32_e32 v56, 0x400, v115
	ds_write2_b32 v56, v62, v58 offset0:8 offset1:24
	ds_write2_b32 v56, v63, v59 offset0:140 offset1:156
	ds_write2_b32 v115, v52, v48 offset0:32 offset1:48
	ds_write2_b32 v115, v53, v49 offset0:164 offset1:180
	ds_write2_b32 v56, v54, v50 offset0:40 offset1:56
	ds_write2_b32 v56, v55, v51 offset0:172 offset1:188
	v_add_u32_e32 v48, 0x2000, v115
	ds_write2_b32 v48, v44, v40 offset0:64 offset1:80
	ds_write2_b32 v48, v45, v41 offset0:196 offset1:212
	v_add_u32_e32 v40, 0x2400, v115
	ds_write2_b32 v40, v46, v42 offset0:72 offset1:88
	ds_write2_b32 v40, v47, v43 offset0:204 offset1:220
	ds_write2_b32 v48, v36, v32 offset0:96 offset1:112
	ds_write2_b32 v48, v37, v33 offset0:228 offset1:244
	ds_write2_b32 v40, v38, v34 offset0:104 offset1:120
	ds_write2_b32 v40, v39, v35 offset0:236 offset1:252
	v_add_u32_e32 v32, 0x4000, v115
	ds_write2_b32 v32, v28, v24 offset0:128 offset1:144
	v_add_u32_e32 v24, 0x4400, v115
	ds_write2_b32 v24, v29, v25 offset0:4 offset1:20
	ds_write2_b32 v24, v30, v26 offset0:136 offset1:152
	v_add_u32_e32 v25, 0x4800, v115
	ds_write2_b32 v25, v31, v27 offset0:12 offset1:28
	ds_write2_b32 v32, v20, v16 offset0:160 offset1:176
	ds_write2_b32 v24, v21, v17 offset0:36 offset1:52
	ds_write2_b32 v24, v22, v18 offset0:168 offset1:184
	ds_write2_b32 v25, v23, v19 offset0:44 offset1:60
	v_add_u32_e32 v16, 0x6000, v115
	ds_write2_b32 v16, v12, v8 offset0:192 offset1:208
	v_add_u32_e32 v8, 0x6400, v115
	ds_write2_b32 v8, v13, v9 offset0:68 offset1:84
	ds_write2_b32 v8, v14, v10 offset0:200 offset1:216
	v_add_u32_e32 v9, 0x6800, v115
	ds_write2_b32 v9, v15, v11 offset0:76 offset1:92
	ds_write2_b32 v16, v4, v0 offset0:224 offset1:240
	ds_write2_b32 v8, v5, v1 offset0:100 offset1:116
	ds_write2_b32 v8, v6, v2 offset0:232 offset1:248
	ds_write2_b32 v9, v7, v3 offset0:108 offset1:124
	v_or_b32_e32 v0, s25, v116
	v_ashrrev_i32_e32 v1, 31, v0
	v_lshlrev_b64 v[2:3], 2, v[0:1]
	v_lshl_add_u64 v[0:1], s[14:15], 0, v[2:3]
	v_lshl_add_u64 v[2:3], s[12:13], 0, v[2:3]
	v_add_u32_e32 v4, s26, v129
	s_mov_b32 s16, 0
	s_waitcnt lgkmcnt(0)
	s_barrier

.LBB0_2096:
	s_and_b32 s29, s28, 0x4000
	s_xor_b32 s30, s29, 0x4000
	s_lshl_b32 s30, s30, 1
	s_add_i32 s30, s30, 32
	s_add_u32 s90, s52, s16
	s_addc_u32 s91, s53, s17
	s_add_i32 m0, s30, s82
	s_lshl_b32 s29, s29, 1
	global_load_lds_dwordx4 v193, s[90:91]
	s_add_i32 m0, s30, s83
	s_add_i32 s29, s29, 32
	global_load_lds_dwordx4 v194, s[90:91]
	s_add_i32 m0, s30, s84
	v_lshlrev_b32_e32 v72, 1, v131
	global_load_lds_dwordx4 v195, s[90:91]
	s_add_i32 m0, s30, s85
	v_add3_u32 v178, s29, v129, v72
	global_load_lds_dwordx4 v196, s[90:91]
	s_add_i32 m0, s30, s86
	v_lshlrev_b32_e32 v154, 1, v121
	global_load_lds_dwordx4 v197, s[90:91]
	s_add_i32 m0, s30, s87
	v_add3_u32 v72, s29, v130, v72
	global_load_lds_dwordx4 v198, s[90:91]
	s_add_i32 m0, s30, s88
	v_add_u32_e32 v174, v178, v154
	global_load_lds_dwordx4 v199, s[90:91]
	s_add_i32 m0, s30, s89
	v_add_u32_e32 v179, v72, v154
	global_load_lds_dwordx4 v200, s[90:91]
	ds_read_b128 v[154:157], v174
	ds_read_b128 v[162:165], v179 offset:16384
	ds_read_b128 v[166:169], v179 offset:18432
	ds_read_b128 v[182:185], v179 offset:20480
	ds_read_b128 v[186:189], v179 offset:22528
	ds_read_b128 v[158:161], v174 offset:2048
	ds_read_b128 v[170:173], v174 offset:4096
	ds_read_b128 v[174:177], v174 offset:6144
	s_setprio 1
	s_waitcnt lgkmcnt(3)
	v_mfma_f32_16x16x32_bf16 v[60:63], v[154:157], v[162:165], v[60:63]
	v_mfma_f32_16x16x32_bf16 v[56:59], v[154:157], v[166:169], v[56:59]
	v_mfma_f32_16x16x32_bf16 v[52:55], v[154:157], v[182:185], v[52:55]
	v_mfma_f32_16x16x32_bf16 v[48:51], v[154:157], v[186:189], v[48:51]
	s_waitcnt lgkmcnt(2)
	v_mfma_f32_16x16x32_bf16 v[44:47], v[158:161], v[162:165], v[44:47]
	v_mfma_f32_16x16x32_bf16 v[40:43], v[158:161], v[166:169], v[40:43]
	v_mfma_f32_16x16x32_bf16 v[36:39], v[158:161], v[182:185], v[36:39]
	v_mfma_f32_16x16x32_bf16 v[32:35], v[158:161], v[186:189], v[32:35]
	s_waitcnt lgkmcnt(1)
	v_mfma_f32_16x16x32_bf16 v[28:31], v[170:173], v[162:165], v[28:31]
	v_mfma_f32_16x16x32_bf16 v[24:27], v[170:173], v[166:169], v[24:27]
	v_mfma_f32_16x16x32_bf16 v[20:23], v[170:173], v[182:185], v[20:23]
	v_mfma_f32_16x16x32_bf16 v[16:19], v[170:173], v[186:189], v[16:19]
	s_waitcnt lgkmcnt(0)
	v_mfma_f32_16x16x32_bf16 v[12:15], v[174:177], v[162:165], v[12:15]
	v_mfma_f32_16x16x32_bf16 v[8:11], v[174:177], v[166:169], v[8:11]
	v_mfma_f32_16x16x32_bf16 v[4:7], v[174:177], v[182:185], v[4:7]
	v_mfma_f32_16x16x32_bf16 v[0:3], v[174:177], v[186:189], v[0:3]
	s_setprio 0
	v_lshlrev_b32_e32 v154, 1, v122
	v_add_u32_e32 v174, v178, v154
	v_add_u32_e32 v72, v72, v154
	ds_read_b128 v[154:157], v174
	ds_read_b128 v[162:165], v72 offset:16384
	ds_read_b128 v[166:169], v72 offset:18432
	ds_read_b128 v[182:185], v72 offset:20480
	ds_read_b128 v[186:189], v72 offset:22528
	ds_read_b128 v[158:161], v174 offset:2048
	ds_read_b128 v[170:173], v174 offset:4096
	ds_read_b128 v[174:177], v174 offset:6144
	s_setprio 1
	s_waitcnt lgkmcnt(3)
	v_mfma_f32_16x16x32_bf16 v[60:63], v[154:157], v[162:165], v[60:63]
	v_mfma_f32_16x16x32_bf16 v[56:59], v[154:157], v[166:169], v[56:59]
	v_mfma_f32_16x16x32_bf16 v[52:55], v[154:157], v[182:185], v[52:55]
	v_mfma_f32_16x16x32_bf16 v[48:51], v[154:157], v[186:189], v[48:51]
	s_waitcnt lgkmcnt(2)
	v_mfma_f32_16x16x32_bf16 v[44:47], v[158:161], v[162:165], v[44:47]
	v_mfma_f32_16x16x32_bf16 v[40:43], v[158:161], v[166:169], v[40:43]
	v_mfma_f32_16x16x32_bf16 v[36:39], v[158:161], v[182:185], v[36:39]
	v_mfma_f32_16x16x32_bf16 v[32:35], v[158:161], v[186:189], v[32:35]
	s_waitcnt lgkmcnt(1)
	v_mfma_f32_16x16x32_bf16 v[28:31], v[170:173], v[162:165], v[28:31]
	v_mfma_f32_16x16x32_bf16 v[24:27], v[170:173], v[166:169], v[24:27]
	v_mfma_f32_16x16x32_bf16 v[20:23], v[170:173], v[182:185], v[20:23]
	v_mfma_f32_16x16x32_bf16 v[16:19], v[170:173], v[186:189], v[16:19]
	s_waitcnt lgkmcnt(0)
	v_mfma_f32_16x16x32_bf16 v[12:15], v[174:177], v[162:165], v[12:15]
	v_mfma_f32_16x16x32_bf16 v[8:11], v[174:177], v[166:169], v[8:11]
	v_mfma_f32_16x16x32_bf16 v[4:7], v[174:177], v[182:185], v[4:7]
	v_mfma_f32_16x16x32_bf16 v[0:3], v[174:177], v[186:189], v[0:3]
	s_setprio 0
	s_add_u32 s16, s16, 0x80
	s_addc_u32 s17, s17, 0
	s_addk_i32 s28, 0x4000
	s_cmpk_eq_i32 s16, 0x1f80
	s_waitcnt vmcnt(0)
	s_barrier
	s_cbranch_scc0 .LBB0_2096
	ds_read_b128 v[98:101], v71 offset:32768
	ds_read_b128 v[102:105], v71 offset:34816
	ds_read_b128 v[106:109], v138 offset:49152
	ds_read_b128 v[110:113], v138 offset:51200
	ds_read_b128 v[154:157], v71 offset:36864
	ds_read_b128 v[158:161], v71 offset:38912
	ds_read_b128 v[162:165], v138 offset:53248
	ds_read_b128 v[166:169], v138 offset:55296
	s_setprio 1
	s_waitcnt lgkmcnt(1)
	v_mfma_f32_16x16x32_bf16 v[4:7], v[158:161], v[162:165], v[4:7]
	s_waitcnt lgkmcnt(0)
	v_mfma_f32_16x16x32_bf16 v[0:3], v[158:161], v[166:169], v[0:3]
	v_mfma_f32_16x16x32_bf16 v[60:63], v[98:101], v[106:109], v[60:63]
	v_mfma_f32_16x16x32_bf16 v[56:59], v[98:101], v[110:113], v[56:59]
	v_mfma_f32_16x16x32_bf16 v[52:55], v[98:101], v[162:165], v[52:55]
	v_mfma_f32_16x16x32_bf16 v[48:51], v[98:101], v[166:169], v[48:51]
	v_mfma_f32_16x16x32_bf16 v[44:47], v[102:105], v[106:109], v[44:47]
	v_mfma_f32_16x16x32_bf16 v[40:43], v[102:105], v[110:113], v[40:43]
	v_mfma_f32_16x16x32_bf16 v[36:39], v[102:105], v[162:165], v[36:39]
	v_mfma_f32_16x16x32_bf16 v[32:35], v[102:105], v[166:169], v[32:35]
	v_mfma_f32_16x16x32_bf16 v[28:31], v[154:157], v[106:109], v[28:31]
	v_mfma_f32_16x16x32_bf16 v[24:27], v[154:157], v[110:113], v[24:27]
	v_mfma_f32_16x16x32_bf16 v[20:23], v[154:157], v[162:165], v[20:23]
	v_mfma_f32_16x16x32_bf16 v[16:19], v[154:157], v[166:169], v[16:19]
	v_mfma_f32_16x16x32_bf16 v[12:15], v[158:161], v[106:109], v[12:15]
	v_mfma_f32_16x16x32_bf16 v[8:11], v[158:161], v[110:113], v[8:11]
	s_setprio 0
	ds_read_b128 v[98:101], v139 offset:32768
	ds_read_b128 v[102:105], v139 offset:34816
	ds_read_b128 v[106:109], v140 offset:49152
	ds_read_b128 v[110:113], v140 offset:51200
	ds_read_b128 v[154:157], v139 offset:36864
	ds_read_b128 v[158:161], v139 offset:38912
	ds_read_b128 v[162:165], v140 offset:53248
	ds_read_b128 v[166:169], v140 offset:55296
	s_setprio 1
	s_waitcnt lgkmcnt(1)
	v_mfma_f32_16x16x32_bf16 v[4:7], v[158:161], v[162:165], v[4:7]
	s_waitcnt lgkmcnt(0)
	v_mfma_f32_16x16x32_bf16 v[0:3], v[158:161], v[166:169], v[0:3]
	v_mfma_f32_16x16x32_bf16 v[60:63], v[98:101], v[106:109], v[60:63]
	v_mfma_f32_16x16x32_bf16 v[56:59], v[98:101], v[110:113], v[56:59]
	v_mfma_f32_16x16x32_bf16 v[52:55], v[98:101], v[162:165], v[52:55]
	v_mfma_f32_16x16x32_bf16 v[48:51], v[98:101], v[166:169], v[48:51]
	v_mfma_f32_16x16x32_bf16 v[44:47], v[102:105], v[106:109], v[44:47]
	v_mfma_f32_16x16x32_bf16 v[40:43], v[102:105], v[110:113], v[40:43]
	v_mfma_f32_16x16x32_bf16 v[36:39], v[102:105], v[162:165], v[36:39]
	v_mfma_f32_16x16x32_bf16 v[32:35], v[102:105], v[166:169], v[32:35]
	v_mfma_f32_16x16x32_bf16 v[28:31], v[154:157], v[106:109], v[28:31]
	v_mfma_f32_16x16x32_bf16 v[24:27], v[154:157], v[110:113], v[24:27]
	v_mfma_f32_16x16x32_bf16 v[20:23], v[154:157], v[162:165], v[20:23]
	v_mfma_f32_16x16x32_bf16 v[16:19], v[154:157], v[166:169], v[16:19]
	v_mfma_f32_16x16x32_bf16 v[12:15], v[158:161], v[106:109], v[12:15]
	v_mfma_f32_16x16x32_bf16 v[8:11], v[158:161], v[110:113], v[8:11]
	s_setprio 0
	s_barrier
	ds_write2_b32 v136, v60, v56 offset1:16
	ds_write2_b32 v136, v61, v57 offset0:132 offset1:148
	v_add_u32_e32 v56, 0x400, v136
	ds_write2_b32 v56, v62, v58 offset0:8 offset1:24
	ds_write2_b32 v56, v63, v59 offset0:140 offset1:156
	ds_write2_b32 v136, v52, v48 offset0:32 offset1:48
	ds_write2_b32 v136, v53, v49 offset0:164 offset1:180
	ds_write2_b32 v56, v54, v50 offset0:40 offset1:56
	ds_write2_b32 v56, v55, v51 offset0:172 offset1:188
	v_add_u32_e32 v48, 0x2000, v136
	ds_write2_b32 v48, v44, v40 offset0:64 offset1:80
	ds_write2_b32 v48, v45, v41 offset0:196 offset1:212
	v_add_u32_e32 v40, 0x2400, v136
	ds_write2_b32 v40, v46, v42 offset0:72 offset1:88
	ds_write2_b32 v40, v47, v43 offset0:204 offset1:220
	ds_write2_b32 v48, v36, v32 offset0:96 offset1:112
	ds_write2_b32 v48, v37, v33 offset0:228 offset1:244
	ds_write2_b32 v40, v38, v34 offset0:104 offset1:120
	ds_write2_b32 v40, v39, v35 offset0:236 offset1:252
	v_add_u32_e32 v32, 0x4000, v136
	ds_write2_b32 v32, v28, v24 offset0:128 offset1:144
	v_add_u32_e32 v24, 0x4400, v136
	ds_write2_b32 v24, v29, v25 offset0:4 offset1:20
	ds_write2_b32 v24, v30, v26 offset0:136 offset1:152
	v_add_u32_e32 v25, 0x4800, v136
	ds_write2_b32 v25, v31, v27 offset0:12 offset1:28
	ds_write2_b32 v32, v20, v16 offset0:160 offset1:176
	ds_write2_b32 v24, v21, v17 offset0:36 offset1:52
	ds_write2_b32 v24, v22, v18 offset0:168 offset1:184
	ds_write2_b32 v25, v23, v19 offset0:44 offset1:60
	v_add_u32_e32 v16, 0x6000, v136
	ds_write2_b32 v16, v12, v8 offset0:192 offset1:208
	v_add_u32_e32 v8, 0x6400, v136
	ds_write2_b32 v8, v13, v9 offset0:68 offset1:84
	ds_write2_b32 v8, v14, v10 offset0:200 offset1:216
	v_add_u32_e32 v9, 0x6800, v136
	ds_write2_b32 v9, v15, v11 offset0:76 offset1:92
	ds_write2_b32 v16, v4, v0 offset0:224 offset1:240
	ds_write2_b32 v8, v5, v1 offset0:100 offset1:116
	ds_write2_b32 v8, v6, v2 offset0:232 offset1:248
	ds_write2_b32 v9, v7, v3 offset0:108 offset1:124
	v_or_b32_e32 v0, s26, v137
	v_lshlrev_b32_e32 v72, 2, v0
	v_lshl_add_u64 v[0:1], s[14:15], 0, v[72:73]
	v_lshl_add_u64 v[2:3], s[12:13], 0, v[72:73]
	v_add_u32_e32 v4, s27, v149
	s_mov_b32 s16, 0
	s_waitcnt lgkmcnt(0)
	s_barrier

.LBB0_2102:
	s_and_b32 s8, s13, 0x4000
	s_xor_b32 s9, s8, 0x4000
	s_lshl_b32 s9, s9, 1
	s_add_i32 s9, s9, 32
	s_add_u32 s90, s52, s6
	s_addc_u32 s91, s53, s7
	s_add_i32 m0, s9, s82
	s_lshl_b32 s8, s8, 1
	global_load_lds_dwordx4 v192, s[90:91]
	s_add_i32 m0, s9, s83
	s_add_i32 s8, s8, 32
	global_load_lds_dwordx4 v193, s[90:91]
	s_add_i32 m0, s9, s84
	v_lshlrev_b32_e32 v85, 1, v80
	global_load_lds_dwordx4 v194, s[90:91]
	s_add_i32 m0, s9, s85
	v_add3_u32 v112, s8, v81, v85
	global_load_lds_dwordx4 v195, s[90:91]
	s_add_i32 m0, s9, s86
	v_lshlrev_b32_e32 v86, 1, v121
	global_load_lds_dwordx4 v196, s[90:91]
	s_add_i32 m0, s9, s87
	v_add3_u32 v113, s8, v82, v85
	global_load_lds_dwordx4 v197, s[90:91]
	s_add_i32 m0, s9, s88
	v_add_u32_e32 v87, v112, v86
	global_load_lds_dwordx4 v198, s[90:91]
	s_add_i32 m0, s9, s89
	v_add_u32_e32 v123, v113, v86
	global_load_lds_dwordx4 v199, s[90:91]
	ds_read_b128 v[88:91], v87
	ds_read_b128 v[96:99], v123 offset:16384
	ds_read_b128 v[100:103], v123 offset:18432
	ds_read_b128 v[124:127], v123 offset:20480
	ds_read_b128 v[128:131], v123 offset:22528
	ds_read_b128 v[92:95], v87 offset:2048
	ds_read_b128 v[104:107], v87 offset:4096
	ds_read_b128 v[108:111], v87 offset:6144
	s_setprio 1
	s_waitcnt lgkmcnt(3)
	v_mfma_f32_16x16x32_bf16 v[60:63], v[88:91], v[96:99], v[60:63]
	v_mfma_f32_16x16x32_bf16 v[56:59], v[88:91], v[100:103], v[56:59]
	v_mfma_f32_16x16x32_bf16 v[52:55], v[88:91], v[124:127], v[52:55]
	v_mfma_f32_16x16x32_bf16 v[48:51], v[88:91], v[128:131], v[48:51]
	s_waitcnt lgkmcnt(2)
	v_mfma_f32_16x16x32_bf16 v[44:47], v[92:95], v[96:99], v[44:47]
	v_mfma_f32_16x16x32_bf16 v[40:43], v[92:95], v[100:103], v[40:43]
	v_mfma_f32_16x16x32_bf16 v[36:39], v[92:95], v[124:127], v[36:39]
	v_mfma_f32_16x16x32_bf16 v[32:35], v[92:95], v[128:131], v[32:35]
	s_waitcnt lgkmcnt(1)
	v_mfma_f32_16x16x32_bf16 v[28:31], v[104:107], v[96:99], v[28:31]
	v_mfma_f32_16x16x32_bf16 v[24:27], v[104:107], v[100:103], v[24:27]
	v_mfma_f32_16x16x32_bf16 v[20:23], v[104:107], v[124:127], v[20:23]
	v_mfma_f32_16x16x32_bf16 v[16:19], v[104:107], v[128:131], v[16:19]
	s_waitcnt lgkmcnt(0)
	v_mfma_f32_16x16x32_bf16 v[12:15], v[108:111], v[96:99], v[12:15]
	v_mfma_f32_16x16x32_bf16 v[8:11], v[108:111], v[100:103], v[8:11]
	v_mfma_f32_16x16x32_bf16 v[4:7], v[108:111], v[124:127], v[4:7]
	v_mfma_f32_16x16x32_bf16 v[0:3], v[108:111], v[128:131], v[0:3]
	s_setprio 0
	v_lshlrev_b32_e32 v87, 1, v122
	v_add_u32_e32 v108, v112, v87
	v_add_u32_e32 v112, v113, v87
	ds_read_b128 v[88:91], v108
	ds_read_b128 v[96:99], v112 offset:16384
	ds_read_b128 v[100:103], v112 offset:18432
	ds_read_b128 v[124:127], v112 offset:20480
	ds_read_b128 v[128:131], v112 offset:22528
	ds_read_b128 v[92:95], v108 offset:2048
	ds_read_b128 v[104:107], v108 offset:4096
	ds_read_b128 v[108:111], v108 offset:6144
	s_setprio 1
	s_waitcnt lgkmcnt(3)
	v_mfma_f32_16x16x32_bf16 v[60:63], v[88:91], v[96:99], v[60:63]
	v_mfma_f32_16x16x32_bf16 v[56:59], v[88:91], v[100:103], v[56:59]
	v_mfma_f32_16x16x32_bf16 v[52:55], v[88:91], v[124:127], v[52:55]
	v_mfma_f32_16x16x32_bf16 v[48:51], v[88:91], v[128:131], v[48:51]
	s_waitcnt lgkmcnt(2)
	v_mfma_f32_16x16x32_bf16 v[44:47], v[92:95], v[96:99], v[44:47]
	v_mfma_f32_16x16x32_bf16 v[40:43], v[92:95], v[100:103], v[40:43]
	v_mfma_f32_16x16x32_bf16 v[36:39], v[92:95], v[124:127], v[36:39]
	v_mfma_f32_16x16x32_bf16 v[32:35], v[92:95], v[128:131], v[32:35]
	s_waitcnt lgkmcnt(1)
	v_mfma_f32_16x16x32_bf16 v[28:31], v[104:107], v[96:99], v[28:31]
	v_mfma_f32_16x16x32_bf16 v[24:27], v[104:107], v[100:103], v[24:27]
	v_mfma_f32_16x16x32_bf16 v[20:23], v[104:107], v[124:127], v[20:23]
	v_mfma_f32_16x16x32_bf16 v[16:19], v[104:107], v[128:131], v[16:19]
	s_waitcnt lgkmcnt(0)
	v_mfma_f32_16x16x32_bf16 v[12:15], v[108:111], v[96:99], v[12:15]
	v_mfma_f32_16x16x32_bf16 v[8:11], v[108:111], v[100:103], v[8:11]
	v_mfma_f32_16x16x32_bf16 v[4:7], v[108:111], v[124:127], v[4:7]
	v_mfma_f32_16x16x32_bf16 v[0:3], v[108:111], v[128:131], v[0:3]
	s_setprio 0
	s_add_u32 s6, s6, 0x80
	s_addc_u32 s7, s7, 0
	s_addk_i32 s13, 0x4000
	s_cmpk_eq_i32 s6, 0x780
	s_waitcnt vmcnt(0)
	s_barrier
	s_cbranch_scc0 .LBB0_2102
	v_add3_u32 v84, 32, v81, v85
	v_add3_u32 v85, 32, v82, v85
	v_add_u32_e32 v88, v84, v86
	v_add_u32_e32 v86, v85, v86
	ds_read_b128 v[64:67], v88 offset:32768
	ds_read_b128 v[68:71], v88 offset:34816
	ds_read_b128 v[72:75], v86 offset:49152
	ds_read_b128 v[76:79], v86 offset:51200
	ds_read_b128 v[80:83], v88 offset:36864
	ds_read_b128 v[88:91], v88 offset:38912
	ds_read_b128 v[92:95], v86 offset:53248
	ds_read_b128 v[96:99], v86 offset:55296
	s_setprio 1
	s_waitcnt lgkmcnt(0)
	v_mfma_f32_16x16x32_bf16 v[0:3], v[88:91], v[96:99], v[0:3]
	v_mfma_f32_16x16x32_bf16 v[60:63], v[64:67], v[72:75], v[60:63]
	v_mfma_f32_16x16x32_bf16 v[56:59], v[64:67], v[76:79], v[56:59]
	v_mfma_f32_16x16x32_bf16 v[52:55], v[64:67], v[92:95], v[52:55]
	v_mfma_f32_16x16x32_bf16 v[48:51], v[64:67], v[96:99], v[48:51]
	v_mfma_f32_16x16x32_bf16 v[44:47], v[68:71], v[72:75], v[44:47]
	v_mfma_f32_16x16x32_bf16 v[40:43], v[68:71], v[76:79], v[40:43]
	v_mfma_f32_16x16x32_bf16 v[36:39], v[68:71], v[92:95], v[36:39]
	v_mfma_f32_16x16x32_bf16 v[32:35], v[68:71], v[96:99], v[32:35]
	v_mfma_f32_16x16x32_bf16 v[28:31], v[80:83], v[72:75], v[28:31]
	v_mfma_f32_16x16x32_bf16 v[24:27], v[80:83], v[76:79], v[24:27]
	v_mfma_f32_16x16x32_bf16 v[20:23], v[80:83], v[92:95], v[20:23]
	v_mfma_f32_16x16x32_bf16 v[16:19], v[80:83], v[96:99], v[16:19]
	v_mfma_f32_16x16x32_bf16 v[12:15], v[88:91], v[72:75], v[12:15]
	v_mfma_f32_16x16x32_bf16 v[8:11], v[88:91], v[76:79], v[8:11]
	v_mfma_f32_16x16x32_bf16 v[4:7], v[88:91], v[92:95], v[4:7]
	s_setprio 0
	v_add_u32_e32 v84, v84, v87
	v_add_u32_e32 v92, v85, v87
	ds_read_b128 v[64:67], v84 offset:32768
	ds_read_b128 v[68:71], v84 offset:34816
	ds_read_b128 v[72:75], v92 offset:49152
	ds_read_b128 v[76:79], v92 offset:51200
	ds_read_b128 v[80:83], v84 offset:36864
	ds_read_b128 v[84:87], v84 offset:38912
	ds_read_b128 v[88:91], v92 offset:53248
	ds_read_b128 v[92:95], v92 offset:55296
	s_setprio 1
	s_waitcnt lgkmcnt(0)
	v_mfma_f32_16x16x32_bf16 v[0:3], v[84:87], v[92:95], v[0:3]
	v_mfma_f32_16x16x32_bf16 v[60:63], v[64:67], v[72:75], v[60:63]
	v_mfma_f32_16x16x32_bf16 v[56:59], v[64:67], v[76:79], v[56:59]
	v_mfma_f32_16x16x32_bf16 v[52:55], v[64:67], v[88:91], v[52:55]
	v_mfma_f32_16x16x32_bf16 v[48:51], v[64:67], v[92:95], v[48:51]
	v_mfma_f32_16x16x32_bf16 v[44:47], v[68:71], v[72:75], v[44:47]
	v_mfma_f32_16x16x32_bf16 v[40:43], v[68:71], v[76:79], v[40:43]
	v_mfma_f32_16x16x32_bf16 v[36:39], v[68:71], v[88:91], v[36:39]
	v_mfma_f32_16x16x32_bf16 v[32:35], v[68:71], v[92:95], v[32:35]
	v_mfma_f32_16x16x32_bf16 v[28:31], v[80:83], v[72:75], v[28:31]
	v_mfma_f32_16x16x32_bf16 v[24:27], v[80:83], v[76:79], v[24:27]
	v_mfma_f32_16x16x32_bf16 v[20:23], v[80:83], v[88:91], v[20:23]
	v_mfma_f32_16x16x32_bf16 v[16:19], v[80:83], v[92:95], v[16:19]
	v_mfma_f32_16x16x32_bf16 v[12:15], v[84:87], v[72:75], v[12:15]
	v_mfma_f32_16x16x32_bf16 v[8:11], v[84:87], v[76:79], v[8:11]
	v_mfma_f32_16x16x32_bf16 v[4:7], v[84:87], v[88:91], v[4:7]
	s_setprio 0
	v_lshl_or_b32 v64, v114, 2, v116
	v_mul_u32_u24_e32 v64, 0x210, v64
	v_add3_u32 v64, v115, v117, v64
	s_barrier
	ds_write2_b32 v64, v60, v56 offset1:16
	ds_write2_b32 v64, v61, v57 offset0:132 offset1:148
	v_add_u32_e32 v56, 0x400, v64
	ds_write2_b32 v56, v62, v58 offset0:8 offset1:24
	ds_write2_b32 v56, v63, v59 offset0:140 offset1:156
	ds_write2_b32 v64, v52, v48 offset0:32 offset1:48
	ds_write2_b32 v64, v53, v49 offset0:164 offset1:180
	ds_write2_b32 v56, v54, v50 offset0:40 offset1:56
	ds_write2_b32 v56, v55, v51 offset0:172 offset1:188
	v_add_u32_e32 v48, 0x2000, v64
	ds_write2_b32 v48, v44, v40 offset0:64 offset1:80
	ds_write2_b32 v48, v45, v41 offset0:196 offset1:212
	v_add_u32_e32 v40, 0x2400, v64
	ds_write2_b32 v40, v46, v42 offset0:72 offset1:88
	ds_write2_b32 v40, v47, v43 offset0:204 offset1:220
	ds_write2_b32 v48, v36, v32 offset0:96 offset1:112
	ds_write2_b32 v48, v37, v33 offset0:228 offset1:244
	ds_write2_b32 v40, v38, v34 offset0:104 offset1:120
	ds_write2_b32 v40, v39, v35 offset0:236 offset1:252
	v_add_u32_e32 v32, 0x4000, v64
	ds_write2_b32 v32, v28, v24 offset0:128 offset1:144
	v_add_u32_e32 v24, 0x4400, v64
	ds_write2_b32 v24, v29, v25 offset0:4 offset1:20
	ds_write2_b32 v24, v30, v26 offset0:136 offset1:152
	v_add_u32_e32 v25, 0x4800, v64
	ds_write2_b32 v25, v31, v27 offset0:12 offset1:28
	ds_write2_b32 v32, v20, v16 offset0:160 offset1:176
	ds_write2_b32 v24, v21, v17 offset0:36 offset1:52
	ds_write2_b32 v24, v22, v18 offset0:168 offset1:184
	ds_write2_b32 v25, v23, v19 offset0:44 offset1:60
	v_add_u32_e32 v16, 0x6000, v64
	ds_write2_b32 v16, v12, v8 offset0:192 offset1:208
	v_add_u32_e32 v8, 0x6400, v64
	ds_write2_b32 v8, v13, v9 offset0:68 offset1:84
	ds_write2_b32 v8, v14, v10 offset0:200 offset1:216
	v_add_u32_e32 v9, 0x6800, v64
	ds_write2_b32 v9, v15, v11 offset0:76 offset1:92
	ds_write2_b32 v16, v4, v0 offset0:224 offset1:240
	ds_write2_b32 v8, v5, v1 offset0:100 offset1:116
	ds_write2_b32 v8, v6, v2 offset0:232 offset1:248
	ds_write2_b32 v9, v7, v3 offset0:108 offset1:124
	v_lshlrev_b32_e32 v0, 4, v180
	v_and_b32_e32 v0, 0x70, v0
	s_lshl_b32 s7, s16, 23
	v_or_b32_e32 v0, s11, v0
	s_add_u32 s8, s14, s7
	s_addc_u32 s9, s15, 0
	v_lshlrev_b32_e32 v0, 2, v0
	v_mov_b32_e32 v1, 0
	v_lshrrev_b32_e32 v2, 3, v180
	v_and_b32_e32 v4, 7, v180
	v_lshl_add_u64 v[0:1], s[8:9], 0, v[0:1]
	s_mov_b64 s[8:9], 0x11600000
	v_mul_u32_u24_e32 v3, 0x210, v2
	v_lshlrev_b32_e32 v4, 6, v4
	s_mov_b32 s6, 0
	v_lshl_add_u64 v[0:1], v[0:1], 0, s[8:9]
	v_add3_u32 v3, v3, v4, 32
	s_mov_b32 s7, 0x38e38e39
	s_mov_b32 s8, 0x1ffffee
	s_movk_i32 s9, 0xf800
	s_waitcnt lgkmcnt(0)
	s_barrier

.LBB0_2270:
	s_and_b32 s31, s30, 0x4000
	s_xor_b32 s34, s31, 0x4000
	s_lshl_b32 s34, s34, 1
	s_add_i32 s34, s34, 32
	s_add_u32 s90, s52, s8
	s_addc_u32 s91, s53, s9
	s_add_i32 m0, s34, s82
	s_lshl_b32 s31, s31, 1
	global_load_lds_dwordx4 v184, s[90:91]
	s_add_i32 m0, s34, s83
	s_add_i32 s31, s31, 32
	global_load_lds_dwordx4 v185, s[90:91]
	s_add_i32 m0, s34, s84
	v_lshl_add_u32 v64, v114, 1, s31
	global_load_lds_dwordx4 v186, s[90:91]
	s_add_i32 m0, s34, s85
	v_lshl_add_u32 v139, v115, 1, s31
	global_load_lds_dwordx4 v187, s[90:91]
	s_add_i32 m0, s34, s86
	v_add_u32_e32 v160, v64, v136
	global_load_lds_dwordx4 v188, s[90:91]
	s_add_i32 m0, s34, s87
	v_add_u32_e32 v168, v139, v136
	global_load_lds_dwordx4 v189, s[90:91]
	s_add_i32 m0, s34, s88
	s_addk_i32 s30, 0x4000
	global_load_lds_dwordx4 v190, s[90:91]
	s_add_i32 m0, s34, s89
	s_add_u32 s8, s8, 0x80
	s_addc_u32 s9, s9, 0
	global_load_lds_dwordx4 v191, s[90:91]
	ds_read_b128 v[140:143], v160
	ds_read_b128 v[148:151], v168 offset:16384
	ds_read_b128 v[152:155], v168 offset:18432
	ds_read_b128 v[164:167], v168 offset:20480
	ds_read_b128 v[168:171], v168 offset:22528
	ds_read_b128 v[144:147], v160 offset:2048
	ds_read_b128 v[156:159], v160 offset:4096
	ds_read_b128 v[160:163], v160 offset:6144
	s_setprio 1
	s_waitcnt lgkmcnt(3)
	v_mfma_f32_16x16x32_bf16 v[60:63], v[140:143], v[148:151], v[60:63]
	v_mfma_f32_16x16x32_bf16 v[56:59], v[140:143], v[152:155], v[56:59]
	v_mfma_f32_16x16x32_bf16 v[52:55], v[140:143], v[164:167], v[52:55]
	v_mfma_f32_16x16x32_bf16 v[48:51], v[140:143], v[168:171], v[48:51]
	s_waitcnt lgkmcnt(2)
	v_mfma_f32_16x16x32_bf16 v[44:47], v[144:147], v[148:151], v[44:47]
	v_mfma_f32_16x16x32_bf16 v[40:43], v[144:147], v[152:155], v[40:43]
	v_mfma_f32_16x16x32_bf16 v[36:39], v[144:147], v[164:167], v[36:39]
	v_mfma_f32_16x16x32_bf16 v[32:35], v[144:147], v[168:171], v[32:35]
	s_waitcnt lgkmcnt(1)
	v_mfma_f32_16x16x32_bf16 v[28:31], v[156:159], v[148:151], v[28:31]
	v_mfma_f32_16x16x32_bf16 v[24:27], v[156:159], v[152:155], v[24:27]
	v_mfma_f32_16x16x32_bf16 v[20:23], v[156:159], v[164:167], v[20:23]
	v_mfma_f32_16x16x32_bf16 v[16:19], v[156:159], v[168:171], v[16:19]
	s_waitcnt lgkmcnt(0)
	v_mfma_f32_16x16x32_bf16 v[12:15], v[160:163], v[148:151], v[12:15]
	v_mfma_f32_16x16x32_bf16 v[8:11], v[160:163], v[152:155], v[8:11]
	v_mfma_f32_16x16x32_bf16 v[4:7], v[160:163], v[164:167], v[4:7]
	v_mfma_f32_16x16x32_bf16 v[0:3], v[160:163], v[168:171], v[0:3]
	s_setprio 0
	v_add_u32_e32 v64, v64, v137
	v_add_u32_e32 v139, v139, v137
	ds_read_b128 v[140:143], v64
	ds_read_b128 v[148:151], v139 offset:16384
	ds_read_b128 v[152:155], v139 offset:18432
	ds_read_b128 v[164:167], v139 offset:20480
	ds_read_b128 v[168:171], v139 offset:22528
	ds_read_b128 v[144:147], v64 offset:2048
	ds_read_b128 v[156:159], v64 offset:4096
	ds_read_b128 v[160:163], v64 offset:6144
	s_setprio 1
	s_waitcnt lgkmcnt(3)
	v_mfma_f32_16x16x32_bf16 v[60:63], v[140:143], v[148:151], v[60:63]
	v_mfma_f32_16x16x32_bf16 v[56:59], v[140:143], v[152:155], v[56:59]
	v_mfma_f32_16x16x32_bf16 v[52:55], v[140:143], v[164:167], v[52:55]
	v_mfma_f32_16x16x32_bf16 v[48:51], v[140:143], v[168:171], v[48:51]
	s_waitcnt lgkmcnt(2)
	v_mfma_f32_16x16x32_bf16 v[44:47], v[144:147], v[148:151], v[44:47]
	v_mfma_f32_16x16x32_bf16 v[40:43], v[144:147], v[152:155], v[40:43]
	v_mfma_f32_16x16x32_bf16 v[36:39], v[144:147], v[164:167], v[36:39]
	v_mfma_f32_16x16x32_bf16 v[32:35], v[144:147], v[168:171], v[32:35]
	s_waitcnt lgkmcnt(1)
	v_mfma_f32_16x16x32_bf16 v[28:31], v[156:159], v[148:151], v[28:31]
	v_mfma_f32_16x16x32_bf16 v[24:27], v[156:159], v[152:155], v[24:27]
	v_mfma_f32_16x16x32_bf16 v[20:23], v[156:159], v[164:167], v[20:23]
	v_mfma_f32_16x16x32_bf16 v[16:19], v[156:159], v[168:171], v[16:19]
	s_waitcnt lgkmcnt(0)
	v_mfma_f32_16x16x32_bf16 v[12:15], v[160:163], v[148:151], v[12:15]
	v_mfma_f32_16x16x32_bf16 v[8:11], v[160:163], v[152:155], v[8:11]
	v_mfma_f32_16x16x32_bf16 v[4:7], v[160:163], v[164:167], v[4:7]
	v_mfma_f32_16x16x32_bf16 v[0:3], v[160:163], v[168:171], v[0:3]
	s_setprio 0
	s_cmpk_eq_i32 s8, 0x780
	s_waitcnt vmcnt(0)
	s_barrier
	s_cbranch_scc0 .LBB0_2270
	ds_read_b128 v[90:93], v116 offset:55296
	ds_read_b128 v[94:97], v116 offset:53248
	ds_read_b128 v[98:101], v117 offset:38912
	ds_read_b128 v[102:105], v117 offset:36864
	ds_read_b128 v[140:143], v116 offset:51200
	ds_read_b128 v[144:147], v116 offset:49152
	ds_read_b128 v[148:151], v117 offset:34816
	ds_read_b128 v[152:155], v117 offset:32768
	s_setprio 1
	s_waitcnt lgkmcnt(4)
	v_mfma_f32_16x16x32_bf16 v[20:23], v[102:105], v[94:97], v[20:23]
	v_mfma_f32_16x16x32_bf16 v[16:19], v[102:105], v[90:93], v[16:19]
	s_waitcnt lgkmcnt(0)
	v_mfma_f32_16x16x32_bf16 v[60:63], v[152:155], v[144:147], v[60:63]
	v_mfma_f32_16x16x32_bf16 v[56:59], v[152:155], v[140:143], v[56:59]
	v_mfma_f32_16x16x32_bf16 v[52:55], v[152:155], v[94:97], v[52:55]
	v_mfma_f32_16x16x32_bf16 v[48:51], v[152:155], v[90:93], v[48:51]
	v_mfma_f32_16x16x32_bf16 v[44:47], v[148:151], v[144:147], v[44:47]
	v_mfma_f32_16x16x32_bf16 v[40:43], v[148:151], v[140:143], v[40:43]
	v_mfma_f32_16x16x32_bf16 v[36:39], v[148:151], v[94:97], v[36:39]
	v_mfma_f32_16x16x32_bf16 v[32:35], v[148:151], v[90:93], v[32:35]
	v_mfma_f32_16x16x32_bf16 v[28:31], v[102:105], v[144:147], v[28:31]
	v_mfma_f32_16x16x32_bf16 v[24:27], v[102:105], v[140:143], v[24:27]
	v_mfma_f32_16x16x32_bf16 v[12:15], v[98:101], v[144:147], v[12:15]
	v_mfma_f32_16x16x32_bf16 v[8:11], v[98:101], v[140:143], v[8:11]
	v_mfma_f32_16x16x32_bf16 v[4:7], v[98:101], v[94:97], v[4:7]
	v_mfma_f32_16x16x32_bf16 v[0:3], v[98:101], v[90:93], v[0:3]
	s_setprio 0
	ds_read_b128 v[90:93], v118 offset:32768
	ds_read_b128 v[94:97], v118 offset:34816
	ds_read_b128 v[98:101], v119 offset:49152
	ds_read_b128 v[102:105], v119 offset:51200
	ds_read_b128 v[140:143], v118 offset:36864
	ds_read_b128 v[144:147], v118 offset:38912
	ds_read_b128 v[148:151], v119 offset:53248
	ds_read_b128 v[152:155], v119 offset:55296
	s_setprio 1
	s_waitcnt lgkmcnt(1)
	v_mfma_f32_16x16x32_bf16 v[20:23], v[140:143], v[148:151], v[20:23]
	s_waitcnt lgkmcnt(0)
	v_mfma_f32_16x16x32_bf16 v[16:19], v[140:143], v[152:155], v[16:19]
	v_mfma_f32_16x16x32_bf16 v[60:63], v[90:93], v[98:101], v[60:63]
	v_mfma_f32_16x16x32_bf16 v[56:59], v[90:93], v[102:105], v[56:59]
	v_mfma_f32_16x16x32_bf16 v[52:55], v[90:93], v[148:151], v[52:55]
	v_mfma_f32_16x16x32_bf16 v[48:51], v[90:93], v[152:155], v[48:51]
	v_mfma_f32_16x16x32_bf16 v[44:47], v[94:97], v[98:101], v[44:47]
	v_mfma_f32_16x16x32_bf16 v[40:43], v[94:97], v[102:105], v[40:43]
	v_mfma_f32_16x16x32_bf16 v[36:39], v[94:97], v[148:151], v[36:39]
	v_mfma_f32_16x16x32_bf16 v[32:35], v[94:97], v[152:155], v[32:35]
	v_mfma_f32_16x16x32_bf16 v[28:31], v[140:143], v[98:101], v[28:31]
	v_mfma_f32_16x16x32_bf16 v[24:27], v[140:143], v[102:105], v[24:27]
	v_mfma_f32_16x16x32_bf16 v[12:15], v[144:147], v[98:101], v[12:15]
	v_mfma_f32_16x16x32_bf16 v[8:11], v[144:147], v[102:105], v[8:11]
	v_mfma_f32_16x16x32_bf16 v[4:7], v[144:147], v[148:151], v[4:7]
	v_mfma_f32_16x16x32_bf16 v[0:3], v[144:147], v[152:155], v[0:3]
	s_setprio 0
	s_barrier
	ds_write2_b32 v120, v60, v56 offset1:16
	ds_write2_b32 v120, v61, v57 offset0:132 offset1:148
	v_add_u32_e32 v56, 0x400, v120
	ds_write2_b32 v56, v62, v58 offset0:8 offset1:24
	ds_write2_b32 v56, v63, v59 offset0:140 offset1:156
	ds_write2_b32 v120, v52, v48 offset0:32 offset1:48
	ds_write2_b32 v120, v53, v49 offset0:164 offset1:180
	ds_write2_b32 v56, v54, v50 offset0:40 offset1:56
	ds_write2_b32 v56, v55, v51 offset0:172 offset1:188
	v_add_u32_e32 v48, 0x2000, v120
	ds_write2_b32 v48, v44, v40 offset0:64 offset1:80
	ds_write2_b32 v48, v45, v41 offset0:196 offset1:212
	v_add_u32_e32 v40, 0x2400, v120
	ds_write2_b32 v40, v46, v42 offset0:72 offset1:88
	ds_write2_b32 v40, v47, v43 offset0:204 offset1:220
	ds_write2_b32 v48, v36, v32 offset0:96 offset1:112
	ds_write2_b32 v48, v37, v33 offset0:228 offset1:244
	ds_write2_b32 v40, v38, v34 offset0:104 offset1:120
	ds_write2_b32 v40, v39, v35 offset0:236 offset1:252
	v_add_u32_e32 v32, 0x4000, v120
	ds_write2_b32 v32, v28, v24 offset0:128 offset1:144
	v_add_u32_e32 v24, 0x4400, v120
	ds_write2_b32 v24, v29, v25 offset0:4 offset1:20
	ds_write2_b32 v24, v30, v26 offset0:136 offset1:152
	v_add_u32_e32 v25, 0x4800, v120
	s_cmp_gt_i32 s28, 5
	ds_write2_b32 v25, v31, v27 offset0:12 offset1:28
	ds_write2_b32 v32, v20, v16 offset0:160 offset1:176
	ds_write2_b32 v24, v21, v17 offset0:36 offset1:52
	ds_write2_b32 v24, v22, v18 offset0:168 offset1:184
	ds_write2_b32 v25, v23, v19 offset0:44 offset1:60
	v_add_u32_e32 v16, 0x6000, v120
	v_or_b32_e32 v64, s29, v121
	s_cselect_b64 s[30:31], -1, 0
	s_ashr_i32 s29, s28, 31
	ds_write2_b32 v16, v12, v8 offset0:192 offset1:208
	v_add_u32_e32 v8, 0x6400, v120
	s_cmp_gt_i32 s28, 3
	ds_write2_b32 v8, v13, v9 offset0:68 offset1:84
	ds_write2_b32 v8, v14, v10 offset0:200 offset1:216
	v_add_u32_e32 v9, 0x6800, v120
	s_cselect_b64 s[34:35], -1, 0
	s_lshl_b64 s[28:29], s[28:29], 2
	ds_write2_b32 v9, v15, v11 offset0:76 offset1:92
	ds_write2_b32 v16, v4, v0 offset0:224 offset1:240
	ds_write2_b32 v8, v5, v1 offset0:100 offset1:116
	ds_write2_b32 v8, v6, v2 offset0:232 offset1:248
	ds_write2_b32 v9, v7, v3 offset0:108 offset1:124
	v_ashrrev_i32_e32 v1, 31, v64
	v_mov_b32_e32 v0, v64
	v_lshlrev_b64 v[2:3], 1, v[64:65]
	s_add_u32 s28, s40, s28
	v_cmp_gt_u32_e64 s[8:9], s44, v64
	v_lshl_add_u64 v[16:17], s[16:17], 0, v[2:3]
	s_addc_u32 s29, s41, s29
	v_lshl_add_u64 v[18:19], s[14:15], 0, v[2:3]
	v_lshl_add_u64 v[20:21], v[0:1], 1, s[12:13]
	v_add_u32_e32 v22, s36, v129
	s_mov_b32 s50, 0
	s_waitcnt lgkmcnt(0)
	s_barrier
	s_branch .LBB0_2273

.LBB0_2292:
	s_and_b32 s24, s23, 0x4000
	s_xor_b32 s25, s24, 0x4000
	s_lshl_b32 s25, s25, 1
	s_add_i32 s25, s25, 32
	s_add_u32 s90, s52, s8
	s_addc_u32 s91, s53, s9
	s_add_i32 m0, s25, s82
	s_lshl_b32 s24, s24, 1
	global_load_lds_dwordx4 v184, s[90:91]
	s_add_i32 m0, s25, s83
	s_add_i32 s24, s24, 32
	global_load_lds_dwordx4 v185, s[90:91]
	s_add_i32 m0, s25, s84
	v_lshl_add_u32 v64, v115, 1, s24
	global_load_lds_dwordx4 v186, s[90:91]
	s_add_i32 m0, s25, s85
	v_lshl_add_u32 v141, v116, 1, s24
	global_load_lds_dwordx4 v187, s[90:91]
	s_add_i32 m0, s25, s86
	v_add_u32_e32 v162, v64, v138
	global_load_lds_dwordx4 v188, s[90:91]
	s_add_i32 m0, s25, s87
	v_add_u32_e32 v170, v141, v138
	global_load_lds_dwordx4 v189, s[90:91]
	s_add_i32 m0, s25, s88
	s_addk_i32 s23, 0x4000
	global_load_lds_dwordx4 v190, s[90:91]
	s_add_i32 m0, s25, s89
	s_add_u32 s8, s8, 0x80
	s_addc_u32 s9, s9, 0
	global_load_lds_dwordx4 v191, s[90:91]
	ds_read_b128 v[142:145], v162
	ds_read_b128 v[150:153], v170 offset:16384
	ds_read_b128 v[154:157], v170 offset:18432
	ds_read_b128 v[166:169], v170 offset:20480
	ds_read_b128 v[170:173], v170 offset:22528
	ds_read_b128 v[146:149], v162 offset:2048
	ds_read_b128 v[158:161], v162 offset:4096
	ds_read_b128 v[162:165], v162 offset:6144
	s_setprio 1
	s_waitcnt lgkmcnt(3)
	v_mfma_f32_16x16x32_bf16 v[60:63], v[142:145], v[150:153], v[60:63]
	v_mfma_f32_16x16x32_bf16 v[56:59], v[142:145], v[154:157], v[56:59]
	v_mfma_f32_16x16x32_bf16 v[52:55], v[142:145], v[166:169], v[52:55]
	v_mfma_f32_16x16x32_bf16 v[48:51], v[142:145], v[170:173], v[48:51]
	s_waitcnt lgkmcnt(2)
	v_mfma_f32_16x16x32_bf16 v[44:47], v[146:149], v[150:153], v[44:47]
	v_mfma_f32_16x16x32_bf16 v[40:43], v[146:149], v[154:157], v[40:43]
	v_mfma_f32_16x16x32_bf16 v[36:39], v[146:149], v[166:169], v[36:39]
	v_mfma_f32_16x16x32_bf16 v[32:35], v[146:149], v[170:173], v[32:35]
	s_waitcnt lgkmcnt(1)
	v_mfma_f32_16x16x32_bf16 v[28:31], v[158:161], v[150:153], v[28:31]
	v_mfma_f32_16x16x32_bf16 v[24:27], v[158:161], v[154:157], v[24:27]
	v_mfma_f32_16x16x32_bf16 v[20:23], v[158:161], v[166:169], v[20:23]
	v_mfma_f32_16x16x32_bf16 v[16:19], v[158:161], v[170:173], v[16:19]
	s_waitcnt lgkmcnt(0)
	v_mfma_f32_16x16x32_bf16 v[12:15], v[162:165], v[150:153], v[12:15]
	v_mfma_f32_16x16x32_bf16 v[8:11], v[162:165], v[154:157], v[8:11]
	v_mfma_f32_16x16x32_bf16 v[4:7], v[162:165], v[166:169], v[4:7]
	v_mfma_f32_16x16x32_bf16 v[0:3], v[162:165], v[170:173], v[0:3]
	s_setprio 0
	v_add_u32_e32 v64, v64, v139
	v_add_u32_e32 v141, v141, v139
	ds_read_b128 v[142:145], v64
	ds_read_b128 v[150:153], v141 offset:16384
	ds_read_b128 v[154:157], v141 offset:18432
	ds_read_b128 v[166:169], v141 offset:20480
	ds_read_b128 v[170:173], v141 offset:22528
	ds_read_b128 v[146:149], v64 offset:2048
	ds_read_b128 v[158:161], v64 offset:4096
	ds_read_b128 v[162:165], v64 offset:6144
	s_setprio 1
	s_waitcnt lgkmcnt(3)
	v_mfma_f32_16x16x32_bf16 v[60:63], v[142:145], v[150:153], v[60:63]
	v_mfma_f32_16x16x32_bf16 v[56:59], v[142:145], v[154:157], v[56:59]
	v_mfma_f32_16x16x32_bf16 v[52:55], v[142:145], v[166:169], v[52:55]
	v_mfma_f32_16x16x32_bf16 v[48:51], v[142:145], v[170:173], v[48:51]
	s_waitcnt lgkmcnt(2)
	v_mfma_f32_16x16x32_bf16 v[44:47], v[146:149], v[150:153], v[44:47]
	v_mfma_f32_16x16x32_bf16 v[40:43], v[146:149], v[154:157], v[40:43]
	v_mfma_f32_16x16x32_bf16 v[36:39], v[146:149], v[166:169], v[36:39]
	v_mfma_f32_16x16x32_bf16 v[32:35], v[146:149], v[170:173], v[32:35]
	s_waitcnt lgkmcnt(1)
	v_mfma_f32_16x16x32_bf16 v[28:31], v[158:161], v[150:153], v[28:31]
	v_mfma_f32_16x16x32_bf16 v[24:27], v[158:161], v[154:157], v[24:27]
	v_mfma_f32_16x16x32_bf16 v[20:23], v[158:161], v[166:169], v[20:23]
	v_mfma_f32_16x16x32_bf16 v[16:19], v[158:161], v[170:173], v[16:19]
	s_waitcnt lgkmcnt(0)
	v_mfma_f32_16x16x32_bf16 v[12:15], v[162:165], v[150:153], v[12:15]
	v_mfma_f32_16x16x32_bf16 v[8:11], v[162:165], v[154:157], v[8:11]
	v_mfma_f32_16x16x32_bf16 v[4:7], v[162:165], v[166:169], v[4:7]
	v_mfma_f32_16x16x32_bf16 v[0:3], v[162:165], v[170:173], v[0:3]
	s_setprio 0
	s_cmpk_eq_i32 s8, 0x780
	s_waitcnt vmcnt(0)
	s_barrier
	s_cbranch_scc0 .LBB0_2292
	ds_read_b128 v[90:93], v117 offset:55296
	ds_read_b128 v[94:97], v117 offset:53248
	ds_read_b128 v[98:101], v118 offset:38912
	ds_read_b128 v[102:105], v118 offset:36864
	ds_read_b128 v[142:145], v117 offset:51200
	ds_read_b128 v[146:149], v117 offset:49152
	ds_read_b128 v[150:153], v118 offset:34816
	ds_read_b128 v[154:157], v118 offset:32768
	s_setprio 1
	s_waitcnt lgkmcnt(4)
	v_mfma_f32_16x16x32_bf16 v[20:23], v[102:105], v[94:97], v[20:23]
	v_mfma_f32_16x16x32_bf16 v[16:19], v[102:105], v[90:93], v[16:19]
	s_waitcnt lgkmcnt(0)
	v_mfma_f32_16x16x32_bf16 v[60:63], v[154:157], v[146:149], v[60:63]
	v_mfma_f32_16x16x32_bf16 v[56:59], v[154:157], v[142:145], v[56:59]
	v_mfma_f32_16x16x32_bf16 v[52:55], v[154:157], v[94:97], v[52:55]
	v_mfma_f32_16x16x32_bf16 v[48:51], v[154:157], v[90:93], v[48:51]
	v_mfma_f32_16x16x32_bf16 v[44:47], v[150:153], v[146:149], v[44:47]
	v_mfma_f32_16x16x32_bf16 v[40:43], v[150:153], v[142:145], v[40:43]
	v_mfma_f32_16x16x32_bf16 v[36:39], v[150:153], v[94:97], v[36:39]
	v_mfma_f32_16x16x32_bf16 v[32:35], v[150:153], v[90:93], v[32:35]
	v_mfma_f32_16x16x32_bf16 v[28:31], v[102:105], v[146:149], v[28:31]
	v_mfma_f32_16x16x32_bf16 v[24:27], v[102:105], v[142:145], v[24:27]
	v_mfma_f32_16x16x32_bf16 v[12:15], v[98:101], v[146:149], v[12:15]
	v_mfma_f32_16x16x32_bf16 v[8:11], v[98:101], v[142:145], v[8:11]
	v_mfma_f32_16x16x32_bf16 v[4:7], v[98:101], v[94:97], v[4:7]
	v_mfma_f32_16x16x32_bf16 v[0:3], v[98:101], v[90:93], v[0:3]
	s_setprio 0
	ds_read_b128 v[90:93], v119 offset:32768
	ds_read_b128 v[94:97], v119 offset:34816
	ds_read_b128 v[98:101], v120 offset:49152
	ds_read_b128 v[102:105], v120 offset:51200
	ds_read_b128 v[142:145], v119 offset:36864
	ds_read_b128 v[146:149], v119 offset:38912
	ds_read_b128 v[150:153], v120 offset:53248
	ds_read_b128 v[154:157], v120 offset:55296
	s_setprio 1
	s_waitcnt lgkmcnt(1)
	v_mfma_f32_16x16x32_bf16 v[20:23], v[142:145], v[150:153], v[20:23]
	s_waitcnt lgkmcnt(0)
	v_mfma_f32_16x16x32_bf16 v[16:19], v[142:145], v[154:157], v[16:19]
	v_mfma_f32_16x16x32_bf16 v[60:63], v[90:93], v[98:101], v[60:63]
	v_mfma_f32_16x16x32_bf16 v[56:59], v[90:93], v[102:105], v[56:59]
	v_mfma_f32_16x16x32_bf16 v[52:55], v[90:93], v[150:153], v[52:55]
	v_mfma_f32_16x16x32_bf16 v[48:51], v[90:93], v[154:157], v[48:51]
	v_mfma_f32_16x16x32_bf16 v[44:47], v[94:97], v[98:101], v[44:47]
	v_mfma_f32_16x16x32_bf16 v[40:43], v[94:97], v[102:105], v[40:43]
	v_mfma_f32_16x16x32_bf16 v[36:39], v[94:97], v[150:153], v[36:39]
	v_mfma_f32_16x16x32_bf16 v[32:35], v[94:97], v[154:157], v[32:35]
	v_mfma_f32_16x16x32_bf16 v[28:31], v[142:145], v[98:101], v[28:31]
	v_mfma_f32_16x16x32_bf16 v[24:27], v[142:145], v[102:105], v[24:27]
	v_mfma_f32_16x16x32_bf16 v[12:15], v[146:149], v[98:101], v[12:15]
	v_mfma_f32_16x16x32_bf16 v[8:11], v[146:149], v[102:105], v[8:11]
	v_mfma_f32_16x16x32_bf16 v[4:7], v[146:149], v[150:153], v[4:7]
	v_mfma_f32_16x16x32_bf16 v[0:3], v[146:149], v[154:157], v[0:3]
	s_setprio 0
	s_barrier
	ds_write2_b32 v121, v60, v56 offset1:16
	ds_write2_b32 v121, v61, v57 offset0:132 offset1:148
	v_add_u32_e32 v56, 0x400, v121
	ds_write2_b32 v56, v62, v58 offset0:8 offset1:24
	ds_write2_b32 v56, v63, v59 offset0:140 offset1:156
	ds_write2_b32 v121, v52, v48 offset0:32 offset1:48
	ds_write2_b32 v121, v53, v49 offset0:164 offset1:180
	ds_write2_b32 v56, v54, v50 offset0:40 offset1:56
	ds_write2_b32 v56, v55, v51 offset0:172 offset1:188
	v_add_u32_e32 v48, 0x2000, v121
	ds_write2_b32 v48, v44, v40 offset0:64 offset1:80
	ds_write2_b32 v48, v45, v41 offset0:196 offset1:212
	v_add_u32_e32 v40, 0x2400, v121
	ds_write2_b32 v40, v46, v42 offset0:72 offset1:88
	ds_write2_b32 v40, v47, v43 offset0:204 offset1:220
	ds_write2_b32 v48, v36, v32 offset0:96 offset1:112
	ds_write2_b32 v48, v37, v33 offset0:228 offset1:244
	ds_write2_b32 v40, v38, v34 offset0:104 offset1:120
	ds_write2_b32 v40, v39, v35 offset0:236 offset1:252
	v_add_u32_e32 v32, 0x4000, v121
	ds_write2_b32 v32, v28, v24 offset0:128 offset1:144
	v_add_u32_e32 v24, 0x4400, v121
	s_ashr_i32 s26, s22, 7
	ds_write2_b32 v24, v29, v25 offset0:4 offset1:20
	ds_write2_b32 v24, v30, v26 offset0:136 offset1:152
	v_add_u32_e32 v25, 0x4800, v121
	s_cmp_gt_i32 s26, 5
	ds_write2_b32 v25, v31, v27 offset0:12 offset1:28
	ds_write2_b32 v32, v20, v16 offset0:160 offset1:176
	ds_write2_b32 v24, v21, v17 offset0:36 offset1:52
	ds_write2_b32 v24, v22, v18 offset0:168 offset1:184
	ds_write2_b32 v25, v23, v19 offset0:44 offset1:60
	v_add_u32_e32 v16, 0x6000, v121
	v_or_b32_e32 v64, s22, v122
	s_cselect_b64 s[22:23], -1, 0
	s_ashr_i32 s27, s26, 31
	ds_write2_b32 v16, v12, v8 offset0:192 offset1:208
	v_add_u32_e32 v8, 0x6400, v121
	s_cmp_gt_i32 s26, 3
	ds_write2_b32 v8, v13, v9 offset0:68 offset1:84
	ds_write2_b32 v8, v14, v10 offset0:200 offset1:216
	v_add_u32_e32 v9, 0x6800, v121
	s_cselect_b64 s[24:25], -1, 0
	s_lshl_b64 s[26:27], s[26:27], 2
	ds_write2_b32 v9, v15, v11 offset0:76 offset1:92
	ds_write2_b32 v16, v4, v0 offset0:224 offset1:240
	ds_write2_b32 v8, v5, v1 offset0:100 offset1:116
	ds_write2_b32 v8, v6, v2 offset0:232 offset1:248
	ds_write2_b32 v9, v7, v3 offset0:108 offset1:124
	v_ashrrev_i32_e32 v1, 31, v64
	v_mov_b32_e32 v0, v64
	v_lshlrev_b64 v[2:3], 1, v[64:65]
	s_add_u32 s26, s40, s26
	v_cmp_gt_u32_e64 s[8:9], s38, v64
	v_lshl_add_u64 v[16:17], s[16:17], 0, v[2:3]
	s_addc_u32 s27, s41, s27
	v_lshl_add_u64 v[18:19], s[14:15], 0, v[2:3]
	v_lshl_add_u64 v[20:21], v[0:1], 1, s[12:13]
	v_add_u32_e32 v22, s28, v131
	s_mov_b32 s43, 0
	s_waitcnt lgkmcnt(0)
	s_barrier
	s_branch .LBB0_2295

.LBB0_2976:
	s_and_b32 s28, s7, 0x4000
	s_xor_b32 s29, s28, 0x4000
	s_lshl_b32 s29, s29, 1
	s_add_i32 s29, s29, 32
	s_add_u32 s90, s52, s4
	s_addc_u32 s91, s53, s5
	s_add_i32 m0, s29, s82
	s_lshl_b32 s28, s28, 1
	global_load_lds_dwordx4 v184, s[90:91]
	s_add_i32 m0, s29, s83
	s_add_i32 s28, s28, 32
	global_load_lds_dwordx4 v185, s[90:91]
	s_add_i32 m0, s29, s84
	v_lshl_add_u32 v64, v114, 1, s28
	global_load_lds_dwordx4 v186, s[90:91]
	s_add_i32 m0, s29, s85
	v_lshl_add_u32 v170, v115, 1, s28
	global_load_lds_dwordx4 v187, s[90:91]
	s_add_i32 m0, s29, s86
	v_add_u32_e32 v158, v64, v136
	global_load_lds_dwordx4 v188, s[90:91]
	s_add_i32 m0, s29, s87
	v_add_u32_e32 v166, v170, v136
	global_load_lds_dwordx4 v189, s[90:91]
	s_add_i32 m0, s29, s88
	s_addk_i32 s7, 0x4000
	global_load_lds_dwordx4 v190, s[90:91]
	s_add_i32 m0, s29, s89
	s_add_u32 s4, s4, 0x80
	s_addc_u32 s5, s5, 0
	global_load_lds_dwordx4 v191, s[90:91]
	ds_read_b128 v[138:141], v158
	ds_read_b128 v[146:149], v166 offset:16384
	ds_read_b128 v[150:153], v166 offset:18432
	ds_read_b128 v[162:165], v166 offset:20480
	ds_read_b128 v[166:169], v166 offset:22528
	ds_read_b128 v[142:145], v158 offset:2048
	ds_read_b128 v[154:157], v158 offset:4096
	ds_read_b128 v[158:161], v158 offset:6144
	s_setprio 1
	s_waitcnt lgkmcnt(3)
	v_mfma_f32_16x16x32_bf16 v[60:63], v[138:141], v[146:149], v[60:63]
	v_mfma_f32_16x16x32_bf16 v[56:59], v[138:141], v[150:153], v[56:59]
	v_mfma_f32_16x16x32_bf16 v[52:55], v[138:141], v[162:165], v[52:55]
	v_mfma_f32_16x16x32_bf16 v[48:51], v[138:141], v[166:169], v[48:51]
	s_waitcnt lgkmcnt(2)
	v_mfma_f32_16x16x32_bf16 v[44:47], v[142:145], v[146:149], v[44:47]
	v_mfma_f32_16x16x32_bf16 v[40:43], v[142:145], v[150:153], v[40:43]
	v_mfma_f32_16x16x32_bf16 v[36:39], v[142:145], v[162:165], v[36:39]
	v_mfma_f32_16x16x32_bf16 v[32:35], v[142:145], v[166:169], v[32:35]
	s_waitcnt lgkmcnt(1)
	v_mfma_f32_16x16x32_bf16 v[28:31], v[154:157], v[146:149], v[28:31]
	v_mfma_f32_16x16x32_bf16 v[24:27], v[154:157], v[150:153], v[24:27]
	v_mfma_f32_16x16x32_bf16 v[20:23], v[154:157], v[162:165], v[20:23]
	v_mfma_f32_16x16x32_bf16 v[16:19], v[154:157], v[166:169], v[16:19]
	s_waitcnt lgkmcnt(0)
	v_mfma_f32_16x16x32_bf16 v[12:15], v[158:161], v[146:149], v[12:15]
	v_mfma_f32_16x16x32_bf16 v[8:11], v[158:161], v[150:153], v[8:11]
	v_mfma_f32_16x16x32_bf16 v[4:7], v[158:161], v[162:165], v[4:7]
	v_mfma_f32_16x16x32_bf16 v[0:3], v[158:161], v[166:169], v[0:3]
	s_setprio 0
	v_add_u32_e32 v64, v64, v137
	v_add_u32_e32 v166, v170, v137
	ds_read_b128 v[138:141], v64
	ds_read_b128 v[146:149], v166 offset:16384
	ds_read_b128 v[150:153], v166 offset:18432
	ds_read_b128 v[162:165], v166 offset:20480
	ds_read_b128 v[166:169], v166 offset:22528
	ds_read_b128 v[142:145], v64 offset:2048
	ds_read_b128 v[154:157], v64 offset:4096
	ds_read_b128 v[158:161], v64 offset:6144
	s_setprio 1
	s_waitcnt lgkmcnt(3)
	v_mfma_f32_16x16x32_bf16 v[60:63], v[138:141], v[146:149], v[60:63]
	v_mfma_f32_16x16x32_bf16 v[56:59], v[138:141], v[150:153], v[56:59]
	v_mfma_f32_16x16x32_bf16 v[52:55], v[138:141], v[162:165], v[52:55]
	v_mfma_f32_16x16x32_bf16 v[48:51], v[138:141], v[166:169], v[48:51]
	s_waitcnt lgkmcnt(2)
	v_mfma_f32_16x16x32_bf16 v[44:47], v[142:145], v[146:149], v[44:47]
	v_mfma_f32_16x16x32_bf16 v[40:43], v[142:145], v[150:153], v[40:43]
	v_mfma_f32_16x16x32_bf16 v[36:39], v[142:145], v[162:165], v[36:39]
	v_mfma_f32_16x16x32_bf16 v[32:35], v[142:145], v[166:169], v[32:35]
	s_waitcnt lgkmcnt(1)
	v_mfma_f32_16x16x32_bf16 v[28:31], v[154:157], v[146:149], v[28:31]
	v_mfma_f32_16x16x32_bf16 v[24:27], v[154:157], v[150:153], v[24:27]
	v_mfma_f32_16x16x32_bf16 v[20:23], v[154:157], v[162:165], v[20:23]
	v_mfma_f32_16x16x32_bf16 v[16:19], v[154:157], v[166:169], v[16:19]
	s_waitcnt lgkmcnt(0)
	v_mfma_f32_16x16x32_bf16 v[12:15], v[158:161], v[146:149], v[12:15]
	v_mfma_f32_16x16x32_bf16 v[8:11], v[158:161], v[150:153], v[8:11]
	v_mfma_f32_16x16x32_bf16 v[4:7], v[158:161], v[162:165], v[4:7]
	v_mfma_f32_16x16x32_bf16 v[0:3], v[158:161], v[166:169], v[0:3]
	s_setprio 0
	s_cmpk_eq_i32 s4, 0x780
	s_waitcnt vmcnt(0)
	s_barrier
	s_cbranch_scc0 .LBB0_2976
	ds_read_b128 v[90:93], v116 offset:55296
	ds_read_b128 v[94:97], v116 offset:53248
	ds_read_b128 v[98:101], v117 offset:38912
	ds_read_b128 v[102:105], v117 offset:36864
	ds_read_b128 v[138:141], v116 offset:51200
	ds_read_b128 v[142:145], v116 offset:49152
	ds_read_b128 v[146:149], v117 offset:34816
	ds_read_b128 v[150:153], v117 offset:32768
	s_setprio 1
	s_waitcnt lgkmcnt(3)
	v_mfma_f32_16x16x32_bf16 v[24:27], v[102:105], v[138:141], v[24:27]
	v_mfma_f32_16x16x32_bf16 v[20:23], v[102:105], v[94:97], v[20:23]
	v_mfma_f32_16x16x32_bf16 v[16:19], v[102:105], v[90:93], v[16:19]
	s_waitcnt lgkmcnt(0)
	v_mfma_f32_16x16x32_bf16 v[60:63], v[150:153], v[142:145], v[60:63]
	v_mfma_f32_16x16x32_bf16 v[56:59], v[150:153], v[138:141], v[56:59]
	v_mfma_f32_16x16x32_bf16 v[52:55], v[150:153], v[94:97], v[52:55]
	v_mfma_f32_16x16x32_bf16 v[48:51], v[150:153], v[90:93], v[48:51]
	v_mfma_f32_16x16x32_bf16 v[44:47], v[146:149], v[142:145], v[44:47]
	v_mfma_f32_16x16x32_bf16 v[40:43], v[146:149], v[138:141], v[40:43]
	v_mfma_f32_16x16x32_bf16 v[36:39], v[146:149], v[94:97], v[36:39]
	v_mfma_f32_16x16x32_bf16 v[32:35], v[146:149], v[90:93], v[32:35]
	v_mfma_f32_16x16x32_bf16 v[28:31], v[102:105], v[142:145], v[28:31]
	v_mfma_f32_16x16x32_bf16 v[12:15], v[98:101], v[142:145], v[12:15]
	v_mfma_f32_16x16x32_bf16 v[8:11], v[98:101], v[138:141], v[8:11]
	v_mfma_f32_16x16x32_bf16 v[4:7], v[98:101], v[94:97], v[4:7]
	v_mfma_f32_16x16x32_bf16 v[0:3], v[98:101], v[90:93], v[0:3]
	s_setprio 0
	ds_read_b128 v[90:93], v118 offset:32768
	ds_read_b128 v[94:97], v118 offset:34816
	ds_read_b128 v[98:101], v119 offset:49152
	ds_read_b128 v[102:105], v119 offset:51200
	ds_read_b128 v[138:141], v118 offset:36864
	ds_read_b128 v[142:145], v118 offset:38912
	ds_read_b128 v[146:149], v119 offset:53248
	ds_read_b128 v[150:153], v119 offset:55296
	s_setprio 1
	s_waitcnt lgkmcnt(3)
	v_mfma_f32_16x16x32_bf16 v[24:27], v[138:141], v[102:105], v[24:27]
	s_waitcnt lgkmcnt(1)
	v_mfma_f32_16x16x32_bf16 v[20:23], v[138:141], v[146:149], v[20:23]
	s_waitcnt lgkmcnt(0)
	v_mfma_f32_16x16x32_bf16 v[16:19], v[138:141], v[150:153], v[16:19]
	v_mfma_f32_16x16x32_bf16 v[60:63], v[90:93], v[98:101], v[60:63]
	v_mfma_f32_16x16x32_bf16 v[56:59], v[90:93], v[102:105], v[56:59]
	v_mfma_f32_16x16x32_bf16 v[52:55], v[90:93], v[146:149], v[52:55]
	v_mfma_f32_16x16x32_bf16 v[48:51], v[90:93], v[150:153], v[48:51]
	v_mfma_f32_16x16x32_bf16 v[44:47], v[94:97], v[98:101], v[44:47]
	v_mfma_f32_16x16x32_bf16 v[40:43], v[94:97], v[102:105], v[40:43]
	v_mfma_f32_16x16x32_bf16 v[36:39], v[94:97], v[146:149], v[36:39]
	v_mfma_f32_16x16x32_bf16 v[32:35], v[94:97], v[150:153], v[32:35]
	v_mfma_f32_16x16x32_bf16 v[28:31], v[138:141], v[98:101], v[28:31]
	v_mfma_f32_16x16x32_bf16 v[12:15], v[142:145], v[98:101], v[12:15]
	v_mfma_f32_16x16x32_bf16 v[8:11], v[142:145], v[102:105], v[8:11]
	v_mfma_f32_16x16x32_bf16 v[4:7], v[142:145], v[146:149], v[4:7]
	v_mfma_f32_16x16x32_bf16 v[0:3], v[142:145], v[150:153], v[0:3]
	s_setprio 0
	s_barrier
	ds_write2_b32 v120, v60, v56 offset1:16
	ds_write2_b32 v120, v61, v57 offset0:132 offset1:148
	v_add_u32_e32 v56, 0x400, v120
	ds_write2_b32 v56, v62, v58 offset0:8 offset1:24
	ds_write2_b32 v56, v63, v59 offset0:140 offset1:156
	ds_write2_b32 v120, v52, v48 offset0:32 offset1:48
	ds_write2_b32 v120, v53, v49 offset0:164 offset1:180
	ds_write2_b32 v56, v54, v50 offset0:40 offset1:56
	ds_write2_b32 v56, v55, v51 offset0:172 offset1:188
	v_add_u32_e32 v48, 0x2000, v120
	ds_write2_b32 v48, v44, v40 offset0:64 offset1:80
	ds_write2_b32 v48, v45, v41 offset0:196 offset1:212
	v_add_u32_e32 v40, 0x2400, v120
	ds_write2_b32 v40, v46, v42 offset0:72 offset1:88
	ds_write2_b32 v40, v47, v43 offset0:204 offset1:220
	ds_write2_b32 v48, v36, v32 offset0:96 offset1:112
	ds_write2_b32 v48, v37, v33 offset0:228 offset1:244
	ds_write2_b32 v40, v38, v34 offset0:104 offset1:120
	ds_write2_b32 v40, v39, v35 offset0:236 offset1:252
	v_add_u32_e32 v32, 0x4000, v120
	ds_write2_b32 v32, v28, v24 offset0:128 offset1:144
	v_add_u32_e32 v24, 0x4400, v120
	ds_write2_b32 v24, v29, v25 offset0:4 offset1:20
	ds_write2_b32 v24, v30, v26 offset0:136 offset1:152
	v_add_u32_e32 v25, 0x4800, v120
	ds_write2_b32 v25, v31, v27 offset0:12 offset1:28
	ds_write2_b32 v32, v20, v16 offset0:160 offset1:176
	ds_write2_b32 v24, v21, v17 offset0:36 offset1:52
	ds_write2_b32 v24, v22, v18 offset0:168 offset1:184
	ds_write2_b32 v25, v23, v19 offset0:44 offset1:60
	v_add_u32_e32 v16, 0x6000, v120
	ds_write2_b32 v16, v12, v8 offset0:192 offset1:208
	v_add_u32_e32 v8, 0x6400, v120
	s_cmpk_gt_u32 s6, 0x3ff
	ds_write2_b32 v8, v13, v9 offset0:68 offset1:84
	ds_write2_b32 v8, v14, v10 offset0:200 offset1:216
	v_add_u32_e32 v9, 0x6800, v120
	v_or_b32_e32 v64, s6, v121
	s_cselect_b64 s[28:29], -1, 0
	s_cmpk_gt_u32 s6, 0x7ff
	ds_write2_b32 v9, v15, v11 offset0:76 offset1:92
	ds_write2_b32 v16, v4, v0 offset0:224 offset1:240
	ds_write2_b32 v8, v5, v1 offset0:100 offset1:116
	ds_write2_b32 v8, v6, v2 offset0:232 offset1:248
	ds_write2_b32 v9, v7, v3 offset0:108 offset1:124
	s_cselect_b64 s[30:31], -1, 0
	s_cmpk_gt_u32 s6, 0xbff
	v_ashrrev_i32_e32 v1, 31, v64
	v_mov_b32_e32 v0, v64
	v_lshlrev_b64 v[2:3], 1, v[64:65]
	v_cmp_lt_i32_e64 s[4:5], s41, v64
	s_cselect_b64 s[34:35], -1, 0
	v_cmp_gt_u32_e64 s[6:7], s42, v64
	v_lshl_add_u64 v[16:17], v[64:65], 2, s[18:19]
	v_lshl_add_u64 v[18:19], s[16:17], 0, v[2:3]
	v_lshl_add_u64 v[20:21], s[14:15], 0, v[2:3]
	v_lshl_add_u64 v[22:23], s[12:13], 0, v[2:3]
	v_lshl_add_u64 v[24:25], v[0:1], 1, s[10:11]
	v_add_u32_e32 v26, s36, v129
	s_mov_b32 s44, 0
	s_waitcnt lgkmcnt(0)
	s_barrier
	s_branch .LBB0_2979

.LBB0_3008:
	s_and_b32 s22, s7, 0x4000
	s_xor_b32 s23, s22, 0x4000
	s_lshl_b32 s23, s23, 1
	s_add_i32 s23, s23, 32
	s_add_u32 s90, s52, s4
	s_addc_u32 s91, s53, s5
	s_add_i32 m0, s23, s82
	s_lshl_b32 s22, s22, 1
	global_load_lds_dwordx4 v184, s[90:91]
	s_add_i32 m0, s23, s83
	s_add_i32 s22, s22, 32
	global_load_lds_dwordx4 v185, s[90:91]
	s_add_i32 m0, s23, s84
	v_lshl_add_u32 v64, v115, 1, s22
	global_load_lds_dwordx4 v186, s[90:91]
	s_add_i32 m0, s23, s85
	v_lshl_add_u32 v168, v116, 1, s22
	global_load_lds_dwordx4 v187, s[90:91]
	s_add_i32 m0, s23, s86
	v_add_u32_e32 v156, v64, v133
	global_load_lds_dwordx4 v188, s[90:91]
	s_add_i32 m0, s23, s87
	v_add_u32_e32 v164, v168, v133
	global_load_lds_dwordx4 v189, s[90:91]
	s_add_i32 m0, s23, s88
	s_addk_i32 s7, 0x4000
	global_load_lds_dwordx4 v190, s[90:91]
	s_add_i32 m0, s23, s89
	s_add_u32 s4, s4, 0x80
	s_addc_u32 s5, s5, 0
	global_load_lds_dwordx4 v191, s[90:91]
	ds_read_b128 v[136:139], v156
	ds_read_b128 v[144:147], v164 offset:16384
	ds_read_b128 v[148:151], v164 offset:18432
	ds_read_b128 v[160:163], v164 offset:20480
	ds_read_b128 v[164:167], v164 offset:22528
	ds_read_b128 v[140:143], v156 offset:2048
	ds_read_b128 v[152:155], v156 offset:4096
	ds_read_b128 v[156:159], v156 offset:6144
	s_setprio 1
	s_waitcnt lgkmcnt(3)
	v_mfma_f32_16x16x32_bf16 v[60:63], v[136:139], v[144:147], v[60:63]
	v_mfma_f32_16x16x32_bf16 v[56:59], v[136:139], v[148:151], v[56:59]
	v_mfma_f32_16x16x32_bf16 v[52:55], v[136:139], v[160:163], v[52:55]
	v_mfma_f32_16x16x32_bf16 v[48:51], v[136:139], v[164:167], v[48:51]
	s_waitcnt lgkmcnt(2)
	v_mfma_f32_16x16x32_bf16 v[44:47], v[140:143], v[144:147], v[44:47]
	v_mfma_f32_16x16x32_bf16 v[40:43], v[140:143], v[148:151], v[40:43]
	v_mfma_f32_16x16x32_bf16 v[36:39], v[140:143], v[160:163], v[36:39]
	v_mfma_f32_16x16x32_bf16 v[32:35], v[140:143], v[164:167], v[32:35]
	s_waitcnt lgkmcnt(1)
	v_mfma_f32_16x16x32_bf16 v[28:31], v[152:155], v[144:147], v[28:31]
	v_mfma_f32_16x16x32_bf16 v[24:27], v[152:155], v[148:151], v[24:27]
	v_mfma_f32_16x16x32_bf16 v[20:23], v[152:155], v[160:163], v[20:23]
	v_mfma_f32_16x16x32_bf16 v[16:19], v[152:155], v[164:167], v[16:19]
	s_waitcnt lgkmcnt(0)
	v_mfma_f32_16x16x32_bf16 v[12:15], v[156:159], v[144:147], v[12:15]
	v_mfma_f32_16x16x32_bf16 v[8:11], v[156:159], v[148:151], v[8:11]
	v_mfma_f32_16x16x32_bf16 v[4:7], v[156:159], v[160:163], v[4:7]
	v_mfma_f32_16x16x32_bf16 v[0:3], v[156:159], v[164:167], v[0:3]
	s_setprio 0
	v_add_u32_e32 v64, v64, v134
	v_add_u32_e32 v164, v168, v134
	ds_read_b128 v[136:139], v64
	ds_read_b128 v[144:147], v164 offset:16384
	ds_read_b128 v[148:151], v164 offset:18432
	ds_read_b128 v[160:163], v164 offset:20480
	ds_read_b128 v[164:167], v164 offset:22528
	ds_read_b128 v[140:143], v64 offset:2048
	ds_read_b128 v[152:155], v64 offset:4096
	ds_read_b128 v[156:159], v64 offset:6144
	s_setprio 1
	s_waitcnt lgkmcnt(3)
	v_mfma_f32_16x16x32_bf16 v[60:63], v[136:139], v[144:147], v[60:63]
	v_mfma_f32_16x16x32_bf16 v[56:59], v[136:139], v[148:151], v[56:59]
	v_mfma_f32_16x16x32_bf16 v[52:55], v[136:139], v[160:163], v[52:55]
	v_mfma_f32_16x16x32_bf16 v[48:51], v[136:139], v[164:167], v[48:51]
	s_waitcnt lgkmcnt(2)
	v_mfma_f32_16x16x32_bf16 v[44:47], v[140:143], v[144:147], v[44:47]
	v_mfma_f32_16x16x32_bf16 v[40:43], v[140:143], v[148:151], v[40:43]
	v_mfma_f32_16x16x32_bf16 v[36:39], v[140:143], v[160:163], v[36:39]
	v_mfma_f32_16x16x32_bf16 v[32:35], v[140:143], v[164:167], v[32:35]
	s_waitcnt lgkmcnt(1)
	v_mfma_f32_16x16x32_bf16 v[28:31], v[152:155], v[144:147], v[28:31]
	v_mfma_f32_16x16x32_bf16 v[24:27], v[152:155], v[148:151], v[24:27]
	v_mfma_f32_16x16x32_bf16 v[20:23], v[152:155], v[160:163], v[20:23]
	v_mfma_f32_16x16x32_bf16 v[16:19], v[152:155], v[164:167], v[16:19]
	s_waitcnt lgkmcnt(0)
	v_mfma_f32_16x16x32_bf16 v[12:15], v[156:159], v[144:147], v[12:15]
	v_mfma_f32_16x16x32_bf16 v[8:11], v[156:159], v[148:151], v[8:11]
	v_mfma_f32_16x16x32_bf16 v[4:7], v[156:159], v[160:163], v[4:7]
	v_mfma_f32_16x16x32_bf16 v[0:3], v[156:159], v[164:167], v[0:3]
	s_setprio 0
	s_cmpk_eq_i32 s4, 0x780
	s_waitcnt vmcnt(0)
	s_barrier
	s_cbranch_scc0 .LBB0_3008
	ds_read_b128 v[90:93], v117 offset:55296
	ds_read_b128 v[94:97], v117 offset:53248
	ds_read_b128 v[98:101], v118 offset:38912
	ds_read_b128 v[102:105], v118 offset:36864
	ds_read_b128 v[136:139], v117 offset:51200
	ds_read_b128 v[140:143], v117 offset:49152
	ds_read_b128 v[144:147], v118 offset:34816
	ds_read_b128 v[148:151], v118 offset:32768
	s_setprio 1
	s_waitcnt lgkmcnt(3)
	v_mfma_f32_16x16x32_bf16 v[24:27], v[102:105], v[136:139], v[24:27]
	v_mfma_f32_16x16x32_bf16 v[20:23], v[102:105], v[94:97], v[20:23]
	v_mfma_f32_16x16x32_bf16 v[16:19], v[102:105], v[90:93], v[16:19]
	s_waitcnt lgkmcnt(0)
	v_mfma_f32_16x16x32_bf16 v[60:63], v[148:151], v[140:143], v[60:63]
	v_mfma_f32_16x16x32_bf16 v[56:59], v[148:151], v[136:139], v[56:59]
	v_mfma_f32_16x16x32_bf16 v[52:55], v[148:151], v[94:97], v[52:55]
	v_mfma_f32_16x16x32_bf16 v[48:51], v[148:151], v[90:93], v[48:51]
	v_mfma_f32_16x16x32_bf16 v[44:47], v[144:147], v[140:143], v[44:47]
	v_mfma_f32_16x16x32_bf16 v[40:43], v[144:147], v[136:139], v[40:43]
	v_mfma_f32_16x16x32_bf16 v[36:39], v[144:147], v[94:97], v[36:39]
	v_mfma_f32_16x16x32_bf16 v[32:35], v[144:147], v[90:93], v[32:35]
	v_mfma_f32_16x16x32_bf16 v[28:31], v[102:105], v[140:143], v[28:31]
	v_mfma_f32_16x16x32_bf16 v[12:15], v[98:101], v[140:143], v[12:15]
	v_mfma_f32_16x16x32_bf16 v[8:11], v[98:101], v[136:139], v[8:11]
	v_mfma_f32_16x16x32_bf16 v[4:7], v[98:101], v[94:97], v[4:7]
	v_mfma_f32_16x16x32_bf16 v[0:3], v[98:101], v[90:93], v[0:3]
	s_setprio 0
	ds_read_b128 v[90:93], v119 offset:32768
	ds_read_b128 v[94:97], v119 offset:34816
	ds_read_b128 v[98:101], v120 offset:49152
	ds_read_b128 v[102:105], v120 offset:51200
	ds_read_b128 v[136:139], v119 offset:36864
	ds_read_b128 v[140:143], v119 offset:38912
	ds_read_b128 v[144:147], v120 offset:53248
	ds_read_b128 v[148:151], v120 offset:55296
	s_setprio 1
	s_waitcnt lgkmcnt(3)
	v_mfma_f32_16x16x32_bf16 v[24:27], v[136:139], v[102:105], v[24:27]
	s_waitcnt lgkmcnt(1)
	v_mfma_f32_16x16x32_bf16 v[20:23], v[136:139], v[144:147], v[20:23]
	s_waitcnt lgkmcnt(0)
	v_mfma_f32_16x16x32_bf16 v[16:19], v[136:139], v[148:151], v[16:19]
	v_mfma_f32_16x16x32_bf16 v[60:63], v[90:93], v[98:101], v[60:63]
	v_mfma_f32_16x16x32_bf16 v[56:59], v[90:93], v[102:105], v[56:59]
	v_mfma_f32_16x16x32_bf16 v[52:55], v[90:93], v[144:147], v[52:55]
	v_mfma_f32_16x16x32_bf16 v[48:51], v[90:93], v[148:151], v[48:51]
	v_mfma_f32_16x16x32_bf16 v[44:47], v[94:97], v[98:101], v[44:47]
	v_mfma_f32_16x16x32_bf16 v[40:43], v[94:97], v[102:105], v[40:43]
	v_mfma_f32_16x16x32_bf16 v[36:39], v[94:97], v[144:147], v[36:39]
	v_mfma_f32_16x16x32_bf16 v[32:35], v[94:97], v[148:151], v[32:35]
	v_mfma_f32_16x16x32_bf16 v[28:31], v[136:139], v[98:101], v[28:31]
	v_mfma_f32_16x16x32_bf16 v[12:15], v[140:143], v[98:101], v[12:15]
	v_mfma_f32_16x16x32_bf16 v[8:11], v[140:143], v[102:105], v[8:11]
	v_mfma_f32_16x16x32_bf16 v[4:7], v[140:143], v[144:147], v[4:7]
	v_mfma_f32_16x16x32_bf16 v[0:3], v[140:143], v[148:151], v[0:3]
	s_setprio 0
	s_barrier
	ds_write2_b32 v121, v60, v56 offset1:16
	ds_write2_b32 v121, v61, v57 offset0:132 offset1:148
	v_add_u32_e32 v56, 0x400, v121
	ds_write2_b32 v56, v62, v58 offset0:8 offset1:24
	ds_write2_b32 v56, v63, v59 offset0:140 offset1:156
	ds_write2_b32 v121, v52, v48 offset0:32 offset1:48
	ds_write2_b32 v121, v53, v49 offset0:164 offset1:180
	ds_write2_b32 v56, v54, v50 offset0:40 offset1:56
	ds_write2_b32 v56, v55, v51 offset0:172 offset1:188
	v_add_u32_e32 v48, 0x2000, v121
	ds_write2_b32 v48, v44, v40 offset0:64 offset1:80
	ds_write2_b32 v48, v45, v41 offset0:196 offset1:212
	v_add_u32_e32 v40, 0x2400, v121
	ds_write2_b32 v40, v46, v42 offset0:72 offset1:88
	ds_write2_b32 v40, v47, v43 offset0:204 offset1:220
	ds_write2_b32 v48, v36, v32 offset0:96 offset1:112
	ds_write2_b32 v48, v37, v33 offset0:228 offset1:244
	ds_write2_b32 v40, v38, v34 offset0:104 offset1:120
	ds_write2_b32 v40, v39, v35 offset0:236 offset1:252
	v_add_u32_e32 v32, 0x4000, v121
	ds_write2_b32 v32, v28, v24 offset0:128 offset1:144
	v_add_u32_e32 v24, 0x4400, v121
	ds_write2_b32 v24, v29, v25 offset0:4 offset1:20
	ds_write2_b32 v24, v30, v26 offset0:136 offset1:152
	v_add_u32_e32 v25, 0x4800, v121
	ds_write2_b32 v25, v31, v27 offset0:12 offset1:28
	ds_write2_b32 v32, v20, v16 offset0:160 offset1:176
	ds_write2_b32 v24, v21, v17 offset0:36 offset1:52
	ds_write2_b32 v24, v22, v18 offset0:168 offset1:184
	ds_write2_b32 v25, v23, v19 offset0:44 offset1:60
	v_add_u32_e32 v16, 0x6000, v121
	ds_write2_b32 v16, v12, v8 offset0:192 offset1:208
	v_add_u32_e32 v8, 0x6400, v121
	s_cmpk_gt_u32 s6, 0x3ff
	ds_write2_b32 v8, v13, v9 offset0:68 offset1:84
	ds_write2_b32 v8, v14, v10 offset0:200 offset1:216
	v_add_u32_e32 v9, 0x6800, v121
	v_or_b32_e32 v64, s6, v122
	s_cselect_b64 s[22:23], -1, 0
	s_cmpk_gt_u32 s6, 0x7ff
	ds_write2_b32 v9, v15, v11 offset0:76 offset1:92
	ds_write2_b32 v16, v4, v0 offset0:224 offset1:240
	ds_write2_b32 v8, v5, v1 offset0:100 offset1:116
	ds_write2_b32 v8, v6, v2 offset0:232 offset1:248
	ds_write2_b32 v9, v7, v3 offset0:108 offset1:124
	s_cselect_b64 s[24:25], -1, 0
	s_cmpk_gt_u32 s6, 0xbff
	v_ashrrev_i32_e32 v1, 31, v64
	v_mov_b32_e32 v0, v64
	v_lshlrev_b64 v[2:3], 1, v[64:65]
	v_cmp_lt_i32_e64 s[4:5], s36, v64
	s_cselect_b64 s[26:27], -1, 0
	v_cmp_gt_u32_e64 s[6:7], s37, v64
	v_lshl_add_u64 v[16:17], v[64:65], 2, s[18:19]
	v_lshl_add_u64 v[18:19], s[16:17], 0, v[2:3]
	v_lshl_add_u64 v[20:21], s[14:15], 0, v[2:3]
	v_lshl_add_u64 v[22:23], s[12:13], 0, v[2:3]
	v_lshl_add_u64 v[24:25], v[0:1], 1, s[10:11]
	v_add_u32_e32 v26, v126, v135
	s_mov_b32 s38, 0
	s_waitcnt lgkmcnt(0)
	s_barrier
	s_branch .LBB0_3011

.LBB0_3222:
	s_and_b32 s27, s26, 0x4000
	s_xor_b32 s28, s27, 0x4000
	s_lshl_b32 s28, s28, 1
	s_add_i32 s28, s28, 32
	s_add_u32 s90, s52, s16
	s_addc_u32 s91, s53, s17
	s_add_i32 m0, s28, s82
	s_lshl_b32 s27, s27, 1
	global_load_lds_dwordx4 v184, s[90:91]
	s_add_i32 m0, s28, s83
	s_add_i32 s27, s27, 32
	global_load_lds_dwordx4 v185, s[90:91]
	s_add_i32 m0, s28, s84
	v_add3_u32 v139, s27, v114, v136
	global_load_lds_dwordx4 v186, s[90:91]
	s_add_i32 m0, s28, s85
	v_add3_u32 v172, s27, v115, v136
	global_load_lds_dwordx4 v187, s[90:91]
	s_add_i32 m0, s28, s86
	v_add_u32_e32 v160, v139, v137
	global_load_lds_dwordx4 v188, s[90:91]
	s_add_i32 m0, s28, s87
	v_add_u32_e32 v168, v172, v137
	global_load_lds_dwordx4 v189, s[90:91]
	s_add_i32 m0, s28, s88
	s_addk_i32 s26, 0x4000
	global_load_lds_dwordx4 v190, s[90:91]
	s_add_i32 m0, s28, s89
	s_add_u32 s16, s16, 0x80
	s_addc_u32 s17, s17, 0
	global_load_lds_dwordx4 v191, s[90:91]
	ds_read_b128 v[140:143], v160
	ds_read_b128 v[148:151], v168 offset:16384
	ds_read_b128 v[152:155], v168 offset:18432
	ds_read_b128 v[164:167], v168 offset:20480
	ds_read_b128 v[168:171], v168 offset:22528
	ds_read_b128 v[144:147], v160 offset:2048
	ds_read_b128 v[156:159], v160 offset:4096
	ds_read_b128 v[160:163], v160 offset:6144
	s_setprio 1
	s_waitcnt lgkmcnt(3)
	v_mfma_f32_16x16x32_bf16 v[60:63], v[140:143], v[148:151], v[60:63]
	v_mfma_f32_16x16x32_bf16 v[56:59], v[140:143], v[152:155], v[56:59]
	v_mfma_f32_16x16x32_bf16 v[52:55], v[140:143], v[164:167], v[52:55]
	v_mfma_f32_16x16x32_bf16 v[48:51], v[140:143], v[168:171], v[48:51]
	s_waitcnt lgkmcnt(2)
	v_mfma_f32_16x16x32_bf16 v[44:47], v[144:147], v[148:151], v[44:47]
	v_mfma_f32_16x16x32_bf16 v[40:43], v[144:147], v[152:155], v[40:43]
	v_mfma_f32_16x16x32_bf16 v[36:39], v[144:147], v[164:167], v[36:39]
	v_mfma_f32_16x16x32_bf16 v[32:35], v[144:147], v[168:171], v[32:35]
	s_waitcnt lgkmcnt(1)
	v_mfma_f32_16x16x32_bf16 v[28:31], v[156:159], v[148:151], v[28:31]
	v_mfma_f32_16x16x32_bf16 v[24:27], v[156:159], v[152:155], v[24:27]
	v_mfma_f32_16x16x32_bf16 v[20:23], v[156:159], v[164:167], v[20:23]
	v_mfma_f32_16x16x32_bf16 v[16:19], v[156:159], v[168:171], v[16:19]
	s_waitcnt lgkmcnt(0)
	v_mfma_f32_16x16x32_bf16 v[12:15], v[160:163], v[148:151], v[12:15]
	v_mfma_f32_16x16x32_bf16 v[8:11], v[160:163], v[152:155], v[8:11]
	v_mfma_f32_16x16x32_bf16 v[4:7], v[160:163], v[164:167], v[4:7]
	v_mfma_f32_16x16x32_bf16 v[0:3], v[160:163], v[168:171], v[0:3]
	s_setprio 0
	v_add_u32_e32 v139, v139, v138
	v_add_u32_e32 v168, v172, v138
	ds_read_b128 v[140:143], v139
	ds_read_b128 v[148:151], v168 offset:16384
	ds_read_b128 v[152:155], v168 offset:18432
	ds_read_b128 v[164:167], v168 offset:20480
	ds_read_b128 v[168:171], v168 offset:22528
	ds_read_b128 v[144:147], v139 offset:2048
	ds_read_b128 v[156:159], v139 offset:4096
	ds_read_b128 v[160:163], v139 offset:6144
	s_setprio 1
	s_waitcnt lgkmcnt(3)
	v_mfma_f32_16x16x32_bf16 v[60:63], v[140:143], v[148:151], v[60:63]
	v_mfma_f32_16x16x32_bf16 v[56:59], v[140:143], v[152:155], v[56:59]
	v_mfma_f32_16x16x32_bf16 v[52:55], v[140:143], v[164:167], v[52:55]
	v_mfma_f32_16x16x32_bf16 v[48:51], v[140:143], v[168:171], v[48:51]
	s_waitcnt lgkmcnt(2)
	v_mfma_f32_16x16x32_bf16 v[44:47], v[144:147], v[148:151], v[44:47]
	v_mfma_f32_16x16x32_bf16 v[40:43], v[144:147], v[152:155], v[40:43]
	v_mfma_f32_16x16x32_bf16 v[36:39], v[144:147], v[164:167], v[36:39]
	v_mfma_f32_16x16x32_bf16 v[32:35], v[144:147], v[168:171], v[32:35]
	s_waitcnt lgkmcnt(1)
	v_mfma_f32_16x16x32_bf16 v[28:31], v[156:159], v[148:151], v[28:31]
	v_mfma_f32_16x16x32_bf16 v[24:27], v[156:159], v[152:155], v[24:27]
	v_mfma_f32_16x16x32_bf16 v[20:23], v[156:159], v[164:167], v[20:23]
	v_mfma_f32_16x16x32_bf16 v[16:19], v[156:159], v[168:171], v[16:19]
	s_waitcnt lgkmcnt(0)
	v_mfma_f32_16x16x32_bf16 v[12:15], v[160:163], v[148:151], v[12:15]
	v_mfma_f32_16x16x32_bf16 v[8:11], v[160:163], v[152:155], v[8:11]
	v_mfma_f32_16x16x32_bf16 v[4:7], v[160:163], v[164:167], v[4:7]
	v_mfma_f32_16x16x32_bf16 v[0:3], v[160:163], v[168:171], v[0:3]
	s_setprio 0
	s_cmpk_eq_i32 s16, 0x780
	s_waitcnt vmcnt(0)
	s_barrier
	s_cbranch_scc0 .LBB0_3222
	ds_read_b128 v[90:93], v118 offset:55296
	ds_read_b128 v[94:97], v118 offset:53248
	ds_read_b128 v[98:101], v119 offset:38912
	ds_read_b128 v[102:105], v119 offset:36864
	ds_read_b128 v[140:143], v118 offset:51200
	ds_read_b128 v[144:147], v118 offset:49152
	ds_read_b128 v[148:151], v119 offset:34816
	ds_read_b128 v[152:155], v119 offset:32768
	s_setprio 1
	s_waitcnt lgkmcnt(5)
	v_mfma_f32_16x16x32_bf16 v[4:7], v[98:101], v[94:97], v[4:7]
	v_mfma_f32_16x16x32_bf16 v[0:3], v[98:101], v[90:93], v[0:3]
	s_waitcnt lgkmcnt(0)
	v_mfma_f32_16x16x32_bf16 v[60:63], v[152:155], v[144:147], v[60:63]
	v_mfma_f32_16x16x32_bf16 v[56:59], v[152:155], v[140:143], v[56:59]
	v_mfma_f32_16x16x32_bf16 v[52:55], v[152:155], v[94:97], v[52:55]
	v_mfma_f32_16x16x32_bf16 v[48:51], v[152:155], v[90:93], v[48:51]
	v_mfma_f32_16x16x32_bf16 v[44:47], v[148:151], v[144:147], v[44:47]
	v_mfma_f32_16x16x32_bf16 v[40:43], v[148:151], v[140:143], v[40:43]
	v_mfma_f32_16x16x32_bf16 v[36:39], v[148:151], v[94:97], v[36:39]
	v_mfma_f32_16x16x32_bf16 v[32:35], v[148:151], v[90:93], v[32:35]
	v_mfma_f32_16x16x32_bf16 v[28:31], v[102:105], v[144:147], v[28:31]
	v_mfma_f32_16x16x32_bf16 v[24:27], v[102:105], v[140:143], v[24:27]
	v_mfma_f32_16x16x32_bf16 v[20:23], v[102:105], v[94:97], v[20:23]
	v_mfma_f32_16x16x32_bf16 v[16:19], v[102:105], v[90:93], v[16:19]
	v_mfma_f32_16x16x32_bf16 v[12:15], v[98:101], v[144:147], v[12:15]
	v_mfma_f32_16x16x32_bf16 v[8:11], v[98:101], v[140:143], v[8:11]
	s_setprio 0
	ds_read_b128 v[90:93], v120 offset:32768
	ds_read_b128 v[94:97], v120 offset:34816
	ds_read_b128 v[98:101], v121 offset:49152
	ds_read_b128 v[102:105], v121 offset:51200
	ds_read_b128 v[140:143], v120 offset:36864
	ds_read_b128 v[144:147], v120 offset:38912
	ds_read_b128 v[148:151], v121 offset:53248
	ds_read_b128 v[152:155], v121 offset:55296
	s_setprio 1
	s_waitcnt lgkmcnt(1)
	v_mfma_f32_16x16x32_bf16 v[4:7], v[144:147], v[148:151], v[4:7]
	s_waitcnt lgkmcnt(0)
	v_mfma_f32_16x16x32_bf16 v[0:3], v[144:147], v[152:155], v[0:3]
	v_mfma_f32_16x16x32_bf16 v[60:63], v[90:93], v[98:101], v[60:63]
	v_mfma_f32_16x16x32_bf16 v[56:59], v[90:93], v[102:105], v[56:59]
	v_mfma_f32_16x16x32_bf16 v[52:55], v[90:93], v[148:151], v[52:55]
	v_mfma_f32_16x16x32_bf16 v[48:51], v[90:93], v[152:155], v[48:51]
	v_mfma_f32_16x16x32_bf16 v[44:47], v[94:97], v[98:101], v[44:47]
	v_mfma_f32_16x16x32_bf16 v[40:43], v[94:97], v[102:105], v[40:43]
	v_mfma_f32_16x16x32_bf16 v[36:39], v[94:97], v[148:151], v[36:39]
	v_mfma_f32_16x16x32_bf16 v[32:35], v[94:97], v[152:155], v[32:35]
	v_mfma_f32_16x16x32_bf16 v[28:31], v[140:143], v[98:101], v[28:31]
	v_mfma_f32_16x16x32_bf16 v[24:27], v[140:143], v[102:105], v[24:27]
	v_mfma_f32_16x16x32_bf16 v[20:23], v[140:143], v[148:151], v[20:23]
	v_mfma_f32_16x16x32_bf16 v[16:19], v[140:143], v[152:155], v[16:19]
	v_mfma_f32_16x16x32_bf16 v[12:15], v[144:147], v[98:101], v[12:15]
	v_mfma_f32_16x16x32_bf16 v[8:11], v[144:147], v[102:105], v[8:11]
	s_setprio 0
	s_barrier
	ds_write2_b32 v116, v60, v56 offset1:16
	ds_write2_b32 v116, v61, v57 offset0:132 offset1:148
	v_add_u32_e32 v56, 0x400, v116
	ds_write2_b32 v56, v62, v58 offset0:8 offset1:24
	ds_write2_b32 v56, v63, v59 offset0:140 offset1:156
	ds_write2_b32 v116, v52, v48 offset0:32 offset1:48
	ds_write2_b32 v116, v53, v49 offset0:164 offset1:180
	ds_write2_b32 v56, v54, v50 offset0:40 offset1:56
	ds_write2_b32 v56, v55, v51 offset0:172 offset1:188
	v_add_u32_e32 v48, 0x2000, v116
	ds_write2_b32 v48, v44, v40 offset0:64 offset1:80
	ds_write2_b32 v48, v45, v41 offset0:196 offset1:212
	v_add_u32_e32 v40, 0x2400, v116
	ds_write2_b32 v40, v46, v42 offset0:72 offset1:88
	ds_write2_b32 v40, v47, v43 offset0:204 offset1:220
	ds_write2_b32 v48, v36, v32 offset0:96 offset1:112
	ds_write2_b32 v48, v37, v33 offset0:228 offset1:244
	ds_write2_b32 v40, v38, v34 offset0:104 offset1:120
	ds_write2_b32 v40, v39, v35 offset0:236 offset1:252
	v_add_u32_e32 v32, 0x4000, v116
	ds_write2_b32 v32, v28, v24 offset0:128 offset1:144
	v_add_u32_e32 v24, 0x4400, v116
	ds_write2_b32 v24, v29, v25 offset0:4 offset1:20
	ds_write2_b32 v24, v30, v26 offset0:136 offset1:152
	v_add_u32_e32 v25, 0x4800, v116
	ds_write2_b32 v25, v31, v27 offset0:12 offset1:28
	ds_write2_b32 v32, v20, v16 offset0:160 offset1:176
	ds_write2_b32 v24, v21, v17 offset0:36 offset1:52
	ds_write2_b32 v24, v22, v18 offset0:168 offset1:184
	ds_write2_b32 v25, v23, v19 offset0:44 offset1:60
	v_add_u32_e32 v16, 0x6000, v116
	ds_write2_b32 v16, v12, v8 offset0:192 offset1:208
	v_add_u32_e32 v8, 0x6400, v116
	ds_write2_b32 v8, v13, v9 offset0:68 offset1:84
	ds_write2_b32 v8, v14, v10 offset0:200 offset1:216
	v_add_u32_e32 v9, 0x6800, v116
	ds_write2_b32 v9, v15, v11 offset0:76 offset1:92
	ds_write2_b32 v16, v4, v0 offset0:224 offset1:240
	ds_write2_b32 v8, v5, v1 offset0:100 offset1:116
	ds_write2_b32 v8, v6, v2 offset0:232 offset1:248
	ds_write2_b32 v9, v7, v3 offset0:108 offset1:124
	v_or_b32_e32 v0, s25, v117
	v_ashrrev_i32_e32 v1, 31, v0
	v_lshlrev_b64 v[2:3], 2, v[0:1]
	v_lshl_add_u64 v[0:1], s[14:15], 0, v[2:3]
	v_lshl_add_u64 v[2:3], s[6:7], 0, v[2:3]
	v_add_u32_e32 v4, s24, v129
	s_mov_b32 s16, 0
	s_waitcnt lgkmcnt(0)
	s_barrier

.LBB0_3231:
	s_and_b32 s23, s22, 0x4000
	s_xor_b32 s24, s23, 0x4000
	s_lshl_b32 s24, s24, 1
	s_add_i32 s24, s24, 32
	s_add_u32 s90, s52, s8
	s_addc_u32 s91, s53, s9
	s_add_i32 m0, s24, s82
	s_lshl_b32 s23, s23, 1
	global_load_lds_dwordx4 v184, s[90:91]
	s_add_i32 m0, s24, s83
	s_add_i32 s23, s23, 32
	global_load_lds_dwordx4 v185, s[90:91]
	s_add_i32 m0, s24, s84
	v_add3_u32 v170, s23, v112, v135
	global_load_lds_dwordx4 v186, s[90:91]
	s_add_i32 m0, s24, s85
	v_add3_u32 v171, s23, v113, v135
	global_load_lds_dwordx4 v187, s[90:91]
	s_add_i32 m0, s24, s86
	v_add_u32_e32 v158, v170, v136
	global_load_lds_dwordx4 v188, s[90:91]
	s_add_i32 m0, s24, s87
	v_add_u32_e32 v166, v171, v136
	global_load_lds_dwordx4 v189, s[90:91]
	s_add_i32 m0, s24, s88
	s_addk_i32 s22, 0x4000
	global_load_lds_dwordx4 v190, s[90:91]
	s_add_i32 m0, s24, s89
	s_add_u32 s8, s8, 0x80
	s_addc_u32 s9, s9, 0
	global_load_lds_dwordx4 v191, s[90:91]
	ds_read_b128 v[138:141], v158
	ds_read_b128 v[146:149], v166 offset:16384
	ds_read_b128 v[150:153], v166 offset:18432
	ds_read_b128 v[162:165], v166 offset:20480
	ds_read_b128 v[166:169], v166 offset:22528
	ds_read_b128 v[142:145], v158 offset:2048
	ds_read_b128 v[154:157], v158 offset:4096
	ds_read_b128 v[158:161], v158 offset:6144
	s_setprio 1
	s_waitcnt lgkmcnt(3)
	v_mfma_f32_16x16x32_bf16 v[60:63], v[138:141], v[146:149], v[60:63]
	v_mfma_f32_16x16x32_bf16 v[56:59], v[138:141], v[150:153], v[56:59]
	v_mfma_f32_16x16x32_bf16 v[52:55], v[138:141], v[162:165], v[52:55]
	v_mfma_f32_16x16x32_bf16 v[48:51], v[138:141], v[166:169], v[48:51]
	s_waitcnt lgkmcnt(2)
	v_mfma_f32_16x16x32_bf16 v[44:47], v[142:145], v[146:149], v[44:47]
	v_mfma_f32_16x16x32_bf16 v[40:43], v[142:145], v[150:153], v[40:43]
	v_mfma_f32_16x16x32_bf16 v[36:39], v[142:145], v[162:165], v[36:39]
	v_mfma_f32_16x16x32_bf16 v[32:35], v[142:145], v[166:169], v[32:35]
	s_waitcnt lgkmcnt(1)
	v_mfma_f32_16x16x32_bf16 v[28:31], v[154:157], v[146:149], v[28:31]
	v_mfma_f32_16x16x32_bf16 v[24:27], v[154:157], v[150:153], v[24:27]
	v_mfma_f32_16x16x32_bf16 v[20:23], v[154:157], v[162:165], v[20:23]
	v_mfma_f32_16x16x32_bf16 v[16:19], v[154:157], v[166:169], v[16:19]
	s_waitcnt lgkmcnt(0)
	v_mfma_f32_16x16x32_bf16 v[12:15], v[158:161], v[146:149], v[12:15]
	v_mfma_f32_16x16x32_bf16 v[8:11], v[158:161], v[150:153], v[8:11]
	v_mfma_f32_16x16x32_bf16 v[4:7], v[158:161], v[162:165], v[4:7]
	v_mfma_f32_16x16x32_bf16 v[0:3], v[158:161], v[166:169], v[0:3]
	s_setprio 0
	v_add_u32_e32 v158, v170, v137
	v_add_u32_e32 v166, v171, v137
	ds_read_b128 v[138:141], v158
	ds_read_b128 v[146:149], v166 offset:16384
	ds_read_b128 v[150:153], v166 offset:18432
	ds_read_b128 v[162:165], v166 offset:20480
	ds_read_b128 v[166:169], v166 offset:22528
	ds_read_b128 v[142:145], v158 offset:2048
	ds_read_b128 v[154:157], v158 offset:4096
	ds_read_b128 v[158:161], v158 offset:6144
	s_setprio 1
	s_waitcnt lgkmcnt(3)
	v_mfma_f32_16x16x32_bf16 v[60:63], v[138:141], v[146:149], v[60:63]
	v_mfma_f32_16x16x32_bf16 v[56:59], v[138:141], v[150:153], v[56:59]
	v_mfma_f32_16x16x32_bf16 v[52:55], v[138:141], v[162:165], v[52:55]
	v_mfma_f32_16x16x32_bf16 v[48:51], v[138:141], v[166:169], v[48:51]
	s_waitcnt lgkmcnt(2)
	v_mfma_f32_16x16x32_bf16 v[44:47], v[142:145], v[146:149], v[44:47]
	v_mfma_f32_16x16x32_bf16 v[40:43], v[142:145], v[150:153], v[40:43]
	v_mfma_f32_16x16x32_bf16 v[36:39], v[142:145], v[162:165], v[36:39]
	v_mfma_f32_16x16x32_bf16 v[32:35], v[142:145], v[166:169], v[32:35]
	s_waitcnt lgkmcnt(1)
	v_mfma_f32_16x16x32_bf16 v[28:31], v[154:157], v[146:149], v[28:31]
	v_mfma_f32_16x16x32_bf16 v[24:27], v[154:157], v[150:153], v[24:27]
	v_mfma_f32_16x16x32_bf16 v[20:23], v[154:157], v[162:165], v[20:23]
	v_mfma_f32_16x16x32_bf16 v[16:19], v[154:157], v[166:169], v[16:19]
	s_waitcnt lgkmcnt(0)
	v_mfma_f32_16x16x32_bf16 v[12:15], v[158:161], v[146:149], v[12:15]
	v_mfma_f32_16x16x32_bf16 v[8:11], v[158:161], v[150:153], v[8:11]
	v_mfma_f32_16x16x32_bf16 v[4:7], v[158:161], v[162:165], v[4:7]
	v_mfma_f32_16x16x32_bf16 v[0:3], v[158:161], v[166:169], v[0:3]
	s_setprio 0
	s_cmpk_eq_i32 s8, 0x780
	s_waitcnt vmcnt(0)
	s_barrier
	s_cbranch_scc0 .LBB0_3231
	ds_read_b128 v[88:91], v116 offset:55296
	ds_read_b128 v[92:95], v116 offset:53248
	ds_read_b128 v[96:99], v117 offset:38912
	ds_read_b128 v[100:103], v117 offset:36864
	ds_read_b128 v[138:141], v116 offset:51200
	ds_read_b128 v[142:145], v116 offset:49152
	ds_read_b128 v[146:149], v117 offset:34816
	ds_read_b128 v[150:153], v117 offset:32768
	s_setprio 1
	s_waitcnt lgkmcnt(5)
	v_mfma_f32_16x16x32_bf16 v[4:7], v[96:99], v[92:95], v[4:7]
	v_mfma_f32_16x16x32_bf16 v[0:3], v[96:99], v[88:91], v[0:3]
	s_waitcnt lgkmcnt(0)
	v_mfma_f32_16x16x32_bf16 v[60:63], v[150:153], v[142:145], v[60:63]
	v_mfma_f32_16x16x32_bf16 v[56:59], v[150:153], v[138:141], v[56:59]
	v_mfma_f32_16x16x32_bf16 v[52:55], v[150:153], v[92:95], v[52:55]
	v_mfma_f32_16x16x32_bf16 v[48:51], v[150:153], v[88:91], v[48:51]
	v_mfma_f32_16x16x32_bf16 v[44:47], v[146:149], v[142:145], v[44:47]
	v_mfma_f32_16x16x32_bf16 v[40:43], v[146:149], v[138:141], v[40:43]
	v_mfma_f32_16x16x32_bf16 v[36:39], v[146:149], v[92:95], v[36:39]
	v_mfma_f32_16x16x32_bf16 v[32:35], v[146:149], v[88:91], v[32:35]
	v_mfma_f32_16x16x32_bf16 v[28:31], v[100:103], v[142:145], v[28:31]
	v_mfma_f32_16x16x32_bf16 v[24:27], v[100:103], v[138:141], v[24:27]
	v_mfma_f32_16x16x32_bf16 v[20:23], v[100:103], v[92:95], v[20:23]
	v_mfma_f32_16x16x32_bf16 v[16:19], v[100:103], v[88:91], v[16:19]
	v_mfma_f32_16x16x32_bf16 v[12:15], v[96:99], v[142:145], v[12:15]
	v_mfma_f32_16x16x32_bf16 v[8:11], v[96:99], v[138:141], v[8:11]
	s_setprio 0
	ds_read_b128 v[88:91], v118 offset:32768
	ds_read_b128 v[92:95], v118 offset:34816
	ds_read_b128 v[96:99], v119 offset:49152
	ds_read_b128 v[100:103], v119 offset:51200
	ds_read_b128 v[138:141], v118 offset:36864
	ds_read_b128 v[142:145], v118 offset:38912
	ds_read_b128 v[146:149], v119 offset:53248
	ds_read_b128 v[150:153], v119 offset:55296
	s_setprio 1
	s_waitcnt lgkmcnt(1)
	v_mfma_f32_16x16x32_bf16 v[4:7], v[142:145], v[146:149], v[4:7]
	s_waitcnt lgkmcnt(0)
	v_mfma_f32_16x16x32_bf16 v[0:3], v[142:145], v[150:153], v[0:3]
	v_mfma_f32_16x16x32_bf16 v[60:63], v[88:91], v[96:99], v[60:63]
	v_mfma_f32_16x16x32_bf16 v[56:59], v[88:91], v[100:103], v[56:59]
	v_mfma_f32_16x16x32_bf16 v[52:55], v[88:91], v[146:149], v[52:55]
	v_mfma_f32_16x16x32_bf16 v[48:51], v[88:91], v[150:153], v[48:51]
	v_mfma_f32_16x16x32_bf16 v[44:47], v[92:95], v[96:99], v[44:47]
	v_mfma_f32_16x16x32_bf16 v[40:43], v[92:95], v[100:103], v[40:43]
	v_mfma_f32_16x16x32_bf16 v[36:39], v[92:95], v[146:149], v[36:39]
	v_mfma_f32_16x16x32_bf16 v[32:35], v[92:95], v[150:153], v[32:35]
	v_mfma_f32_16x16x32_bf16 v[28:31], v[138:141], v[96:99], v[28:31]
	v_mfma_f32_16x16x32_bf16 v[24:27], v[138:141], v[100:103], v[24:27]
	v_mfma_f32_16x16x32_bf16 v[20:23], v[138:141], v[146:149], v[20:23]
	v_mfma_f32_16x16x32_bf16 v[16:19], v[138:141], v[150:153], v[16:19]
	v_mfma_f32_16x16x32_bf16 v[12:15], v[142:145], v[96:99], v[12:15]
	v_mfma_f32_16x16x32_bf16 v[8:11], v[142:145], v[100:103], v[8:11]
	s_setprio 0
	s_barrier
	ds_write2_b32 v114, v60, v56 offset1:16
	ds_write2_b32 v114, v61, v57 offset0:132 offset1:148
	v_add_u32_e32 v56, 0x400, v114
	ds_write2_b32 v56, v62, v58 offset0:8 offset1:24
	ds_write2_b32 v56, v63, v59 offset0:140 offset1:156
	ds_write2_b32 v114, v52, v48 offset0:32 offset1:48
	ds_write2_b32 v114, v53, v49 offset0:164 offset1:180
	ds_write2_b32 v56, v54, v50 offset0:40 offset1:56
	ds_write2_b32 v56, v55, v51 offset0:172 offset1:188
	v_add_u32_e32 v48, 0x2000, v114
	ds_write2_b32 v48, v44, v40 offset0:64 offset1:80
	ds_write2_b32 v48, v45, v41 offset0:196 offset1:212
	v_add_u32_e32 v40, 0x2400, v114
	ds_write2_b32 v40, v46, v42 offset0:72 offset1:88
	ds_write2_b32 v40, v47, v43 offset0:204 offset1:220
	ds_write2_b32 v48, v36, v32 offset0:96 offset1:112
	ds_write2_b32 v48, v37, v33 offset0:228 offset1:244
	ds_write2_b32 v40, v38, v34 offset0:104 offset1:120
	ds_write2_b32 v40, v39, v35 offset0:236 offset1:252
	v_add_u32_e32 v32, 0x4000, v114
	ds_write2_b32 v32, v28, v24 offset0:128 offset1:144
	v_add_u32_e32 v24, 0x4400, v114
	ds_write2_b32 v24, v29, v25 offset0:4 offset1:20
	ds_write2_b32 v24, v30, v26 offset0:136 offset1:152
	v_add_u32_e32 v25, 0x4800, v114
	ds_write2_b32 v25, v31, v27 offset0:12 offset1:28
	ds_write2_b32 v32, v20, v16 offset0:160 offset1:176
	ds_write2_b32 v24, v21, v17 offset0:36 offset1:52
	ds_write2_b32 v24, v22, v18 offset0:168 offset1:184
	ds_write2_b32 v25, v23, v19 offset0:44 offset1:60
	v_add_u32_e32 v16, 0x6000, v114
	ds_write2_b32 v16, v12, v8 offset0:192 offset1:208
	v_add_u32_e32 v8, 0x6400, v114
	ds_write2_b32 v8, v13, v9 offset0:68 offset1:84
	ds_write2_b32 v8, v14, v10 offset0:200 offset1:216
	v_add_u32_e32 v9, 0x6800, v114
	ds_write2_b32 v9, v15, v11 offset0:76 offset1:92
	ds_write2_b32 v16, v4, v0 offset0:224 offset1:240
	ds_write2_b32 v8, v5, v1 offset0:100 offset1:116
	ds_write2_b32 v8, v6, v2 offset0:232 offset1:248
	ds_write2_b32 v9, v7, v3 offset0:108 offset1:124
	v_or_b32_e32 v0, s21, v115
	v_ashrrev_i32_e32 v1, 31, v0
	v_lshlrev_b64 v[2:3], 2, v[0:1]
	v_lshl_add_u64 v[0:1], s[10:11], 0, v[2:3]
	v_lshl_add_u64 v[2:3], s[6:7], 0, v[2:3]
	v_add_u32_e32 v4, s20, v128
	s_mov_b32 s8, 0
	s_waitcnt lgkmcnt(0)
	s_barrier

.LBB0_3388:
	s_and_b32 s20, s19, 0x4000
	s_xor_b32 s21, s20, 0x4000
	s_lshl_b32 s21, s21, 1
	s_add_i32 s21, s21, 32
	s_add_u32 s90, s52, s12
	s_addc_u32 s91, s53, s13
	s_add_i32 m0, s21, s82
	s_lshl_b32 s20, s20, 1
	global_load_lds_dwordx4 v184, s[90:91]
	s_add_i32 m0, s21, s83
	s_add_i32 s20, s20, 32
	global_load_lds_dwordx4 v185, s[90:91]
	s_add_i32 m0, s21, s84
	v_lshl_add_u32 v170, v114, 1, s20
	global_load_lds_dwordx4 v186, s[90:91]
	s_add_i32 m0, s21, s85
	v_lshl_add_u32 v171, v115, 1, s20
	global_load_lds_dwordx4 v187, s[90:91]
	s_add_i32 m0, s21, s86
	v_add_u32_e32 v158, v170, v136
	global_load_lds_dwordx4 v188, s[90:91]
	s_add_i32 m0, s21, s87
	v_add_u32_e32 v166, v171, v136
	global_load_lds_dwordx4 v189, s[90:91]
	s_add_i32 m0, s21, s88
	s_addk_i32 s19, 0x4000
	global_load_lds_dwordx4 v190, s[90:91]
	s_add_i32 m0, s21, s89
	s_add_u32 s12, s12, 0x80
	s_addc_u32 s13, s13, 0
	global_load_lds_dwordx4 v191, s[90:91]
	ds_read_b128 v[138:141], v158
	ds_read_b128 v[146:149], v166 offset:16384
	ds_read_b128 v[150:153], v166 offset:18432
	ds_read_b128 v[162:165], v166 offset:20480
	ds_read_b128 v[166:169], v166 offset:22528
	ds_read_b128 v[142:145], v158 offset:2048
	ds_read_b128 v[154:157], v158 offset:4096
	ds_read_b128 v[158:161], v158 offset:6144
	s_setprio 1
	s_waitcnt lgkmcnt(3)
	v_mfma_f32_16x16x32_bf16 v[60:63], v[138:141], v[146:149], v[60:63]
	v_mfma_f32_16x16x32_bf16 v[56:59], v[138:141], v[150:153], v[56:59]
	v_mfma_f32_16x16x32_bf16 v[52:55], v[138:141], v[162:165], v[52:55]
	v_mfma_f32_16x16x32_bf16 v[48:51], v[138:141], v[166:169], v[48:51]
	s_waitcnt lgkmcnt(2)
	v_mfma_f32_16x16x32_bf16 v[44:47], v[142:145], v[146:149], v[44:47]
	v_mfma_f32_16x16x32_bf16 v[40:43], v[142:145], v[150:153], v[40:43]
	v_mfma_f32_16x16x32_bf16 v[36:39], v[142:145], v[162:165], v[36:39]
	v_mfma_f32_16x16x32_bf16 v[32:35], v[142:145], v[166:169], v[32:35]
	s_waitcnt lgkmcnt(1)
	v_mfma_f32_16x16x32_bf16 v[28:31], v[154:157], v[146:149], v[28:31]
	v_mfma_f32_16x16x32_bf16 v[24:27], v[154:157], v[150:153], v[24:27]
	v_mfma_f32_16x16x32_bf16 v[20:23], v[154:157], v[162:165], v[20:23]
	v_mfma_f32_16x16x32_bf16 v[16:19], v[154:157], v[166:169], v[16:19]
	s_waitcnt lgkmcnt(0)
	v_mfma_f32_16x16x32_bf16 v[12:15], v[158:161], v[146:149], v[12:15]
	v_mfma_f32_16x16x32_bf16 v[8:11], v[158:161], v[150:153], v[8:11]
	v_mfma_f32_16x16x32_bf16 v[4:7], v[158:161], v[162:165], v[4:7]
	v_mfma_f32_16x16x32_bf16 v[0:3], v[158:161], v[166:169], v[0:3]
	s_setprio 0
	v_add_u32_e32 v158, v170, v137
	v_add_u32_e32 v166, v171, v137
	ds_read_b128 v[138:141], v158
	ds_read_b128 v[146:149], v166 offset:16384
	ds_read_b128 v[150:153], v166 offset:18432
	ds_read_b128 v[162:165], v166 offset:20480
	ds_read_b128 v[166:169], v166 offset:22528
	ds_read_b128 v[142:145], v158 offset:2048
	ds_read_b128 v[154:157], v158 offset:4096
	ds_read_b128 v[158:161], v158 offset:6144
	s_setprio 1
	s_waitcnt lgkmcnt(3)
	v_mfma_f32_16x16x32_bf16 v[60:63], v[138:141], v[146:149], v[60:63]
	v_mfma_f32_16x16x32_bf16 v[56:59], v[138:141], v[150:153], v[56:59]
	v_mfma_f32_16x16x32_bf16 v[52:55], v[138:141], v[162:165], v[52:55]
	v_mfma_f32_16x16x32_bf16 v[48:51], v[138:141], v[166:169], v[48:51]
	s_waitcnt lgkmcnt(2)
	v_mfma_f32_16x16x32_bf16 v[44:47], v[142:145], v[146:149], v[44:47]
	v_mfma_f32_16x16x32_bf16 v[40:43], v[142:145], v[150:153], v[40:43]
	v_mfma_f32_16x16x32_bf16 v[36:39], v[142:145], v[162:165], v[36:39]
	v_mfma_f32_16x16x32_bf16 v[32:35], v[142:145], v[166:169], v[32:35]
	s_waitcnt lgkmcnt(1)
	v_mfma_f32_16x16x32_bf16 v[28:31], v[154:157], v[146:149], v[28:31]
	v_mfma_f32_16x16x32_bf16 v[24:27], v[154:157], v[150:153], v[24:27]
	v_mfma_f32_16x16x32_bf16 v[20:23], v[154:157], v[162:165], v[20:23]
	v_mfma_f32_16x16x32_bf16 v[16:19], v[154:157], v[166:169], v[16:19]
	s_waitcnt lgkmcnt(0)
	v_mfma_f32_16x16x32_bf16 v[12:15], v[158:161], v[146:149], v[12:15]
	v_mfma_f32_16x16x32_bf16 v[8:11], v[158:161], v[150:153], v[8:11]
	v_mfma_f32_16x16x32_bf16 v[4:7], v[158:161], v[162:165], v[4:7]
	v_mfma_f32_16x16x32_bf16 v[0:3], v[158:161], v[166:169], v[0:3]
	s_setprio 0
	s_cmpk_eq_i32 s12, 0x780
	s_waitcnt vmcnt(0)
	s_barrier
	s_cbranch_scc0 .LBB0_3388
	ds_read_b128 v[90:93], v116 offset:55296
	ds_read_b128 v[94:97], v116 offset:53248
	ds_read_b128 v[98:101], v117 offset:38912
	ds_read_b128 v[102:105], v117 offset:36864
	ds_read_b128 v[138:141], v116 offset:51200
	ds_read_b128 v[142:145], v116 offset:49152
	ds_read_b128 v[146:149], v117 offset:34816
	ds_read_b128 v[150:153], v117 offset:32768
	s_setprio 1
	s_waitcnt lgkmcnt(5)
	v_mfma_f32_16x16x32_bf16 v[0:3], v[98:101], v[90:93], v[0:3]
	s_waitcnt lgkmcnt(0)
	v_mfma_f32_16x16x32_bf16 v[60:63], v[150:153], v[142:145], v[60:63]
	v_mfma_f32_16x16x32_bf16 v[56:59], v[150:153], v[138:141], v[56:59]
	v_mfma_f32_16x16x32_bf16 v[52:55], v[150:153], v[94:97], v[52:55]
	v_mfma_f32_16x16x32_bf16 v[48:51], v[150:153], v[90:93], v[48:51]
	v_mfma_f32_16x16x32_bf16 v[44:47], v[146:149], v[142:145], v[44:47]
	v_mfma_f32_16x16x32_bf16 v[40:43], v[146:149], v[138:141], v[40:43]
	v_mfma_f32_16x16x32_bf16 v[36:39], v[146:149], v[94:97], v[36:39]
	v_mfma_f32_16x16x32_bf16 v[32:35], v[146:149], v[90:93], v[32:35]
	v_mfma_f32_16x16x32_bf16 v[28:31], v[102:105], v[142:145], v[28:31]
	v_mfma_f32_16x16x32_bf16 v[24:27], v[102:105], v[138:141], v[24:27]
	v_mfma_f32_16x16x32_bf16 v[20:23], v[102:105], v[94:97], v[20:23]
	v_mfma_f32_16x16x32_bf16 v[16:19], v[102:105], v[90:93], v[16:19]
	v_mfma_f32_16x16x32_bf16 v[12:15], v[98:101], v[142:145], v[12:15]
	v_mfma_f32_16x16x32_bf16 v[8:11], v[98:101], v[138:141], v[8:11]
	v_mfma_f32_16x16x32_bf16 v[4:7], v[98:101], v[94:97], v[4:7]
	s_setprio 0
	ds_read_b128 v[90:93], v118 offset:32768
	ds_read_b128 v[94:97], v118 offset:34816
	ds_read_b128 v[98:101], v119 offset:49152
	ds_read_b128 v[102:105], v119 offset:51200
	ds_read_b128 v[138:141], v118 offset:36864
	ds_read_b128 v[142:145], v118 offset:38912
	ds_read_b128 v[146:149], v119 offset:53248
	ds_read_b128 v[150:153], v119 offset:55296
	s_setprio 1
	s_waitcnt lgkmcnt(0)
	v_mfma_f32_16x16x32_bf16 v[0:3], v[142:145], v[150:153], v[0:3]
	v_mfma_f32_16x16x32_bf16 v[60:63], v[90:93], v[98:101], v[60:63]
	v_mfma_f32_16x16x32_bf16 v[56:59], v[90:93], v[102:105], v[56:59]
	v_mfma_f32_16x16x32_bf16 v[52:55], v[90:93], v[146:149], v[52:55]
	v_mfma_f32_16x16x32_bf16 v[48:51], v[90:93], v[150:153], v[48:51]
	v_mfma_f32_16x16x32_bf16 v[44:47], v[94:97], v[98:101], v[44:47]
	v_mfma_f32_16x16x32_bf16 v[40:43], v[94:97], v[102:105], v[40:43]
	v_mfma_f32_16x16x32_bf16 v[36:39], v[94:97], v[146:149], v[36:39]
	v_mfma_f32_16x16x32_bf16 v[32:35], v[94:97], v[150:153], v[32:35]
	v_mfma_f32_16x16x32_bf16 v[28:31], v[138:141], v[98:101], v[28:31]
	v_mfma_f32_16x16x32_bf16 v[24:27], v[138:141], v[102:105], v[24:27]
	v_mfma_f32_16x16x32_bf16 v[20:23], v[138:141], v[146:149], v[20:23]
	v_mfma_f32_16x16x32_bf16 v[16:19], v[138:141], v[150:153], v[16:19]
	v_mfma_f32_16x16x32_bf16 v[12:15], v[142:145], v[98:101], v[12:15]
	v_mfma_f32_16x16x32_bf16 v[8:11], v[142:145], v[102:105], v[8:11]
	v_mfma_f32_16x16x32_bf16 v[4:7], v[142:145], v[146:149], v[4:7]
	s_setprio 0
	s_barrier
	ds_write2_b32 v120, v60, v56 offset1:16
	ds_write2_b32 v120, v61, v57 offset0:132 offset1:148
	v_add_u32_e32 v56, 0x400, v120
	ds_write2_b32 v56, v62, v58 offset0:8 offset1:24
	ds_write2_b32 v56, v63, v59 offset0:140 offset1:156
	ds_write2_b32 v120, v52, v48 offset0:32 offset1:48
	ds_write2_b32 v120, v53, v49 offset0:164 offset1:180
	ds_write2_b32 v56, v54, v50 offset0:40 offset1:56
	ds_write2_b32 v56, v55, v51 offset0:172 offset1:188
	v_add_u32_e32 v48, 0x2000, v120
	ds_write2_b32 v48, v44, v40 offset0:64 offset1:80
	ds_write2_b32 v48, v45, v41 offset0:196 offset1:212
	v_add_u32_e32 v40, 0x2400, v120
	ds_write2_b32 v40, v46, v42 offset0:72 offset1:88
	ds_write2_b32 v40, v47, v43 offset0:204 offset1:220
	ds_write2_b32 v48, v36, v32 offset0:96 offset1:112
	ds_write2_b32 v48, v37, v33 offset0:228 offset1:244
	ds_write2_b32 v40, v38, v34 offset0:104 offset1:120
	ds_write2_b32 v40, v39, v35 offset0:236 offset1:252
	v_add_u32_e32 v32, 0x4000, v120
	ds_write2_b32 v32, v28, v24 offset0:128 offset1:144
	v_add_u32_e32 v24, 0x4400, v120
	ds_write2_b32 v24, v29, v25 offset0:4 offset1:20
	ds_write2_b32 v24, v30, v26 offset0:136 offset1:152
	v_add_u32_e32 v25, 0x4800, v120
	ds_write2_b32 v25, v31, v27 offset0:12 offset1:28
	ds_write2_b32 v32, v20, v16 offset0:160 offset1:176
	ds_write2_b32 v24, v21, v17 offset0:36 offset1:52
	ds_write2_b32 v24, v22, v18 offset0:168 offset1:184
	ds_write2_b32 v25, v23, v19 offset0:44 offset1:60
	v_add_u32_e32 v16, 0x6000, v120
	ds_write2_b32 v16, v12, v8 offset0:192 offset1:208
	v_add_u32_e32 v8, 0x6400, v120
	ds_write2_b32 v8, v13, v9 offset0:68 offset1:84
	ds_write2_b32 v8, v14, v10 offset0:200 offset1:216
	v_add_u32_e32 v9, 0x6800, v120
	ds_write2_b32 v9, v15, v11 offset0:76 offset1:92
	ds_write2_b32 v16, v4, v0 offset0:224 offset1:240
	ds_write2_b32 v8, v5, v1 offset0:100 offset1:116
	ds_write2_b32 v8, v6, v2 offset0:232 offset1:248
	ds_write2_b32 v9, v7, v3 offset0:108 offset1:124
	v_or_b32_e32 v0, s18, v121
	v_ashrrev_i32_e32 v1, 31, v0
	v_lshl_add_u64 v[0:1], v[0:1], 1, s[6:7]
	v_add_u32_e32 v2, s17, v129
	s_mov_b32 s12, 0
	s_waitcnt lgkmcnt(0)
	s_barrier

.LBB0_3399:
	s_and_b32 s18, s17, 0x4000
	s_xor_b32 s19, s18, 0x4000
	s_lshl_b32 s19, s19, 1
	s_add_i32 s19, s19, 32
	s_add_u32 s90, s52, s8
	s_addc_u32 s91, s53, s9
	s_add_i32 m0, s19, s82
	s_lshl_b32 s18, s18, 1
	global_load_lds_dwordx4 v184, s[90:91]
	s_add_i32 m0, s19, s83
	s_add_i32 s18, s18, 32
	global_load_lds_dwordx4 v185, s[90:91]
	s_add_i32 m0, s19, s84
	v_lshl_add_u32 v168, v112, 1, s18
	global_load_lds_dwordx4 v186, s[90:91]
	s_add_i32 m0, s19, s85
	v_lshl_add_u32 v169, v113, 1, s18
	global_load_lds_dwordx4 v187, s[90:91]
	s_add_i32 m0, s19, s86
	v_add_u32_e32 v156, v168, v134
	global_load_lds_dwordx4 v188, s[90:91]
	s_add_i32 m0, s19, s87
	v_add_u32_e32 v164, v169, v134
	global_load_lds_dwordx4 v189, s[90:91]
	s_add_i32 m0, s19, s88
	s_addk_i32 s17, 0x4000
	global_load_lds_dwordx4 v190, s[90:91]
	s_add_i32 m0, s19, s89
	s_add_u32 s8, s8, 0x80
	s_addc_u32 s9, s9, 0
	global_load_lds_dwordx4 v191, s[90:91]
	ds_read_b128 v[136:139], v156
	ds_read_b128 v[144:147], v164 offset:16384
	ds_read_b128 v[148:151], v164 offset:18432
	ds_read_b128 v[160:163], v164 offset:20480
	ds_read_b128 v[164:167], v164 offset:22528
	ds_read_b128 v[140:143], v156 offset:2048
	ds_read_b128 v[152:155], v156 offset:4096
	ds_read_b128 v[156:159], v156 offset:6144
	s_setprio 1
	s_waitcnt lgkmcnt(3)
	v_mfma_f32_16x16x32_bf16 v[60:63], v[136:139], v[144:147], v[60:63]
	v_mfma_f32_16x16x32_bf16 v[56:59], v[136:139], v[148:151], v[56:59]
	v_mfma_f32_16x16x32_bf16 v[52:55], v[136:139], v[160:163], v[52:55]
	v_mfma_f32_16x16x32_bf16 v[48:51], v[136:139], v[164:167], v[48:51]
	s_waitcnt lgkmcnt(2)
	v_mfma_f32_16x16x32_bf16 v[44:47], v[140:143], v[144:147], v[44:47]
	v_mfma_f32_16x16x32_bf16 v[40:43], v[140:143], v[148:151], v[40:43]
	v_mfma_f32_16x16x32_bf16 v[36:39], v[140:143], v[160:163], v[36:39]
	v_mfma_f32_16x16x32_bf16 v[32:35], v[140:143], v[164:167], v[32:35]
	s_waitcnt lgkmcnt(1)
	v_mfma_f32_16x16x32_bf16 v[28:31], v[152:155], v[144:147], v[28:31]
	v_mfma_f32_16x16x32_bf16 v[24:27], v[152:155], v[148:151], v[24:27]
	v_mfma_f32_16x16x32_bf16 v[20:23], v[152:155], v[160:163], v[20:23]
	v_mfma_f32_16x16x32_bf16 v[16:19], v[152:155], v[164:167], v[16:19]
	s_waitcnt lgkmcnt(0)
	v_mfma_f32_16x16x32_bf16 v[12:15], v[156:159], v[144:147], v[12:15]
	v_mfma_f32_16x16x32_bf16 v[8:11], v[156:159], v[148:151], v[8:11]
	v_mfma_f32_16x16x32_bf16 v[4:7], v[156:159], v[160:163], v[4:7]
	v_mfma_f32_16x16x32_bf16 v[0:3], v[156:159], v[164:167], v[0:3]
	s_setprio 0
	v_add_u32_e32 v156, v168, v135
	v_add_u32_e32 v164, v169, v135
	ds_read_b128 v[136:139], v156
	ds_read_b128 v[144:147], v164 offset:16384
	ds_read_b128 v[148:151], v164 offset:18432
	ds_read_b128 v[160:163], v164 offset:20480
	ds_read_b128 v[164:167], v164 offset:22528
	ds_read_b128 v[140:143], v156 offset:2048
	ds_read_b128 v[152:155], v156 offset:4096
	ds_read_b128 v[156:159], v156 offset:6144
	s_setprio 1
	s_waitcnt lgkmcnt(3)
	v_mfma_f32_16x16x32_bf16 v[60:63], v[136:139], v[144:147], v[60:63]
	v_mfma_f32_16x16x32_bf16 v[56:59], v[136:139], v[148:151], v[56:59]
	v_mfma_f32_16x16x32_bf16 v[52:55], v[136:139], v[160:163], v[52:55]
	v_mfma_f32_16x16x32_bf16 v[48:51], v[136:139], v[164:167], v[48:51]
	s_waitcnt lgkmcnt(2)
	v_mfma_f32_16x16x32_bf16 v[44:47], v[140:143], v[144:147], v[44:47]
	v_mfma_f32_16x16x32_bf16 v[40:43], v[140:143], v[148:151], v[40:43]
	v_mfma_f32_16x16x32_bf16 v[36:39], v[140:143], v[160:163], v[36:39]
	v_mfma_f32_16x16x32_bf16 v[32:35], v[140:143], v[164:167], v[32:35]
	s_waitcnt lgkmcnt(1)
	v_mfma_f32_16x16x32_bf16 v[28:31], v[152:155], v[144:147], v[28:31]
	v_mfma_f32_16x16x32_bf16 v[24:27], v[152:155], v[148:151], v[24:27]
	v_mfma_f32_16x16x32_bf16 v[20:23], v[152:155], v[160:163], v[20:23]
	v_mfma_f32_16x16x32_bf16 v[16:19], v[152:155], v[164:167], v[16:19]
	s_waitcnt lgkmcnt(0)
	v_mfma_f32_16x16x32_bf16 v[12:15], v[156:159], v[144:147], v[12:15]
	v_mfma_f32_16x16x32_bf16 v[8:11], v[156:159], v[148:151], v[8:11]
	v_mfma_f32_16x16x32_bf16 v[4:7], v[156:159], v[160:163], v[4:7]
	v_mfma_f32_16x16x32_bf16 v[0:3], v[156:159], v[164:167], v[0:3]
	s_setprio 0
	s_cmpk_eq_i32 s8, 0x780
	s_waitcnt vmcnt(0)
	s_barrier
	s_cbranch_scc0 .LBB0_3399
	ds_read_b128 v[88:91], v114 offset:55296
	ds_read_b128 v[92:95], v114 offset:53248
	ds_read_b128 v[96:99], v115 offset:38912
	ds_read_b128 v[100:103], v115 offset:36864
	ds_read_b128 v[136:139], v114 offset:51200
	ds_read_b128 v[140:143], v114 offset:49152
	ds_read_b128 v[144:147], v115 offset:34816
	ds_read_b128 v[148:151], v115 offset:32768
	s_setprio 1
	s_waitcnt lgkmcnt(5)
	v_mfma_f32_16x16x32_bf16 v[0:3], v[96:99], v[88:91], v[0:3]
	s_waitcnt lgkmcnt(0)
	v_mfma_f32_16x16x32_bf16 v[60:63], v[148:151], v[140:143], v[60:63]
	v_mfma_f32_16x16x32_bf16 v[56:59], v[148:151], v[136:139], v[56:59]
	v_mfma_f32_16x16x32_bf16 v[52:55], v[148:151], v[92:95], v[52:55]
	v_mfma_f32_16x16x32_bf16 v[48:51], v[148:151], v[88:91], v[48:51]
	v_mfma_f32_16x16x32_bf16 v[44:47], v[144:147], v[140:143], v[44:47]
	v_mfma_f32_16x16x32_bf16 v[40:43], v[144:147], v[136:139], v[40:43]
	v_mfma_f32_16x16x32_bf16 v[36:39], v[144:147], v[92:95], v[36:39]
	v_mfma_f32_16x16x32_bf16 v[32:35], v[144:147], v[88:91], v[32:35]
	v_mfma_f32_16x16x32_bf16 v[28:31], v[100:103], v[140:143], v[28:31]
	v_mfma_f32_16x16x32_bf16 v[24:27], v[100:103], v[136:139], v[24:27]
	v_mfma_f32_16x16x32_bf16 v[20:23], v[100:103], v[92:95], v[20:23]
	v_mfma_f32_16x16x32_bf16 v[16:19], v[100:103], v[88:91], v[16:19]
	v_mfma_f32_16x16x32_bf16 v[12:15], v[96:99], v[140:143], v[12:15]
	v_mfma_f32_16x16x32_bf16 v[8:11], v[96:99], v[136:139], v[8:11]
	v_mfma_f32_16x16x32_bf16 v[4:7], v[96:99], v[92:95], v[4:7]
	s_setprio 0
	ds_read_b128 v[88:91], v116 offset:32768
	ds_read_b128 v[92:95], v116 offset:34816
	ds_read_b128 v[96:99], v117 offset:49152
	ds_read_b128 v[100:103], v117 offset:51200
	ds_read_b128 v[136:139], v116 offset:36864
	ds_read_b128 v[140:143], v116 offset:38912
	ds_read_b128 v[144:147], v117 offset:53248
	ds_read_b128 v[148:151], v117 offset:55296
	s_setprio 1
	s_waitcnt lgkmcnt(0)
	v_mfma_f32_16x16x32_bf16 v[0:3], v[140:143], v[148:151], v[0:3]
	v_mfma_f32_16x16x32_bf16 v[60:63], v[88:91], v[96:99], v[60:63]
	v_mfma_f32_16x16x32_bf16 v[56:59], v[88:91], v[100:103], v[56:59]
	v_mfma_f32_16x16x32_bf16 v[52:55], v[88:91], v[144:147], v[52:55]
	v_mfma_f32_16x16x32_bf16 v[48:51], v[88:91], v[148:151], v[48:51]
	v_mfma_f32_16x16x32_bf16 v[44:47], v[92:95], v[96:99], v[44:47]
	v_mfma_f32_16x16x32_bf16 v[40:43], v[92:95], v[100:103], v[40:43]
	v_mfma_f32_16x16x32_bf16 v[36:39], v[92:95], v[144:147], v[36:39]
	v_mfma_f32_16x16x32_bf16 v[32:35], v[92:95], v[148:151], v[32:35]
	v_mfma_f32_16x16x32_bf16 v[28:31], v[136:139], v[96:99], v[28:31]
	v_mfma_f32_16x16x32_bf16 v[24:27], v[136:139], v[100:103], v[24:27]
	v_mfma_f32_16x16x32_bf16 v[20:23], v[136:139], v[144:147], v[20:23]
	v_mfma_f32_16x16x32_bf16 v[16:19], v[136:139], v[148:151], v[16:19]
	v_mfma_f32_16x16x32_bf16 v[12:15], v[140:143], v[96:99], v[12:15]
	v_mfma_f32_16x16x32_bf16 v[8:11], v[140:143], v[100:103], v[8:11]
	v_mfma_f32_16x16x32_bf16 v[4:7], v[140:143], v[144:147], v[4:7]
	s_setprio 0
	s_barrier
	ds_write2_b32 v118, v60, v56 offset1:16
	ds_write2_b32 v118, v61, v57 offset0:132 offset1:148
	v_add_u32_e32 v56, 0x400, v118
	ds_write2_b32 v56, v62, v58 offset0:8 offset1:24
	ds_write2_b32 v56, v63, v59 offset0:140 offset1:156
	ds_write2_b32 v118, v52, v48 offset0:32 offset1:48
	ds_write2_b32 v118, v53, v49 offset0:164 offset1:180
	ds_write2_b32 v56, v54, v50 offset0:40 offset1:56
	ds_write2_b32 v56, v55, v51 offset0:172 offset1:188
	v_add_u32_e32 v48, 0x2000, v118
	ds_write2_b32 v48, v44, v40 offset0:64 offset1:80
	ds_write2_b32 v48, v45, v41 offset0:196 offset1:212
	v_add_u32_e32 v40, 0x2400, v118
	ds_write2_b32 v40, v46, v42 offset0:72 offset1:88
	ds_write2_b32 v40, v47, v43 offset0:204 offset1:220
	ds_write2_b32 v48, v36, v32 offset0:96 offset1:112
	ds_write2_b32 v48, v37, v33 offset0:228 offset1:244
	ds_write2_b32 v40, v38, v34 offset0:104 offset1:120
	ds_write2_b32 v40, v39, v35 offset0:236 offset1:252
	v_add_u32_e32 v32, 0x4000, v118
	ds_write2_b32 v32, v28, v24 offset0:128 offset1:144
	v_add_u32_e32 v24, 0x4400, v118
	ds_write2_b32 v24, v29, v25 offset0:4 offset1:20
	ds_write2_b32 v24, v30, v26 offset0:136 offset1:152
	v_add_u32_e32 v25, 0x4800, v118
	ds_write2_b32 v25, v31, v27 offset0:12 offset1:28
	ds_write2_b32 v32, v20, v16 offset0:160 offset1:176
	ds_write2_b32 v24, v21, v17 offset0:36 offset1:52
	ds_write2_b32 v24, v22, v18 offset0:168 offset1:184
	ds_write2_b32 v25, v23, v19 offset0:44 offset1:60
	v_add_u32_e32 v16, 0x6000, v118
	ds_write2_b32 v16, v12, v8 offset0:192 offset1:208
	v_add_u32_e32 v8, 0x6400, v118
	ds_write2_b32 v8, v13, v9 offset0:68 offset1:84
	ds_write2_b32 v8, v14, v10 offset0:200 offset1:216
	v_add_u32_e32 v9, 0x6800, v118
	ds_write2_b32 v9, v15, v11 offset0:76 offset1:92
	ds_write2_b32 v16, v4, v0 offset0:224 offset1:240
	ds_write2_b32 v8, v5, v1 offset0:100 offset1:116
	ds_write2_b32 v8, v6, v2 offset0:232 offset1:248
	ds_write2_b32 v9, v7, v3 offset0:108 offset1:124
	v_or_b32_e32 v0, s16, v119
	v_ashrrev_i32_e32 v1, 31, v0
	v_lshl_add_u64 v[0:1], v[0:1], 1, s[6:7]
	v_add_u32_e32 v2, s15, v127
	s_mov_b32 s8, 0
	s_waitcnt lgkmcnt(0)
	s_barrier

.LBB0_3463:
	s_and_b32 s27, s26, 0x4000
	s_xor_b32 s28, s27, 0x4000
	s_lshl_b32 s28, s28, 1
	s_add_i32 s28, s28, 32
	s_add_u32 s90, s52, s16
	s_addc_u32 s91, s53, s17
	s_add_i32 m0, s28, s82
	s_lshl_b32 s27, s27, 1
	global_load_lds_dwordx4 v184, s[90:91]
	s_add_i32 m0, s28, s83
	s_add_i32 s27, s27, 32
	global_load_lds_dwordx4 v185, s[90:91]
	s_add_i32 m0, s28, s84
	v_add3_u32 v139, s27, v114, v136
	global_load_lds_dwordx4 v186, s[90:91]
	s_add_i32 m0, s28, s85
	v_add3_u32 v172, s27, v115, v136
	global_load_lds_dwordx4 v187, s[90:91]
	s_add_i32 m0, s28, s86
	v_add_u32_e32 v160, v139, v137
	global_load_lds_dwordx4 v188, s[90:91]
	s_add_i32 m0, s28, s87
	v_add_u32_e32 v168, v172, v137
	global_load_lds_dwordx4 v189, s[90:91]
	s_add_i32 m0, s28, s88
	s_addk_i32 s26, 0x4000
	global_load_lds_dwordx4 v190, s[90:91]
	s_add_i32 m0, s28, s89
	s_add_u32 s16, s16, 0x80
	s_addc_u32 s17, s17, 0
	global_load_lds_dwordx4 v191, s[90:91]
	ds_read_b128 v[140:143], v160
	ds_read_b128 v[148:151], v168 offset:16384
	ds_read_b128 v[152:155], v168 offset:18432
	ds_read_b128 v[164:167], v168 offset:20480
	ds_read_b128 v[168:171], v168 offset:22528
	ds_read_b128 v[144:147], v160 offset:2048
	ds_read_b128 v[156:159], v160 offset:4096
	ds_read_b128 v[160:163], v160 offset:6144
	s_setprio 1
	s_waitcnt lgkmcnt(3)
	v_mfma_f32_16x16x32_bf16 v[60:63], v[140:143], v[148:151], v[60:63]
	v_mfma_f32_16x16x32_bf16 v[56:59], v[140:143], v[152:155], v[56:59]
	v_mfma_f32_16x16x32_bf16 v[52:55], v[140:143], v[164:167], v[52:55]
	v_mfma_f32_16x16x32_bf16 v[48:51], v[140:143], v[168:171], v[48:51]
	s_waitcnt lgkmcnt(2)
	v_mfma_f32_16x16x32_bf16 v[44:47], v[144:147], v[148:151], v[44:47]
	v_mfma_f32_16x16x32_bf16 v[40:43], v[144:147], v[152:155], v[40:43]
	v_mfma_f32_16x16x32_bf16 v[36:39], v[144:147], v[164:167], v[36:39]
	v_mfma_f32_16x16x32_bf16 v[32:35], v[144:147], v[168:171], v[32:35]
	s_waitcnt lgkmcnt(1)
	v_mfma_f32_16x16x32_bf16 v[28:31], v[156:159], v[148:151], v[28:31]
	v_mfma_f32_16x16x32_bf16 v[24:27], v[156:159], v[152:155], v[24:27]
	v_mfma_f32_16x16x32_bf16 v[20:23], v[156:159], v[164:167], v[20:23]
	v_mfma_f32_16x16x32_bf16 v[16:19], v[156:159], v[168:171], v[16:19]
	s_waitcnt lgkmcnt(0)
	v_mfma_f32_16x16x32_bf16 v[12:15], v[160:163], v[148:151], v[12:15]
	v_mfma_f32_16x16x32_bf16 v[8:11], v[160:163], v[152:155], v[8:11]
	v_mfma_f32_16x16x32_bf16 v[4:7], v[160:163], v[164:167], v[4:7]
	v_mfma_f32_16x16x32_bf16 v[0:3], v[160:163], v[168:171], v[0:3]
	s_setprio 0
	v_add_u32_e32 v139, v139, v138
	v_add_u32_e32 v168, v172, v138
	ds_read_b128 v[140:143], v139
	ds_read_b128 v[148:151], v168 offset:16384
	ds_read_b128 v[152:155], v168 offset:18432
	ds_read_b128 v[164:167], v168 offset:20480
	ds_read_b128 v[168:171], v168 offset:22528
	ds_read_b128 v[144:147], v139 offset:2048
	ds_read_b128 v[156:159], v139 offset:4096
	ds_read_b128 v[160:163], v139 offset:6144
	s_setprio 1
	s_waitcnt lgkmcnt(3)
	v_mfma_f32_16x16x32_bf16 v[60:63], v[140:143], v[148:151], v[60:63]
	v_mfma_f32_16x16x32_bf16 v[56:59], v[140:143], v[152:155], v[56:59]
	v_mfma_f32_16x16x32_bf16 v[52:55], v[140:143], v[164:167], v[52:55]
	v_mfma_f32_16x16x32_bf16 v[48:51], v[140:143], v[168:171], v[48:51]
	s_waitcnt lgkmcnt(2)
	v_mfma_f32_16x16x32_bf16 v[44:47], v[144:147], v[148:151], v[44:47]
	v_mfma_f32_16x16x32_bf16 v[40:43], v[144:147], v[152:155], v[40:43]
	v_mfma_f32_16x16x32_bf16 v[36:39], v[144:147], v[164:167], v[36:39]
	v_mfma_f32_16x16x32_bf16 v[32:35], v[144:147], v[168:171], v[32:35]
	s_waitcnt lgkmcnt(1)
	v_mfma_f32_16x16x32_bf16 v[28:31], v[156:159], v[148:151], v[28:31]
	v_mfma_f32_16x16x32_bf16 v[24:27], v[156:159], v[152:155], v[24:27]
	v_mfma_f32_16x16x32_bf16 v[20:23], v[156:159], v[164:167], v[20:23]
	v_mfma_f32_16x16x32_bf16 v[16:19], v[156:159], v[168:171], v[16:19]
	s_waitcnt lgkmcnt(0)
	v_mfma_f32_16x16x32_bf16 v[12:15], v[160:163], v[148:151], v[12:15]
	v_mfma_f32_16x16x32_bf16 v[8:11], v[160:163], v[152:155], v[8:11]
	v_mfma_f32_16x16x32_bf16 v[4:7], v[160:163], v[164:167], v[4:7]
	v_mfma_f32_16x16x32_bf16 v[0:3], v[160:163], v[168:171], v[0:3]
	s_setprio 0
	s_cmpk_eq_i32 s16, 0x1f80
	s_waitcnt vmcnt(0)
	s_barrier
	s_cbranch_scc0 .LBB0_3463
	ds_read_b128 v[90:93], v118 offset:55296
	ds_read_b128 v[94:97], v118 offset:53248
	ds_read_b128 v[98:101], v119 offset:38912
	ds_read_b128 v[102:105], v119 offset:36864
	ds_read_b128 v[140:143], v118 offset:51200
	ds_read_b128 v[144:147], v118 offset:49152
	ds_read_b128 v[148:151], v119 offset:34816
	ds_read_b128 v[152:155], v119 offset:32768
	s_setprio 1
	s_waitcnt lgkmcnt(5)
	v_mfma_f32_16x16x32_bf16 v[4:7], v[98:101], v[94:97], v[4:7]
	v_mfma_f32_16x16x32_bf16 v[0:3], v[98:101], v[90:93], v[0:3]
	s_waitcnt lgkmcnt(0)
	v_mfma_f32_16x16x32_bf16 v[60:63], v[152:155], v[144:147], v[60:63]
	v_mfma_f32_16x16x32_bf16 v[56:59], v[152:155], v[140:143], v[56:59]
	v_mfma_f32_16x16x32_bf16 v[52:55], v[152:155], v[94:97], v[52:55]
	v_mfma_f32_16x16x32_bf16 v[48:51], v[152:155], v[90:93], v[48:51]
	v_mfma_f32_16x16x32_bf16 v[44:47], v[148:151], v[144:147], v[44:47]
	v_mfma_f32_16x16x32_bf16 v[40:43], v[148:151], v[140:143], v[40:43]
	v_mfma_f32_16x16x32_bf16 v[36:39], v[148:151], v[94:97], v[36:39]
	v_mfma_f32_16x16x32_bf16 v[32:35], v[148:151], v[90:93], v[32:35]
	v_mfma_f32_16x16x32_bf16 v[28:31], v[102:105], v[144:147], v[28:31]
	v_mfma_f32_16x16x32_bf16 v[24:27], v[102:105], v[140:143], v[24:27]
	v_mfma_f32_16x16x32_bf16 v[20:23], v[102:105], v[94:97], v[20:23]
	v_mfma_f32_16x16x32_bf16 v[16:19], v[102:105], v[90:93], v[16:19]
	v_mfma_f32_16x16x32_bf16 v[12:15], v[98:101], v[144:147], v[12:15]
	v_mfma_f32_16x16x32_bf16 v[8:11], v[98:101], v[140:143], v[8:11]
	s_setprio 0
	ds_read_b128 v[90:93], v120 offset:32768
	ds_read_b128 v[94:97], v120 offset:34816
	ds_read_b128 v[98:101], v121 offset:49152
	ds_read_b128 v[102:105], v121 offset:51200
	ds_read_b128 v[140:143], v120 offset:36864
	ds_read_b128 v[144:147], v120 offset:38912
	ds_read_b128 v[148:151], v121 offset:53248
	ds_read_b128 v[152:155], v121 offset:55296
	s_setprio 1
	s_waitcnt lgkmcnt(1)
	v_mfma_f32_16x16x32_bf16 v[4:7], v[144:147], v[148:151], v[4:7]
	s_waitcnt lgkmcnt(0)
	v_mfma_f32_16x16x32_bf16 v[0:3], v[144:147], v[152:155], v[0:3]
	v_mfma_f32_16x16x32_bf16 v[60:63], v[90:93], v[98:101], v[60:63]
	v_mfma_f32_16x16x32_bf16 v[56:59], v[90:93], v[102:105], v[56:59]
	v_mfma_f32_16x16x32_bf16 v[52:55], v[90:93], v[148:151], v[52:55]
	v_mfma_f32_16x16x32_bf16 v[48:51], v[90:93], v[152:155], v[48:51]
	v_mfma_f32_16x16x32_bf16 v[44:47], v[94:97], v[98:101], v[44:47]
	v_mfma_f32_16x16x32_bf16 v[40:43], v[94:97], v[102:105], v[40:43]
	v_mfma_f32_16x16x32_bf16 v[36:39], v[94:97], v[148:151], v[36:39]
	v_mfma_f32_16x16x32_bf16 v[32:35], v[94:97], v[152:155], v[32:35]
	v_mfma_f32_16x16x32_bf16 v[28:31], v[140:143], v[98:101], v[28:31]
	v_mfma_f32_16x16x32_bf16 v[24:27], v[140:143], v[102:105], v[24:27]
	v_mfma_f32_16x16x32_bf16 v[20:23], v[140:143], v[148:151], v[20:23]
	v_mfma_f32_16x16x32_bf16 v[16:19], v[140:143], v[152:155], v[16:19]
	v_mfma_f32_16x16x32_bf16 v[12:15], v[144:147], v[98:101], v[12:15]
	v_mfma_f32_16x16x32_bf16 v[8:11], v[144:147], v[102:105], v[8:11]
	s_setprio 0
	s_barrier
	ds_write2_b32 v116, v60, v56 offset1:16
	ds_write2_b32 v116, v61, v57 offset0:132 offset1:148
	v_add_u32_e32 v56, 0x400, v116
	ds_write2_b32 v56, v62, v58 offset0:8 offset1:24
	ds_write2_b32 v56, v63, v59 offset0:140 offset1:156
	ds_write2_b32 v116, v52, v48 offset0:32 offset1:48
	ds_write2_b32 v116, v53, v49 offset0:164 offset1:180
	ds_write2_b32 v56, v54, v50 offset0:40 offset1:56
	ds_write2_b32 v56, v55, v51 offset0:172 offset1:188
	v_add_u32_e32 v48, 0x2000, v116
	ds_write2_b32 v48, v44, v40 offset0:64 offset1:80
	ds_write2_b32 v48, v45, v41 offset0:196 offset1:212
	v_add_u32_e32 v40, 0x2400, v116
	ds_write2_b32 v40, v46, v42 offset0:72 offset1:88
	ds_write2_b32 v40, v47, v43 offset0:204 offset1:220
	ds_write2_b32 v48, v36, v32 offset0:96 offset1:112
	ds_write2_b32 v48, v37, v33 offset0:228 offset1:244
	ds_write2_b32 v40, v38, v34 offset0:104 offset1:120
	ds_write2_b32 v40, v39, v35 offset0:236 offset1:252
	v_add_u32_e32 v32, 0x4000, v116
	ds_write2_b32 v32, v28, v24 offset0:128 offset1:144
	v_add_u32_e32 v24, 0x4400, v116
	ds_write2_b32 v24, v29, v25 offset0:4 offset1:20
	ds_write2_b32 v24, v30, v26 offset0:136 offset1:152
	v_add_u32_e32 v25, 0x4800, v116
	ds_write2_b32 v25, v31, v27 offset0:12 offset1:28
	ds_write2_b32 v32, v20, v16 offset0:160 offset1:176
	ds_write2_b32 v24, v21, v17 offset0:36 offset1:52
	ds_write2_b32 v24, v22, v18 offset0:168 offset1:184
	ds_write2_b32 v25, v23, v19 offset0:44 offset1:60
	v_add_u32_e32 v16, 0x6000, v116
	ds_write2_b32 v16, v12, v8 offset0:192 offset1:208
	v_add_u32_e32 v8, 0x6400, v116
	ds_write2_b32 v8, v13, v9 offset0:68 offset1:84
	ds_write2_b32 v8, v14, v10 offset0:200 offset1:216
	v_add_u32_e32 v9, 0x6800, v116
	ds_write2_b32 v9, v15, v11 offset0:76 offset1:92
	ds_write2_b32 v16, v4, v0 offset0:224 offset1:240
	ds_write2_b32 v8, v5, v1 offset0:100 offset1:116
	ds_write2_b32 v8, v6, v2 offset0:232 offset1:248
	ds_write2_b32 v9, v7, v3 offset0:108 offset1:124
	v_or_b32_e32 v0, s25, v117
	v_ashrrev_i32_e32 v1, 31, v0
	v_lshlrev_b64 v[2:3], 2, v[0:1]
	v_lshl_add_u64 v[0:1], s[14:15], 0, v[2:3]
	v_lshl_add_u64 v[2:3], s[6:7], 0, v[2:3]
	v_add_u32_e32 v4, s24, v129
	s_mov_b32 s16, 0
	s_waitcnt lgkmcnt(0)
	s_barrier

.LBB0_3472:
	s_and_b32 s23, s22, 0x4000
	s_xor_b32 s24, s23, 0x4000
	s_lshl_b32 s24, s24, 1
	s_add_i32 s24, s24, 32
	s_add_u32 s90, s52, s8
	s_addc_u32 s91, s53, s9
	s_add_i32 m0, s24, s82
	s_lshl_b32 s23, s23, 1
	global_load_lds_dwordx4 v184, s[90:91]
	s_add_i32 m0, s24, s83
	s_add_i32 s23, s23, 32
	global_load_lds_dwordx4 v185, s[90:91]
	s_add_i32 m0, s24, s84
	v_add3_u32 v170, s23, v112, v135
	global_load_lds_dwordx4 v186, s[90:91]
	s_add_i32 m0, s24, s85
	v_add3_u32 v171, s23, v113, v135
	global_load_lds_dwordx4 v187, s[90:91]
	s_add_i32 m0, s24, s86
	v_add_u32_e32 v158, v170, v136
	global_load_lds_dwordx4 v188, s[90:91]
	s_add_i32 m0, s24, s87
	v_add_u32_e32 v166, v171, v136
	global_load_lds_dwordx4 v189, s[90:91]
	s_add_i32 m0, s24, s88
	s_addk_i32 s22, 0x4000
	global_load_lds_dwordx4 v190, s[90:91]
	s_add_i32 m0, s24, s89
	s_add_u32 s8, s8, 0x80
	s_addc_u32 s9, s9, 0
	global_load_lds_dwordx4 v191, s[90:91]
	ds_read_b128 v[138:141], v158
	ds_read_b128 v[146:149], v166 offset:16384
	ds_read_b128 v[150:153], v166 offset:18432
	ds_read_b128 v[162:165], v166 offset:20480
	ds_read_b128 v[166:169], v166 offset:22528
	ds_read_b128 v[142:145], v158 offset:2048
	ds_read_b128 v[154:157], v158 offset:4096
	ds_read_b128 v[158:161], v158 offset:6144
	s_setprio 1
	s_waitcnt lgkmcnt(3)
	v_mfma_f32_16x16x32_bf16 v[60:63], v[138:141], v[146:149], v[60:63]
	v_mfma_f32_16x16x32_bf16 v[56:59], v[138:141], v[150:153], v[56:59]
	v_mfma_f32_16x16x32_bf16 v[52:55], v[138:141], v[162:165], v[52:55]
	v_mfma_f32_16x16x32_bf16 v[48:51], v[138:141], v[166:169], v[48:51]
	s_waitcnt lgkmcnt(2)
	v_mfma_f32_16x16x32_bf16 v[44:47], v[142:145], v[146:149], v[44:47]
	v_mfma_f32_16x16x32_bf16 v[40:43], v[142:145], v[150:153], v[40:43]
	v_mfma_f32_16x16x32_bf16 v[36:39], v[142:145], v[162:165], v[36:39]
	v_mfma_f32_16x16x32_bf16 v[32:35], v[142:145], v[166:169], v[32:35]
	s_waitcnt lgkmcnt(1)
	v_mfma_f32_16x16x32_bf16 v[28:31], v[154:157], v[146:149], v[28:31]
	v_mfma_f32_16x16x32_bf16 v[24:27], v[154:157], v[150:153], v[24:27]
	v_mfma_f32_16x16x32_bf16 v[20:23], v[154:157], v[162:165], v[20:23]
	v_mfma_f32_16x16x32_bf16 v[16:19], v[154:157], v[166:169], v[16:19]
	s_waitcnt lgkmcnt(0)
	v_mfma_f32_16x16x32_bf16 v[12:15], v[158:161], v[146:149], v[12:15]
	v_mfma_f32_16x16x32_bf16 v[8:11], v[158:161], v[150:153], v[8:11]
	v_mfma_f32_16x16x32_bf16 v[4:7], v[158:161], v[162:165], v[4:7]
	v_mfma_f32_16x16x32_bf16 v[0:3], v[158:161], v[166:169], v[0:3]
	s_setprio 0
	v_add_u32_e32 v158, v170, v137
	v_add_u32_e32 v166, v171, v137
	ds_read_b128 v[138:141], v158
	ds_read_b128 v[146:149], v166 offset:16384
	ds_read_b128 v[150:153], v166 offset:18432
	ds_read_b128 v[162:165], v166 offset:20480
	ds_read_b128 v[166:169], v166 offset:22528
	ds_read_b128 v[142:145], v158 offset:2048
	ds_read_b128 v[154:157], v158 offset:4096
	ds_read_b128 v[158:161], v158 offset:6144
	s_setprio 1
	s_waitcnt lgkmcnt(3)
	v_mfma_f32_16x16x32_bf16 v[60:63], v[138:141], v[146:149], v[60:63]
	v_mfma_f32_16x16x32_bf16 v[56:59], v[138:141], v[150:153], v[56:59]
	v_mfma_f32_16x16x32_bf16 v[52:55], v[138:141], v[162:165], v[52:55]
	v_mfma_f32_16x16x32_bf16 v[48:51], v[138:141], v[166:169], v[48:51]
	s_waitcnt lgkmcnt(2)
	v_mfma_f32_16x16x32_bf16 v[44:47], v[142:145], v[146:149], v[44:47]
	v_mfma_f32_16x16x32_bf16 v[40:43], v[142:145], v[150:153], v[40:43]
	v_mfma_f32_16x16x32_bf16 v[36:39], v[142:145], v[162:165], v[36:39]
	v_mfma_f32_16x16x32_bf16 v[32:35], v[142:145], v[166:169], v[32:35]
	s_waitcnt lgkmcnt(1)
	v_mfma_f32_16x16x32_bf16 v[28:31], v[154:157], v[146:149], v[28:31]
	v_mfma_f32_16x16x32_bf16 v[24:27], v[154:157], v[150:153], v[24:27]
	v_mfma_f32_16x16x32_bf16 v[20:23], v[154:157], v[162:165], v[20:23]
	v_mfma_f32_16x16x32_bf16 v[16:19], v[154:157], v[166:169], v[16:19]
	s_waitcnt lgkmcnt(0)
	v_mfma_f32_16x16x32_bf16 v[12:15], v[158:161], v[146:149], v[12:15]
	v_mfma_f32_16x16x32_bf16 v[8:11], v[158:161], v[150:153], v[8:11]
	v_mfma_f32_16x16x32_bf16 v[4:7], v[158:161], v[162:165], v[4:7]
	v_mfma_f32_16x16x32_bf16 v[0:3], v[158:161], v[166:169], v[0:3]
	s_setprio 0
	s_cmpk_eq_i32 s8, 0x1f80
	s_waitcnt vmcnt(0)
	s_barrier
	s_cbranch_scc0 .LBB0_3472
	ds_read_b128 v[88:91], v116 offset:55296
	ds_read_b128 v[92:95], v116 offset:53248
	ds_read_b128 v[96:99], v117 offset:38912
	ds_read_b128 v[100:103], v117 offset:36864
	ds_read_b128 v[138:141], v116 offset:51200
	ds_read_b128 v[142:145], v116 offset:49152
	ds_read_b128 v[146:149], v117 offset:34816
	ds_read_b128 v[150:153], v117 offset:32768
	s_setprio 1
	s_waitcnt lgkmcnt(5)
	v_mfma_f32_16x16x32_bf16 v[4:7], v[96:99], v[92:95], v[4:7]
	v_mfma_f32_16x16x32_bf16 v[0:3], v[96:99], v[88:91], v[0:3]
	s_waitcnt lgkmcnt(0)
	v_mfma_f32_16x16x32_bf16 v[60:63], v[150:153], v[142:145], v[60:63]
	v_mfma_f32_16x16x32_bf16 v[56:59], v[150:153], v[138:141], v[56:59]
	v_mfma_f32_16x16x32_bf16 v[52:55], v[150:153], v[92:95], v[52:55]
	v_mfma_f32_16x16x32_bf16 v[48:51], v[150:153], v[88:91], v[48:51]
	v_mfma_f32_16x16x32_bf16 v[44:47], v[146:149], v[142:145], v[44:47]
	v_mfma_f32_16x16x32_bf16 v[40:43], v[146:149], v[138:141], v[40:43]
	v_mfma_f32_16x16x32_bf16 v[36:39], v[146:149], v[92:95], v[36:39]
	v_mfma_f32_16x16x32_bf16 v[32:35], v[146:149], v[88:91], v[32:35]
	v_mfma_f32_16x16x32_bf16 v[28:31], v[100:103], v[142:145], v[28:31]
	v_mfma_f32_16x16x32_bf16 v[24:27], v[100:103], v[138:141], v[24:27]
	v_mfma_f32_16x16x32_bf16 v[20:23], v[100:103], v[92:95], v[20:23]
	v_mfma_f32_16x16x32_bf16 v[16:19], v[100:103], v[88:91], v[16:19]
	v_mfma_f32_16x16x32_bf16 v[12:15], v[96:99], v[142:145], v[12:15]
	v_mfma_f32_16x16x32_bf16 v[8:11], v[96:99], v[138:141], v[8:11]
	s_setprio 0
	ds_read_b128 v[88:91], v118 offset:32768
	ds_read_b128 v[92:95], v118 offset:34816
	ds_read_b128 v[96:99], v119 offset:49152
	ds_read_b128 v[100:103], v119 offset:51200
	ds_read_b128 v[138:141], v118 offset:36864
	ds_read_b128 v[142:145], v118 offset:38912
	ds_read_b128 v[146:149], v119 offset:53248
	ds_read_b128 v[150:153], v119 offset:55296
	s_setprio 1
	s_waitcnt lgkmcnt(1)
	v_mfma_f32_16x16x32_bf16 v[4:7], v[142:145], v[146:149], v[4:7]
	s_waitcnt lgkmcnt(0)
	v_mfma_f32_16x16x32_bf16 v[0:3], v[142:145], v[150:153], v[0:3]
	v_mfma_f32_16x16x32_bf16 v[60:63], v[88:91], v[96:99], v[60:63]
	v_mfma_f32_16x16x32_bf16 v[56:59], v[88:91], v[100:103], v[56:59]
	v_mfma_f32_16x16x32_bf16 v[52:55], v[88:91], v[146:149], v[52:55]
	v_mfma_f32_16x16x32_bf16 v[48:51], v[88:91], v[150:153], v[48:51]
	v_mfma_f32_16x16x32_bf16 v[44:47], v[92:95], v[96:99], v[44:47]
	v_mfma_f32_16x16x32_bf16 v[40:43], v[92:95], v[100:103], v[40:43]
	v_mfma_f32_16x16x32_bf16 v[36:39], v[92:95], v[146:149], v[36:39]
	v_mfma_f32_16x16x32_bf16 v[32:35], v[92:95], v[150:153], v[32:35]
	v_mfma_f32_16x16x32_bf16 v[28:31], v[138:141], v[96:99], v[28:31]
	v_mfma_f32_16x16x32_bf16 v[24:27], v[138:141], v[100:103], v[24:27]
	v_mfma_f32_16x16x32_bf16 v[20:23], v[138:141], v[146:149], v[20:23]
	v_mfma_f32_16x16x32_bf16 v[16:19], v[138:141], v[150:153], v[16:19]
	v_mfma_f32_16x16x32_bf16 v[12:15], v[142:145], v[96:99], v[12:15]
	v_mfma_f32_16x16x32_bf16 v[8:11], v[142:145], v[100:103], v[8:11]
	s_setprio 0
	s_barrier
	ds_write2_b32 v114, v60, v56 offset1:16
	ds_write2_b32 v114, v61, v57 offset0:132 offset1:148
	v_add_u32_e32 v56, 0x400, v114
	ds_write2_b32 v56, v62, v58 offset0:8 offset1:24
	ds_write2_b32 v56, v63, v59 offset0:140 offset1:156
	ds_write2_b32 v114, v52, v48 offset0:32 offset1:48
	ds_write2_b32 v114, v53, v49 offset0:164 offset1:180
	ds_write2_b32 v56, v54, v50 offset0:40 offset1:56
	ds_write2_b32 v56, v55, v51 offset0:172 offset1:188
	v_add_u32_e32 v48, 0x2000, v114
	ds_write2_b32 v48, v44, v40 offset0:64 offset1:80
	ds_write2_b32 v48, v45, v41 offset0:196 offset1:212
	v_add_u32_e32 v40, 0x2400, v114
	ds_write2_b32 v40, v46, v42 offset0:72 offset1:88
	ds_write2_b32 v40, v47, v43 offset0:204 offset1:220
	ds_write2_b32 v48, v36, v32 offset0:96 offset1:112
	ds_write2_b32 v48, v37, v33 offset0:228 offset1:244
	ds_write2_b32 v40, v38, v34 offset0:104 offset1:120
	ds_write2_b32 v40, v39, v35 offset0:236 offset1:252
	v_add_u32_e32 v32, 0x4000, v114
	ds_write2_b32 v32, v28, v24 offset0:128 offset1:144
	v_add_u32_e32 v24, 0x4400, v114
	ds_write2_b32 v24, v29, v25 offset0:4 offset1:20
	ds_write2_b32 v24, v30, v26 offset0:136 offset1:152
	v_add_u32_e32 v25, 0x4800, v114
	ds_write2_b32 v25, v31, v27 offset0:12 offset1:28
	ds_write2_b32 v32, v20, v16 offset0:160 offset1:176
	ds_write2_b32 v24, v21, v17 offset0:36 offset1:52
	ds_write2_b32 v24, v22, v18 offset0:168 offset1:184
	ds_write2_b32 v25, v23, v19 offset0:44 offset1:60
	v_add_u32_e32 v16, 0x6000, v114
	ds_write2_b32 v16, v12, v8 offset0:192 offset1:208
	v_add_u32_e32 v8, 0x6400, v114
	ds_write2_b32 v8, v13, v9 offset0:68 offset1:84
	ds_write2_b32 v8, v14, v10 offset0:200 offset1:216
	v_add_u32_e32 v9, 0x6800, v114
	ds_write2_b32 v9, v15, v11 offset0:76 offset1:92
	ds_write2_b32 v16, v4, v0 offset0:224 offset1:240
	ds_write2_b32 v8, v5, v1 offset0:100 offset1:116
	ds_write2_b32 v8, v6, v2 offset0:232 offset1:248
	ds_write2_b32 v9, v7, v3 offset0:108 offset1:124
	v_or_b32_e32 v0, s21, v115
	v_ashrrev_i32_e32 v1, 31, v0
	v_lshlrev_b64 v[2:3], 2, v[0:1]
	v_lshl_add_u64 v[0:1], s[10:11], 0, v[2:3]
	v_lshl_add_u64 v[2:3], s[6:7], 0, v[2:3]
	v_add_u32_e32 v4, s20, v128
	s_mov_b32 s8, 0
	s_waitcnt lgkmcnt(0)
	s_barrier
